# added next-tile DMA prefetch in the tail K-steps for ffn_in/inproj
# baseline (speedup 1.0000x reference)
.LBB0_208:
	s_and_b32 s8, s66, 0xffffff80
	s_ashr_i32 s9, s8, 31
	s_lshl_b32 s7, s68, 11
	s_lshl_b64 s[8:9], s[8:9], 11
	s_and_b32 s20, s7, 0xfc0000
	s_add_i32 s2, s2, s3
	s_cmpk_gt_i32 s2, 0xc3f
	s_cselect_b64 s[54:55], -1, 0
	s_lshl_b32 s7, s2, 18
	s_and_b32 s7, s7, 0xfc0000
	s_add_u32 s7, s18, s7
	v_lshl_add_u64 v[126:127], v[114:115], 0, s[8:9]
	s_addc_u32 s10, s19, 0
	s_ashr_i32 s8, s2, 6
	s_ashr_i32 s9, s8, 31
	s_lshl_b64 s[8:9], s[8:9], 18
	v_lshl_add_u64 v[128:129], v[116:117], 0, s[20:21]
	s_add_u32 s20, s16, s8
	s_addc_u32 s11, s17, s9
	s_cmpk_lt_i32 s2, 0xc40
	s_cselect_b64 vcc, -1, 0
	s_and_b64 s[8:9], vcc, exec
	s_cselect_b32 s9, s10, 0
	s_cselect_b32 s8, s7, 0
	v_lshl_add_u64 v[2:3], s[8:9], 0, v[118:119]
	v_lshl_add_u64 v[0:1], v[122:123], 0, s[44:45]
	s_cselect_b32 s11, s11, 0
	s_cselect_b32 s10, s20, 0
	v_lshl_add_u64 v[2:3], v[2:3], 0, v[120:121]
	v_cndmask_b32_e32 v97, v1, v3, vcc
	v_cndmask_b32_e32 v98, v0, v2, vcc
	v_lshl_add_u64 v[0:1], s[10:11], 0, v[118:119]
	v_lshl_add_u64 v[0:1], v[0:1], 0, v[120:121]
	v_lshl_add_u64 v[2:3], v[124:125], 0, s[44:45]
	v_cndmask_b32_e32 v142, v2, v0, vcc
	v_mov_b32_e32 v0, 0
	v_lshl_add_u64 v[144:145], v[122:123], 0, s[28:29]
	v_lshl_add_u64 v[130:131], v[122:123], 0, s[30:31]
	v_lshl_add_u64 v[148:149], v[122:123], 0, s[34:35]
	v_lshl_add_u64 v[132:133], v[122:123], 0, s[36:37]
	v_lshl_add_u64 v[150:151], v[122:123], 0, s[38:39]
	v_lshl_add_u64 v[134:135], v[122:123], 0, s[40:41]
	v_lshl_add_u64 v[152:153], v[122:123], 0, s[42:43]
	v_lshl_add_u64 v[146:147], v[124:125], 0, s[28:29]
	v_lshl_add_u64 v[136:137], v[124:125], 0, s[30:31]
	v_lshl_add_u64 v[154:155], v[124:125], 0, s[34:35]
	v_lshl_add_u64 v[138:139], v[124:125], 0, s[36:37]
	v_lshl_add_u64 v[156:157], v[124:125], 0, s[38:39]
	v_lshl_add_u64 v[140:141], v[124:125], 0, s[40:41]
	v_lshl_add_u64 v[158:159], v[124:125], 0, s[42:43]
	v_cndmask_b32_e32 v143, v3, v1, vcc
	s_mov_b32 s7, -2
	v_mov_b32_e32 v1, v0
	v_mov_b32_e32 v2, v0
	v_mov_b32_e32 v3, v0
	v_mov_b32_e32 v20, v0
	v_mov_b32_e32 v21, v0
	v_mov_b32_e32 v22, v0
	v_mov_b32_e32 v23, v0
	v_mov_b32_e32 v24, v0
	v_mov_b32_e32 v25, v0
	v_mov_b32_e32 v26, v0
	v_mov_b32_e32 v27, v0
	v_mov_b32_e32 v32, v0
	v_mov_b32_e32 v33, v0
	v_mov_b32_e32 v34, v0
	v_mov_b32_e32 v35, v0
	v_mov_b32_e32 v8, v0
	v_mov_b32_e32 v9, v0
	v_mov_b32_e32 v10, v0
	v_mov_b32_e32 v11, v0
	v_mov_b32_e32 v4, v0
	v_mov_b32_e32 v5, v0
	v_mov_b32_e32 v6, v0
	v_mov_b32_e32 v7, v0
	v_mov_b32_e32 v12, v0
	v_mov_b32_e32 v13, v0
	v_mov_b32_e32 v14, v0
	v_mov_b32_e32 v15, v0
	v_mov_b32_e32 v16, v0
	v_mov_b32_e32 v17, v0
	v_mov_b32_e32 v18, v0
	v_mov_b32_e32 v19, v0
	v_mov_b32_e32 v28, v0
	v_mov_b32_e32 v29, v0
	v_mov_b32_e32 v30, v0
	v_mov_b32_e32 v31, v0
	v_mov_b32_e32 v36, v0
	v_mov_b32_e32 v37, v0
	v_mov_b32_e32 v38, v0
	v_mov_b32_e32 v39, v0
	v_mov_b32_e32 v40, v0
	v_mov_b32_e32 v41, v0
	v_mov_b32_e32 v42, v0
	v_mov_b32_e32 v43, v0
	v_mov_b32_e32 v44, v0
	v_mov_b32_e32 v45, v0
	v_mov_b32_e32 v46, v0
	v_mov_b32_e32 v47, v0
	v_mov_b32_e32 v48, v0
	v_mov_b32_e32 v49, v0
	v_mov_b32_e32 v50, v0
	v_mov_b32_e32 v51, v0
	v_mov_b32_e32 v52, v0
	v_mov_b32_e32 v53, v0
	v_mov_b32_e32 v54, v0
	v_mov_b32_e32 v55, v0
	v_mov_b32_e32 v56, v0
	v_mov_b32_e32 v57, v0
	v_mov_b32_e32 v58, v0
	v_mov_b32_e32 v59, v0
	v_mov_b32_e32 v60, v0
	v_mov_b32_e32 v61, v0
	v_mov_b32_e32 v62, v0
	v_mov_b32_e32 v63, v0
	v_readfirstlane_b32 s8, v122
	v_readfirstlane_b32 s9, v123
	v_readfirstlane_b32 s62, v124
	v_readfirstlane_b32 s63, v125
	v_readfirstlane_b32 s7, v247
	s_nop 3
	s_mul_i32 s64, s7, 0x4000
	s_sub_u32 s8, s8, s64
	s_subb_u32 s9, s9, 0
	s_sub_u32 s62, s62, s64
	s_subb_u32 s63, s63, 0
	s_lshl_b32 s7, s7, 12
	s_sub_u32 s64, s2, s3
	s_cmp_eq_u32 s64, s58
	s_cbranch_scc1 .Lg2_first
	v_mov_b32_e32 v60, 0
	v_mov_b32_e32 v61, 0
	v_mov_b32_e32 v62, 0
	v_mov_b32_e32 v63, 0
	v_mov_b32_e32 v56, 0
	v_mov_b32_e32 v57, 0
	v_mov_b32_e32 v58, 0
	v_mov_b32_e32 v59, 0
	v_mov_b32_e32 v52, 0
	v_mov_b32_e32 v53, 0
	v_mov_b32_e32 v54, 0
	v_mov_b32_e32 v55, 0
	v_mov_b32_e32 v48, 0
	v_mov_b32_e32 v49, 0
	v_mov_b32_e32 v50, 0
	v_mov_b32_e32 v51, 0
	v_mov_b32_e32 v44, 0
	v_mov_b32_e32 v45, 0
	v_mov_b32_e32 v46, 0
	v_mov_b32_e32 v47, 0
	v_mov_b32_e32 v40, 0
	v_mov_b32_e32 v41, 0
	v_mov_b32_e32 v42, 0
	v_mov_b32_e32 v43, 0
	v_mov_b32_e32 v36, 0
	v_mov_b32_e32 v37, 0
	v_mov_b32_e32 v38, 0
	v_mov_b32_e32 v39, 0
	v_mov_b32_e32 v28, 0
	v_mov_b32_e32 v29, 0
	v_mov_b32_e32 v30, 0
	v_mov_b32_e32 v31, 0
	v_mov_b32_e32 v16, 0
	v_mov_b32_e32 v17, 0
	v_mov_b32_e32 v18, 0
	v_mov_b32_e32 v19, 0
	v_mov_b32_e32 v12, 0
	v_mov_b32_e32 v13, 0
	v_mov_b32_e32 v14, 0
	v_mov_b32_e32 v15, 0
	v_mov_b32_e32 v4, 0
	v_mov_b32_e32 v5, 0
	v_mov_b32_e32 v6, 0
	v_mov_b32_e32 v7, 0
	v_mov_b32_e32 v8, 0
	v_mov_b32_e32 v9, 0
	v_mov_b32_e32 v10, 0
	v_mov_b32_e32 v11, 0
	v_mov_b32_e32 v32, 0
	v_mov_b32_e32 v33, 0
	v_mov_b32_e32 v34, 0
	v_mov_b32_e32 v35, 0
	v_mov_b32_e32 v24, 0
	v_mov_b32_e32 v25, 0
	v_mov_b32_e32 v26, 0
	v_mov_b32_e32 v27, 0
	v_mov_b32_e32 v20, 0
	v_mov_b32_e32 v21, 0
	v_mov_b32_e32 v22, 0
	v_mov_b32_e32 v23, 0
	v_mov_b32_e32 v0, 0
	v_mov_b32_e32 v1, 0
	v_mov_b32_e32 v2, 0
	v_mov_b32_e32 v3, 0
	s_add_u32 s8, s8, 0x100
	s_addc_u32 s9, s9, 0
	s_add_u32 s62, s62, 0x100
	s_addc_u32 s63, s63, 0
	s_waitcnt vmcnt(8)
	s_barrier
	ds_read_b128 v[80:83], v252 offset:0
	ds_read_b128 v[144:147], v254 offset:32768
	ds_read_b128 v[148:151], v254 offset:34816
	ds_read_b128 v[152:155], v254 offset:36864
	ds_read_b128 v[156:159], v254 offset:38912
	ds_read_b128 v[84:87], v252 offset:2048
	ds_read_b128 v[88:91], v252 offset:4096
	ds_read_b128 v[92:95], v252 offset:6144
	ds_read_b128 v[124:127], v253 offset:0
	ds_read_b128 v[172:175], v255 offset:32768
	ds_read_b128 v[176:179], v255 offset:34816
	ds_read_b128 v[180:183], v255 offset:36864
	ds_read_b128 v[184:187], v255 offset:38912
	s_waitcnt lgkmcnt(11)
	v_mfma_f32_16x16x32_bf16 v[60:63], v[80:83], v[144:147], v[60:63]
	s_waitcnt lgkmcnt(10)
	v_mfma_f32_16x16x32_bf16 v[56:59], v[80:83], v[148:151], v[56:59]
	s_waitcnt lgkmcnt(9)
	v_mfma_f32_16x16x32_bf16 v[52:55], v[80:83], v[152:155], v[52:55]
	s_waitcnt lgkmcnt(8)
	v_mfma_f32_16x16x32_bf16 v[48:51], v[80:83], v[156:159], v[48:51]
	ds_read_b128 v[132:135], v253 offset:2048
	ds_read_b128 v[136:139], v253 offset:4096
	ds_read_b128 v[140:143], v253 offset:6144
	s_waitcnt lgkmcnt(10)
	v_mfma_f32_16x16x32_bf16 v[44:47], v[84:87], v[144:147], v[44:47]
	v_mfma_f32_16x16x32_bf16 v[40:43], v[84:87], v[148:151], v[40:43]
	v_mfma_f32_16x16x32_bf16 v[36:39], v[84:87], v[152:155], v[36:39]
	v_mfma_f32_16x16x32_bf16 v[28:31], v[84:87], v[156:159], v[28:31]
	s_waitcnt lgkmcnt(9)
	v_mfma_f32_16x16x32_bf16 v[16:19], v[88:91], v[144:147], v[16:19]
	v_mfma_f32_16x16x32_bf16 v[12:15], v[88:91], v[148:151], v[12:15]
	v_mfma_f32_16x16x32_bf16 v[4:7], v[88:91], v[152:155], v[4:7]
	v_mfma_f32_16x16x32_bf16 v[8:11], v[88:91], v[156:159], v[8:11]
	s_waitcnt lgkmcnt(8)
	v_mfma_f32_16x16x32_bf16 v[32:35], v[92:95], v[144:147], v[32:35]
	v_mfma_f32_16x16x32_bf16 v[24:27], v[92:95], v[148:151], v[24:27]
	v_mfma_f32_16x16x32_bf16 v[20:23], v[92:95], v[152:155], v[20:23]
	v_mfma_f32_16x16x32_bf16 v[0:3], v[92:95], v[156:159], v[0:3]
	s_waitcnt lgkmcnt(0)
	s_barrier
	s_add_u32 m0, s7, 0x0
	v_mfma_f32_16x16x32_bf16 v[60:63], v[124:127], v[172:175], v[60:63]
	global_load_lds_dwordx4 v248, s[8:9]
	v_mfma_f32_16x16x32_bf16 v[56:59], v[124:127], v[176:179], v[56:59]
	s_add_u32 m0, s7, 0x400
	v_mfma_f32_16x16x32_bf16 v[52:55], v[124:127], v[180:183], v[52:55]
	global_load_lds_dwordx4 v249, s[8:9]
	v_mfma_f32_16x16x32_bf16 v[48:51], v[124:127], v[184:187], v[48:51]
	s_add_u32 m0, s7, 0x800
	v_mfma_f32_16x16x32_bf16 v[44:47], v[132:135], v[172:175], v[44:47]
	global_load_lds_dwordx4 v250, s[8:9]
	v_mfma_f32_16x16x32_bf16 v[40:43], v[132:135], v[176:179], v[40:43]
	s_add_u32 m0, s7, 0xc00
	v_mfma_f32_16x16x32_bf16 v[36:39], v[132:135], v[180:183], v[36:39]
	global_load_lds_dwordx4 v251, s[8:9]
	v_mfma_f32_16x16x32_bf16 v[28:31], v[132:135], v[184:187], v[28:31]
	s_add_u32 m0, s7, 0x8000
	v_mfma_f32_16x16x32_bf16 v[16:19], v[136:139], v[172:175], v[16:19]
	global_load_lds_dwordx4 v248, s[62:63]
	v_mfma_f32_16x16x32_bf16 v[12:15], v[136:139], v[176:179], v[12:15]
	s_add_u32 m0, s7, 0x8400
	v_mfma_f32_16x16x32_bf16 v[4:7], v[136:139], v[180:183], v[4:7]
	global_load_lds_dwordx4 v249, s[62:63]
	v_mfma_f32_16x16x32_bf16 v[8:11], v[136:139], v[184:187], v[8:11]
	s_add_u32 m0, s7, 0x8800
	v_mfma_f32_16x16x32_bf16 v[32:35], v[140:143], v[172:175], v[32:35]
	global_load_lds_dwordx4 v250, s[62:63]
	v_mfma_f32_16x16x32_bf16 v[24:27], v[140:143], v[176:179], v[24:27]
	s_add_u32 m0, s7, 0x8c00
	v_mfma_f32_16x16x32_bf16 v[20:23], v[140:143], v[180:183], v[20:23]
	global_load_lds_dwordx4 v251, s[62:63]
	v_mfma_f32_16x16x32_bf16 v[0:3], v[140:143], v[184:187], v[0:3]
	s_add_u32 s8, s8, 0x80
	s_addc_u32 s9, s9, 0
	s_add_u32 s62, s62, 0x80
	s_addc_u32 s63, s63, 0
	s_waitcnt vmcnt(8)
	s_barrier
	ds_read_b128 v[80:83], v252 offset:16384
	ds_read_b128 v[144:147], v254 offset:49152
	ds_read_b128 v[148:151], v254 offset:51200
	ds_read_b128 v[152:155], v254 offset:53248
	ds_read_b128 v[156:159], v254 offset:55296
	ds_read_b128 v[84:87], v252 offset:18432
	ds_read_b128 v[88:91], v252 offset:20480
	ds_read_b128 v[92:95], v252 offset:22528
	ds_read_b128 v[124:127], v253 offset:16384
	ds_read_b128 v[172:175], v255 offset:49152
	ds_read_b128 v[176:179], v255 offset:51200
	ds_read_b128 v[180:183], v255 offset:53248
	ds_read_b128 v[184:187], v255 offset:55296
	s_waitcnt lgkmcnt(11)
	v_mfma_f32_16x16x32_bf16 v[60:63], v[80:83], v[144:147], v[60:63]
	s_waitcnt lgkmcnt(10)
	v_mfma_f32_16x16x32_bf16 v[56:59], v[80:83], v[148:151], v[56:59]
	s_waitcnt lgkmcnt(9)
	v_mfma_f32_16x16x32_bf16 v[52:55], v[80:83], v[152:155], v[52:55]
	s_waitcnt lgkmcnt(8)
	v_mfma_f32_16x16x32_bf16 v[48:51], v[80:83], v[156:159], v[48:51]
	ds_read_b128 v[132:135], v253 offset:18432
	ds_read_b128 v[136:139], v253 offset:20480
	ds_read_b128 v[140:143], v253 offset:22528
	s_waitcnt lgkmcnt(10)
	v_mfma_f32_16x16x32_bf16 v[44:47], v[84:87], v[144:147], v[44:47]
	v_mfma_f32_16x16x32_bf16 v[40:43], v[84:87], v[148:151], v[40:43]
	v_mfma_f32_16x16x32_bf16 v[36:39], v[84:87], v[152:155], v[36:39]
	v_mfma_f32_16x16x32_bf16 v[28:31], v[84:87], v[156:159], v[28:31]
	s_waitcnt lgkmcnt(9)
	v_mfma_f32_16x16x32_bf16 v[16:19], v[88:91], v[144:147], v[16:19]
	v_mfma_f32_16x16x32_bf16 v[12:15], v[88:91], v[148:151], v[12:15]
	v_mfma_f32_16x16x32_bf16 v[4:7], v[88:91], v[152:155], v[4:7]
	v_mfma_f32_16x16x32_bf16 v[8:11], v[88:91], v[156:159], v[8:11]
	s_waitcnt lgkmcnt(8)
	v_mfma_f32_16x16x32_bf16 v[32:35], v[92:95], v[144:147], v[32:35]
	v_mfma_f32_16x16x32_bf16 v[24:27], v[92:95], v[148:151], v[24:27]
	v_mfma_f32_16x16x32_bf16 v[20:23], v[92:95], v[152:155], v[20:23]
	v_mfma_f32_16x16x32_bf16 v[0:3], v[92:95], v[156:159], v[0:3]
	s_waitcnt lgkmcnt(0)
	s_barrier
	s_add_u32 m0, s7, 0x4000
	v_mfma_f32_16x16x32_bf16 v[60:63], v[124:127], v[172:175], v[60:63]
	global_load_lds_dwordx4 v248, s[8:9]
	v_mfma_f32_16x16x32_bf16 v[56:59], v[124:127], v[176:179], v[56:59]
	s_add_u32 m0, s7, 0x4400
	v_mfma_f32_16x16x32_bf16 v[52:55], v[124:127], v[180:183], v[52:55]
	global_load_lds_dwordx4 v249, s[8:9]
	v_mfma_f32_16x16x32_bf16 v[48:51], v[124:127], v[184:187], v[48:51]
	s_add_u32 m0, s7, 0x4800
	v_mfma_f32_16x16x32_bf16 v[44:47], v[132:135], v[172:175], v[44:47]
	global_load_lds_dwordx4 v250, s[8:9]
	v_mfma_f32_16x16x32_bf16 v[40:43], v[132:135], v[176:179], v[40:43]
	s_add_u32 m0, s7, 0x4c00
	v_mfma_f32_16x16x32_bf16 v[36:39], v[132:135], v[180:183], v[36:39]
	global_load_lds_dwordx4 v251, s[8:9]
	v_mfma_f32_16x16x32_bf16 v[28:31], v[132:135], v[184:187], v[28:31]
	s_add_u32 m0, s7, 0xc000
	v_mfma_f32_16x16x32_bf16 v[16:19], v[136:139], v[172:175], v[16:19]
	global_load_lds_dwordx4 v248, s[62:63]
	v_mfma_f32_16x16x32_bf16 v[12:15], v[136:139], v[176:179], v[12:15]
	s_add_u32 m0, s7, 0xc400
	v_mfma_f32_16x16x32_bf16 v[4:7], v[136:139], v[180:183], v[4:7]
	global_load_lds_dwordx4 v249, s[62:63]
	v_mfma_f32_16x16x32_bf16 v[8:11], v[136:139], v[184:187], v[8:11]
	s_add_u32 m0, s7, 0xc800
	v_mfma_f32_16x16x32_bf16 v[32:35], v[140:143], v[172:175], v[32:35]
	global_load_lds_dwordx4 v250, s[62:63]
	v_mfma_f32_16x16x32_bf16 v[24:27], v[140:143], v[176:179], v[24:27]
	s_add_u32 m0, s7, 0xcc00
	v_mfma_f32_16x16x32_bf16 v[20:23], v[140:143], v[180:183], v[20:23]
	global_load_lds_dwordx4 v251, s[62:63]
	v_mfma_f32_16x16x32_bf16 v[0:3], v[140:143], v[184:187], v[0:3]
	s_add_u32 s8, s8, 0x80
	s_addc_u32 s9, s9, 0
	s_add_u32 s62, s62, 0x80
	s_addc_u32 s63, s63, 0
	s_branch .Lg2_main
.Lg2_first:
	s_add_u32 m0, s7, 0x0
	v_mov_b32_e32 v60, 0
	global_load_lds_dwordx4 v248, s[8:9]
	v_mov_b32_e32 v61, 0
	s_add_u32 m0, s7, 0x400
	v_mov_b32_e32 v62, 0
	global_load_lds_dwordx4 v249, s[8:9]
	v_mov_b32_e32 v63, 0
	s_add_u32 m0, s7, 0x800
	v_mov_b32_e32 v56, 0
	global_load_lds_dwordx4 v250, s[8:9]
	v_mov_b32_e32 v57, 0
	s_add_u32 m0, s7, 0xc00
	v_mov_b32_e32 v58, 0
	global_load_lds_dwordx4 v251, s[8:9]
	v_mov_b32_e32 v59, 0
	s_add_u32 m0, s7, 0x8000
	v_mov_b32_e32 v52, 0
	global_load_lds_dwordx4 v248, s[62:63]
	v_mov_b32_e32 v53, 0
	s_add_u32 m0, s7, 0x8400
	v_mov_b32_e32 v54, 0
	global_load_lds_dwordx4 v249, s[62:63]
	v_mov_b32_e32 v55, 0
	s_add_u32 m0, s7, 0x8800
	v_mov_b32_e32 v48, 0
	global_load_lds_dwordx4 v250, s[62:63]
	v_mov_b32_e32 v49, 0
	s_add_u32 m0, s7, 0x8c00
	v_mov_b32_e32 v50, 0
	global_load_lds_dwordx4 v251, s[62:63]
	v_mov_b32_e32 v51, 0
	s_add_u32 s8, s8, 0x80
	s_addc_u32 s9, s9, 0
	s_add_u32 s62, s62, 0x80
	s_addc_u32 s63, s63, 0
	s_add_u32 m0, s7, 0x4000
	v_mov_b32_e32 v44, 0
	global_load_lds_dwordx4 v248, s[8:9]
	v_mov_b32_e32 v45, 0
	s_add_u32 m0, s7, 0x4400
	v_mov_b32_e32 v46, 0
	global_load_lds_dwordx4 v249, s[8:9]
	v_mov_b32_e32 v47, 0
	s_add_u32 m0, s7, 0x4800
	v_mov_b32_e32 v40, 0
	global_load_lds_dwordx4 v250, s[8:9]
	v_mov_b32_e32 v41, 0
	s_add_u32 m0, s7, 0x4c00
	v_mov_b32_e32 v42, 0
	global_load_lds_dwordx4 v251, s[8:9]
	v_mov_b32_e32 v43, 0
	s_add_u32 m0, s7, 0xc000
	v_mov_b32_e32 v36, 0
	global_load_lds_dwordx4 v248, s[62:63]
	v_mov_b32_e32 v37, 0
	s_add_u32 m0, s7, 0xc400
	v_mov_b32_e32 v38, 0
	global_load_lds_dwordx4 v249, s[62:63]
	v_mov_b32_e32 v39, 0
	s_add_u32 m0, s7, 0xc800
	v_mov_b32_e32 v28, 0
	global_load_lds_dwordx4 v250, s[62:63]
	v_mov_b32_e32 v29, 0
	s_add_u32 m0, s7, 0xcc00
	v_mov_b32_e32 v30, 0
	global_load_lds_dwordx4 v251, s[62:63]
	v_mov_b32_e32 v31, 0
	s_add_u32 s8, s8, 0x80
	s_addc_u32 s9, s9, 0
	s_add_u32 s62, s62, 0x80
	s_addc_u32 s63, s63, 0
	v_mov_b32_e32 v16, 0
	v_mov_b32_e32 v17, 0
	v_mov_b32_e32 v18, 0
	v_mov_b32_e32 v19, 0
	v_mov_b32_e32 v12, 0
	v_mov_b32_e32 v13, 0
	v_mov_b32_e32 v14, 0
	v_mov_b32_e32 v15, 0
	v_mov_b32_e32 v4, 0
	v_mov_b32_e32 v5, 0
	v_mov_b32_e32 v6, 0
	v_mov_b32_e32 v7, 0
	v_mov_b32_e32 v8, 0
	v_mov_b32_e32 v9, 0
	v_mov_b32_e32 v10, 0
	v_mov_b32_e32 v11, 0
	v_mov_b32_e32 v32, 0
	v_mov_b32_e32 v33, 0
	v_mov_b32_e32 v34, 0
	v_mov_b32_e32 v35, 0
	v_mov_b32_e32 v24, 0
	v_mov_b32_e32 v25, 0
	v_mov_b32_e32 v26, 0
	v_mov_b32_e32 v27, 0
	v_mov_b32_e32 v20, 0
	v_mov_b32_e32 v21, 0
	v_mov_b32_e32 v22, 0
	v_mov_b32_e32 v23, 0
	v_mov_b32_e32 v0, 0
	v_mov_b32_e32 v1, 0
	v_mov_b32_e32 v2, 0
	v_mov_b32_e32 v3, 0
	s_waitcnt vmcnt(8)
	s_barrier
	ds_read_b128 v[80:83], v252 offset:0
	ds_read_b128 v[144:147], v254 offset:32768
	ds_read_b128 v[148:151], v254 offset:34816
	ds_read_b128 v[152:155], v254 offset:36864
	ds_read_b128 v[156:159], v254 offset:38912
	ds_read_b128 v[84:87], v252 offset:2048
	ds_read_b128 v[88:91], v252 offset:4096
	ds_read_b128 v[92:95], v252 offset:6144
	ds_read_b128 v[124:127], v253 offset:0
	ds_read_b128 v[172:175], v255 offset:32768
	ds_read_b128 v[176:179], v255 offset:34816
	ds_read_b128 v[180:183], v255 offset:36864
	ds_read_b128 v[184:187], v255 offset:38912
	s_waitcnt lgkmcnt(11)
	v_mfma_f32_16x16x32_bf16 v[60:63], v[80:83], v[144:147], v[60:63]
	s_waitcnt lgkmcnt(10)
	v_mfma_f32_16x16x32_bf16 v[56:59], v[80:83], v[148:151], v[56:59]
	s_waitcnt lgkmcnt(9)
	v_mfma_f32_16x16x32_bf16 v[52:55], v[80:83], v[152:155], v[52:55]
	s_waitcnt lgkmcnt(8)
	v_mfma_f32_16x16x32_bf16 v[48:51], v[80:83], v[156:159], v[48:51]
	ds_read_b128 v[132:135], v253 offset:2048
	ds_read_b128 v[136:139], v253 offset:4096
	ds_read_b128 v[140:143], v253 offset:6144
	s_waitcnt lgkmcnt(10)
	v_mfma_f32_16x16x32_bf16 v[44:47], v[84:87], v[144:147], v[44:47]
	v_mfma_f32_16x16x32_bf16 v[40:43], v[84:87], v[148:151], v[40:43]
	v_mfma_f32_16x16x32_bf16 v[36:39], v[84:87], v[152:155], v[36:39]
	v_mfma_f32_16x16x32_bf16 v[28:31], v[84:87], v[156:159], v[28:31]
	s_waitcnt lgkmcnt(9)
	v_mfma_f32_16x16x32_bf16 v[16:19], v[88:91], v[144:147], v[16:19]
	v_mfma_f32_16x16x32_bf16 v[12:15], v[88:91], v[148:151], v[12:15]
	v_mfma_f32_16x16x32_bf16 v[4:7], v[88:91], v[152:155], v[4:7]
	v_mfma_f32_16x16x32_bf16 v[8:11], v[88:91], v[156:159], v[8:11]
	s_waitcnt lgkmcnt(8)
	v_mfma_f32_16x16x32_bf16 v[32:35], v[92:95], v[144:147], v[32:35]
	v_mfma_f32_16x16x32_bf16 v[24:27], v[92:95], v[148:151], v[24:27]
	v_mfma_f32_16x16x32_bf16 v[20:23], v[92:95], v[152:155], v[20:23]
	v_mfma_f32_16x16x32_bf16 v[0:3], v[92:95], v[156:159], v[0:3]
	s_waitcnt lgkmcnt(0)
	s_barrier
	s_add_u32 m0, s7, 0x0
	v_mfma_f32_16x16x32_bf16 v[60:63], v[124:127], v[172:175], v[60:63]
	global_load_lds_dwordx4 v248, s[8:9]
	v_mfma_f32_16x16x32_bf16 v[56:59], v[124:127], v[176:179], v[56:59]
	s_add_u32 m0, s7, 0x400
	v_mfma_f32_16x16x32_bf16 v[52:55], v[124:127], v[180:183], v[52:55]
	global_load_lds_dwordx4 v249, s[8:9]
	v_mfma_f32_16x16x32_bf16 v[48:51], v[124:127], v[184:187], v[48:51]
	s_add_u32 m0, s7, 0x800
	v_mfma_f32_16x16x32_bf16 v[44:47], v[132:135], v[172:175], v[44:47]
	global_load_lds_dwordx4 v250, s[8:9]
	v_mfma_f32_16x16x32_bf16 v[40:43], v[132:135], v[176:179], v[40:43]
	s_add_u32 m0, s7, 0xc00
	v_mfma_f32_16x16x32_bf16 v[36:39], v[132:135], v[180:183], v[36:39]
	global_load_lds_dwordx4 v251, s[8:9]
	v_mfma_f32_16x16x32_bf16 v[28:31], v[132:135], v[184:187], v[28:31]
	s_add_u32 m0, s7, 0x8000
	v_mfma_f32_16x16x32_bf16 v[16:19], v[136:139], v[172:175], v[16:19]
	global_load_lds_dwordx4 v248, s[62:63]
	v_mfma_f32_16x16x32_bf16 v[12:15], v[136:139], v[176:179], v[12:15]
	s_add_u32 m0, s7, 0x8400
	v_mfma_f32_16x16x32_bf16 v[4:7], v[136:139], v[180:183], v[4:7]
	global_load_lds_dwordx4 v249, s[62:63]
	v_mfma_f32_16x16x32_bf16 v[8:11], v[136:139], v[184:187], v[8:11]
	s_add_u32 m0, s7, 0x8800
	v_mfma_f32_16x16x32_bf16 v[32:35], v[140:143], v[172:175], v[32:35]
	global_load_lds_dwordx4 v250, s[62:63]
	v_mfma_f32_16x16x32_bf16 v[24:27], v[140:143], v[176:179], v[24:27]
	s_add_u32 m0, s7, 0x8c00
	v_mfma_f32_16x16x32_bf16 v[20:23], v[140:143], v[180:183], v[20:23]
	global_load_lds_dwordx4 v251, s[62:63]
	v_mfma_f32_16x16x32_bf16 v[0:3], v[140:143], v[184:187], v[0:3]
	s_add_u32 s8, s8, 0x80
	s_addc_u32 s9, s9, 0
	s_add_u32 s62, s62, 0x80
	s_addc_u32 s63, s63, 0
	s_waitcnt vmcnt(8)
	s_barrier
	ds_read_b128 v[80:83], v252 offset:16384
	ds_read_b128 v[144:147], v254 offset:49152
	ds_read_b128 v[148:151], v254 offset:51200
	ds_read_b128 v[152:155], v254 offset:53248
	ds_read_b128 v[156:159], v254 offset:55296
	ds_read_b128 v[84:87], v252 offset:18432
	ds_read_b128 v[88:91], v252 offset:20480
	ds_read_b128 v[92:95], v252 offset:22528
	ds_read_b128 v[124:127], v253 offset:16384
	ds_read_b128 v[172:175], v255 offset:49152
	ds_read_b128 v[176:179], v255 offset:51200
	ds_read_b128 v[180:183], v255 offset:53248
	ds_read_b128 v[184:187], v255 offset:55296
	s_waitcnt lgkmcnt(11)
	v_mfma_f32_16x16x32_bf16 v[60:63], v[80:83], v[144:147], v[60:63]
	s_waitcnt lgkmcnt(10)
	v_mfma_f32_16x16x32_bf16 v[56:59], v[80:83], v[148:151], v[56:59]
	s_waitcnt lgkmcnt(9)
	v_mfma_f32_16x16x32_bf16 v[52:55], v[80:83], v[152:155], v[52:55]
	s_waitcnt lgkmcnt(8)
	v_mfma_f32_16x16x32_bf16 v[48:51], v[80:83], v[156:159], v[48:51]
	ds_read_b128 v[132:135], v253 offset:18432
	ds_read_b128 v[136:139], v253 offset:20480
	ds_read_b128 v[140:143], v253 offset:22528
	s_waitcnt lgkmcnt(10)
	v_mfma_f32_16x16x32_bf16 v[44:47], v[84:87], v[144:147], v[44:47]
	v_mfma_f32_16x16x32_bf16 v[40:43], v[84:87], v[148:151], v[40:43]
	v_mfma_f32_16x16x32_bf16 v[36:39], v[84:87], v[152:155], v[36:39]
	v_mfma_f32_16x16x32_bf16 v[28:31], v[84:87], v[156:159], v[28:31]
	s_waitcnt lgkmcnt(9)
	v_mfma_f32_16x16x32_bf16 v[16:19], v[88:91], v[144:147], v[16:19]
	v_mfma_f32_16x16x32_bf16 v[12:15], v[88:91], v[148:151], v[12:15]
	v_mfma_f32_16x16x32_bf16 v[4:7], v[88:91], v[152:155], v[4:7]
	v_mfma_f32_16x16x32_bf16 v[8:11], v[88:91], v[156:159], v[8:11]
	s_waitcnt lgkmcnt(8)
	v_mfma_f32_16x16x32_bf16 v[32:35], v[92:95], v[144:147], v[32:35]
	v_mfma_f32_16x16x32_bf16 v[24:27], v[92:95], v[148:151], v[24:27]
	v_mfma_f32_16x16x32_bf16 v[20:23], v[92:95], v[152:155], v[20:23]
	v_mfma_f32_16x16x32_bf16 v[0:3], v[92:95], v[156:159], v[0:3]
	s_waitcnt lgkmcnt(0)
	s_barrier
	s_add_u32 m0, s7, 0x4000
	v_mfma_f32_16x16x32_bf16 v[60:63], v[124:127], v[172:175], v[60:63]
	global_load_lds_dwordx4 v248, s[8:9]
	v_mfma_f32_16x16x32_bf16 v[56:59], v[124:127], v[176:179], v[56:59]
	s_add_u32 m0, s7, 0x4400
	v_mfma_f32_16x16x32_bf16 v[52:55], v[124:127], v[180:183], v[52:55]
	global_load_lds_dwordx4 v249, s[8:9]
	v_mfma_f32_16x16x32_bf16 v[48:51], v[124:127], v[184:187], v[48:51]
	s_add_u32 m0, s7, 0x4800
	v_mfma_f32_16x16x32_bf16 v[44:47], v[132:135], v[172:175], v[44:47]
	global_load_lds_dwordx4 v250, s[8:9]
	v_mfma_f32_16x16x32_bf16 v[40:43], v[132:135], v[176:179], v[40:43]
	s_add_u32 m0, s7, 0x4c00
	v_mfma_f32_16x16x32_bf16 v[36:39], v[132:135], v[180:183], v[36:39]
	global_load_lds_dwordx4 v251, s[8:9]
	v_mfma_f32_16x16x32_bf16 v[28:31], v[132:135], v[184:187], v[28:31]
	s_add_u32 m0, s7, 0xc000
	v_mfma_f32_16x16x32_bf16 v[16:19], v[136:139], v[172:175], v[16:19]
	global_load_lds_dwordx4 v248, s[62:63]
	v_mfma_f32_16x16x32_bf16 v[12:15], v[136:139], v[176:179], v[12:15]
	s_add_u32 m0, s7, 0xc400
	v_mfma_f32_16x16x32_bf16 v[4:7], v[136:139], v[180:183], v[4:7]
	global_load_lds_dwordx4 v249, s[62:63]
	v_mfma_f32_16x16x32_bf16 v[8:11], v[136:139], v[184:187], v[8:11]
	s_add_u32 m0, s7, 0xc800
	v_mfma_f32_16x16x32_bf16 v[32:35], v[140:143], v[172:175], v[32:35]
	global_load_lds_dwordx4 v250, s[62:63]
	v_mfma_f32_16x16x32_bf16 v[24:27], v[140:143], v[176:179], v[24:27]
	s_add_u32 m0, s7, 0xcc00
	v_mfma_f32_16x16x32_bf16 v[20:23], v[140:143], v[180:183], v[20:23]
	global_load_lds_dwordx4 v251, s[62:63]
	v_mfma_f32_16x16x32_bf16 v[0:3], v[140:143], v[184:187], v[0:3]
	s_add_u32 s8, s8, 0x80
	s_addc_u32 s9, s9, 0
	s_add_u32 s62, s62, 0x80
	s_addc_u32 s63, s63, 0
.Lg2_main:
	s_mov_b32 s32, 6
.Lg2_loop:
	s_waitcnt vmcnt(8)
	s_barrier
	ds_read_b128 v[80:83], v252 offset:0
	ds_read_b128 v[144:147], v254 offset:32768
	ds_read_b128 v[148:151], v254 offset:34816
	ds_read_b128 v[152:155], v254 offset:36864
	ds_read_b128 v[156:159], v254 offset:38912
	ds_read_b128 v[84:87], v252 offset:2048
	ds_read_b128 v[88:91], v252 offset:4096
	ds_read_b128 v[92:95], v252 offset:6144
	ds_read_b128 v[124:127], v253 offset:0
	ds_read_b128 v[172:175], v255 offset:32768
	ds_read_b128 v[176:179], v255 offset:34816
	ds_read_b128 v[180:183], v255 offset:36864
	ds_read_b128 v[184:187], v255 offset:38912
	s_waitcnt lgkmcnt(11)
	v_mfma_f32_16x16x32_bf16 v[60:63], v[80:83], v[144:147], v[60:63]
	s_waitcnt lgkmcnt(10)
	v_mfma_f32_16x16x32_bf16 v[56:59], v[80:83], v[148:151], v[56:59]
	s_waitcnt lgkmcnt(9)
	v_mfma_f32_16x16x32_bf16 v[52:55], v[80:83], v[152:155], v[52:55]
	s_waitcnt lgkmcnt(8)
	v_mfma_f32_16x16x32_bf16 v[48:51], v[80:83], v[156:159], v[48:51]
	ds_read_b128 v[132:135], v253 offset:2048
	ds_read_b128 v[136:139], v253 offset:4096
	ds_read_b128 v[140:143], v253 offset:6144
	s_waitcnt lgkmcnt(10)
	v_mfma_f32_16x16x32_bf16 v[44:47], v[84:87], v[144:147], v[44:47]
	v_mfma_f32_16x16x32_bf16 v[40:43], v[84:87], v[148:151], v[40:43]
	v_mfma_f32_16x16x32_bf16 v[36:39], v[84:87], v[152:155], v[36:39]
	v_mfma_f32_16x16x32_bf16 v[28:31], v[84:87], v[156:159], v[28:31]
	s_waitcnt lgkmcnt(9)
	v_mfma_f32_16x16x32_bf16 v[16:19], v[88:91], v[144:147], v[16:19]
	v_mfma_f32_16x16x32_bf16 v[12:15], v[88:91], v[148:151], v[12:15]
	v_mfma_f32_16x16x32_bf16 v[4:7], v[88:91], v[152:155], v[4:7]
	v_mfma_f32_16x16x32_bf16 v[8:11], v[88:91], v[156:159], v[8:11]
	s_waitcnt lgkmcnt(8)
	v_mfma_f32_16x16x32_bf16 v[32:35], v[92:95], v[144:147], v[32:35]
	v_mfma_f32_16x16x32_bf16 v[24:27], v[92:95], v[148:151], v[24:27]
	v_mfma_f32_16x16x32_bf16 v[20:23], v[92:95], v[152:155], v[20:23]
	v_mfma_f32_16x16x32_bf16 v[0:3], v[92:95], v[156:159], v[0:3]
	s_waitcnt lgkmcnt(0)
	s_barrier
	s_add_u32 m0, s7, 0x0
	v_mfma_f32_16x16x32_bf16 v[60:63], v[124:127], v[172:175], v[60:63]
	global_load_lds_dwordx4 v248, s[8:9]
	v_mfma_f32_16x16x32_bf16 v[56:59], v[124:127], v[176:179], v[56:59]
	s_add_u32 m0, s7, 0x400
	v_mfma_f32_16x16x32_bf16 v[52:55], v[124:127], v[180:183], v[52:55]
	global_load_lds_dwordx4 v249, s[8:9]
	v_mfma_f32_16x16x32_bf16 v[48:51], v[124:127], v[184:187], v[48:51]
	s_add_u32 m0, s7, 0x800
	v_mfma_f32_16x16x32_bf16 v[44:47], v[132:135], v[172:175], v[44:47]
	global_load_lds_dwordx4 v250, s[8:9]
	v_mfma_f32_16x16x32_bf16 v[40:43], v[132:135], v[176:179], v[40:43]
	s_add_u32 m0, s7, 0xc00
	v_mfma_f32_16x16x32_bf16 v[36:39], v[132:135], v[180:183], v[36:39]
	global_load_lds_dwordx4 v251, s[8:9]
	v_mfma_f32_16x16x32_bf16 v[28:31], v[132:135], v[184:187], v[28:31]
	s_add_u32 m0, s7, 0x8000
	v_mfma_f32_16x16x32_bf16 v[16:19], v[136:139], v[172:175], v[16:19]
	global_load_lds_dwordx4 v248, s[62:63]
	v_mfma_f32_16x16x32_bf16 v[12:15], v[136:139], v[176:179], v[12:15]
	s_add_u32 m0, s7, 0x8400
	v_mfma_f32_16x16x32_bf16 v[4:7], v[136:139], v[180:183], v[4:7]
	global_load_lds_dwordx4 v249, s[62:63]
	v_mfma_f32_16x16x32_bf16 v[8:11], v[136:139], v[184:187], v[8:11]
	s_add_u32 m0, s7, 0x8800
	v_mfma_f32_16x16x32_bf16 v[32:35], v[140:143], v[172:175], v[32:35]
	global_load_lds_dwordx4 v250, s[62:63]
	v_mfma_f32_16x16x32_bf16 v[24:27], v[140:143], v[176:179], v[24:27]
	s_add_u32 m0, s7, 0x8c00
	v_mfma_f32_16x16x32_bf16 v[20:23], v[140:143], v[180:183], v[20:23]
	global_load_lds_dwordx4 v251, s[62:63]
	v_mfma_f32_16x16x32_bf16 v[0:3], v[140:143], v[184:187], v[0:3]
	s_add_u32 s8, s8, 0x80
	s_addc_u32 s9, s9, 0
	s_add_u32 s62, s62, 0x80
	s_addc_u32 s63, s63, 0
	s_waitcnt vmcnt(8)
	s_barrier
	ds_read_b128 v[80:83], v252 offset:16384
	ds_read_b128 v[144:147], v254 offset:49152
	ds_read_b128 v[148:151], v254 offset:51200
	ds_read_b128 v[152:155], v254 offset:53248
	ds_read_b128 v[156:159], v254 offset:55296
	ds_read_b128 v[84:87], v252 offset:18432
	ds_read_b128 v[88:91], v252 offset:20480
	ds_read_b128 v[92:95], v252 offset:22528
	ds_read_b128 v[124:127], v253 offset:16384
	ds_read_b128 v[172:175], v255 offset:49152
	ds_read_b128 v[176:179], v255 offset:51200
	ds_read_b128 v[180:183], v255 offset:53248
	ds_read_b128 v[184:187], v255 offset:55296
	s_waitcnt lgkmcnt(11)
	v_mfma_f32_16x16x32_bf16 v[60:63], v[80:83], v[144:147], v[60:63]
	s_waitcnt lgkmcnt(10)
	v_mfma_f32_16x16x32_bf16 v[56:59], v[80:83], v[148:151], v[56:59]
	s_waitcnt lgkmcnt(9)
	v_mfma_f32_16x16x32_bf16 v[52:55], v[80:83], v[152:155], v[52:55]
	s_waitcnt lgkmcnt(8)
	v_mfma_f32_16x16x32_bf16 v[48:51], v[80:83], v[156:159], v[48:51]
	ds_read_b128 v[132:135], v253 offset:18432
	ds_read_b128 v[136:139], v253 offset:20480
	ds_read_b128 v[140:143], v253 offset:22528
	s_waitcnt lgkmcnt(10)
	v_mfma_f32_16x16x32_bf16 v[44:47], v[84:87], v[144:147], v[44:47]
	v_mfma_f32_16x16x32_bf16 v[40:43], v[84:87], v[148:151], v[40:43]
	v_mfma_f32_16x16x32_bf16 v[36:39], v[84:87], v[152:155], v[36:39]
	v_mfma_f32_16x16x32_bf16 v[28:31], v[84:87], v[156:159], v[28:31]
	s_waitcnt lgkmcnt(9)
	v_mfma_f32_16x16x32_bf16 v[16:19], v[88:91], v[144:147], v[16:19]
	v_mfma_f32_16x16x32_bf16 v[12:15], v[88:91], v[148:151], v[12:15]
	v_mfma_f32_16x16x32_bf16 v[4:7], v[88:91], v[152:155], v[4:7]
	v_mfma_f32_16x16x32_bf16 v[8:11], v[88:91], v[156:159], v[8:11]
	s_waitcnt lgkmcnt(8)
	v_mfma_f32_16x16x32_bf16 v[32:35], v[92:95], v[144:147], v[32:35]
	v_mfma_f32_16x16x32_bf16 v[24:27], v[92:95], v[148:151], v[24:27]
	v_mfma_f32_16x16x32_bf16 v[20:23], v[92:95], v[152:155], v[20:23]
	v_mfma_f32_16x16x32_bf16 v[0:3], v[92:95], v[156:159], v[0:3]
	s_waitcnt lgkmcnt(0)
	s_barrier
	s_add_u32 m0, s7, 0x4000
	v_mfma_f32_16x16x32_bf16 v[60:63], v[124:127], v[172:175], v[60:63]
	global_load_lds_dwordx4 v248, s[8:9]
	v_mfma_f32_16x16x32_bf16 v[56:59], v[124:127], v[176:179], v[56:59]
	s_add_u32 m0, s7, 0x4400
	v_mfma_f32_16x16x32_bf16 v[52:55], v[124:127], v[180:183], v[52:55]
	global_load_lds_dwordx4 v249, s[8:9]
	v_mfma_f32_16x16x32_bf16 v[48:51], v[124:127], v[184:187], v[48:51]
	s_add_u32 m0, s7, 0x4800
	v_mfma_f32_16x16x32_bf16 v[44:47], v[132:135], v[172:175], v[44:47]
	global_load_lds_dwordx4 v250, s[8:9]
	v_mfma_f32_16x16x32_bf16 v[40:43], v[132:135], v[176:179], v[40:43]
	s_add_u32 m0, s7, 0x4c00
	v_mfma_f32_16x16x32_bf16 v[36:39], v[132:135], v[180:183], v[36:39]
	global_load_lds_dwordx4 v251, s[8:9]
	v_mfma_f32_16x16x32_bf16 v[28:31], v[132:135], v[184:187], v[28:31]
	s_add_u32 m0, s7, 0xc000
	v_mfma_f32_16x16x32_bf16 v[16:19], v[136:139], v[172:175], v[16:19]
	global_load_lds_dwordx4 v248, s[62:63]
	v_mfma_f32_16x16x32_bf16 v[12:15], v[136:139], v[176:179], v[12:15]
	s_add_u32 m0, s7, 0xc400
	v_mfma_f32_16x16x32_bf16 v[4:7], v[136:139], v[180:183], v[4:7]
	global_load_lds_dwordx4 v249, s[62:63]
	v_mfma_f32_16x16x32_bf16 v[8:11], v[136:139], v[184:187], v[8:11]
	s_add_u32 m0, s7, 0xc800
	v_mfma_f32_16x16x32_bf16 v[32:35], v[140:143], v[172:175], v[32:35]
	global_load_lds_dwordx4 v250, s[62:63]
	v_mfma_f32_16x16x32_bf16 v[24:27], v[140:143], v[176:179], v[24:27]
	s_add_u32 m0, s7, 0xcc00
	v_mfma_f32_16x16x32_bf16 v[20:23], v[140:143], v[180:183], v[20:23]
	global_load_lds_dwordx4 v251, s[62:63]
	v_mfma_f32_16x16x32_bf16 v[0:3], v[140:143], v[184:187], v[0:3]
	s_add_u32 s8, s8, 0x80
	s_addc_u32 s9, s9, 0
	s_add_u32 s62, s62, 0x80
	s_addc_u32 s63, s63, 0
	s_sub_u32 s32, s32, 1
	s_cmp_lg_u32 s32, 0
	s_cbranch_scc1 .Lg2_loop
	s_cmp_lt_u32 s2, 0xc40
	s_cbranch_scc0 .Lg2_tailplain
	s_sub_u32 s32, s2, s3
	s_and_b32 s32, s32, 63
	s_and_b32 s64, s2, 63
	s_sub_i32 s64, s64, s32
	s_mul_i32 s64, s64, 0x40000
	s_sub_i32 s64, s64, 0x800
	s_ashr_i32 s32, s64, 31
	s_add_u32 s8, s8, s64
	s_addc_u32 s9, s9, s32
	s_sub_u32 s32, s2, s3
	s_lshr_b32 s32, s32, 6
	s_lshr_b32 s64, s2, 6
	s_sub_i32 s64, s64, s32
	s_mul_i32 s64, s64, 0x40000
	s_sub_i32 s64, s64, 0x800
	s_ashr_i32 s32, s64, 31
	s_add_u32 s62, s62, s64
	s_addc_u32 s63, s63, s32
	s_waitcnt vmcnt(8)
	s_barrier
	ds_read_b128 v[80:83], v252 offset:0
	ds_read_b128 v[144:147], v254 offset:32768
	ds_read_b128 v[148:151], v254 offset:34816
	ds_read_b128 v[152:155], v254 offset:36864
	ds_read_b128 v[156:159], v254 offset:38912
	ds_read_b128 v[84:87], v252 offset:2048
	ds_read_b128 v[88:91], v252 offset:4096
	ds_read_b128 v[92:95], v252 offset:6144
	ds_read_b128 v[124:127], v253 offset:0
	ds_read_b128 v[172:175], v255 offset:32768
	ds_read_b128 v[176:179], v255 offset:34816
	ds_read_b128 v[180:183], v255 offset:36864
	ds_read_b128 v[184:187], v255 offset:38912
	s_waitcnt lgkmcnt(11)
	v_mfma_f32_16x16x32_bf16 v[60:63], v[80:83], v[144:147], v[60:63]
	s_waitcnt lgkmcnt(10)
	v_mfma_f32_16x16x32_bf16 v[56:59], v[80:83], v[148:151], v[56:59]
	s_waitcnt lgkmcnt(9)
	v_mfma_f32_16x16x32_bf16 v[52:55], v[80:83], v[152:155], v[52:55]
	s_waitcnt lgkmcnt(8)
	v_mfma_f32_16x16x32_bf16 v[48:51], v[80:83], v[156:159], v[48:51]
	ds_read_b128 v[132:135], v253 offset:2048
	ds_read_b128 v[136:139], v253 offset:4096
	ds_read_b128 v[140:143], v253 offset:6144
	s_waitcnt lgkmcnt(10)
	v_mfma_f32_16x16x32_bf16 v[44:47], v[84:87], v[144:147], v[44:47]
	v_mfma_f32_16x16x32_bf16 v[40:43], v[84:87], v[148:151], v[40:43]
	v_mfma_f32_16x16x32_bf16 v[36:39], v[84:87], v[152:155], v[36:39]
	v_mfma_f32_16x16x32_bf16 v[28:31], v[84:87], v[156:159], v[28:31]
	s_waitcnt lgkmcnt(9)
	v_mfma_f32_16x16x32_bf16 v[16:19], v[88:91], v[144:147], v[16:19]
	v_mfma_f32_16x16x32_bf16 v[12:15], v[88:91], v[148:151], v[12:15]
	v_mfma_f32_16x16x32_bf16 v[4:7], v[88:91], v[152:155], v[4:7]
	v_mfma_f32_16x16x32_bf16 v[8:11], v[88:91], v[156:159], v[8:11]
	s_waitcnt lgkmcnt(8)
	v_mfma_f32_16x16x32_bf16 v[32:35], v[92:95], v[144:147], v[32:35]
	v_mfma_f32_16x16x32_bf16 v[24:27], v[92:95], v[148:151], v[24:27]
	v_mfma_f32_16x16x32_bf16 v[20:23], v[92:95], v[152:155], v[20:23]
	v_mfma_f32_16x16x32_bf16 v[0:3], v[92:95], v[156:159], v[0:3]
	s_waitcnt lgkmcnt(0)
	s_barrier
	s_add_u32 m0, s7, 0x0
	v_mfma_f32_16x16x32_bf16 v[60:63], v[124:127], v[172:175], v[60:63]
	global_load_lds_dwordx4 v248, s[8:9]
	v_mfma_f32_16x16x32_bf16 v[56:59], v[124:127], v[176:179], v[56:59]
	s_add_u32 m0, s7, 0x400
	v_mfma_f32_16x16x32_bf16 v[52:55], v[124:127], v[180:183], v[52:55]
	global_load_lds_dwordx4 v249, s[8:9]
	v_mfma_f32_16x16x32_bf16 v[48:51], v[124:127], v[184:187], v[48:51]
	s_add_u32 m0, s7, 0x800
	v_mfma_f32_16x16x32_bf16 v[44:47], v[132:135], v[172:175], v[44:47]
	global_load_lds_dwordx4 v250, s[8:9]
	v_mfma_f32_16x16x32_bf16 v[40:43], v[132:135], v[176:179], v[40:43]
	s_add_u32 m0, s7, 0xc00
	v_mfma_f32_16x16x32_bf16 v[36:39], v[132:135], v[180:183], v[36:39]
	global_load_lds_dwordx4 v251, s[8:9]
	v_mfma_f32_16x16x32_bf16 v[28:31], v[132:135], v[184:187], v[28:31]
	s_add_u32 m0, s7, 0x8000
	v_mfma_f32_16x16x32_bf16 v[16:19], v[136:139], v[172:175], v[16:19]
	global_load_lds_dwordx4 v248, s[62:63]
	v_mfma_f32_16x16x32_bf16 v[12:15], v[136:139], v[176:179], v[12:15]
	s_add_u32 m0, s7, 0x8400
	v_mfma_f32_16x16x32_bf16 v[4:7], v[136:139], v[180:183], v[4:7]
	global_load_lds_dwordx4 v249, s[62:63]
	v_mfma_f32_16x16x32_bf16 v[8:11], v[136:139], v[184:187], v[8:11]
	s_add_u32 m0, s7, 0x8800
	v_mfma_f32_16x16x32_bf16 v[32:35], v[140:143], v[172:175], v[32:35]
	global_load_lds_dwordx4 v250, s[62:63]
	v_mfma_f32_16x16x32_bf16 v[24:27], v[140:143], v[176:179], v[24:27]
	s_add_u32 m0, s7, 0x8c00
	v_mfma_f32_16x16x32_bf16 v[20:23], v[140:143], v[180:183], v[20:23]
	global_load_lds_dwordx4 v251, s[62:63]
	v_mfma_f32_16x16x32_bf16 v[0:3], v[140:143], v[184:187], v[0:3]
	s_add_u32 s8, s8, 0x80
	s_addc_u32 s9, s9, 0
	s_add_u32 s62, s62, 0x80
	s_addc_u32 s63, s63, 0
	s_waitcnt vmcnt(8)
	s_barrier
	ds_read_b128 v[80:83], v252 offset:16384
	ds_read_b128 v[144:147], v254 offset:49152
	ds_read_b128 v[148:151], v254 offset:51200
	ds_read_b128 v[152:155], v254 offset:53248
	ds_read_b128 v[156:159], v254 offset:55296
	ds_read_b128 v[84:87], v252 offset:18432
	ds_read_b128 v[88:91], v252 offset:20480
	ds_read_b128 v[92:95], v252 offset:22528
	ds_read_b128 v[124:127], v253 offset:16384
	ds_read_b128 v[172:175], v255 offset:49152
	ds_read_b128 v[176:179], v255 offset:51200
	ds_read_b128 v[180:183], v255 offset:53248
	ds_read_b128 v[184:187], v255 offset:55296
	s_waitcnt lgkmcnt(11)
	v_mfma_f32_16x16x32_bf16 v[60:63], v[80:83], v[144:147], v[60:63]
	s_waitcnt lgkmcnt(10)
	v_mfma_f32_16x16x32_bf16 v[56:59], v[80:83], v[148:151], v[56:59]
	s_waitcnt lgkmcnt(9)
	v_mfma_f32_16x16x32_bf16 v[52:55], v[80:83], v[152:155], v[52:55]
	s_waitcnt lgkmcnt(8)
	v_mfma_f32_16x16x32_bf16 v[48:51], v[80:83], v[156:159], v[48:51]
	ds_read_b128 v[132:135], v253 offset:18432
	ds_read_b128 v[136:139], v253 offset:20480
	ds_read_b128 v[140:143], v253 offset:22528
	s_waitcnt lgkmcnt(10)
	v_mfma_f32_16x16x32_bf16 v[44:47], v[84:87], v[144:147], v[44:47]
	v_mfma_f32_16x16x32_bf16 v[40:43], v[84:87], v[148:151], v[40:43]
	v_mfma_f32_16x16x32_bf16 v[36:39], v[84:87], v[152:155], v[36:39]
	v_mfma_f32_16x16x32_bf16 v[28:31], v[84:87], v[156:159], v[28:31]
	s_waitcnt lgkmcnt(9)
	v_mfma_f32_16x16x32_bf16 v[16:19], v[88:91], v[144:147], v[16:19]
	v_mfma_f32_16x16x32_bf16 v[12:15], v[88:91], v[148:151], v[12:15]
	v_mfma_f32_16x16x32_bf16 v[4:7], v[88:91], v[152:155], v[4:7]
	v_mfma_f32_16x16x32_bf16 v[8:11], v[88:91], v[156:159], v[8:11]
	s_waitcnt lgkmcnt(8)
	v_mfma_f32_16x16x32_bf16 v[32:35], v[92:95], v[144:147], v[32:35]
	v_mfma_f32_16x16x32_bf16 v[24:27], v[92:95], v[148:151], v[24:27]
	v_mfma_f32_16x16x32_bf16 v[20:23], v[92:95], v[152:155], v[20:23]
	v_mfma_f32_16x16x32_bf16 v[0:3], v[92:95], v[156:159], v[0:3]
	s_waitcnt lgkmcnt(0)
	s_barrier
	s_add_u32 m0, s7, 0x4000
	v_mfma_f32_16x16x32_bf16 v[60:63], v[124:127], v[172:175], v[60:63]
	global_load_lds_dwordx4 v248, s[8:9]
	v_mfma_f32_16x16x32_bf16 v[56:59], v[124:127], v[176:179], v[56:59]
	s_add_u32 m0, s7, 0x4400
	v_mfma_f32_16x16x32_bf16 v[52:55], v[124:127], v[180:183], v[52:55]
	global_load_lds_dwordx4 v249, s[8:9]
	v_mfma_f32_16x16x32_bf16 v[48:51], v[124:127], v[184:187], v[48:51]
	s_add_u32 m0, s7, 0x4800
	v_mfma_f32_16x16x32_bf16 v[44:47], v[132:135], v[172:175], v[44:47]
	global_load_lds_dwordx4 v250, s[8:9]
	v_mfma_f32_16x16x32_bf16 v[40:43], v[132:135], v[176:179], v[40:43]
	s_add_u32 m0, s7, 0x4c00
	v_mfma_f32_16x16x32_bf16 v[36:39], v[132:135], v[180:183], v[36:39]
	global_load_lds_dwordx4 v251, s[8:9]
	v_mfma_f32_16x16x32_bf16 v[28:31], v[132:135], v[184:187], v[28:31]
	s_add_u32 m0, s7, 0xc000
	v_mfma_f32_16x16x32_bf16 v[16:19], v[136:139], v[172:175], v[16:19]
	global_load_lds_dwordx4 v248, s[62:63]
	v_mfma_f32_16x16x32_bf16 v[12:15], v[136:139], v[176:179], v[12:15]
	s_add_u32 m0, s7, 0xc400
	v_mfma_f32_16x16x32_bf16 v[4:7], v[136:139], v[180:183], v[4:7]
	global_load_lds_dwordx4 v249, s[62:63]
	v_mfma_f32_16x16x32_bf16 v[8:11], v[136:139], v[184:187], v[8:11]
	s_add_u32 m0, s7, 0xc800
	v_mfma_f32_16x16x32_bf16 v[32:35], v[140:143], v[172:175], v[32:35]
	global_load_lds_dwordx4 v250, s[62:63]
	v_mfma_f32_16x16x32_bf16 v[24:27], v[140:143], v[176:179], v[24:27]
	s_add_u32 m0, s7, 0xcc00
	v_mfma_f32_16x16x32_bf16 v[20:23], v[140:143], v[180:183], v[20:23]
	global_load_lds_dwordx4 v251, s[62:63]
	v_mfma_f32_16x16x32_bf16 v[0:3], v[140:143], v[184:187], v[0:3]
	s_add_u32 s8, s8, 0x80
	s_addc_u32 s9, s9, 0
	s_add_u32 s62, s62, 0x80
	s_addc_u32 s63, s63, 0
	s_branch .Lg2_done
.Lg2_tailplain:
	s_waitcnt vmcnt(8)
	s_barrier
	ds_read_b128 v[80:83], v252 offset:0
	ds_read_b128 v[144:147], v254 offset:32768
	ds_read_b128 v[148:151], v254 offset:34816
	ds_read_b128 v[152:155], v254 offset:36864
	ds_read_b128 v[156:159], v254 offset:38912
	ds_read_b128 v[84:87], v252 offset:2048
	ds_read_b128 v[88:91], v252 offset:4096
	ds_read_b128 v[92:95], v252 offset:6144
	ds_read_b128 v[124:127], v253 offset:0
	ds_read_b128 v[172:175], v255 offset:32768
	ds_read_b128 v[176:179], v255 offset:34816
	ds_read_b128 v[180:183], v255 offset:36864
	ds_read_b128 v[184:187], v255 offset:38912
	s_waitcnt lgkmcnt(11)
	v_mfma_f32_16x16x32_bf16 v[60:63], v[80:83], v[144:147], v[60:63]
	s_waitcnt lgkmcnt(10)
	v_mfma_f32_16x16x32_bf16 v[56:59], v[80:83], v[148:151], v[56:59]
	s_waitcnt lgkmcnt(9)
	v_mfma_f32_16x16x32_bf16 v[52:55], v[80:83], v[152:155], v[52:55]
	s_waitcnt lgkmcnt(8)
	v_mfma_f32_16x16x32_bf16 v[48:51], v[80:83], v[156:159], v[48:51]
	ds_read_b128 v[132:135], v253 offset:2048
	ds_read_b128 v[136:139], v253 offset:4096
	ds_read_b128 v[140:143], v253 offset:6144
	s_waitcnt lgkmcnt(10)
	v_mfma_f32_16x16x32_bf16 v[44:47], v[84:87], v[144:147], v[44:47]
	v_mfma_f32_16x16x32_bf16 v[40:43], v[84:87], v[148:151], v[40:43]
	v_mfma_f32_16x16x32_bf16 v[36:39], v[84:87], v[152:155], v[36:39]
	v_mfma_f32_16x16x32_bf16 v[28:31], v[84:87], v[156:159], v[28:31]
	s_waitcnt lgkmcnt(9)
	v_mfma_f32_16x16x32_bf16 v[16:19], v[88:91], v[144:147], v[16:19]
	v_mfma_f32_16x16x32_bf16 v[12:15], v[88:91], v[148:151], v[12:15]
	v_mfma_f32_16x16x32_bf16 v[4:7], v[88:91], v[152:155], v[4:7]
	v_mfma_f32_16x16x32_bf16 v[8:11], v[88:91], v[156:159], v[8:11]
	s_waitcnt lgkmcnt(8)
	v_mfma_f32_16x16x32_bf16 v[32:35], v[92:95], v[144:147], v[32:35]
	v_mfma_f32_16x16x32_bf16 v[24:27], v[92:95], v[148:151], v[24:27]
	v_mfma_f32_16x16x32_bf16 v[20:23], v[92:95], v[152:155], v[20:23]
	v_mfma_f32_16x16x32_bf16 v[0:3], v[92:95], v[156:159], v[0:3]
	s_waitcnt lgkmcnt(0)
	s_barrier
	v_mfma_f32_16x16x32_bf16 v[60:63], v[124:127], v[172:175], v[60:63]
	v_mfma_f32_16x16x32_bf16 v[56:59], v[124:127], v[176:179], v[56:59]
	v_mfma_f32_16x16x32_bf16 v[52:55], v[124:127], v[180:183], v[52:55]
	v_mfma_f32_16x16x32_bf16 v[48:51], v[124:127], v[184:187], v[48:51]
	v_mfma_f32_16x16x32_bf16 v[44:47], v[132:135], v[172:175], v[44:47]
	v_mfma_f32_16x16x32_bf16 v[40:43], v[132:135], v[176:179], v[40:43]
	v_mfma_f32_16x16x32_bf16 v[36:39], v[132:135], v[180:183], v[36:39]
	v_mfma_f32_16x16x32_bf16 v[28:31], v[132:135], v[184:187], v[28:31]
	v_mfma_f32_16x16x32_bf16 v[16:19], v[136:139], v[172:175], v[16:19]
	v_mfma_f32_16x16x32_bf16 v[12:15], v[136:139], v[176:179], v[12:15]
	v_mfma_f32_16x16x32_bf16 v[4:7], v[136:139], v[180:183], v[4:7]
	v_mfma_f32_16x16x32_bf16 v[8:11], v[136:139], v[184:187], v[8:11]
	v_mfma_f32_16x16x32_bf16 v[32:35], v[140:143], v[172:175], v[32:35]
	v_mfma_f32_16x16x32_bf16 v[24:27], v[140:143], v[176:179], v[24:27]
	v_mfma_f32_16x16x32_bf16 v[20:23], v[140:143], v[180:183], v[20:23]
	v_mfma_f32_16x16x32_bf16 v[0:3], v[140:143], v[184:187], v[0:3]
	s_waitcnt vmcnt(0)
	s_barrier
	ds_read_b128 v[80:83], v252 offset:16384
	ds_read_b128 v[144:147], v254 offset:49152
	ds_read_b128 v[148:151], v254 offset:51200
	ds_read_b128 v[152:155], v254 offset:53248
	ds_read_b128 v[156:159], v254 offset:55296
	ds_read_b128 v[84:87], v252 offset:18432
	ds_read_b128 v[88:91], v252 offset:20480
	ds_read_b128 v[92:95], v252 offset:22528
	ds_read_b128 v[124:127], v253 offset:16384
	ds_read_b128 v[172:175], v255 offset:49152
	ds_read_b128 v[176:179], v255 offset:51200
	ds_read_b128 v[180:183], v255 offset:53248
	ds_read_b128 v[184:187], v255 offset:55296
	s_waitcnt lgkmcnt(11)
	v_mfma_f32_16x16x32_bf16 v[60:63], v[80:83], v[144:147], v[60:63]
	s_waitcnt lgkmcnt(10)
	v_mfma_f32_16x16x32_bf16 v[56:59], v[80:83], v[148:151], v[56:59]
	s_waitcnt lgkmcnt(9)
	v_mfma_f32_16x16x32_bf16 v[52:55], v[80:83], v[152:155], v[52:55]
	s_waitcnt lgkmcnt(8)
	v_mfma_f32_16x16x32_bf16 v[48:51], v[80:83], v[156:159], v[48:51]
	ds_read_b128 v[132:135], v253 offset:18432
	ds_read_b128 v[136:139], v253 offset:20480
	ds_read_b128 v[140:143], v253 offset:22528
	s_waitcnt lgkmcnt(10)
	v_mfma_f32_16x16x32_bf16 v[44:47], v[84:87], v[144:147], v[44:47]
	v_mfma_f32_16x16x32_bf16 v[40:43], v[84:87], v[148:151], v[40:43]
	v_mfma_f32_16x16x32_bf16 v[36:39], v[84:87], v[152:155], v[36:39]
	v_mfma_f32_16x16x32_bf16 v[28:31], v[84:87], v[156:159], v[28:31]
	s_waitcnt lgkmcnt(9)
	v_mfma_f32_16x16x32_bf16 v[16:19], v[88:91], v[144:147], v[16:19]
	v_mfma_f32_16x16x32_bf16 v[12:15], v[88:91], v[148:151], v[12:15]
	v_mfma_f32_16x16x32_bf16 v[4:7], v[88:91], v[152:155], v[4:7]
	v_mfma_f32_16x16x32_bf16 v[8:11], v[88:91], v[156:159], v[8:11]
	s_waitcnt lgkmcnt(8)
	v_mfma_f32_16x16x32_bf16 v[32:35], v[92:95], v[144:147], v[32:35]
	v_mfma_f32_16x16x32_bf16 v[24:27], v[92:95], v[148:151], v[24:27]
	v_mfma_f32_16x16x32_bf16 v[20:23], v[92:95], v[152:155], v[20:23]
	v_mfma_f32_16x16x32_bf16 v[0:3], v[92:95], v[156:159], v[0:3]
	s_waitcnt lgkmcnt(0)
	s_barrier
	v_mfma_f32_16x16x32_bf16 v[60:63], v[124:127], v[172:175], v[60:63]
	v_mfma_f32_16x16x32_bf16 v[56:59], v[124:127], v[176:179], v[56:59]
	v_mfma_f32_16x16x32_bf16 v[52:55], v[124:127], v[180:183], v[52:55]
	v_mfma_f32_16x16x32_bf16 v[48:51], v[124:127], v[184:187], v[48:51]
	v_mfma_f32_16x16x32_bf16 v[44:47], v[132:135], v[172:175], v[44:47]
	v_mfma_f32_16x16x32_bf16 v[40:43], v[132:135], v[176:179], v[40:43]
	v_mfma_f32_16x16x32_bf16 v[36:39], v[132:135], v[180:183], v[36:39]
	v_mfma_f32_16x16x32_bf16 v[28:31], v[132:135], v[184:187], v[28:31]
	v_mfma_f32_16x16x32_bf16 v[16:19], v[136:139], v[172:175], v[16:19]
	v_mfma_f32_16x16x32_bf16 v[12:15], v[136:139], v[176:179], v[12:15]
	v_mfma_f32_16x16x32_bf16 v[4:7], v[136:139], v[180:183], v[4:7]
	v_mfma_f32_16x16x32_bf16 v[8:11], v[136:139], v[184:187], v[8:11]
	v_mfma_f32_16x16x32_bf16 v[32:35], v[140:143], v[172:175], v[32:35]
	v_mfma_f32_16x16x32_bf16 v[24:27], v[140:143], v[176:179], v[24:27]
	v_mfma_f32_16x16x32_bf16 v[20:23], v[140:143], v[180:183], v[20:23]
	v_mfma_f32_16x16x32_bf16 v[0:3], v[140:143], v[184:187], v[0:3]
.Lg2_done:
	s_nop 7
	s_nop 1
	v_add_u32_e32 v80, s12, v168
	v_or_b32_e32 v64, s6, v169
	s_cmpk_gt_i32 s6, 0x3ff
	s_mov_b64 s[6:7], -1
	s_cbranch_scc0 .LBB0_416
	s_cmpk_gt_u32 s13, 0xbff
	s_cbranch_scc0 .LBB0_413
	s_cmpk_gt_u32 s13, 0x13ff
	s_cbranch_scc0 .LBB0_236
	s_cmpk_gt_u32 s13, 0x17ff
	s_cbranch_scc0 .LBB0_217
	s_and_saveexec_b64 s[6:7], s[4:5]
	s_cbranch_execz .LBB0_216
	v_lshlrev_b32_e32 v98, 7, v80
	v_lshl_add_u64 v[66:67], v[104:105], 0, v[98:99]
	global_store_dword v[66:67], v60, off
	global_store_dword v[66:67], v61, off offset:128
	global_store_dword v[66:67], v62, off offset:256
	global_store_dword v[66:67], v63, off offset:384
	global_store_dword v[66:67], v56, off offset:64
	global_store_dword v[66:67], v57, off offset:192
	global_store_dword v[66:67], v58, off offset:320
	global_store_dword v[66:67], v59, off offset:448
	global_store_dword v[66:67], v44, off offset:2048
	global_store_dword v[66:67], v45, off offset:2176
	global_store_dword v[66:67], v46, off offset:2304
	global_store_dword v[66:67], v47, off offset:2432
	global_store_dword v[66:67], v40, off offset:2112
	global_store_dword v[66:67], v41, off offset:2240
	global_store_dword v[66:67], v42, off offset:2368
	global_store_dword v[66:67], v43, off offset:2496
	v_or_b32_e32 v66, 0x1000, v98
	v_mov_b32_e32 v67, v99
	v_lshl_add_u64 v[68:69], v[104:105], 0, v[66:67]
	global_store_dword v[68:69], v16, off
	v_or_b32_e32 v68, 0x1080, v98
	v_mov_b32_e32 v69, v99
	v_lshl_add_u64 v[70:71], v[104:105], 0, v[68:69]
	global_store_dword v[70:71], v17, off
	v_or_b32_e32 v70, 0x1100, v98
	v_mov_b32_e32 v71, v99
	v_lshl_add_u64 v[66:67], v[106:107], 0, v[66:67]
	v_lshl_add_u64 v[72:73], v[104:105], 0, v[70:71]
	global_store_dword v[66:67], v12, off
	v_lshl_add_u64 v[66:67], v[106:107], 0, v[68:69]
	global_store_dword v[72:73], v18, off
	v_or_b32_e32 v72, 0x1180, v98
	v_mov_b32_e32 v73, v99
	global_store_dword v[66:67], v13, off
	v_lshl_add_u64 v[66:67], v[106:107], 0, v[70:71]
	global_store_dword v[66:67], v14, off
	v_lshl_add_u64 v[66:67], v[106:107], 0, v[72:73]
	global_store_dword v[66:67], v15, off
	v_or_b32_e32 v66, 0x1800, v98
	v_mov_b32_e32 v67, v99
	v_lshl_add_u64 v[68:69], v[104:105], 0, v[66:67]
	global_store_dword v[68:69], v32, off
	v_or_b32_e32 v68, 0x1880, v98
	v_mov_b32_e32 v69, v99
	v_lshl_add_u64 v[70:71], v[104:105], 0, v[68:69]
	v_lshl_add_u64 v[66:67], v[106:107], 0, v[66:67]
	global_store_dword v[70:71], v33, off
	v_or_b32_e32 v70, 0x1900, v98
	v_mov_b32_e32 v71, v99
	global_store_dword v[66:67], v24, off
	v_lshl_add_u64 v[66:67], v[106:107], 0, v[68:69]
	v_lshl_add_u64 v[74:75], v[104:105], 0, v[72:73]
	v_lshl_add_u64 v[72:73], v[104:105], 0, v[70:71]
	v_or_b32_e32 v98, 0x1980, v98
	global_store_dword v[66:67], v25, off
	v_lshl_add_u64 v[66:67], v[106:107], 0, v[70:71]
	global_store_dword v[72:73], v34, off
	v_lshl_add_u64 v[72:73], v[104:105], 0, v[98:99]
	global_store_dword v[66:67], v26, off
	v_lshl_add_u64 v[66:67], v[106:107], 0, v[98:99]
	global_store_dword v[74:75], v19, off
	global_store_dword v[72:73], v35, off
	global_store_dword v[66:67], v27, off

.Lg6_loop:
	s_waitcnt vmcnt(8)
	s_barrier
	ds_read_b128 v[64:67], v252 offset:0
	ds_read_b128 v[104:107], v254 offset:32768
	ds_read_b128 v[108:111], v254 offset:34816
	ds_read_b128 v[112:115], v254 offset:36864
	ds_read_b128 v[116:119], v254 offset:38912
	ds_read_b128 v[68:71], v252 offset:2048
	ds_read_b128 v[72:75], v252 offset:4096
	ds_read_b128 v[76:79], v252 offset:6144
	ds_read_b128 v[80:83], v253 offset:0
	ds_read_b128 v[120:123], v255 offset:32768
	ds_read_b128 v[124:127], v255 offset:34816
	ds_read_b128 v[132:135], v255 offset:36864
	ds_read_b128 v[136:139], v255 offset:38912
	s_waitcnt lgkmcnt(11)
	v_mfma_f32_16x16x32_bf16 v[60:63], v[64:67], v[104:107], v[60:63]
	s_waitcnt lgkmcnt(10)
	v_mfma_f32_16x16x32_bf16 v[44:47], v[64:67], v[108:111], v[44:47]
	s_waitcnt lgkmcnt(9)
	v_mfma_f32_16x16x32_bf16 v[28:31], v[64:67], v[112:115], v[28:31]
	s_waitcnt lgkmcnt(8)
	v_mfma_f32_16x16x32_bf16 v[12:15], v[64:67], v[116:119], v[12:15]
	ds_read_b128 v[84:87], v253 offset:2048
	ds_read_b128 v[88:91], v253 offset:4096
	ds_read_b128 v[92:95], v253 offset:6144
	s_waitcnt lgkmcnt(10)
	v_mfma_f32_16x16x32_bf16 v[56:59], v[68:71], v[104:107], v[56:59]
	v_mfma_f32_16x16x32_bf16 v[40:43], v[68:71], v[108:111], v[40:43]
	v_mfma_f32_16x16x32_bf16 v[20:23], v[68:71], v[112:115], v[20:23]
	v_mfma_f32_16x16x32_bf16 v[4:7], v[68:71], v[116:119], v[4:7]
	s_waitcnt lgkmcnt(9)
	v_mfma_f32_16x16x32_bf16 v[52:55], v[72:75], v[104:107], v[52:55]
	v_mfma_f32_16x16x32_bf16 v[32:35], v[72:75], v[108:111], v[32:35]
	v_mfma_f32_16x16x32_bf16 v[16:19], v[72:75], v[112:115], v[16:19]
	v_mfma_f32_16x16x32_bf16 v[0:3], v[72:75], v[116:119], v[0:3]
	s_waitcnt lgkmcnt(8)
	v_mfma_f32_16x16x32_bf16 v[48:51], v[76:79], v[104:107], v[48:51]
	v_mfma_f32_16x16x32_bf16 v[36:39], v[76:79], v[108:111], v[36:39]
	v_mfma_f32_16x16x32_bf16 v[24:27], v[76:79], v[112:115], v[24:27]
	v_mfma_f32_16x16x32_bf16 v[8:11], v[76:79], v[116:119], v[8:11]
	s_waitcnt lgkmcnt(0)
	s_barrier
	s_add_u32 m0, s6, 0x0
	v_mfma_f32_16x16x32_bf16 v[60:63], v[80:83], v[120:123], v[60:63]
	global_load_lds_dwordx4 v248, s[40:41]
	v_mfma_f32_16x16x32_bf16 v[44:47], v[80:83], v[124:127], v[44:47]
	s_add_u32 m0, s6, 0x400
	v_mfma_f32_16x16x32_bf16 v[28:31], v[80:83], v[132:135], v[28:31]
	global_load_lds_dwordx4 v249, s[40:41]
	v_mfma_f32_16x16x32_bf16 v[12:15], v[80:83], v[136:139], v[12:15]
	s_add_u32 m0, s6, 0x800
	v_mfma_f32_16x16x32_bf16 v[56:59], v[84:87], v[120:123], v[56:59]
	global_load_lds_dwordx4 v250, s[40:41]
	v_mfma_f32_16x16x32_bf16 v[40:43], v[84:87], v[124:127], v[40:43]
	s_add_u32 m0, s6, 0xc00
	v_mfma_f32_16x16x32_bf16 v[20:23], v[84:87], v[132:135], v[20:23]
	global_load_lds_dwordx4 v251, s[40:41]
	v_mfma_f32_16x16x32_bf16 v[4:7], v[84:87], v[136:139], v[4:7]
	s_add_u32 m0, s6, 0x8000
	v_mfma_f32_16x16x32_bf16 v[52:55], v[88:91], v[120:123], v[52:55]
	global_load_lds_dwordx4 v248, s[48:49]
	v_mfma_f32_16x16x32_bf16 v[32:35], v[88:91], v[124:127], v[32:35]
	s_add_u32 m0, s6, 0x8400
	v_mfma_f32_16x16x32_bf16 v[16:19], v[88:91], v[132:135], v[16:19]
	global_load_lds_dwordx4 v249, s[48:49]
	v_mfma_f32_16x16x32_bf16 v[0:3], v[88:91], v[136:139], v[0:3]
	s_add_u32 m0, s6, 0x8800
	v_mfma_f32_16x16x32_bf16 v[48:51], v[92:95], v[120:123], v[48:51]
	global_load_lds_dwordx4 v250, s[48:49]
	v_mfma_f32_16x16x32_bf16 v[36:39], v[92:95], v[124:127], v[36:39]
	s_add_u32 m0, s6, 0x8c00
	v_mfma_f32_16x16x32_bf16 v[24:27], v[92:95], v[132:135], v[24:27]
	global_load_lds_dwordx4 v251, s[48:49]
	v_mfma_f32_16x16x32_bf16 v[8:11], v[92:95], v[136:139], v[8:11]
	s_add_u32 s40, s40, 0x80
	s_addc_u32 s41, s41, 0
	s_add_u32 s48, s48, 0x80
	s_addc_u32 s49, s49, 0
	s_waitcnt vmcnt(8)
	s_barrier
	ds_read_b128 v[64:67], v252 offset:16384
	ds_read_b128 v[104:107], v254 offset:49152
	ds_read_b128 v[108:111], v254 offset:51200
	ds_read_b128 v[112:115], v254 offset:53248
	ds_read_b128 v[116:119], v254 offset:55296
	ds_read_b128 v[68:71], v252 offset:18432
	ds_read_b128 v[72:75], v252 offset:20480
	ds_read_b128 v[76:79], v252 offset:22528
	ds_read_b128 v[80:83], v253 offset:16384
	ds_read_b128 v[120:123], v255 offset:49152
	ds_read_b128 v[124:127], v255 offset:51200
	ds_read_b128 v[132:135], v255 offset:53248
	ds_read_b128 v[136:139], v255 offset:55296
	s_waitcnt lgkmcnt(11)
	v_mfma_f32_16x16x32_bf16 v[60:63], v[64:67], v[104:107], v[60:63]
	s_waitcnt lgkmcnt(10)
	v_mfma_f32_16x16x32_bf16 v[44:47], v[64:67], v[108:111], v[44:47]
	s_waitcnt lgkmcnt(9)
	v_mfma_f32_16x16x32_bf16 v[28:31], v[64:67], v[112:115], v[28:31]
	s_waitcnt lgkmcnt(8)
	v_mfma_f32_16x16x32_bf16 v[12:15], v[64:67], v[116:119], v[12:15]
	ds_read_b128 v[84:87], v253 offset:18432
	ds_read_b128 v[88:91], v253 offset:20480
	ds_read_b128 v[92:95], v253 offset:22528
	s_waitcnt lgkmcnt(10)
	v_mfma_f32_16x16x32_bf16 v[56:59], v[68:71], v[104:107], v[56:59]
	v_mfma_f32_16x16x32_bf16 v[40:43], v[68:71], v[108:111], v[40:43]
	v_mfma_f32_16x16x32_bf16 v[20:23], v[68:71], v[112:115], v[20:23]
	v_mfma_f32_16x16x32_bf16 v[4:7], v[68:71], v[116:119], v[4:7]
	s_waitcnt lgkmcnt(9)
	v_mfma_f32_16x16x32_bf16 v[52:55], v[72:75], v[104:107], v[52:55]
	v_mfma_f32_16x16x32_bf16 v[32:35], v[72:75], v[108:111], v[32:35]
	v_mfma_f32_16x16x32_bf16 v[16:19], v[72:75], v[112:115], v[16:19]
	v_mfma_f32_16x16x32_bf16 v[0:3], v[72:75], v[116:119], v[0:3]
	s_waitcnt lgkmcnt(8)
	v_mfma_f32_16x16x32_bf16 v[48:51], v[76:79], v[104:107], v[48:51]
	v_mfma_f32_16x16x32_bf16 v[36:39], v[76:79], v[108:111], v[36:39]
	v_mfma_f32_16x16x32_bf16 v[24:27], v[76:79], v[112:115], v[24:27]
	v_mfma_f32_16x16x32_bf16 v[8:11], v[76:79], v[116:119], v[8:11]
	s_waitcnt lgkmcnt(0)
	s_barrier
	s_add_u32 m0, s6, 0x4000
	v_mfma_f32_16x16x32_bf16 v[60:63], v[80:83], v[120:123], v[60:63]
	global_load_lds_dwordx4 v248, s[40:41]
	v_mfma_f32_16x16x32_bf16 v[44:47], v[80:83], v[124:127], v[44:47]
	s_add_u32 m0, s6, 0x4400
	v_mfma_f32_16x16x32_bf16 v[28:31], v[80:83], v[132:135], v[28:31]
	global_load_lds_dwordx4 v249, s[40:41]
	v_mfma_f32_16x16x32_bf16 v[12:15], v[80:83], v[136:139], v[12:15]
	s_add_u32 m0, s6, 0x4800
	v_mfma_f32_16x16x32_bf16 v[56:59], v[84:87], v[120:123], v[56:59]
	global_load_lds_dwordx4 v250, s[40:41]
	v_mfma_f32_16x16x32_bf16 v[40:43], v[84:87], v[124:127], v[40:43]
	s_add_u32 m0, s6, 0x4c00
	v_mfma_f32_16x16x32_bf16 v[20:23], v[84:87], v[132:135], v[20:23]
	global_load_lds_dwordx4 v251, s[40:41]
	v_mfma_f32_16x16x32_bf16 v[4:7], v[84:87], v[136:139], v[4:7]
	s_add_u32 m0, s6, 0xc000
	v_mfma_f32_16x16x32_bf16 v[52:55], v[88:91], v[120:123], v[52:55]
	global_load_lds_dwordx4 v248, s[48:49]
	v_mfma_f32_16x16x32_bf16 v[32:35], v[88:91], v[124:127], v[32:35]
	s_add_u32 m0, s6, 0xc400
	v_mfma_f32_16x16x32_bf16 v[16:19], v[88:91], v[132:135], v[16:19]
	global_load_lds_dwordx4 v249, s[48:49]
	v_mfma_f32_16x16x32_bf16 v[0:3], v[88:91], v[136:139], v[0:3]
	s_add_u32 m0, s6, 0xc800
	v_mfma_f32_16x16x32_bf16 v[48:51], v[92:95], v[120:123], v[48:51]
	global_load_lds_dwordx4 v250, s[48:49]
	v_mfma_f32_16x16x32_bf16 v[36:39], v[92:95], v[124:127], v[36:39]
	s_add_u32 m0, s6, 0xcc00
	v_mfma_f32_16x16x32_bf16 v[24:27], v[92:95], v[132:135], v[24:27]
	global_load_lds_dwordx4 v251, s[48:49]
	v_mfma_f32_16x16x32_bf16 v[8:11], v[92:95], v[136:139], v[8:11]
	s_add_u32 s40, s40, 0x80
	s_addc_u32 s41, s41, 0
	s_add_u32 s48, s48, 0x80
	s_addc_u32 s49, s49, 0
	s_sub_u32 s31, s31, 1
	s_cmp_lg_u32 s31, 0
	s_cbranch_scc1 .Lg6_loop
	s_waitcnt vmcnt(8)
	s_barrier
	ds_read_b128 v[64:67], v252 offset:0
	ds_read_b128 v[104:107], v254 offset:32768
	ds_read_b128 v[108:111], v254 offset:34816
	ds_read_b128 v[112:115], v254 offset:36864
	ds_read_b128 v[116:119], v254 offset:38912
	ds_read_b128 v[68:71], v252 offset:2048
	ds_read_b128 v[72:75], v252 offset:4096
	ds_read_b128 v[76:79], v252 offset:6144
	ds_read_b128 v[80:83], v253 offset:0
	ds_read_b128 v[120:123], v255 offset:32768
	ds_read_b128 v[124:127], v255 offset:34816
	ds_read_b128 v[132:135], v255 offset:36864
	ds_read_b128 v[136:139], v255 offset:38912
	s_waitcnt lgkmcnt(11)
	v_mfma_f32_16x16x32_bf16 v[60:63], v[64:67], v[104:107], v[60:63]
	s_waitcnt lgkmcnt(10)
	v_mfma_f32_16x16x32_bf16 v[44:47], v[64:67], v[108:111], v[44:47]
	s_waitcnt lgkmcnt(9)
	v_mfma_f32_16x16x32_bf16 v[28:31], v[64:67], v[112:115], v[28:31]
	s_waitcnt lgkmcnt(8)
	v_mfma_f32_16x16x32_bf16 v[12:15], v[64:67], v[116:119], v[12:15]
	ds_read_b128 v[84:87], v253 offset:2048
	ds_read_b128 v[88:91], v253 offset:4096
	ds_read_b128 v[92:95], v253 offset:6144
	s_waitcnt lgkmcnt(10)
	v_mfma_f32_16x16x32_bf16 v[56:59], v[68:71], v[104:107], v[56:59]
	v_mfma_f32_16x16x32_bf16 v[40:43], v[68:71], v[108:111], v[40:43]
	v_mfma_f32_16x16x32_bf16 v[20:23], v[68:71], v[112:115], v[20:23]
	v_mfma_f32_16x16x32_bf16 v[4:7], v[68:71], v[116:119], v[4:7]
	s_waitcnt lgkmcnt(9)
	v_mfma_f32_16x16x32_bf16 v[52:55], v[72:75], v[104:107], v[52:55]
	v_mfma_f32_16x16x32_bf16 v[32:35], v[72:75], v[108:111], v[32:35]
	v_mfma_f32_16x16x32_bf16 v[16:19], v[72:75], v[112:115], v[16:19]
	v_mfma_f32_16x16x32_bf16 v[0:3], v[72:75], v[116:119], v[0:3]
	s_waitcnt lgkmcnt(8)
	v_mfma_f32_16x16x32_bf16 v[48:51], v[76:79], v[104:107], v[48:51]
	v_mfma_f32_16x16x32_bf16 v[36:39], v[76:79], v[108:111], v[36:39]
	v_mfma_f32_16x16x32_bf16 v[24:27], v[76:79], v[112:115], v[24:27]
	v_mfma_f32_16x16x32_bf16 v[8:11], v[76:79], v[116:119], v[8:11]
	s_waitcnt lgkmcnt(0)
	s_barrier
	v_mfma_f32_16x16x32_bf16 v[60:63], v[80:83], v[120:123], v[60:63]
	v_mfma_f32_16x16x32_bf16 v[44:47], v[80:83], v[124:127], v[44:47]
	v_mfma_f32_16x16x32_bf16 v[28:31], v[80:83], v[132:135], v[28:31]
	v_mfma_f32_16x16x32_bf16 v[12:15], v[80:83], v[136:139], v[12:15]
	v_mfma_f32_16x16x32_bf16 v[56:59], v[84:87], v[120:123], v[56:59]
	v_mfma_f32_16x16x32_bf16 v[40:43], v[84:87], v[124:127], v[40:43]
	v_mfma_f32_16x16x32_bf16 v[20:23], v[84:87], v[132:135], v[20:23]
	v_mfma_f32_16x16x32_bf16 v[4:7], v[84:87], v[136:139], v[4:7]
	v_mfma_f32_16x16x32_bf16 v[52:55], v[88:91], v[120:123], v[52:55]
	v_mfma_f32_16x16x32_bf16 v[32:35], v[88:91], v[124:127], v[32:35]
	v_mfma_f32_16x16x32_bf16 v[16:19], v[88:91], v[132:135], v[16:19]
	v_mfma_f32_16x16x32_bf16 v[0:3], v[88:91], v[136:139], v[0:3]
	v_mfma_f32_16x16x32_bf16 v[48:51], v[92:95], v[120:123], v[48:51]
	v_mfma_f32_16x16x32_bf16 v[36:39], v[92:95], v[124:127], v[36:39]
	v_mfma_f32_16x16x32_bf16 v[24:27], v[92:95], v[132:135], v[24:27]
	v_mfma_f32_16x16x32_bf16 v[8:11], v[92:95], v[136:139], v[8:11]
	s_waitcnt vmcnt(0)
	s_barrier
	ds_read_b128 v[64:67], v252 offset:16384
	ds_read_b128 v[104:107], v254 offset:49152
	ds_read_b128 v[108:111], v254 offset:51200
	ds_read_b128 v[112:115], v254 offset:53248
	ds_read_b128 v[116:119], v254 offset:55296
	ds_read_b128 v[68:71], v252 offset:18432
	ds_read_b128 v[72:75], v252 offset:20480
	ds_read_b128 v[76:79], v252 offset:22528
	ds_read_b128 v[80:83], v253 offset:16384
	ds_read_b128 v[120:123], v255 offset:49152
	ds_read_b128 v[124:127], v255 offset:51200
	ds_read_b128 v[132:135], v255 offset:53248
	ds_read_b128 v[136:139], v255 offset:55296
	s_waitcnt lgkmcnt(11)
	v_mfma_f32_16x16x32_bf16 v[60:63], v[64:67], v[104:107], v[60:63]
	s_waitcnt lgkmcnt(10)
	v_mfma_f32_16x16x32_bf16 v[44:47], v[64:67], v[108:111], v[44:47]
	s_waitcnt lgkmcnt(9)
	v_mfma_f32_16x16x32_bf16 v[28:31], v[64:67], v[112:115], v[28:31]
	s_waitcnt lgkmcnt(8)
	v_mfma_f32_16x16x32_bf16 v[12:15], v[64:67], v[116:119], v[12:15]
	ds_read_b128 v[84:87], v253 offset:18432
	ds_read_b128 v[88:91], v253 offset:20480
	ds_read_b128 v[92:95], v253 offset:22528
	s_waitcnt lgkmcnt(10)
	v_mfma_f32_16x16x32_bf16 v[56:59], v[68:71], v[104:107], v[56:59]
	v_mfma_f32_16x16x32_bf16 v[40:43], v[68:71], v[108:111], v[40:43]
	v_mfma_f32_16x16x32_bf16 v[20:23], v[68:71], v[112:115], v[20:23]
	v_mfma_f32_16x16x32_bf16 v[4:7], v[68:71], v[116:119], v[4:7]
	s_waitcnt lgkmcnt(9)
	v_mfma_f32_16x16x32_bf16 v[52:55], v[72:75], v[104:107], v[52:55]
	v_mfma_f32_16x16x32_bf16 v[32:35], v[72:75], v[108:111], v[32:35]
	v_mfma_f32_16x16x32_bf16 v[16:19], v[72:75], v[112:115], v[16:19]
	v_mfma_f32_16x16x32_bf16 v[0:3], v[72:75], v[116:119], v[0:3]
	s_waitcnt lgkmcnt(8)
	v_mfma_f32_16x16x32_bf16 v[48:51], v[76:79], v[104:107], v[48:51]
	v_mfma_f32_16x16x32_bf16 v[36:39], v[76:79], v[108:111], v[36:39]
	v_mfma_f32_16x16x32_bf16 v[24:27], v[76:79], v[112:115], v[24:27]
	v_mfma_f32_16x16x32_bf16 v[8:11], v[76:79], v[116:119], v[8:11]
	s_waitcnt lgkmcnt(0)
	s_barrier
	v_mfma_f32_16x16x32_bf16 v[60:63], v[80:83], v[120:123], v[60:63]
	v_mfma_f32_16x16x32_bf16 v[44:47], v[80:83], v[124:127], v[44:47]
	v_mfma_f32_16x16x32_bf16 v[28:31], v[80:83], v[132:135], v[28:31]
	v_mfma_f32_16x16x32_bf16 v[12:15], v[80:83], v[136:139], v[12:15]
	v_mfma_f32_16x16x32_bf16 v[56:59], v[84:87], v[120:123], v[56:59]
	v_mfma_f32_16x16x32_bf16 v[40:43], v[84:87], v[124:127], v[40:43]
	v_mfma_f32_16x16x32_bf16 v[20:23], v[84:87], v[132:135], v[20:23]
	v_mfma_f32_16x16x32_bf16 v[4:7], v[84:87], v[136:139], v[4:7]
	v_mfma_f32_16x16x32_bf16 v[52:55], v[88:91], v[120:123], v[52:55]
	v_mfma_f32_16x16x32_bf16 v[32:35], v[88:91], v[124:127], v[32:35]
	v_mfma_f32_16x16x32_bf16 v[16:19], v[88:91], v[132:135], v[16:19]
	v_mfma_f32_16x16x32_bf16 v[0:3], v[88:91], v[136:139], v[0:3]
	v_mfma_f32_16x16x32_bf16 v[48:51], v[92:95], v[120:123], v[48:51]
	v_mfma_f32_16x16x32_bf16 v[36:39], v[92:95], v[124:127], v[36:39]
	v_mfma_f32_16x16x32_bf16 v[24:27], v[92:95], v[132:135], v[24:27]
	v_mfma_f32_16x16x32_bf16 v[8:11], v[92:95], v[136:139], v[8:11]
	s_nop 7
	s_nop 1
	v_sub_co_u32_e32 v64, vcc, s39, v150
	s_nop 0
	v_readfirstlane_b32 s6, v64
	s_lshr_b32 s6, s6, 10
	s_add_i32 s6, s6, 1
	s_and_b64 s[40:41], vcc, exec
	s_cselect_b32 s6, 0, s6
	s_mul_hi_u32 s31, s6, 0x6000
	s_mulk_i32 s6, 0x6000
	v_or_b32_e32 v64, s30, v148
	s_add_u32 s40, s2, s6
	v_ashrrev_i32_e32 v65, 31, v64
	s_addc_u32 s41, s3, s31
	v_add_lshl_u32 v94, v149, s39, 12
	v_lshlrev_b64 v[66:67], 2, v[64:65]
	v_lshl_add_u64 v[102:103], s[40:41], 0, v[66:67]
	v_lshl_add_u64 v[136:137], s[4:5], 0, v[66:67]
	v_mov_b32_e32 v95, v97
	v_or_b32_e32 v66, 0x1000, v94
	v_mov_b32_e32 v67, v97
	v_lshl_add_u64 v[104:105], v[136:137], 0, v[94:95]
	global_load_dword v65, v[102:103], off
	global_load_dword v151, v[104:105], off
	v_lshl_add_u64 v[106:107], v[136:137], 0, v[66:67]
	v_or_b32_e32 v68, 0x2000, v94
	v_mov_b32_e32 v69, v97
	v_or_b32_e32 v70, 0x3000, v94
	v_mov_b32_e32 v71, v97
	v_or_b32_e32 v72, 0x10000, v94
	v_mov_b32_e32 v73, v97
	global_load_dword v152, v[106:107], off
	v_lshl_add_u64 v[108:109], v[136:137], 0, v[68:69]
	v_lshl_add_u64 v[110:111], v[136:137], 0, v[70:71]
	v_lshl_add_u64 v[112:113], v[136:137], 0, v[72:73]
	v_or_b32_e32 v74, 0x11000, v94
	v_mov_b32_e32 v75, v97
	global_load_dword v153, v[108:109], off
	global_load_dword v154, v[110:111], off
	global_load_dword v155, v[112:113], off
	v_lshl_add_u64 v[114:115], v[136:137], 0, v[74:75]
	v_or_b32_e32 v76, 0x12000, v94
	v_mov_b32_e32 v77, v97
	v_or_b32_e32 v78, 0x13000, v94
	v_mov_b32_e32 v79, v97
	v_or_b32_e32 v80, 0x20000, v94
	v_mov_b32_e32 v81, v97
	global_load_dword v156, v[114:115], off
	v_or_b32_e32 v96, 0x30000, v94
	v_lshl_add_u64 v[116:117], v[136:137], 0, v[76:77]
	v_lshl_add_u64 v[118:119], v[136:137], 0, v[78:79]
	v_lshl_add_u64 v[120:121], v[136:137], 0, v[80:81]
	v_or_b32_e32 v82, 0x21000, v94
	v_mov_b32_e32 v83, v97
	global_load_dword v157, v[116:117], off
	global_load_dword v158, v[118:119], off
	global_load_dword v159, v[120:121], off
	v_lshl_add_u64 v[122:123], v[136:137], 0, v[82:83]
	v_or_b32_e32 v84, 0x22000, v94
	v_mov_b32_e32 v85, v97
	v_or_b32_e32 v86, 0x23000, v94
	v_mov_b32_e32 v87, v97
	v_lshl_add_u64 v[130:131], v[136:137], 0, v[96:97]
	v_lshl_add_u64 v[124:125], v[136:137], 0, v[84:85]
	v_lshl_add_u64 v[126:127], v[136:137], 0, v[86:87]
	global_load_dword v160, v[122:123], off
	global_load_dword v161, v[124:125], off
	global_load_dword v170, v[126:127], off
	global_load_dword v171, v[130:131], off
	v_or_b32_e32 v88, 0x31000, v94
	v_mov_b32_e32 v89, v97
	v_lshl_add_u64 v[132:133], v[136:137], 0, v[88:89]
	v_or_b32_e32 v90, 0x32000, v94
	v_mov_b32_e32 v91, v97
	v_or_b32_e32 v92, 0x33000, v94
	v_mov_b32_e32 v93, v97
	v_lshl_add_u64 v[134:135], v[136:137], 0, v[90:91]
	v_lshl_add_u64 v[136:137], v[136:137], 0, v[92:93]
	global_load_dword v172, v[132:133], off
	global_load_dword v173, v[134:135], off
	global_load_dword v174, v[136:137], off
	v_or_b32_e32 v138, 16, v64
	v_ashrrev_i32_e32 v139, 31, v138
	v_lshlrev_b64 v[138:139], 2, v[138:139]
	v_lshl_add_u64 v[94:95], s[4:5], 0, v[94:95]
	global_load_dword v175, v[102:103], off offset:64
	v_lshl_add_u64 v[142:143], s[4:5], 0, v[138:139]
	v_lshl_add_u64 v[138:139], v[94:95], 0, v[138:139]
	v_add_f32_e32 v60, 0, v60
	v_lshl_add_u64 v[140:141], v[142:143], 0, v[66:67]
	global_load_dword v176, v[138:139], off
	global_load_dword v177, v[140:141], off
	global_load_dword v178, v[102:103], off offset:128
	global_load_dword v179, v[102:103], off offset:192
	v_lshl_add_u64 v[102:103], v[142:143], 0, v[68:69]
	global_load_dword v180, v[102:103], off
	v_add_f32_e32 v56, 0, v56
	v_add_f32_e32 v58, 0, v58
	v_add_f32_e32 v52, 0, v52
	v_add_f32_e32 v48, 0, v48
	v_add_f32_e32 v44, 0, v44
	v_add_f32_e32 v50, 0, v50
	v_add_f32_e32 v32, 0, v32
	v_add_f32_e32 v34, 0, v34
	v_add_f32_e32 v40, 0, v40
	v_add_f32_e32 v38, 0, v38
	v_add_f32_e32 v36, 0, v36
	v_add_f32_e32 v28, 0, v28
	v_add_f32_e32 v30, 0, v30
	v_add_f32_e32 v20, 0, v20
	s_waitcnt vmcnt(21)
	v_fmac_f32_e32 v151, v60, v65
	v_add_f32_e32 v60, 0, v61
	global_store_dword v[104:105], v151, off
	v_lshl_add_u64 v[104:105], v[142:143], 0, v[72:73]
	v_add_f32_e32 v16, 0, v16
	v_add_f32_e32 v0, 0, v0
	v_add_f32_e32 v12, 0, v12
	v_add_f32_e32 v4, 0, v4
	s_waitcnt vmcnt(21)
	v_fmac_f32_e32 v152, v60, v65
	v_add_f32_e32 v60, 0, v62
	v_add_f32_e32 v62, 0, v63
	global_store_dword v[106:107], v152, off
	v_lshl_add_u64 v[106:107], v[142:143], 0, v[76:77]
	global_load_dword v152, v[104:105], off
	s_waitcnt vmcnt(22)
	v_fmac_f32_e32 v153, v60, v65
	global_store_dword v[108:109], v153, off
	s_waitcnt vmcnt(21)
	v_fmac_f32_e32 v155, v56, v65
	v_add_f32_e32 v56, 0, v57
	v_lshl_add_u64 v[108:109], v[142:143], 0, v[80:81]
	v_lshl_add_u64 v[60:61], v[142:143], 0, v[70:71]
	global_store_dword v[112:113], v155, off
	v_add_f32_e32 v112, 0, v59
	v_fmac_f32_e32 v154, v62, v65
	global_store_dword v[110:111], v154, off
	s_waitcnt vmcnt(22)
	v_fmac_f32_e32 v156, v56, v65
	global_store_dword v[114:115], v156, off
	global_load_dword v156, v[108:109], off
	v_lshl_add_u64 v[62:63], v[142:143], 0, v[74:75]
	global_load_dword v151, v[60:61], off
	global_load_dword v154, v[106:107], off
	v_lshl_add_u64 v[110:111], v[142:143], 0, v[82:83]
	s_waitcnt vmcnt(25)
	v_fmac_f32_e32 v157, v58, v65
	v_lshl_add_u64 v[58:59], v[142:143], 0, v[84:85]
	s_waitcnt vmcnt(23)
	v_fmac_f32_e32 v159, v52, v65
	v_add_f32_e32 v52, 0, v53
	global_store_dword v[116:117], v157, off
	global_load_dword v157, v[58:59], off
	v_fmac_f32_e32 v158, v112, v65
	v_lshl_add_u64 v[112:113], v[142:143], 0, v[86:87]
	global_load_dword v182, v[112:113], off
	s_waitcnt vmcnt(25)
	v_fmac_f32_e32 v160, v52, v65
	v_add_f32_e32 v52, 0, v54
	s_waitcnt vmcnt(24)
	v_fmac_f32_e32 v161, v52, v65
	s_waitcnt vmcnt(22)
	v_fmac_f32_e32 v171, v48, v65
	v_add_f32_e32 v48, 0, v49
	v_lshl_add_u64 v[52:53], v[142:143], 0, v[90:91]
	v_lshl_add_u64 v[114:115], v[142:143], 0, v[96:97]
	global_store_dword v[120:121], v159, off
	global_load_dword v120, v[52:53], off
	v_lshl_add_u64 v[56:57], v[142:143], 0, v[78:79]
	global_load_dword v181, v[110:111], off
	global_load_dword v155, v[56:57], off
	s_waitcnt vmcnt(25)
	v_fmac_f32_e32 v172, v48, v65
	v_lshl_add_u64 v[48:49], v[142:143], 0, v[92:93]
	global_load_dword v121, v[48:49], off
	s_waitcnt vmcnt(25)
	v_fmac_f32_e32 v173, v50, v65
	global_store_dword v[118:119], v158, off
	global_load_dword v118, v[114:115], off
	v_add_f32_e32 v50, 0, v51
	global_load_dword v153, v[62:63], off
	s_waitcnt vmcnt(25)
	v_fmac_f32_e32 v176, v44, v175
	v_add_f32_e32 v44, 0, v45
	s_waitcnt vmcnt(24)
	v_fmac_f32_e32 v177, v44, v175
	v_add_f32_e32 v44, 0, v46
	v_add_f32_e32 v54, 0, v55
	s_waitcnt vmcnt(21)
	v_fmac_f32_e32 v180, v44, v175
	v_or_b32_e32 v44, 32, v64
	v_ashrrev_i32_e32 v45, 31, v44
	v_lshlrev_b64 v[44:45], 2, v[44:45]
	v_fmac_f32_e32 v174, v50, v65
	v_lshl_add_u64 v[50:51], v[94:95], 0, v[44:45]
	v_lshl_add_u64 v[44:45], s[4:5], 0, v[44:45]
	v_fmac_f32_e32 v170, v54, v65
	v_lshl_add_u64 v[54:55], v[44:45], 0, v[78:79]
	v_add_f32_e32 v46, 0, v47
	v_lshl_add_u64 v[116:117], v[142:143], 0, v[88:89]
	global_load_dword v119, v[116:117], off
	v_or_b32_e32 v64, 48, v64
	global_store_dword v[102:103], v180, off
	v_ashrrev_i32_e32 v65, 31, v64
	v_lshlrev_b64 v[64:65], 2, v[64:65]
	global_store_dword v[122:123], v160, off
	global_store_dword v[124:125], v161, off
	global_store_dword v[126:127], v170, off
	global_store_dword v[130:131], v171, off
	global_store_dword v[132:133], v172, off
	global_store_dword v[134:135], v173, off
	global_store_dword v[136:137], v174, off
	global_store_dword v[138:139], v176, off
	global_store_dword v[140:141], v177, off
	v_lshl_add_u64 v[94:95], v[94:95], 0, v[64:65]
	v_lshl_add_u64 v[64:65], s[4:5], 0, v[64:65]
	v_add_f32_e32 v21, 0, v21
	s_waitcnt vmcnt(29)
	v_fmac_f32_e32 v152, v40, v175
	v_add_f32_e32 v40, 0, v41
	global_store_dword v[104:105], v152, off
	s_add_i32 s38, s38, s34
	s_cmpk_gt_i32 s38, 0x1ff
	s_waitcnt vmcnt(25)
	v_fmac_f32_e32 v156, v32, v175
	global_store_dword v[108:109], v156, off
	global_load_dword v109, v[54:55], off
	s_waitcnt vmcnt(26)
	v_fmac_f32_e32 v151, v46, v175
	v_lshl_add_u64 v[46:47], v[44:45], 0, v[66:67]
	global_load_dword v102, v[50:51], off
	global_load_dword v103, v[46:47], off
	v_add_f32_e32 v32, 0, v33
	global_store_dword v[60:61], v151, off
	v_lshl_add_u64 v[60:61], v[44:45], 0, v[88:89]
	s_waitcnt vmcnt(26)
	v_fmac_f32_e32 v157, v34, v175
	global_store_dword v[58:59], v157, off
	v_add_f32_e32 v34, 0, v35
	v_add_f32_e32 v58, 0, v39
	s_waitcnt vmcnt(26)
	v_fmac_f32_e32 v182, v34, v175
	global_store_dword v[112:113], v182, off
	v_lshl_add_u64 v[34:35], v[44:45], 0, v[72:73]
	v_lshl_add_u64 v[66:67], v[64:65], 0, v[66:67]
	s_waitcnt vmcnt(25)
	v_fmac_f32_e32 v120, v38, v175
	global_store_dword v[52:53], v120, off
	s_waitcnt vmcnt(25)
	v_fmac_f32_e32 v181, v32, v175
	v_lshl_add_u64 v[52:53], v[44:45], 0, v[82:83]
	global_store_dword v[110:111], v181, off
	v_lshl_add_u64 v[32:33], v[44:45], 0, v[70:71]
	s_waitcnt vmcnt(24)
	v_fmac_f32_e32 v121, v58, v175
	v_lshl_add_u64 v[58:59], v[44:45], 0, v[86:87]
	global_load_dword v113, v[58:59], off
	global_load_dword v111, v[52:53], off
	s_waitcnt vmcnt(24)
	v_fmac_f32_e32 v118, v36, v175
	s_waitcnt vmcnt(23)
	v_fmac_f32_e32 v153, v40, v175
	v_add_f32_e32 v40, 0, v42
	v_add_f32_e32 v42, 0, v43
	v_fmac_f32_e32 v155, v42, v175
	global_store_dword v[56:57], v155, off
	v_lshl_add_u64 v[56:57], v[44:45], 0, v[80:81]
	global_store_dword v[114:115], v118, off
	global_load_dword v110, v[56:57], off
	global_load_dword v105, v[32:33], off
	v_add_f32_e32 v36, 0, v37
	global_load_dword v115, v[60:61], off
	v_fmac_f32_e32 v154, v40, v175
	v_lshl_add_u64 v[40:41], v[44:45], 0, v[68:69]
	global_load_dword v104, v[40:41], off
	v_lshl_add_u64 v[42:43], v[44:45], 0, v[76:77]
	global_store_dword v[106:107], v154, off
	global_load_dword v106, v[34:35], off
	s_waitcnt vmcnt(30)
	v_fmac_f32_e32 v119, v36, v175
	global_store_dword v[48:49], v121, off
	v_lshl_add_u64 v[48:49], v[44:45], 0, v[96:97]
	global_store_dword v[62:63], v153, off
	v_lshl_add_u64 v[36:37], v[44:45], 0, v[74:75]
	global_store_dword v[116:117], v119, off
	v_lshl_add_u64 v[38:39], v[44:45], 0, v[84:85]
	global_load_dword v114, v[48:49], off
	v_lshl_add_u64 v[62:63], v[44:45], 0, v[90:91]
	global_load_dword v107, v[36:37], off
	global_load_dword v108, v[42:43], off
	global_load_dword v112, v[38:39], off
	v_lshl_add_u64 v[44:45], v[44:45], 0, v[92:93]
	global_load_dword v116, v[62:63], off
	global_load_dword v117, v[44:45], off
	v_lshl_add_u64 v[68:69], v[64:65], 0, v[68:69]
	global_load_dword v120, v[68:69], off
	global_load_dword v118, v[94:95], off
	global_load_dword v119, v[66:67], off
	s_waitcnt vmcnt(28)
	v_fmac_f32_e32 v102, v28, v178
	global_store_dword v[50:51], v102, off
	v_lshl_add_u64 v[50:51], v[64:65], 0, v[70:71]
	v_add_f32_e32 v70, 0, v29
	v_lshl_add_u64 v[28:29], v[64:65], 0, v[72:73]
	s_waitcnt vmcnt(28)
	v_fmac_f32_e32 v103, v70, v178
	v_lshl_add_u64 v[70:71], v[64:65], 0, v[74:75]
	v_lshl_add_u64 v[72:73], v[64:65], 0, v[78:79]
	v_lshl_add_u64 v[74:75], v[64:65], 0, v[80:81]
	global_load_dword v122, v[70:71], off
	global_load_dword v123, v[72:73], off
	global_load_dword v124, v[74:75], off
	global_load_dword v102, v[50:51], off
	global_load_dword v121, v[28:29], off
	v_lshl_add_u64 v[78:79], v[64:65], 0, v[88:89]
	global_store_dword v[46:47], v103, off
	v_lshl_add_u64 v[46:47], v[64:65], 0, v[76:77]
	global_load_dword v103, v[46:47], off
	v_add_f32_e32 v76, 0, v31
	v_lshl_add_u64 v[80:81], v[64:65], 0, v[90:91]
	s_waitcnt vmcnt(25)
	v_fmac_f32_e32 v110, v16, v178
	s_waitcnt vmcnt(24)
	v_fmac_f32_e32 v105, v76, v178
	v_lshl_add_u64 v[76:77], v[64:65], 0, v[86:87]
	global_store_dword v[32:33], v105, off
	v_lshl_add_u64 v[32:33], v[64:65], 0, v[96:97]
	global_load_dword v86, v[78:79], off
	s_waitcnt vmcnt(24)
	v_fmac_f32_e32 v104, v30, v178
	global_store_dword v[40:41], v104, off
	v_lshl_add_u64 v[40:41], v[64:65], 0, v[82:83]
	global_load_dword v82, v[40:41], off
	v_lshl_add_u64 v[30:31], v[64:65], 0, v[84:85]
	global_load_dword v83, v[30:31], off
	global_load_dword v85, v[32:33], off
	global_load_dword v84, v[76:77], off
	s_waitcnt vmcnt(27)
	v_fmac_f32_e32 v106, v20, v178
	global_load_dword v20, v[80:81], off
	v_add_f32_e32 v16, 0, v17
	global_store_dword v[34:35], v106, off
	v_lshl_add_u64 v[34:35], v[64:65], 0, v[92:93]
	global_load_dword v64, v[34:35], off
	v_fmac_f32_e32 v111, v16, v178
	v_add_f32_e32 v16, 0, v18
	s_waitcnt vmcnt(23)
	v_fmac_f32_e32 v112, v16, v178
	v_add_f32_e32 v16, 0, v19
	v_fmac_f32_e32 v113, v16, v178
	v_add_f32_e32 v16, 0, v24
	v_fmac_f32_e32 v114, v16, v178
	v_add_f32_e32 v16, 0, v25
	s_waitcnt vmcnt(19)
	v_fmac_f32_e32 v118, v12, v179
	v_add_f32_e32 v12, 0, v13
	v_fmac_f32_e32 v107, v21, v178
	v_add_f32_e32 v21, 0, v22
	v_fmac_f32_e32 v115, v16, v178
	v_add_f32_e32 v16, 0, v26
	s_waitcnt vmcnt(18)
	v_fmac_f32_e32 v119, v12, v179
	v_add_f32_e32 v12, 0, v14
	v_fmac_f32_e32 v108, v21, v178
	v_add_f32_e32 v21, 0, v23
	v_fmac_f32_e32 v116, v16, v178
	v_add_f32_e32 v16, 0, v27
	v_fmac_f32_e32 v120, v12, v179
	v_add_f32_e32 v12, 0, v15
	v_fmac_f32_e32 v109, v21, v178
	v_fmac_f32_e32 v117, v16, v178
	global_store_dword v[36:37], v107, off
	global_store_dword v[42:43], v108, off
	global_store_dword v[54:55], v109, off
	global_store_dword v[56:57], v110, off
	global_store_dword v[52:53], v111, off
	global_store_dword v[38:39], v112, off
	global_store_dword v[58:59], v113, off
	global_store_dword v[48:49], v114, off
	global_store_dword v[60:61], v115, off
	global_store_dword v[62:63], v116, off
	global_store_dword v[44:45], v117, off
	global_store_dword v[94:95], v118, off
	s_waitcnt vmcnt(26)
	v_fmac_f32_e32 v124, v0, v179
	v_add_f32_e32 v0, 0, v1
	s_waitcnt vmcnt(24)
	v_fmac_f32_e32 v121, v4, v179
	v_add_f32_e32 v4, 0, v5
	v_fmac_f32_e32 v122, v4, v179
	v_add_f32_e32 v4, 0, v6
	s_waitcnt vmcnt(22)
	v_fmac_f32_e32 v103, v4, v179
	v_add_f32_e32 v4, 0, v7
	v_fmac_f32_e32 v102, v12, v179
	v_fmac_f32_e32 v123, v4, v179
	global_store_dword v[66:67], v119, off
	global_store_dword v[68:69], v120, off
	global_store_dword v[50:51], v102, off
	global_store_dword v[28:29], v121, off
	global_store_dword v[70:71], v122, off
	global_store_dword v[46:47], v103, off
	global_store_dword v[72:73], v123, off
	global_store_dword v[74:75], v124, off
	s_waitcnt vmcnt(26)
	v_fmac_f32_e32 v82, v0, v179
	v_add_f32_e32 v0, 0, v2
	s_waitcnt vmcnt(25)
	v_fmac_f32_e32 v83, v0, v179
	v_add_f32_e32 v0, 0, v3
	s_waitcnt vmcnt(23)
	v_fmac_f32_e32 v84, v0, v179
	v_add_f32_e32 v0, 0, v8
	v_fmac_f32_e32 v85, v0, v179
	v_add_f32_e32 v0, 0, v9
	v_fmac_f32_e32 v86, v0, v179
	v_add_f32_e32 v0, 0, v10
	s_waitcnt vmcnt(22)
	v_fmac_f32_e32 v20, v0, v179
	v_add_f32_e32 v0, 0, v11
	s_waitcnt vmcnt(20)
	v_fmac_f32_e32 v64, v0, v179
	global_store_dword v[40:41], v82, off
	global_store_dword v[30:31], v83, off
	global_store_dword v[76:77], v84, off
	global_store_dword v[32:33], v85, off
	global_store_dword v[78:79], v86, off
	global_store_dword v[80:81], v20, off
	global_store_dword v[34:35], v64, off
	s_cbranch_scc0 .LBB0_836

.LBB0_958:
	s_lshl_b32 s8, s3, 11
	s_and_b32 s8, s8, 0xfc0000
	s_add_i32 s51, s55, s2
	s_cmpk_gt_i32 s51, 0xaff
	v_lshl_add_u64 v[116:117], v[106:107], 0, s[8:9]
	s_cselect_b64 s[26:27], -1, 0
	s_lshl_b32 s8, s51, 18
	s_and_b32 s8, s8, 0xfc0000
	s_add_u32 s8, s4, s8
	s_addc_u32 s59, s5, 0
	s_ashr_i32 s30, s51, 6
	s_ashr_i32 s31, s30, 31
	s_lshl_b64 s[30:31], s[30:31], 18
	s_add_u32 s62, s6, s30
	s_addc_u32 s63, s7, s31
	s_cmpk_lt_i32 s51, 0xb00
	s_cselect_b64 vcc, -1, 0
	s_and_b64 s[30:31], vcc, exec
	s_cselect_b32 s31, s59, 0
	s_cselect_b32 s30, s8, 0
	v_lshl_add_u64 v[2:3], s[30:31], 0, v[108:109]
	v_lshl_add_u64 v[0:1], v[112:113], 0, s[24:25]
	s_cselect_b32 s63, s63, 0
	s_cselect_b32 s62, s62, 0
	v_lshl_add_u64 v[2:3], v[2:3], 0, v[110:111]
	v_cndmask_b32_e32 v129, v1, v3, vcc
	v_cndmask_b32_e32 v96, v0, v2, vcc
	v_lshl_add_u64 v[0:1], s[62:63], 0, v[108:109]
	v_lshl_add_u64 v[0:1], v[0:1], 0, v[110:111]
	v_lshl_add_u64 v[2:3], v[114:115], 0, s[24:25]
	v_cndmask_b32_e32 v132, v2, v0, vcc
	v_mov_b32_e32 v0, 0
	v_lshl_add_u64 v[136:137], v[112:113], 0, s[10:11]
	v_lshl_add_u64 v[118:119], v[112:113], 0, s[12:13]
	v_lshl_add_u64 v[140:141], v[112:113], 0, s[14:15]
	v_lshl_add_u64 v[120:121], v[112:113], 0, s[16:17]
	v_lshl_add_u64 v[142:143], v[112:113], 0, s[18:19]
	v_lshl_add_u64 v[122:123], v[112:113], 0, s[20:21]
	v_lshl_add_u64 v[144:145], v[112:113], 0, s[22:23]
	v_lshl_add_u64 v[138:139], v[114:115], 0, s[10:11]
	v_lshl_add_u64 v[124:125], v[114:115], 0, s[12:13]
	v_lshl_add_u64 v[146:147], v[114:115], 0, s[14:15]
	v_lshl_add_u64 v[126:127], v[114:115], 0, s[16:17]
	v_lshl_add_u64 v[148:149], v[114:115], 0, s[18:19]
	v_lshl_add_u64 v[130:131], v[114:115], 0, s[20:21]
	v_lshl_add_u64 v[150:151], v[114:115], 0, s[22:23]
	v_cndmask_b32_e32 v133, v3, v1, vcc
	v_lshl_add_u64 v[134:135], v[104:105], 0, s[28:29]
	s_mov_b32 s28, -2
	v_mov_b32_e32 v1, v0
	v_mov_b32_e32 v2, v0
	v_mov_b32_e32 v3, v0
	v_mov_b32_e32 v16, v0
	v_mov_b32_e32 v17, v0
	v_mov_b32_e32 v18, v0
	v_mov_b32_e32 v19, v0
	v_mov_b32_e32 v4, v0
	v_mov_b32_e32 v5, v0
	v_mov_b32_e32 v6, v0
	v_mov_b32_e32 v7, v0
	v_mov_b32_e32 v20, v0
	v_mov_b32_e32 v21, v0
	v_mov_b32_e32 v22, v0
	v_mov_b32_e32 v23, v0
	v_mov_b32_e32 v12, v0
	v_mov_b32_e32 v13, v0
	v_mov_b32_e32 v14, v0
	v_mov_b32_e32 v15, v0
	v_mov_b32_e32 v24, v0
	v_mov_b32_e32 v25, v0
	v_mov_b32_e32 v26, v0
	v_mov_b32_e32 v27, v0
	v_mov_b32_e32 v8, v0
	v_mov_b32_e32 v9, v0
	v_mov_b32_e32 v10, v0
	v_mov_b32_e32 v11, v0
	v_mov_b32_e32 v32, v0
	v_mov_b32_e32 v33, v0
	v_mov_b32_e32 v34, v0
	v_mov_b32_e32 v35, v0
	v_mov_b32_e32 v64, v0
	v_mov_b32_e32 v65, v0
	v_mov_b32_e32 v66, v0
	v_mov_b32_e32 v67, v0
	v_mov_b32_e32 v72, v0
	v_mov_b32_e32 v73, v0
	v_mov_b32_e32 v74, v0
	v_mov_b32_e32 v75, v0
	v_mov_b32_e32 v68, v0
	v_mov_b32_e32 v69, v0
	v_mov_b32_e32 v70, v0
	v_mov_b32_e32 v71, v0
	v_mov_b32_e32 v76, v0
	v_mov_b32_e32 v77, v0
	v_mov_b32_e32 v78, v0
	v_mov_b32_e32 v79, v0
	v_mov_b32_e32 v80, v0
	v_mov_b32_e32 v81, v0
	v_mov_b32_e32 v82, v0
	v_mov_b32_e32 v83, v0
	v_mov_b32_e32 v88, v0
	v_mov_b32_e32 v89, v0
	v_mov_b32_e32 v90, v0
	v_mov_b32_e32 v91, v0
	v_mov_b32_e32 v84, v0
	v_mov_b32_e32 v85, v0
	v_mov_b32_e32 v86, v0
	v_mov_b32_e32 v87, v0
	v_mov_b32_e32 v92, v0
	v_mov_b32_e32 v93, v0
	v_mov_b32_e32 v94, v0
	v_mov_b32_e32 v95, v0
	v_readfirstlane_b32 s30, v112
	v_readfirstlane_b32 s31, v113
	v_readfirstlane_b32 s62, v114
	v_readfirstlane_b32 s63, v115
	v_readfirstlane_b32 s8, v247
	s_nop 3
	s_mul_i32 s59, s8, 0x4000
	s_sub_u32 s30, s30, s59
	s_subb_u32 s31, s31, 0
	s_sub_u32 s62, s62, s59
	s_subb_u32 s63, s63, 0
	s_lshl_b32 s8, s8, 12
	s_cmp_eq_u32 s55, s58
	s_cbranch_scc1 .Lg8_first
	v_mov_b32_e32 v92, 0
	v_mov_b32_e32 v93, 0
	v_mov_b32_e32 v94, 0
	v_mov_b32_e32 v95, 0
	v_mov_b32_e32 v84, 0
	v_mov_b32_e32 v85, 0
	v_mov_b32_e32 v86, 0
	v_mov_b32_e32 v87, 0
	v_mov_b32_e32 v88, 0
	v_mov_b32_e32 v89, 0
	v_mov_b32_e32 v90, 0
	v_mov_b32_e32 v91, 0
	v_mov_b32_e32 v80, 0
	v_mov_b32_e32 v81, 0
	v_mov_b32_e32 v82, 0
	v_mov_b32_e32 v83, 0
	v_mov_b32_e32 v76, 0
	v_mov_b32_e32 v77, 0
	v_mov_b32_e32 v78, 0
	v_mov_b32_e32 v79, 0
	v_mov_b32_e32 v68, 0
	v_mov_b32_e32 v69, 0
	v_mov_b32_e32 v70, 0
	v_mov_b32_e32 v71, 0
	v_mov_b32_e32 v72, 0
	v_mov_b32_e32 v73, 0
	v_mov_b32_e32 v74, 0
	v_mov_b32_e32 v75, 0
	v_mov_b32_e32 v64, 0
	v_mov_b32_e32 v65, 0
	v_mov_b32_e32 v66, 0
	v_mov_b32_e32 v67, 0
	v_mov_b32_e32 v32, 0
	v_mov_b32_e32 v33, 0
	v_mov_b32_e32 v34, 0
	v_mov_b32_e32 v35, 0
	v_mov_b32_e32 v8, 0
	v_mov_b32_e32 v9, 0
	v_mov_b32_e32 v10, 0
	v_mov_b32_e32 v11, 0
	v_mov_b32_e32 v24, 0
	v_mov_b32_e32 v25, 0
	v_mov_b32_e32 v26, 0
	v_mov_b32_e32 v27, 0
	v_mov_b32_e32 v12, 0
	v_mov_b32_e32 v13, 0
	v_mov_b32_e32 v14, 0
	v_mov_b32_e32 v15, 0
	v_mov_b32_e32 v20, 0
	v_mov_b32_e32 v21, 0
	v_mov_b32_e32 v22, 0
	v_mov_b32_e32 v23, 0
	v_mov_b32_e32 v4, 0
	v_mov_b32_e32 v5, 0
	v_mov_b32_e32 v6, 0
	v_mov_b32_e32 v7, 0
	v_mov_b32_e32 v16, 0
	v_mov_b32_e32 v17, 0
	v_mov_b32_e32 v18, 0
	v_mov_b32_e32 v19, 0
	v_mov_b32_e32 v0, 0
	v_mov_b32_e32 v1, 0
	v_mov_b32_e32 v2, 0
	v_mov_b32_e32 v3, 0
	s_add_u32 s30, s30, 0x100
	s_addc_u32 s31, s31, 0
	s_add_u32 s62, s62, 0x100
	s_addc_u32 s63, s63, 0
	s_waitcnt vmcnt(40)
	s_barrier
	ds_read_b128 v[28:31], v252 offset:0
	ds_read_b128 v[112:115], v254 offset:32768
	ds_read_b128 v[116:119], v254 offset:34816
	ds_read_b128 v[120:123], v254 offset:36864
	ds_read_b128 v[124:127], v254 offset:38912
	ds_read_b128 v[36:39], v252 offset:2048
	ds_read_b128 v[40:43], v252 offset:4096
	ds_read_b128 v[44:47], v252 offset:6144
	ds_read_b128 v[48:51], v253 offset:0
	ds_read_b128 v[132:135], v255 offset:32768
	ds_read_b128 v[136:139], v255 offset:34816
	ds_read_b128 v[140:143], v255 offset:36864
	ds_read_b128 v[144:147], v255 offset:38912
	s_waitcnt lgkmcnt(11)
	v_mfma_f32_16x16x32_bf16 v[92:95], v[28:31], v[112:115], v[92:95]
	s_waitcnt lgkmcnt(10)
	v_mfma_f32_16x16x32_bf16 v[84:87], v[28:31], v[116:119], v[84:87]
	s_waitcnt lgkmcnt(9)
	v_mfma_f32_16x16x32_bf16 v[88:91], v[28:31], v[120:123], v[88:91]
	s_waitcnt lgkmcnt(8)
	v_mfma_f32_16x16x32_bf16 v[80:83], v[28:31], v[124:127], v[80:83]
	ds_read_b128 v[52:55], v253 offset:2048
	ds_read_b128 v[56:59], v253 offset:4096
	ds_read_b128 v[60:63], v253 offset:6144
	s_waitcnt lgkmcnt(10)
	v_mfma_f32_16x16x32_bf16 v[76:79], v[36:39], v[112:115], v[76:79]
	v_mfma_f32_16x16x32_bf16 v[68:71], v[36:39], v[116:119], v[68:71]
	v_mfma_f32_16x16x32_bf16 v[72:75], v[36:39], v[120:123], v[72:75]
	v_mfma_f32_16x16x32_bf16 v[64:67], v[36:39], v[124:127], v[64:67]
	s_waitcnt lgkmcnt(9)
	v_mfma_f32_16x16x32_bf16 v[32:35], v[40:43], v[112:115], v[32:35]
	v_mfma_f32_16x16x32_bf16 v[8:11], v[40:43], v[116:119], v[8:11]
	v_mfma_f32_16x16x32_bf16 v[24:27], v[40:43], v[120:123], v[24:27]
	v_mfma_f32_16x16x32_bf16 v[12:15], v[40:43], v[124:127], v[12:15]
	s_waitcnt lgkmcnt(8)
	v_mfma_f32_16x16x32_bf16 v[20:23], v[44:47], v[112:115], v[20:23]
	v_mfma_f32_16x16x32_bf16 v[4:7], v[44:47], v[116:119], v[4:7]
	v_mfma_f32_16x16x32_bf16 v[16:19], v[44:47], v[120:123], v[16:19]
	v_mfma_f32_16x16x32_bf16 v[0:3], v[44:47], v[124:127], v[0:3]
	s_waitcnt lgkmcnt(0)
	s_barrier
	s_add_u32 m0, s8, 0x0
	v_mfma_f32_16x16x32_bf16 v[92:95], v[48:51], v[132:135], v[92:95]
	global_load_lds_dwordx4 v248, s[30:31]
	v_mfma_f32_16x16x32_bf16 v[84:87], v[48:51], v[136:139], v[84:87]
	s_add_u32 m0, s8, 0x400
	v_mfma_f32_16x16x32_bf16 v[88:91], v[48:51], v[140:143], v[88:91]
	global_load_lds_dwordx4 v249, s[30:31]
	v_mfma_f32_16x16x32_bf16 v[80:83], v[48:51], v[144:147], v[80:83]
	s_add_u32 m0, s8, 0x800
	v_mfma_f32_16x16x32_bf16 v[76:79], v[52:55], v[132:135], v[76:79]
	global_load_lds_dwordx4 v250, s[30:31]
	v_mfma_f32_16x16x32_bf16 v[68:71], v[52:55], v[136:139], v[68:71]
	s_add_u32 m0, s8, 0xc00
	v_mfma_f32_16x16x32_bf16 v[72:75], v[52:55], v[140:143], v[72:75]
	global_load_lds_dwordx4 v251, s[30:31]
	v_mfma_f32_16x16x32_bf16 v[64:67], v[52:55], v[144:147], v[64:67]
	s_add_u32 m0, s8, 0x8000
	v_mfma_f32_16x16x32_bf16 v[32:35], v[56:59], v[132:135], v[32:35]
	global_load_lds_dwordx4 v248, s[62:63]
	v_mfma_f32_16x16x32_bf16 v[8:11], v[56:59], v[136:139], v[8:11]
	s_add_u32 m0, s8, 0x8400
	v_mfma_f32_16x16x32_bf16 v[24:27], v[56:59], v[140:143], v[24:27]
	global_load_lds_dwordx4 v249, s[62:63]
	v_mfma_f32_16x16x32_bf16 v[12:15], v[56:59], v[144:147], v[12:15]
	s_add_u32 m0, s8, 0x8800
	v_mfma_f32_16x16x32_bf16 v[20:23], v[60:63], v[132:135], v[20:23]
	global_load_lds_dwordx4 v250, s[62:63]
	v_mfma_f32_16x16x32_bf16 v[4:7], v[60:63], v[136:139], v[4:7]
	s_add_u32 m0, s8, 0x8c00
	v_mfma_f32_16x16x32_bf16 v[16:19], v[60:63], v[140:143], v[16:19]
	global_load_lds_dwordx4 v251, s[62:63]
	v_mfma_f32_16x16x32_bf16 v[0:3], v[60:63], v[144:147], v[0:3]
	s_add_u32 s30, s30, 0x80
	s_addc_u32 s31, s31, 0
	s_add_u32 s62, s62, 0x80
	s_addc_u32 s63, s63, 0
	s_waitcnt vmcnt(40)
	s_barrier
	ds_read_b128 v[28:31], v252 offset:16384
	ds_read_b128 v[112:115], v254 offset:49152
	ds_read_b128 v[116:119], v254 offset:51200
	ds_read_b128 v[120:123], v254 offset:53248
	ds_read_b128 v[124:127], v254 offset:55296
	ds_read_b128 v[36:39], v252 offset:18432
	ds_read_b128 v[40:43], v252 offset:20480
	ds_read_b128 v[44:47], v252 offset:22528
	ds_read_b128 v[48:51], v253 offset:16384
	ds_read_b128 v[132:135], v255 offset:49152
	ds_read_b128 v[136:139], v255 offset:51200
	ds_read_b128 v[140:143], v255 offset:53248
	ds_read_b128 v[144:147], v255 offset:55296
	s_waitcnt lgkmcnt(11)
	v_mfma_f32_16x16x32_bf16 v[92:95], v[28:31], v[112:115], v[92:95]
	s_waitcnt lgkmcnt(10)
	v_mfma_f32_16x16x32_bf16 v[84:87], v[28:31], v[116:119], v[84:87]
	s_waitcnt lgkmcnt(9)
	v_mfma_f32_16x16x32_bf16 v[88:91], v[28:31], v[120:123], v[88:91]
	s_waitcnt lgkmcnt(8)
	v_mfma_f32_16x16x32_bf16 v[80:83], v[28:31], v[124:127], v[80:83]
	ds_read_b128 v[52:55], v253 offset:18432
	ds_read_b128 v[56:59], v253 offset:20480
	ds_read_b128 v[60:63], v253 offset:22528
	s_waitcnt lgkmcnt(10)
	v_mfma_f32_16x16x32_bf16 v[76:79], v[36:39], v[112:115], v[76:79]
	v_mfma_f32_16x16x32_bf16 v[68:71], v[36:39], v[116:119], v[68:71]
	v_mfma_f32_16x16x32_bf16 v[72:75], v[36:39], v[120:123], v[72:75]
	v_mfma_f32_16x16x32_bf16 v[64:67], v[36:39], v[124:127], v[64:67]
	s_waitcnt lgkmcnt(9)
	v_mfma_f32_16x16x32_bf16 v[32:35], v[40:43], v[112:115], v[32:35]
	v_mfma_f32_16x16x32_bf16 v[8:11], v[40:43], v[116:119], v[8:11]
	v_mfma_f32_16x16x32_bf16 v[24:27], v[40:43], v[120:123], v[24:27]
	v_mfma_f32_16x16x32_bf16 v[12:15], v[40:43], v[124:127], v[12:15]
	s_waitcnt lgkmcnt(8)
	v_mfma_f32_16x16x32_bf16 v[20:23], v[44:47], v[112:115], v[20:23]
	v_mfma_f32_16x16x32_bf16 v[4:7], v[44:47], v[116:119], v[4:7]
	v_mfma_f32_16x16x32_bf16 v[16:19], v[44:47], v[120:123], v[16:19]
	v_mfma_f32_16x16x32_bf16 v[0:3], v[44:47], v[124:127], v[0:3]
	s_waitcnt lgkmcnt(0)
	s_barrier
	s_add_u32 m0, s8, 0x4000
	v_mfma_f32_16x16x32_bf16 v[92:95], v[48:51], v[132:135], v[92:95]
	global_load_lds_dwordx4 v248, s[30:31]
	v_mfma_f32_16x16x32_bf16 v[84:87], v[48:51], v[136:139], v[84:87]
	s_add_u32 m0, s8, 0x4400
	v_mfma_f32_16x16x32_bf16 v[88:91], v[48:51], v[140:143], v[88:91]
	global_load_lds_dwordx4 v249, s[30:31]
	v_mfma_f32_16x16x32_bf16 v[80:83], v[48:51], v[144:147], v[80:83]
	s_add_u32 m0, s8, 0x4800
	v_mfma_f32_16x16x32_bf16 v[76:79], v[52:55], v[132:135], v[76:79]
	global_load_lds_dwordx4 v250, s[30:31]
	v_mfma_f32_16x16x32_bf16 v[68:71], v[52:55], v[136:139], v[68:71]
	s_add_u32 m0, s8, 0x4c00
	v_mfma_f32_16x16x32_bf16 v[72:75], v[52:55], v[140:143], v[72:75]
	global_load_lds_dwordx4 v251, s[30:31]
	v_mfma_f32_16x16x32_bf16 v[64:67], v[52:55], v[144:147], v[64:67]
	s_add_u32 m0, s8, 0xc000
	v_mfma_f32_16x16x32_bf16 v[32:35], v[56:59], v[132:135], v[32:35]
	global_load_lds_dwordx4 v248, s[62:63]
	v_mfma_f32_16x16x32_bf16 v[8:11], v[56:59], v[136:139], v[8:11]
	s_add_u32 m0, s8, 0xc400
	v_mfma_f32_16x16x32_bf16 v[24:27], v[56:59], v[140:143], v[24:27]
	global_load_lds_dwordx4 v249, s[62:63]
	v_mfma_f32_16x16x32_bf16 v[12:15], v[56:59], v[144:147], v[12:15]
	s_add_u32 m0, s8, 0xc800
	v_mfma_f32_16x16x32_bf16 v[20:23], v[60:63], v[132:135], v[20:23]
	global_load_lds_dwordx4 v250, s[62:63]
	v_mfma_f32_16x16x32_bf16 v[4:7], v[60:63], v[136:139], v[4:7]
	s_add_u32 m0, s8, 0xcc00
	v_mfma_f32_16x16x32_bf16 v[16:19], v[60:63], v[140:143], v[16:19]
	global_load_lds_dwordx4 v251, s[62:63]
	v_mfma_f32_16x16x32_bf16 v[0:3], v[60:63], v[144:147], v[0:3]
	s_add_u32 s30, s30, 0x80
	s_addc_u32 s31, s31, 0
	s_add_u32 s62, s62, 0x80
	s_addc_u32 s63, s63, 0
	s_branch .Lg8_main
.Lg8_first:
	s_add_u32 m0, s8, 0x0
	v_mov_b32_e32 v92, 0
	global_load_lds_dwordx4 v248, s[30:31]
	v_mov_b32_e32 v93, 0
	s_add_u32 m0, s8, 0x400
	v_mov_b32_e32 v94, 0
	global_load_lds_dwordx4 v249, s[30:31]
	v_mov_b32_e32 v95, 0
	s_add_u32 m0, s8, 0x800
	v_mov_b32_e32 v84, 0
	global_load_lds_dwordx4 v250, s[30:31]
	v_mov_b32_e32 v85, 0
	s_add_u32 m0, s8, 0xc00
	v_mov_b32_e32 v86, 0
	global_load_lds_dwordx4 v251, s[30:31]
	v_mov_b32_e32 v87, 0
	s_add_u32 m0, s8, 0x8000
	v_mov_b32_e32 v88, 0
	global_load_lds_dwordx4 v248, s[62:63]
	v_mov_b32_e32 v89, 0
	s_add_u32 m0, s8, 0x8400
	v_mov_b32_e32 v90, 0
	global_load_lds_dwordx4 v249, s[62:63]
	v_mov_b32_e32 v91, 0
	s_add_u32 m0, s8, 0x8800
	v_mov_b32_e32 v80, 0
	global_load_lds_dwordx4 v250, s[62:63]
	v_mov_b32_e32 v81, 0
	s_add_u32 m0, s8, 0x8c00
	v_mov_b32_e32 v82, 0
	global_load_lds_dwordx4 v251, s[62:63]
	v_mov_b32_e32 v83, 0
	s_add_u32 s30, s30, 0x80
	s_addc_u32 s31, s31, 0
	s_add_u32 s62, s62, 0x80
	s_addc_u32 s63, s63, 0
	s_add_u32 m0, s8, 0x4000
	v_mov_b32_e32 v76, 0
	global_load_lds_dwordx4 v248, s[30:31]
	v_mov_b32_e32 v77, 0
	s_add_u32 m0, s8, 0x4400
	v_mov_b32_e32 v78, 0
	global_load_lds_dwordx4 v249, s[30:31]
	v_mov_b32_e32 v79, 0
	s_add_u32 m0, s8, 0x4800
	v_mov_b32_e32 v68, 0
	global_load_lds_dwordx4 v250, s[30:31]
	v_mov_b32_e32 v69, 0
	s_add_u32 m0, s8, 0x4c00
	v_mov_b32_e32 v70, 0
	global_load_lds_dwordx4 v251, s[30:31]
	v_mov_b32_e32 v71, 0
	s_add_u32 m0, s8, 0xc000
	v_mov_b32_e32 v72, 0
	global_load_lds_dwordx4 v248, s[62:63]
	v_mov_b32_e32 v73, 0
	s_add_u32 m0, s8, 0xc400
	v_mov_b32_e32 v74, 0
	global_load_lds_dwordx4 v249, s[62:63]
	v_mov_b32_e32 v75, 0
	s_add_u32 m0, s8, 0xc800
	v_mov_b32_e32 v64, 0
	global_load_lds_dwordx4 v250, s[62:63]
	v_mov_b32_e32 v65, 0
	s_add_u32 m0, s8, 0xcc00
	v_mov_b32_e32 v66, 0
	global_load_lds_dwordx4 v251, s[62:63]
	v_mov_b32_e32 v67, 0
	s_add_u32 s30, s30, 0x80
	s_addc_u32 s31, s31, 0
	s_add_u32 s62, s62, 0x80
	s_addc_u32 s63, s63, 0
	v_mov_b32_e32 v32, 0
	v_mov_b32_e32 v33, 0
	v_mov_b32_e32 v34, 0
	v_mov_b32_e32 v35, 0
	v_mov_b32_e32 v8, 0
	v_mov_b32_e32 v9, 0
	v_mov_b32_e32 v10, 0
	v_mov_b32_e32 v11, 0
	v_mov_b32_e32 v24, 0
	v_mov_b32_e32 v25, 0
	v_mov_b32_e32 v26, 0
	v_mov_b32_e32 v27, 0
	v_mov_b32_e32 v12, 0
	v_mov_b32_e32 v13, 0
	v_mov_b32_e32 v14, 0
	v_mov_b32_e32 v15, 0
	v_mov_b32_e32 v20, 0
	v_mov_b32_e32 v21, 0
	v_mov_b32_e32 v22, 0
	v_mov_b32_e32 v23, 0
	v_mov_b32_e32 v4, 0
	v_mov_b32_e32 v5, 0
	v_mov_b32_e32 v6, 0
	v_mov_b32_e32 v7, 0
	v_mov_b32_e32 v16, 0
	v_mov_b32_e32 v17, 0
	v_mov_b32_e32 v18, 0
	v_mov_b32_e32 v19, 0
	v_mov_b32_e32 v0, 0
	v_mov_b32_e32 v1, 0
	v_mov_b32_e32 v2, 0
	v_mov_b32_e32 v3, 0
	s_waitcnt vmcnt(8)
	s_barrier
	ds_read_b128 v[28:31], v252 offset:0
	ds_read_b128 v[112:115], v254 offset:32768
	ds_read_b128 v[116:119], v254 offset:34816
	ds_read_b128 v[120:123], v254 offset:36864
	ds_read_b128 v[124:127], v254 offset:38912
	ds_read_b128 v[36:39], v252 offset:2048
	ds_read_b128 v[40:43], v252 offset:4096
	ds_read_b128 v[44:47], v252 offset:6144
	ds_read_b128 v[48:51], v253 offset:0
	ds_read_b128 v[132:135], v255 offset:32768
	ds_read_b128 v[136:139], v255 offset:34816
	ds_read_b128 v[140:143], v255 offset:36864
	ds_read_b128 v[144:147], v255 offset:38912
	s_waitcnt lgkmcnt(11)
	v_mfma_f32_16x16x32_bf16 v[92:95], v[28:31], v[112:115], v[92:95]
	s_waitcnt lgkmcnt(10)
	v_mfma_f32_16x16x32_bf16 v[84:87], v[28:31], v[116:119], v[84:87]
	s_waitcnt lgkmcnt(9)
	v_mfma_f32_16x16x32_bf16 v[88:91], v[28:31], v[120:123], v[88:91]
	s_waitcnt lgkmcnt(8)
	v_mfma_f32_16x16x32_bf16 v[80:83], v[28:31], v[124:127], v[80:83]
	ds_read_b128 v[52:55], v253 offset:2048
	ds_read_b128 v[56:59], v253 offset:4096
	ds_read_b128 v[60:63], v253 offset:6144
	s_waitcnt lgkmcnt(10)
	v_mfma_f32_16x16x32_bf16 v[76:79], v[36:39], v[112:115], v[76:79]
	v_mfma_f32_16x16x32_bf16 v[68:71], v[36:39], v[116:119], v[68:71]
	v_mfma_f32_16x16x32_bf16 v[72:75], v[36:39], v[120:123], v[72:75]
	v_mfma_f32_16x16x32_bf16 v[64:67], v[36:39], v[124:127], v[64:67]
	s_waitcnt lgkmcnt(9)
	v_mfma_f32_16x16x32_bf16 v[32:35], v[40:43], v[112:115], v[32:35]
	v_mfma_f32_16x16x32_bf16 v[8:11], v[40:43], v[116:119], v[8:11]
	v_mfma_f32_16x16x32_bf16 v[24:27], v[40:43], v[120:123], v[24:27]
	v_mfma_f32_16x16x32_bf16 v[12:15], v[40:43], v[124:127], v[12:15]
	s_waitcnt lgkmcnt(8)
	v_mfma_f32_16x16x32_bf16 v[20:23], v[44:47], v[112:115], v[20:23]
	v_mfma_f32_16x16x32_bf16 v[4:7], v[44:47], v[116:119], v[4:7]
	v_mfma_f32_16x16x32_bf16 v[16:19], v[44:47], v[120:123], v[16:19]
	v_mfma_f32_16x16x32_bf16 v[0:3], v[44:47], v[124:127], v[0:3]
	s_waitcnt lgkmcnt(0)
	s_barrier
	s_add_u32 m0, s8, 0x0
	v_mfma_f32_16x16x32_bf16 v[92:95], v[48:51], v[132:135], v[92:95]
	global_load_lds_dwordx4 v248, s[30:31]
	v_mfma_f32_16x16x32_bf16 v[84:87], v[48:51], v[136:139], v[84:87]
	s_add_u32 m0, s8, 0x400
	v_mfma_f32_16x16x32_bf16 v[88:91], v[48:51], v[140:143], v[88:91]
	global_load_lds_dwordx4 v249, s[30:31]
	v_mfma_f32_16x16x32_bf16 v[80:83], v[48:51], v[144:147], v[80:83]
	s_add_u32 m0, s8, 0x800
	v_mfma_f32_16x16x32_bf16 v[76:79], v[52:55], v[132:135], v[76:79]
	global_load_lds_dwordx4 v250, s[30:31]
	v_mfma_f32_16x16x32_bf16 v[68:71], v[52:55], v[136:139], v[68:71]
	s_add_u32 m0, s8, 0xc00
	v_mfma_f32_16x16x32_bf16 v[72:75], v[52:55], v[140:143], v[72:75]
	global_load_lds_dwordx4 v251, s[30:31]
	v_mfma_f32_16x16x32_bf16 v[64:67], v[52:55], v[144:147], v[64:67]
	s_add_u32 m0, s8, 0x8000
	v_mfma_f32_16x16x32_bf16 v[32:35], v[56:59], v[132:135], v[32:35]
	global_load_lds_dwordx4 v248, s[62:63]
	v_mfma_f32_16x16x32_bf16 v[8:11], v[56:59], v[136:139], v[8:11]
	s_add_u32 m0, s8, 0x8400
	v_mfma_f32_16x16x32_bf16 v[24:27], v[56:59], v[140:143], v[24:27]
	global_load_lds_dwordx4 v249, s[62:63]
	v_mfma_f32_16x16x32_bf16 v[12:15], v[56:59], v[144:147], v[12:15]
	s_add_u32 m0, s8, 0x8800
	v_mfma_f32_16x16x32_bf16 v[20:23], v[60:63], v[132:135], v[20:23]
	global_load_lds_dwordx4 v250, s[62:63]
	v_mfma_f32_16x16x32_bf16 v[4:7], v[60:63], v[136:139], v[4:7]
	s_add_u32 m0, s8, 0x8c00
	v_mfma_f32_16x16x32_bf16 v[16:19], v[60:63], v[140:143], v[16:19]
	global_load_lds_dwordx4 v251, s[62:63]
	v_mfma_f32_16x16x32_bf16 v[0:3], v[60:63], v[144:147], v[0:3]
	s_add_u32 s30, s30, 0x80
	s_addc_u32 s31, s31, 0
	s_add_u32 s62, s62, 0x80
	s_addc_u32 s63, s63, 0
	s_waitcnt vmcnt(8)
	s_barrier
	ds_read_b128 v[28:31], v252 offset:16384
	ds_read_b128 v[112:115], v254 offset:49152
	ds_read_b128 v[116:119], v254 offset:51200
	ds_read_b128 v[120:123], v254 offset:53248
	ds_read_b128 v[124:127], v254 offset:55296
	ds_read_b128 v[36:39], v252 offset:18432
	ds_read_b128 v[40:43], v252 offset:20480
	ds_read_b128 v[44:47], v252 offset:22528
	ds_read_b128 v[48:51], v253 offset:16384
	ds_read_b128 v[132:135], v255 offset:49152
	ds_read_b128 v[136:139], v255 offset:51200
	ds_read_b128 v[140:143], v255 offset:53248
	ds_read_b128 v[144:147], v255 offset:55296
	s_waitcnt lgkmcnt(11)
	v_mfma_f32_16x16x32_bf16 v[92:95], v[28:31], v[112:115], v[92:95]
	s_waitcnt lgkmcnt(10)
	v_mfma_f32_16x16x32_bf16 v[84:87], v[28:31], v[116:119], v[84:87]
	s_waitcnt lgkmcnt(9)
	v_mfma_f32_16x16x32_bf16 v[88:91], v[28:31], v[120:123], v[88:91]
	s_waitcnt lgkmcnt(8)
	v_mfma_f32_16x16x32_bf16 v[80:83], v[28:31], v[124:127], v[80:83]
	ds_read_b128 v[52:55], v253 offset:18432
	ds_read_b128 v[56:59], v253 offset:20480
	ds_read_b128 v[60:63], v253 offset:22528
	s_waitcnt lgkmcnt(10)
	v_mfma_f32_16x16x32_bf16 v[76:79], v[36:39], v[112:115], v[76:79]
	v_mfma_f32_16x16x32_bf16 v[68:71], v[36:39], v[116:119], v[68:71]
	v_mfma_f32_16x16x32_bf16 v[72:75], v[36:39], v[120:123], v[72:75]
	v_mfma_f32_16x16x32_bf16 v[64:67], v[36:39], v[124:127], v[64:67]
	s_waitcnt lgkmcnt(9)
	v_mfma_f32_16x16x32_bf16 v[32:35], v[40:43], v[112:115], v[32:35]
	v_mfma_f32_16x16x32_bf16 v[8:11], v[40:43], v[116:119], v[8:11]
	v_mfma_f32_16x16x32_bf16 v[24:27], v[40:43], v[120:123], v[24:27]
	v_mfma_f32_16x16x32_bf16 v[12:15], v[40:43], v[124:127], v[12:15]
	s_waitcnt lgkmcnt(8)
	v_mfma_f32_16x16x32_bf16 v[20:23], v[44:47], v[112:115], v[20:23]
	v_mfma_f32_16x16x32_bf16 v[4:7], v[44:47], v[116:119], v[4:7]
	v_mfma_f32_16x16x32_bf16 v[16:19], v[44:47], v[120:123], v[16:19]
	v_mfma_f32_16x16x32_bf16 v[0:3], v[44:47], v[124:127], v[0:3]
	s_waitcnt lgkmcnt(0)
	s_barrier
	s_add_u32 m0, s8, 0x4000
	v_mfma_f32_16x16x32_bf16 v[92:95], v[48:51], v[132:135], v[92:95]
	global_load_lds_dwordx4 v248, s[30:31]
	v_mfma_f32_16x16x32_bf16 v[84:87], v[48:51], v[136:139], v[84:87]
	s_add_u32 m0, s8, 0x4400
	v_mfma_f32_16x16x32_bf16 v[88:91], v[48:51], v[140:143], v[88:91]
	global_load_lds_dwordx4 v249, s[30:31]
	v_mfma_f32_16x16x32_bf16 v[80:83], v[48:51], v[144:147], v[80:83]
	s_add_u32 m0, s8, 0x4800
	v_mfma_f32_16x16x32_bf16 v[76:79], v[52:55], v[132:135], v[76:79]
	global_load_lds_dwordx4 v250, s[30:31]
	v_mfma_f32_16x16x32_bf16 v[68:71], v[52:55], v[136:139], v[68:71]
	s_add_u32 m0, s8, 0x4c00
	v_mfma_f32_16x16x32_bf16 v[72:75], v[52:55], v[140:143], v[72:75]
	global_load_lds_dwordx4 v251, s[30:31]
	v_mfma_f32_16x16x32_bf16 v[64:67], v[52:55], v[144:147], v[64:67]
	s_add_u32 m0, s8, 0xc000
	v_mfma_f32_16x16x32_bf16 v[32:35], v[56:59], v[132:135], v[32:35]
	global_load_lds_dwordx4 v248, s[62:63]
	v_mfma_f32_16x16x32_bf16 v[8:11], v[56:59], v[136:139], v[8:11]
	s_add_u32 m0, s8, 0xc400
	v_mfma_f32_16x16x32_bf16 v[24:27], v[56:59], v[140:143], v[24:27]
	global_load_lds_dwordx4 v249, s[62:63]
	v_mfma_f32_16x16x32_bf16 v[12:15], v[56:59], v[144:147], v[12:15]
	s_add_u32 m0, s8, 0xc800
	v_mfma_f32_16x16x32_bf16 v[20:23], v[60:63], v[132:135], v[20:23]
	global_load_lds_dwordx4 v250, s[62:63]
	v_mfma_f32_16x16x32_bf16 v[4:7], v[60:63], v[136:139], v[4:7]
	s_add_u32 m0, s8, 0xcc00
	v_mfma_f32_16x16x32_bf16 v[16:19], v[60:63], v[140:143], v[16:19]
	global_load_lds_dwordx4 v251, s[62:63]
	v_mfma_f32_16x16x32_bf16 v[0:3], v[60:63], v[144:147], v[0:3]
	s_add_u32 s30, s30, 0x80
	s_addc_u32 s31, s31, 0
	s_add_u32 s62, s62, 0x80
	s_addc_u32 s63, s63, 0

.Lg8_loop:
	s_waitcnt vmcnt(8)
	s_barrier
	ds_read_b128 v[28:31], v252 offset:0
	ds_read_b128 v[112:115], v254 offset:32768
	ds_read_b128 v[116:119], v254 offset:34816
	ds_read_b128 v[120:123], v254 offset:36864
	ds_read_b128 v[124:127], v254 offset:38912
	ds_read_b128 v[36:39], v252 offset:2048
	ds_read_b128 v[40:43], v252 offset:4096
	ds_read_b128 v[44:47], v252 offset:6144
	ds_read_b128 v[48:51], v253 offset:0
	ds_read_b128 v[132:135], v255 offset:32768
	ds_read_b128 v[136:139], v255 offset:34816
	ds_read_b128 v[140:143], v255 offset:36864
	ds_read_b128 v[144:147], v255 offset:38912
	s_waitcnt lgkmcnt(11)
	v_mfma_f32_16x16x32_bf16 v[92:95], v[28:31], v[112:115], v[92:95]
	s_waitcnt lgkmcnt(10)
	v_mfma_f32_16x16x32_bf16 v[84:87], v[28:31], v[116:119], v[84:87]
	s_waitcnt lgkmcnt(9)
	v_mfma_f32_16x16x32_bf16 v[88:91], v[28:31], v[120:123], v[88:91]
	s_waitcnt lgkmcnt(8)
	v_mfma_f32_16x16x32_bf16 v[80:83], v[28:31], v[124:127], v[80:83]
	ds_read_b128 v[52:55], v253 offset:2048
	ds_read_b128 v[56:59], v253 offset:4096
	ds_read_b128 v[60:63], v253 offset:6144
	s_waitcnt lgkmcnt(10)
	v_mfma_f32_16x16x32_bf16 v[76:79], v[36:39], v[112:115], v[76:79]
	v_mfma_f32_16x16x32_bf16 v[68:71], v[36:39], v[116:119], v[68:71]
	v_mfma_f32_16x16x32_bf16 v[72:75], v[36:39], v[120:123], v[72:75]
	v_mfma_f32_16x16x32_bf16 v[64:67], v[36:39], v[124:127], v[64:67]
	s_waitcnt lgkmcnt(9)
	v_mfma_f32_16x16x32_bf16 v[32:35], v[40:43], v[112:115], v[32:35]
	v_mfma_f32_16x16x32_bf16 v[8:11], v[40:43], v[116:119], v[8:11]
	v_mfma_f32_16x16x32_bf16 v[24:27], v[40:43], v[120:123], v[24:27]
	v_mfma_f32_16x16x32_bf16 v[12:15], v[40:43], v[124:127], v[12:15]
	s_waitcnt lgkmcnt(8)
	v_mfma_f32_16x16x32_bf16 v[20:23], v[44:47], v[112:115], v[20:23]
	v_mfma_f32_16x16x32_bf16 v[4:7], v[44:47], v[116:119], v[4:7]
	v_mfma_f32_16x16x32_bf16 v[16:19], v[44:47], v[120:123], v[16:19]
	v_mfma_f32_16x16x32_bf16 v[0:3], v[44:47], v[124:127], v[0:3]
	s_waitcnt lgkmcnt(0)
	s_barrier
	s_add_u32 m0, s8, 0x0
	v_mfma_f32_16x16x32_bf16 v[92:95], v[48:51], v[132:135], v[92:95]
	global_load_lds_dwordx4 v248, s[30:31]
	v_mfma_f32_16x16x32_bf16 v[84:87], v[48:51], v[136:139], v[84:87]
	s_add_u32 m0, s8, 0x400
	v_mfma_f32_16x16x32_bf16 v[88:91], v[48:51], v[140:143], v[88:91]
	global_load_lds_dwordx4 v249, s[30:31]
	v_mfma_f32_16x16x32_bf16 v[80:83], v[48:51], v[144:147], v[80:83]
	s_add_u32 m0, s8, 0x800
	v_mfma_f32_16x16x32_bf16 v[76:79], v[52:55], v[132:135], v[76:79]
	global_load_lds_dwordx4 v250, s[30:31]
	v_mfma_f32_16x16x32_bf16 v[68:71], v[52:55], v[136:139], v[68:71]
	s_add_u32 m0, s8, 0xc00
	v_mfma_f32_16x16x32_bf16 v[72:75], v[52:55], v[140:143], v[72:75]
	global_load_lds_dwordx4 v251, s[30:31]
	v_mfma_f32_16x16x32_bf16 v[64:67], v[52:55], v[144:147], v[64:67]
	s_add_u32 m0, s8, 0x8000
	v_mfma_f32_16x16x32_bf16 v[32:35], v[56:59], v[132:135], v[32:35]
	global_load_lds_dwordx4 v248, s[62:63]
	v_mfma_f32_16x16x32_bf16 v[8:11], v[56:59], v[136:139], v[8:11]
	s_add_u32 m0, s8, 0x8400
	v_mfma_f32_16x16x32_bf16 v[24:27], v[56:59], v[140:143], v[24:27]
	global_load_lds_dwordx4 v249, s[62:63]
	v_mfma_f32_16x16x32_bf16 v[12:15], v[56:59], v[144:147], v[12:15]
	s_add_u32 m0, s8, 0x8800
	v_mfma_f32_16x16x32_bf16 v[20:23], v[60:63], v[132:135], v[20:23]
	global_load_lds_dwordx4 v250, s[62:63]
	v_mfma_f32_16x16x32_bf16 v[4:7], v[60:63], v[136:139], v[4:7]
	s_add_u32 m0, s8, 0x8c00
	v_mfma_f32_16x16x32_bf16 v[16:19], v[60:63], v[140:143], v[16:19]
	global_load_lds_dwordx4 v251, s[62:63]
	v_mfma_f32_16x16x32_bf16 v[0:3], v[60:63], v[144:147], v[0:3]
	s_add_u32 s30, s30, 0x80
	s_addc_u32 s31, s31, 0
	s_add_u32 s62, s62, 0x80
	s_addc_u32 s63, s63, 0
	s_waitcnt vmcnt(8)
	s_barrier
	ds_read_b128 v[28:31], v252 offset:16384
	ds_read_b128 v[112:115], v254 offset:49152
	ds_read_b128 v[116:119], v254 offset:51200
	ds_read_b128 v[120:123], v254 offset:53248
	ds_read_b128 v[124:127], v254 offset:55296
	ds_read_b128 v[36:39], v252 offset:18432
	ds_read_b128 v[40:43], v252 offset:20480
	ds_read_b128 v[44:47], v252 offset:22528
	ds_read_b128 v[48:51], v253 offset:16384
	ds_read_b128 v[132:135], v255 offset:49152
	ds_read_b128 v[136:139], v255 offset:51200
	ds_read_b128 v[140:143], v255 offset:53248
	ds_read_b128 v[144:147], v255 offset:55296
	s_waitcnt lgkmcnt(11)
	v_mfma_f32_16x16x32_bf16 v[92:95], v[28:31], v[112:115], v[92:95]
	s_waitcnt lgkmcnt(10)
	v_mfma_f32_16x16x32_bf16 v[84:87], v[28:31], v[116:119], v[84:87]
	s_waitcnt lgkmcnt(9)
	v_mfma_f32_16x16x32_bf16 v[88:91], v[28:31], v[120:123], v[88:91]
	s_waitcnt lgkmcnt(8)
	v_mfma_f32_16x16x32_bf16 v[80:83], v[28:31], v[124:127], v[80:83]
	ds_read_b128 v[52:55], v253 offset:18432
	ds_read_b128 v[56:59], v253 offset:20480
	ds_read_b128 v[60:63], v253 offset:22528
	s_waitcnt lgkmcnt(10)
	v_mfma_f32_16x16x32_bf16 v[76:79], v[36:39], v[112:115], v[76:79]
	v_mfma_f32_16x16x32_bf16 v[68:71], v[36:39], v[116:119], v[68:71]
	v_mfma_f32_16x16x32_bf16 v[72:75], v[36:39], v[120:123], v[72:75]
	v_mfma_f32_16x16x32_bf16 v[64:67], v[36:39], v[124:127], v[64:67]
	s_waitcnt lgkmcnt(9)
	v_mfma_f32_16x16x32_bf16 v[32:35], v[40:43], v[112:115], v[32:35]
	v_mfma_f32_16x16x32_bf16 v[8:11], v[40:43], v[116:119], v[8:11]
	v_mfma_f32_16x16x32_bf16 v[24:27], v[40:43], v[120:123], v[24:27]
	v_mfma_f32_16x16x32_bf16 v[12:15], v[40:43], v[124:127], v[12:15]
	s_waitcnt lgkmcnt(8)
	v_mfma_f32_16x16x32_bf16 v[20:23], v[44:47], v[112:115], v[20:23]
	v_mfma_f32_16x16x32_bf16 v[4:7], v[44:47], v[116:119], v[4:7]
	v_mfma_f32_16x16x32_bf16 v[16:19], v[44:47], v[120:123], v[16:19]
	v_mfma_f32_16x16x32_bf16 v[0:3], v[44:47], v[124:127], v[0:3]
	s_waitcnt lgkmcnt(0)
	s_barrier
	s_add_u32 m0, s8, 0x4000
	v_mfma_f32_16x16x32_bf16 v[92:95], v[48:51], v[132:135], v[92:95]
	global_load_lds_dwordx4 v248, s[30:31]
	v_mfma_f32_16x16x32_bf16 v[84:87], v[48:51], v[136:139], v[84:87]
	s_add_u32 m0, s8, 0x4400
	v_mfma_f32_16x16x32_bf16 v[88:91], v[48:51], v[140:143], v[88:91]
	global_load_lds_dwordx4 v249, s[30:31]
	v_mfma_f32_16x16x32_bf16 v[80:83], v[48:51], v[144:147], v[80:83]
	s_add_u32 m0, s8, 0x4800
	v_mfma_f32_16x16x32_bf16 v[76:79], v[52:55], v[132:135], v[76:79]
	global_load_lds_dwordx4 v250, s[30:31]
	v_mfma_f32_16x16x32_bf16 v[68:71], v[52:55], v[136:139], v[68:71]
	s_add_u32 m0, s8, 0x4c00
	v_mfma_f32_16x16x32_bf16 v[72:75], v[52:55], v[140:143], v[72:75]
	global_load_lds_dwordx4 v251, s[30:31]
	v_mfma_f32_16x16x32_bf16 v[64:67], v[52:55], v[144:147], v[64:67]
	s_add_u32 m0, s8, 0xc000
	v_mfma_f32_16x16x32_bf16 v[32:35], v[56:59], v[132:135], v[32:35]
	global_load_lds_dwordx4 v248, s[62:63]
	v_mfma_f32_16x16x32_bf16 v[8:11], v[56:59], v[136:139], v[8:11]
	s_add_u32 m0, s8, 0xc400
	v_mfma_f32_16x16x32_bf16 v[24:27], v[56:59], v[140:143], v[24:27]
	global_load_lds_dwordx4 v249, s[62:63]
	v_mfma_f32_16x16x32_bf16 v[12:15], v[56:59], v[144:147], v[12:15]
	s_add_u32 m0, s8, 0xc800
	v_mfma_f32_16x16x32_bf16 v[20:23], v[60:63], v[132:135], v[20:23]
	global_load_lds_dwordx4 v250, s[62:63]
	v_mfma_f32_16x16x32_bf16 v[4:7], v[60:63], v[136:139], v[4:7]
	s_add_u32 m0, s8, 0xcc00
	v_mfma_f32_16x16x32_bf16 v[16:19], v[60:63], v[140:143], v[16:19]
	global_load_lds_dwordx4 v251, s[62:63]
	v_mfma_f32_16x16x32_bf16 v[0:3], v[60:63], v[144:147], v[0:3]
	s_add_u32 s30, s30, 0x80
	s_addc_u32 s31, s31, 0
	s_add_u32 s62, s62, 0x80
	s_addc_u32 s63, s63, 0
	s_sub_u32 s32, s32, 1
	s_cmp_lg_u32 s32, 0
	s_cbranch_scc1 .Lg8_loop
	s_cmp_lt_u32 s51, 0xb00
	s_cbranch_scc0 .Lg8_tailplain
	s_mov_b32 s32, s55
	s_and_b32 s32, s32, 63
	s_and_b32 s59, s51, 63
	s_sub_i32 s59, s59, s32
	s_mul_i32 s59, s59, 0x40000
	s_sub_i32 s59, s59, 0x800
	s_ashr_i32 s32, s59, 31
	s_add_u32 s30, s30, s59
	s_addc_u32 s31, s31, s32
	s_mov_b32 s32, s55
	s_lshr_b32 s32, s32, 6
	s_lshr_b32 s59, s51, 6
	s_sub_i32 s59, s59, s32
	s_mul_i32 s59, s59, 0x40000
	s_sub_i32 s59, s59, 0x800
	s_ashr_i32 s32, s59, 31
	s_add_u32 s62, s62, s59
	s_addc_u32 s63, s63, s32
	s_waitcnt vmcnt(8)
	s_barrier
	ds_read_b128 v[28:31], v252 offset:0
	ds_read_b128 v[112:115], v254 offset:32768
	ds_read_b128 v[116:119], v254 offset:34816
	ds_read_b128 v[120:123], v254 offset:36864
	ds_read_b128 v[124:127], v254 offset:38912
	ds_read_b128 v[36:39], v252 offset:2048
	ds_read_b128 v[40:43], v252 offset:4096
	ds_read_b128 v[44:47], v252 offset:6144
	ds_read_b128 v[48:51], v253 offset:0
	ds_read_b128 v[132:135], v255 offset:32768
	ds_read_b128 v[136:139], v255 offset:34816
	ds_read_b128 v[140:143], v255 offset:36864
	ds_read_b128 v[144:147], v255 offset:38912
	s_waitcnt lgkmcnt(11)
	v_mfma_f32_16x16x32_bf16 v[92:95], v[28:31], v[112:115], v[92:95]
	s_waitcnt lgkmcnt(10)
	v_mfma_f32_16x16x32_bf16 v[84:87], v[28:31], v[116:119], v[84:87]
	s_waitcnt lgkmcnt(9)
	v_mfma_f32_16x16x32_bf16 v[88:91], v[28:31], v[120:123], v[88:91]
	s_waitcnt lgkmcnt(8)
	v_mfma_f32_16x16x32_bf16 v[80:83], v[28:31], v[124:127], v[80:83]
	ds_read_b128 v[52:55], v253 offset:2048
	ds_read_b128 v[56:59], v253 offset:4096
	ds_read_b128 v[60:63], v253 offset:6144
	s_waitcnt lgkmcnt(10)
	v_mfma_f32_16x16x32_bf16 v[76:79], v[36:39], v[112:115], v[76:79]
	v_mfma_f32_16x16x32_bf16 v[68:71], v[36:39], v[116:119], v[68:71]
	v_mfma_f32_16x16x32_bf16 v[72:75], v[36:39], v[120:123], v[72:75]
	v_mfma_f32_16x16x32_bf16 v[64:67], v[36:39], v[124:127], v[64:67]
	s_waitcnt lgkmcnt(9)
	v_mfma_f32_16x16x32_bf16 v[32:35], v[40:43], v[112:115], v[32:35]
	v_mfma_f32_16x16x32_bf16 v[8:11], v[40:43], v[116:119], v[8:11]
	v_mfma_f32_16x16x32_bf16 v[24:27], v[40:43], v[120:123], v[24:27]
	v_mfma_f32_16x16x32_bf16 v[12:15], v[40:43], v[124:127], v[12:15]
	s_waitcnt lgkmcnt(8)
	v_mfma_f32_16x16x32_bf16 v[20:23], v[44:47], v[112:115], v[20:23]
	v_mfma_f32_16x16x32_bf16 v[4:7], v[44:47], v[116:119], v[4:7]
	v_mfma_f32_16x16x32_bf16 v[16:19], v[44:47], v[120:123], v[16:19]
	v_mfma_f32_16x16x32_bf16 v[0:3], v[44:47], v[124:127], v[0:3]
	s_waitcnt lgkmcnt(0)
	s_barrier
	s_add_u32 m0, s8, 0x0
	v_mfma_f32_16x16x32_bf16 v[92:95], v[48:51], v[132:135], v[92:95]
	global_load_lds_dwordx4 v248, s[30:31]
	v_mfma_f32_16x16x32_bf16 v[84:87], v[48:51], v[136:139], v[84:87]
	s_add_u32 m0, s8, 0x400
	v_mfma_f32_16x16x32_bf16 v[88:91], v[48:51], v[140:143], v[88:91]
	global_load_lds_dwordx4 v249, s[30:31]
	v_mfma_f32_16x16x32_bf16 v[80:83], v[48:51], v[144:147], v[80:83]
	s_add_u32 m0, s8, 0x800
	v_mfma_f32_16x16x32_bf16 v[76:79], v[52:55], v[132:135], v[76:79]
	global_load_lds_dwordx4 v250, s[30:31]
	v_mfma_f32_16x16x32_bf16 v[68:71], v[52:55], v[136:139], v[68:71]
	s_add_u32 m0, s8, 0xc00
	v_mfma_f32_16x16x32_bf16 v[72:75], v[52:55], v[140:143], v[72:75]
	global_load_lds_dwordx4 v251, s[30:31]
	v_mfma_f32_16x16x32_bf16 v[64:67], v[52:55], v[144:147], v[64:67]
	s_add_u32 m0, s8, 0x8000
	v_mfma_f32_16x16x32_bf16 v[32:35], v[56:59], v[132:135], v[32:35]
	global_load_lds_dwordx4 v248, s[62:63]
	v_mfma_f32_16x16x32_bf16 v[8:11], v[56:59], v[136:139], v[8:11]
	s_add_u32 m0, s8, 0x8400
	v_mfma_f32_16x16x32_bf16 v[24:27], v[56:59], v[140:143], v[24:27]
	global_load_lds_dwordx4 v249, s[62:63]
	v_mfma_f32_16x16x32_bf16 v[12:15], v[56:59], v[144:147], v[12:15]
	s_add_u32 m0, s8, 0x8800
	v_mfma_f32_16x16x32_bf16 v[20:23], v[60:63], v[132:135], v[20:23]
	global_load_lds_dwordx4 v250, s[62:63]
	v_mfma_f32_16x16x32_bf16 v[4:7], v[60:63], v[136:139], v[4:7]
	s_add_u32 m0, s8, 0x8c00
	v_mfma_f32_16x16x32_bf16 v[16:19], v[60:63], v[140:143], v[16:19]
	global_load_lds_dwordx4 v251, s[62:63]
	v_mfma_f32_16x16x32_bf16 v[0:3], v[60:63], v[144:147], v[0:3]
	s_add_u32 s30, s30, 0x80
	s_addc_u32 s31, s31, 0
	s_add_u32 s62, s62, 0x80
	s_addc_u32 s63, s63, 0
	s_waitcnt vmcnt(8)
	s_barrier
	ds_read_b128 v[28:31], v252 offset:16384
	ds_read_b128 v[112:115], v254 offset:49152
	ds_read_b128 v[116:119], v254 offset:51200
	ds_read_b128 v[120:123], v254 offset:53248
	ds_read_b128 v[124:127], v254 offset:55296
	ds_read_b128 v[36:39], v252 offset:18432
	ds_read_b128 v[40:43], v252 offset:20480
	ds_read_b128 v[44:47], v252 offset:22528
	ds_read_b128 v[48:51], v253 offset:16384
	ds_read_b128 v[132:135], v255 offset:49152
	ds_read_b128 v[136:139], v255 offset:51200
	ds_read_b128 v[140:143], v255 offset:53248
	ds_read_b128 v[144:147], v255 offset:55296
	s_waitcnt lgkmcnt(11)
	v_mfma_f32_16x16x32_bf16 v[92:95], v[28:31], v[112:115], v[92:95]
	s_waitcnt lgkmcnt(10)
	v_mfma_f32_16x16x32_bf16 v[84:87], v[28:31], v[116:119], v[84:87]
	s_waitcnt lgkmcnt(9)
	v_mfma_f32_16x16x32_bf16 v[88:91], v[28:31], v[120:123], v[88:91]
	s_waitcnt lgkmcnt(8)
	v_mfma_f32_16x16x32_bf16 v[80:83], v[28:31], v[124:127], v[80:83]
	ds_read_b128 v[52:55], v253 offset:18432
	ds_read_b128 v[56:59], v253 offset:20480
	ds_read_b128 v[60:63], v253 offset:22528
	s_waitcnt lgkmcnt(10)
	v_mfma_f32_16x16x32_bf16 v[76:79], v[36:39], v[112:115], v[76:79]
	v_mfma_f32_16x16x32_bf16 v[68:71], v[36:39], v[116:119], v[68:71]
	v_mfma_f32_16x16x32_bf16 v[72:75], v[36:39], v[120:123], v[72:75]
	v_mfma_f32_16x16x32_bf16 v[64:67], v[36:39], v[124:127], v[64:67]
	s_waitcnt lgkmcnt(9)
	v_mfma_f32_16x16x32_bf16 v[32:35], v[40:43], v[112:115], v[32:35]
	v_mfma_f32_16x16x32_bf16 v[8:11], v[40:43], v[116:119], v[8:11]
	v_mfma_f32_16x16x32_bf16 v[24:27], v[40:43], v[120:123], v[24:27]
	v_mfma_f32_16x16x32_bf16 v[12:15], v[40:43], v[124:127], v[12:15]
	s_waitcnt lgkmcnt(8)
	v_mfma_f32_16x16x32_bf16 v[20:23], v[44:47], v[112:115], v[20:23]
	v_mfma_f32_16x16x32_bf16 v[4:7], v[44:47], v[116:119], v[4:7]
	v_mfma_f32_16x16x32_bf16 v[16:19], v[44:47], v[120:123], v[16:19]
	v_mfma_f32_16x16x32_bf16 v[0:3], v[44:47], v[124:127], v[0:3]
	s_waitcnt lgkmcnt(0)
	s_barrier
	s_add_u32 m0, s8, 0x4000
	v_mfma_f32_16x16x32_bf16 v[92:95], v[48:51], v[132:135], v[92:95]
	global_load_lds_dwordx4 v248, s[30:31]
	v_mfma_f32_16x16x32_bf16 v[84:87], v[48:51], v[136:139], v[84:87]
	s_add_u32 m0, s8, 0x4400
	v_mfma_f32_16x16x32_bf16 v[88:91], v[48:51], v[140:143], v[88:91]
	global_load_lds_dwordx4 v249, s[30:31]
	v_mfma_f32_16x16x32_bf16 v[80:83], v[48:51], v[144:147], v[80:83]
	s_add_u32 m0, s8, 0x4800
	v_mfma_f32_16x16x32_bf16 v[76:79], v[52:55], v[132:135], v[76:79]
	global_load_lds_dwordx4 v250, s[30:31]
	v_mfma_f32_16x16x32_bf16 v[68:71], v[52:55], v[136:139], v[68:71]
	s_add_u32 m0, s8, 0x4c00
	v_mfma_f32_16x16x32_bf16 v[72:75], v[52:55], v[140:143], v[72:75]
	global_load_lds_dwordx4 v251, s[30:31]
	v_mfma_f32_16x16x32_bf16 v[64:67], v[52:55], v[144:147], v[64:67]
	s_add_u32 m0, s8, 0xc000
	v_mfma_f32_16x16x32_bf16 v[32:35], v[56:59], v[132:135], v[32:35]
	global_load_lds_dwordx4 v248, s[62:63]
	v_mfma_f32_16x16x32_bf16 v[8:11], v[56:59], v[136:139], v[8:11]
	s_add_u32 m0, s8, 0xc400
	v_mfma_f32_16x16x32_bf16 v[24:27], v[56:59], v[140:143], v[24:27]
	global_load_lds_dwordx4 v249, s[62:63]
	v_mfma_f32_16x16x32_bf16 v[12:15], v[56:59], v[144:147], v[12:15]
	s_add_u32 m0, s8, 0xc800
	v_mfma_f32_16x16x32_bf16 v[20:23], v[60:63], v[132:135], v[20:23]
	global_load_lds_dwordx4 v250, s[62:63]
	v_mfma_f32_16x16x32_bf16 v[4:7], v[60:63], v[136:139], v[4:7]
	s_add_u32 m0, s8, 0xcc00
	v_mfma_f32_16x16x32_bf16 v[16:19], v[60:63], v[140:143], v[16:19]
	global_load_lds_dwordx4 v251, s[62:63]
	v_mfma_f32_16x16x32_bf16 v[0:3], v[60:63], v[144:147], v[0:3]
	s_add_u32 s30, s30, 0x80
	s_addc_u32 s31, s31, 0
	s_add_u32 s62, s62, 0x80
	s_addc_u32 s63, s63, 0
	s_branch .Lg8_done
.Lg8_tailplain:
	s_waitcnt vmcnt(8)
	s_barrier
	ds_read_b128 v[28:31], v252 offset:0
	ds_read_b128 v[112:115], v254 offset:32768
	ds_read_b128 v[116:119], v254 offset:34816
	ds_read_b128 v[120:123], v254 offset:36864
	ds_read_b128 v[124:127], v254 offset:38912
	ds_read_b128 v[36:39], v252 offset:2048
	ds_read_b128 v[40:43], v252 offset:4096
	ds_read_b128 v[44:47], v252 offset:6144
	ds_read_b128 v[48:51], v253 offset:0
	ds_read_b128 v[132:135], v255 offset:32768
	ds_read_b128 v[136:139], v255 offset:34816
	ds_read_b128 v[140:143], v255 offset:36864
	ds_read_b128 v[144:147], v255 offset:38912
	s_waitcnt lgkmcnt(11)
	v_mfma_f32_16x16x32_bf16 v[92:95], v[28:31], v[112:115], v[92:95]
	s_waitcnt lgkmcnt(10)
	v_mfma_f32_16x16x32_bf16 v[84:87], v[28:31], v[116:119], v[84:87]
	s_waitcnt lgkmcnt(9)
	v_mfma_f32_16x16x32_bf16 v[88:91], v[28:31], v[120:123], v[88:91]
	s_waitcnt lgkmcnt(8)
	v_mfma_f32_16x16x32_bf16 v[80:83], v[28:31], v[124:127], v[80:83]
	ds_read_b128 v[52:55], v253 offset:2048
	ds_read_b128 v[56:59], v253 offset:4096
	ds_read_b128 v[60:63], v253 offset:6144
	s_waitcnt lgkmcnt(10)
	v_mfma_f32_16x16x32_bf16 v[76:79], v[36:39], v[112:115], v[76:79]
	v_mfma_f32_16x16x32_bf16 v[68:71], v[36:39], v[116:119], v[68:71]
	v_mfma_f32_16x16x32_bf16 v[72:75], v[36:39], v[120:123], v[72:75]
	v_mfma_f32_16x16x32_bf16 v[64:67], v[36:39], v[124:127], v[64:67]
	s_waitcnt lgkmcnt(9)
	v_mfma_f32_16x16x32_bf16 v[32:35], v[40:43], v[112:115], v[32:35]
	v_mfma_f32_16x16x32_bf16 v[8:11], v[40:43], v[116:119], v[8:11]
	v_mfma_f32_16x16x32_bf16 v[24:27], v[40:43], v[120:123], v[24:27]
	v_mfma_f32_16x16x32_bf16 v[12:15], v[40:43], v[124:127], v[12:15]
	s_waitcnt lgkmcnt(8)
	v_mfma_f32_16x16x32_bf16 v[20:23], v[44:47], v[112:115], v[20:23]
	v_mfma_f32_16x16x32_bf16 v[4:7], v[44:47], v[116:119], v[4:7]
	v_mfma_f32_16x16x32_bf16 v[16:19], v[44:47], v[120:123], v[16:19]
	v_mfma_f32_16x16x32_bf16 v[0:3], v[44:47], v[124:127], v[0:3]
	s_waitcnt lgkmcnt(0)
	s_barrier
	v_mfma_f32_16x16x32_bf16 v[92:95], v[48:51], v[132:135], v[92:95]
	v_mfma_f32_16x16x32_bf16 v[84:87], v[48:51], v[136:139], v[84:87]
	v_mfma_f32_16x16x32_bf16 v[88:91], v[48:51], v[140:143], v[88:91]
	v_mfma_f32_16x16x32_bf16 v[80:83], v[48:51], v[144:147], v[80:83]
	v_mfma_f32_16x16x32_bf16 v[76:79], v[52:55], v[132:135], v[76:79]
	v_mfma_f32_16x16x32_bf16 v[68:71], v[52:55], v[136:139], v[68:71]
	v_mfma_f32_16x16x32_bf16 v[72:75], v[52:55], v[140:143], v[72:75]
	v_mfma_f32_16x16x32_bf16 v[64:67], v[52:55], v[144:147], v[64:67]
	v_mfma_f32_16x16x32_bf16 v[32:35], v[56:59], v[132:135], v[32:35]
	v_mfma_f32_16x16x32_bf16 v[8:11], v[56:59], v[136:139], v[8:11]
	v_mfma_f32_16x16x32_bf16 v[24:27], v[56:59], v[140:143], v[24:27]
	v_mfma_f32_16x16x32_bf16 v[12:15], v[56:59], v[144:147], v[12:15]
	v_mfma_f32_16x16x32_bf16 v[20:23], v[60:63], v[132:135], v[20:23]
	v_mfma_f32_16x16x32_bf16 v[4:7], v[60:63], v[136:139], v[4:7]
	v_mfma_f32_16x16x32_bf16 v[16:19], v[60:63], v[140:143], v[16:19]
	v_mfma_f32_16x16x32_bf16 v[0:3], v[60:63], v[144:147], v[0:3]
	s_waitcnt vmcnt(0)
	s_barrier
	ds_read_b128 v[28:31], v252 offset:16384
	ds_read_b128 v[112:115], v254 offset:49152
	ds_read_b128 v[116:119], v254 offset:51200
	ds_read_b128 v[120:123], v254 offset:53248
	ds_read_b128 v[124:127], v254 offset:55296
	ds_read_b128 v[36:39], v252 offset:18432
	ds_read_b128 v[40:43], v252 offset:20480
	ds_read_b128 v[44:47], v252 offset:22528
	ds_read_b128 v[48:51], v253 offset:16384
	ds_read_b128 v[132:135], v255 offset:49152
	ds_read_b128 v[136:139], v255 offset:51200
	ds_read_b128 v[140:143], v255 offset:53248
	ds_read_b128 v[144:147], v255 offset:55296
	s_waitcnt lgkmcnt(11)
	v_mfma_f32_16x16x32_bf16 v[92:95], v[28:31], v[112:115], v[92:95]
	s_waitcnt lgkmcnt(10)
	v_mfma_f32_16x16x32_bf16 v[84:87], v[28:31], v[116:119], v[84:87]
	s_waitcnt lgkmcnt(9)
	v_mfma_f32_16x16x32_bf16 v[88:91], v[28:31], v[120:123], v[88:91]
	s_waitcnt lgkmcnt(8)
	v_mfma_f32_16x16x32_bf16 v[80:83], v[28:31], v[124:127], v[80:83]
	ds_read_b128 v[52:55], v253 offset:18432
	ds_read_b128 v[56:59], v253 offset:20480
	ds_read_b128 v[60:63], v253 offset:22528
	s_waitcnt lgkmcnt(10)
	v_mfma_f32_16x16x32_bf16 v[76:79], v[36:39], v[112:115], v[76:79]
	v_mfma_f32_16x16x32_bf16 v[68:71], v[36:39], v[116:119], v[68:71]
	v_mfma_f32_16x16x32_bf16 v[72:75], v[36:39], v[120:123], v[72:75]
	v_mfma_f32_16x16x32_bf16 v[64:67], v[36:39], v[124:127], v[64:67]
	s_waitcnt lgkmcnt(9)
	v_mfma_f32_16x16x32_bf16 v[32:35], v[40:43], v[112:115], v[32:35]
	v_mfma_f32_16x16x32_bf16 v[8:11], v[40:43], v[116:119], v[8:11]
	v_mfma_f32_16x16x32_bf16 v[24:27], v[40:43], v[120:123], v[24:27]
	v_mfma_f32_16x16x32_bf16 v[12:15], v[40:43], v[124:127], v[12:15]
	s_waitcnt lgkmcnt(8)
	v_mfma_f32_16x16x32_bf16 v[20:23], v[44:47], v[112:115], v[20:23]
	v_mfma_f32_16x16x32_bf16 v[4:7], v[44:47], v[116:119], v[4:7]
	v_mfma_f32_16x16x32_bf16 v[16:19], v[44:47], v[120:123], v[16:19]
	v_mfma_f32_16x16x32_bf16 v[0:3], v[44:47], v[124:127], v[0:3]
	s_waitcnt lgkmcnt(0)
	s_barrier
	v_mfma_f32_16x16x32_bf16 v[92:95], v[48:51], v[132:135], v[92:95]
	v_mfma_f32_16x16x32_bf16 v[84:87], v[48:51], v[136:139], v[84:87]
	v_mfma_f32_16x16x32_bf16 v[88:91], v[48:51], v[140:143], v[88:91]
	v_mfma_f32_16x16x32_bf16 v[80:83], v[48:51], v[144:147], v[80:83]
	v_mfma_f32_16x16x32_bf16 v[76:79], v[52:55], v[132:135], v[76:79]
	v_mfma_f32_16x16x32_bf16 v[68:71], v[52:55], v[136:139], v[68:71]
	v_mfma_f32_16x16x32_bf16 v[72:75], v[52:55], v[140:143], v[72:75]
	v_mfma_f32_16x16x32_bf16 v[64:67], v[52:55], v[144:147], v[64:67]
	v_mfma_f32_16x16x32_bf16 v[32:35], v[56:59], v[132:135], v[32:35]
	v_mfma_f32_16x16x32_bf16 v[8:11], v[56:59], v[136:139], v[8:11]
	v_mfma_f32_16x16x32_bf16 v[24:27], v[56:59], v[140:143], v[24:27]
	v_mfma_f32_16x16x32_bf16 v[12:15], v[56:59], v[144:147], v[12:15]
	v_mfma_f32_16x16x32_bf16 v[20:23], v[60:63], v[132:135], v[20:23]
	v_mfma_f32_16x16x32_bf16 v[4:7], v[60:63], v[136:139], v[4:7]
	v_mfma_f32_16x16x32_bf16 v[16:19], v[60:63], v[140:143], v[16:19]
	v_mfma_f32_16x16x32_bf16 v[0:3], v[60:63], v[144:147], v[0:3]
.Lg8_done:
	s_nop 7
	s_nop 1
	v_mul_f32_e32 v28, 0xbfb8aa3b, v92
	v_exp_f32_e32 v30, v28
	v_mul_f32_e32 v36, 0xbfb8aa3b, v93
	v_exp_f32_e32 v36, v36
	s_and_b32 s8, s55, 0xffffffc0
	v_add_f32_e32 v30, 1.0, v30
	v_rcp_f32_e32 v30, v30
	v_add_f32_e32 v36, 1.0, v36
	v_or_b32_e32 v28, s8, v157
	v_rcp_f32_e32 v36, v36
	v_add_u32_e32 v31, s54, v158
	v_ashrrev_i32_e32 v29, 31, v28
	v_mul_f32_e32 v30, v92, v30
	v_lshl_add_u64 v[28:29], v[28:29], 1, v[102:103]
	v_mul_f32_e32 v30, v88, v30
	v_mul_u32_u24_e32 v96, 0x1600, v31
	v_cvt_pk_bf16_f32 v30, v30, s0
	v_lshl_add_u64 v[28:29], v[28:29], 0, v[96:97]
	global_store_short v[28:29], v30, off
	v_mul_f32_e32 v30, v93, v36
	v_mul_f32_e32 v30, v89, v30
	v_cvt_pk_bf16_f32 v36, v30, s0
	v_mul_f32_e32 v30, 0xbfb8aa3b, v94
	v_exp_f32_e32 v37, v30
	v_add_co_u32_e32 v30, vcc, s37, v28
	s_add_i32 s3, s3, s34
	s_nop 0
	v_addc_co_u32_e32 v31, vcc, 0, v29, vcc
	global_store_short v[30:31], v36, off offset:1536
	v_mul_f32_e32 v36, 0xbfb8aa3b, v95
	v_exp_f32_e32 v36, v36
	v_add_f32_e32 v37, 1.0, v37
	v_rcp_f32_e32 v37, v37
	s_mov_b64 s[30:31], -1
	v_add_f32_e32 v36, 1.0, v36
	v_rcp_f32_e32 v39, v36
	v_mul_f32_e32 v37, v94, v37
	v_mul_f32_e32 v37, v90, v37
	v_add_co_u32_e32 v36, vcc, s38, v28
	v_cvt_pk_bf16_f32 v38, v37, s0
	s_nop 0
	v_addc_co_u32_e32 v37, vcc, 0, v29, vcc
	global_store_short v[36:37], v38, off offset:3072
	v_mul_f32_e32 v38, v95, v39
	v_mul_f32_e32 v38, v91, v38
	v_cvt_pk_bf16_f32 v40, v38, s0
	v_mul_f32_e32 v38, 0xbfb8aa3b, v84
	v_exp_f32_e32 v41, v38
	v_add_co_u32_e32 v38, vcc, s39, v28
	s_mov_b32 s55, s51
	s_nop 0
	v_addc_co_u32_e32 v39, vcc, 0, v29, vcc
	global_store_short v[38:39], v40, off offset:512
	v_mul_f32_e32 v40, 0xbfb8aa3b, v85
	v_exp_f32_e32 v40, v40
	v_add_f32_e32 v41, 1.0, v41
	v_rcp_f32_e32 v41, v41
	v_add_f32_e32 v40, 1.0, v40
	v_rcp_f32_e32 v40, v40
	v_mul_f32_e32 v41, v84, v41
	v_mul_f32_e32 v41, v80, v41
	v_cvt_pk_bf16_f32 v41, v41, s0
	global_store_short v[28:29], v41, off offset:32
	v_mul_f32_e32 v41, 0xbfb8aa3b, v86
	v_mul_f32_e32 v40, v85, v40
	v_exp_f32_e32 v41, v41
	v_mul_f32_e32 v40, v81, v40
	v_cvt_pk_bf16_f32 v40, v40, s0
	global_store_short v[30:31], v40, off offset:1568
	v_mul_f32_e32 v30, 0xbfb8aa3b, v87
	v_exp_f32_e32 v30, v30
	v_add_f32_e32 v41, 1.0, v41
	v_rcp_f32_e32 v41, v41
	v_add_f32_e32 v30, 1.0, v30
	v_rcp_f32_e32 v30, v30
	v_mul_f32_e32 v31, v86, v41
	v_mul_f32_e32 v31, v82, v31
	v_cvt_pk_bf16_f32 v31, v31, s0
	global_store_short v[36:37], v31, off offset:3104
	v_mul_f32_e32 v31, 0xbfb8aa3b, v76
	v_mul_f32_e32 v30, v87, v30
	v_exp_f32_e32 v31, v31
	v_mul_f32_e32 v30, v83, v30
	v_cvt_pk_bf16_f32 v30, v30, s0
	global_store_short v[38:39], v30, off offset:544
	v_mul_f32_e32 v30, 0xbfb8aa3b, v77
	v_exp_f32_e32 v30, v30
	v_add_f32_e32 v31, 1.0, v31
	v_rcp_f32_e32 v31, v31
	v_add_f32_e32 v30, 1.0, v30
	v_rcp_f32_e32 v37, v30
	v_mul_f32_e32 v31, v76, v31
	v_mul_f32_e32 v31, v72, v31
	v_add_co_u32_e32 v30, vcc, s40, v28
	v_cvt_pk_bf16_f32 v36, v31, s0
	s_nop 0
	v_addc_co_u32_e32 v31, vcc, 0, v29, vcc
	global_store_short v[30:31], v36, off
	v_mul_f32_e32 v36, v77, v37
	v_mul_f32_e32 v36, v73, v36
	v_cvt_pk_bf16_f32 v38, v36, s0
	v_mul_f32_e32 v36, 0xbfb8aa3b, v78
	v_exp_f32_e32 v39, v36
	v_add_co_u32_e32 v36, vcc, s41, v28
	v_add_f32_e32 v39, 1.0, v39
	s_nop 0
	v_addc_co_u32_e32 v37, vcc, 0, v29, vcc
	global_store_short v[36:37], v38, off offset:1536
	v_mul_f32_e32 v38, 0xbfb8aa3b, v79
	v_exp_f32_e32 v38, v38
	v_rcp_f32_e32 v39, v39
	v_add_f32_e32 v38, 1.0, v38
	v_rcp_f32_e32 v41, v38
	v_mul_f32_e32 v39, v78, v39
	v_mul_f32_e32 v39, v74, v39
	v_add_co_u32_e32 v38, vcc, s42, v28
	v_cvt_pk_bf16_f32 v40, v39, s0
	s_nop 0
	v_addc_co_u32_e32 v39, vcc, 0, v29, vcc
	global_store_short v[38:39], v40, off offset:3072
	v_mul_f32_e32 v40, v79, v41
	v_mul_f32_e32 v40, v75, v40
	v_cvt_pk_bf16_f32 v42, v40, s0
	v_mul_f32_e32 v40, 0xbfb8aa3b, v68
	v_exp_f32_e32 v43, v40
	v_add_co_u32_e32 v40, vcc, s43, v28
	v_add_f32_e32 v43, 1.0, v43
	s_nop 0
	v_addc_co_u32_e32 v41, vcc, 0, v29, vcc
	v_rcp_f32_e32 v43, v43
	global_store_short v[40:41], v42, off offset:512
	v_mul_f32_e32 v42, 0xbfb8aa3b, v69
	v_exp_f32_e32 v42, v42
	v_mul_f32_e32 v43, v68, v43
	v_mul_f32_e32 v43, v64, v43
	v_cvt_pk_bf16_f32 v43, v43, s0
	v_add_f32_e32 v42, 1.0, v42
	v_rcp_f32_e32 v42, v42
	global_store_short v[30:31], v43, off offset:32
	v_mul_f32_e32 v30, 0xbfb8aa3b, v70
	v_exp_f32_e32 v30, v30
	v_mul_f32_e32 v31, v69, v42
	v_mul_f32_e32 v31, v65, v31
	v_cvt_pk_bf16_f32 v31, v31, s0
	v_add_f32_e32 v30, 1.0, v30
	v_rcp_f32_e32 v30, v30
	global_store_short v[36:37], v31, off offset:1568
	v_mul_f32_e32 v31, 0xbfb8aa3b, v71
	v_exp_f32_e32 v31, v31
	v_mul_f32_e32 v30, v70, v30
	v_mul_f32_e32 v30, v66, v30
	v_cvt_pk_bf16_f32 v30, v30, s0
	v_add_f32_e32 v31, 1.0, v31
	v_rcp_f32_e32 v31, v31
	global_store_short v[38:39], v30, off offset:3104
	v_mul_f32_e32 v30, 0xbfb8aa3b, v32
	v_exp_f32_e32 v30, v30
	v_mul_f32_e32 v31, v71, v31
	v_mul_f32_e32 v31, v67, v31
	v_cvt_pk_bf16_f32 v31, v31, s0
	v_add_f32_e32 v30, 1.0, v30
	v_rcp_f32_e32 v30, v30
	global_store_short v[40:41], v31, off offset:544
	v_mul_f32_e32 v31, 0xbfb8aa3b, v33
	v_exp_f32_e32 v31, v31
	v_mul_f32_e32 v30, v32, v30
	v_mul_f32_e32 v24, v24, v30
	v_cvt_pk_bf16_f32 v24, v24, s0
	v_add_f32_e32 v30, 1.0, v31
	v_rcp_f32_e32 v32, v30
	v_add_co_u32_e32 v30, vcc, s44, v28
	s_nop 1
	v_addc_co_u32_e32 v31, vcc, 0, v29, vcc
	global_store_short v[30:31], v24, off
	v_mul_f32_e32 v24, v33, v32
	v_mul_f32_e32 v24, v25, v24
	v_cvt_pk_bf16_f32 v32, v24, s0
	v_mul_f32_e32 v24, 0xbfb8aa3b, v34
	v_exp_f32_e32 v33, v24
	v_add_co_u32_e32 v24, vcc, s45, v28
	v_add_f32_e32 v33, 1.0, v33
	s_nop 0
	v_addc_co_u32_e32 v25, vcc, 0, v29, vcc
	global_store_short v[24:25], v32, off offset:1536
	v_mul_f32_e32 v32, 0xbfb8aa3b, v35
	v_exp_f32_e32 v32, v32
	v_rcp_f32_e32 v33, v33
	v_add_f32_e32 v32, 1.0, v32
	v_mul_f32_e32 v33, v34, v33
	v_rcp_f32_e32 v34, v32
	v_mul_f32_e32 v26, v26, v33
	v_add_co_u32_e32 v32, vcc, s46, v28
	v_cvt_pk_bf16_f32 v26, v26, s0
	s_nop 0
	v_addc_co_u32_e32 v33, vcc, 0, v29, vcc
	global_store_short v[32:33], v26, off offset:3072
	v_mul_f32_e32 v26, v35, v34
	v_mul_f32_e32 v26, v27, v26
	v_cvt_pk_bf16_f32 v34, v26, s0
	v_mul_f32_e32 v26, 0xbfb8aa3b, v8
	v_exp_f32_e32 v35, v26
	v_add_co_u32_e32 v26, vcc, s36, v28
	v_add_f32_e32 v35, 1.0, v35
	s_nop 0
	v_addc_co_u32_e32 v27, vcc, 0, v29, vcc
	v_rcp_f32_e32 v35, v35
	global_store_short v[26:27], v34, off offset:512
	v_mul_f32_e32 v34, 0xbfb8aa3b, v9
	v_exp_f32_e32 v34, v34
	v_mul_f32_e32 v8, v8, v35
	v_mul_f32_e32 v8, v12, v8
	v_cvt_pk_bf16_f32 v8, v8, s0
	v_add_f32_e32 v12, 1.0, v34
	v_rcp_f32_e32 v12, v12
	global_store_short v[30:31], v8, off offset:32
	v_mul_f32_e32 v8, 0xbfb8aa3b, v10
	v_exp_f32_e32 v8, v8
	v_mul_f32_e32 v9, v9, v12
	v_mul_f32_e32 v9, v13, v9
	v_cvt_pk_bf16_f32 v9, v9, s0
	v_add_f32_e32 v8, 1.0, v8
	v_rcp_f32_e32 v8, v8
	global_store_short v[24:25], v9, off offset:1568
	v_mul_f32_e32 v9, 0xbfb8aa3b, v11
	v_exp_f32_e32 v9, v9
	v_mul_f32_e32 v8, v10, v8
	v_mul_f32_e32 v8, v14, v8
	v_cvt_pk_bf16_f32 v8, v8, s0
	v_add_f32_e32 v9, 1.0, v9
	v_rcp_f32_e32 v9, v9
	global_store_short v[32:33], v8, off offset:3104
	v_mul_f32_e32 v8, 0xbfb8aa3b, v20
	v_exp_f32_e32 v8, v8
	v_mul_f32_e32 v9, v11, v9
	v_mul_f32_e32 v9, v15, v9
	v_cvt_pk_bf16_f32 v9, v9, s0
	v_add_f32_e32 v8, 1.0, v8
	v_rcp_f32_e32 v8, v8
	global_store_short v[26:27], v9, off offset:544
	v_mul_f32_e32 v9, 0xbfb8aa3b, v21
	v_exp_f32_e32 v9, v9
	v_mul_f32_e32 v8, v20, v8
	v_mul_f32_e32 v8, v16, v8
	v_cvt_pk_bf16_f32 v10, v8, s0
	v_add_f32_e32 v8, 1.0, v9
	v_rcp_f32_e32 v11, v8
	v_add_co_u32_e32 v8, vcc, s47, v28
	s_nop 1
	v_addc_co_u32_e32 v9, vcc, 0, v29, vcc
	global_store_short v[8:9], v10, off
	v_mul_f32_e32 v10, v21, v11
	v_mul_f32_e32 v10, v17, v10
	v_cvt_pk_bf16_f32 v12, v10, s0
	v_mul_f32_e32 v10, 0xbfb8aa3b, v22
	v_exp_f32_e32 v13, v10
	v_add_co_u32_e32 v10, vcc, s48, v28
	v_add_f32_e32 v13, 1.0, v13
	s_nop 0
	v_addc_co_u32_e32 v11, vcc, 0, v29, vcc
	global_store_short v[10:11], v12, off offset:1536
	v_mul_f32_e32 v12, 0xbfb8aa3b, v23
	v_exp_f32_e32 v12, v12
	v_rcp_f32_e32 v13, v13
	v_add_f32_e32 v12, 1.0, v12
	v_rcp_f32_e32 v15, v12
	v_mul_f32_e32 v13, v22, v13
	v_mul_f32_e32 v13, v18, v13
	v_add_co_u32_e32 v12, vcc, s49, v28
	v_cvt_pk_bf16_f32 v14, v13, s0
	s_nop 0
	v_addc_co_u32_e32 v13, vcc, 0, v29, vcc
	global_store_short v[12:13], v14, off offset:3072
	v_mul_f32_e32 v14, v23, v15
	v_mul_f32_e32 v14, v19, v14
	v_cvt_pk_bf16_f32 v16, v14, s0
	v_mul_f32_e32 v14, 0xbfb8aa3b, v4
	v_exp_f32_e32 v17, v14
	v_add_co_u32_e32 v14, vcc, s50, v28
	v_add_f32_e32 v17, 1.0, v17
	s_nop 0
	v_addc_co_u32_e32 v15, vcc, 0, v29, vcc
	v_rcp_f32_e32 v17, v17
	global_store_short v[14:15], v16, off offset:512
	v_mul_f32_e32 v16, 0xbfb8aa3b, v5
	v_exp_f32_e32 v16, v16
	v_mul_f32_e32 v4, v4, v17
	v_mul_f32_e32 v0, v0, v4
	v_cvt_pk_bf16_f32 v0, v0, s0
	v_add_f32_e32 v4, 1.0, v16
	v_rcp_f32_e32 v4, v4
	v_mul_f32_e32 v16, 0xbfb8aa3b, v6
	v_exp_f32_e32 v16, v16
	global_store_short v[8:9], v0, off offset:32
	v_mul_f32_e32 v0, v5, v4
	v_mul_f32_e32 v0, v1, v0
	v_add_f32_e32 v1, 1.0, v16
	v_mul_f32_e32 v4, 0xbfb8aa3b, v7
	v_rcp_f32_e32 v1, v1
	v_exp_f32_e32 v4, v4
	v_cvt_pk_bf16_f32 v0, v0, s0
	global_store_short v[10:11], v0, off offset:1568
	v_mul_f32_e32 v0, v6, v1
	v_add_f32_e32 v1, 1.0, v4
	v_rcp_f32_e32 v1, v1
	v_mul_f32_e32 v0, v2, v0
	v_cvt_pk_bf16_f32 v0, v0, s0
	global_store_short v[12:13], v0, off offset:3104
	v_mul_f32_e32 v0, v7, v1
	v_mul_f32_e32 v0, v3, v0
	v_cvt_pk_bf16_f32 v0, v0, s0
	s_andn2_b64 vcc, exec, s[26:27]
	global_store_short v[14:15], v0, off offset:544
	s_cbranch_vccnz .LBB0_954

.Lg9_loop:
	s_waitcnt vmcnt(8)
	s_barrier
	ds_read_b128 v[64:67], v252 offset:0
	ds_read_b128 v[104:107], v254 offset:32768
	ds_read_b128 v[108:111], v254 offset:34816
	ds_read_b128 v[112:115], v254 offset:36864
	ds_read_b128 v[116:119], v254 offset:38912
	ds_read_b128 v[68:71], v252 offset:2048
	ds_read_b128 v[72:75], v252 offset:4096
	ds_read_b128 v[76:79], v252 offset:6144
	ds_read_b128 v[80:83], v253 offset:0
	ds_read_b128 v[120:123], v255 offset:32768
	ds_read_b128 v[124:127], v255 offset:34816
	ds_read_b128 v[132:135], v255 offset:36864
	ds_read_b128 v[136:139], v255 offset:38912
	s_waitcnt lgkmcnt(11)
	v_mfma_f32_16x16x32_bf16 v[60:63], v[64:67], v[104:107], v[60:63]
	s_waitcnt lgkmcnt(10)
	v_mfma_f32_16x16x32_bf16 v[44:47], v[64:67], v[108:111], v[44:47]
	s_waitcnt lgkmcnt(9)
	v_mfma_f32_16x16x32_bf16 v[28:31], v[64:67], v[112:115], v[28:31]
	s_waitcnt lgkmcnt(8)
	v_mfma_f32_16x16x32_bf16 v[12:15], v[64:67], v[116:119], v[12:15]
	ds_read_b128 v[84:87], v253 offset:2048
	ds_read_b128 v[88:91], v253 offset:4096
	ds_read_b128 v[92:95], v253 offset:6144
	s_waitcnt lgkmcnt(10)
	v_mfma_f32_16x16x32_bf16 v[56:59], v[68:71], v[104:107], v[56:59]
	v_mfma_f32_16x16x32_bf16 v[40:43], v[68:71], v[108:111], v[40:43]
	v_mfma_f32_16x16x32_bf16 v[20:23], v[68:71], v[112:115], v[20:23]
	v_mfma_f32_16x16x32_bf16 v[4:7], v[68:71], v[116:119], v[4:7]
	s_waitcnt lgkmcnt(9)
	v_mfma_f32_16x16x32_bf16 v[52:55], v[72:75], v[104:107], v[52:55]
	v_mfma_f32_16x16x32_bf16 v[32:35], v[72:75], v[108:111], v[32:35]
	v_mfma_f32_16x16x32_bf16 v[16:19], v[72:75], v[112:115], v[16:19]
	v_mfma_f32_16x16x32_bf16 v[0:3], v[72:75], v[116:119], v[0:3]
	s_waitcnt lgkmcnt(8)
	v_mfma_f32_16x16x32_bf16 v[48:51], v[76:79], v[104:107], v[48:51]
	v_mfma_f32_16x16x32_bf16 v[36:39], v[76:79], v[108:111], v[36:39]
	v_mfma_f32_16x16x32_bf16 v[24:27], v[76:79], v[112:115], v[24:27]
	v_mfma_f32_16x16x32_bf16 v[8:11], v[76:79], v[116:119], v[8:11]
	s_waitcnt lgkmcnt(0)
	s_barrier
	s_add_u32 m0, s6, 0x0
	v_mfma_f32_16x16x32_bf16 v[60:63], v[80:83], v[120:123], v[60:63]
	global_load_lds_dwordx4 v248, s[40:41]
	v_mfma_f32_16x16x32_bf16 v[44:47], v[80:83], v[124:127], v[44:47]
	s_add_u32 m0, s6, 0x400
	v_mfma_f32_16x16x32_bf16 v[28:31], v[80:83], v[132:135], v[28:31]
	global_load_lds_dwordx4 v249, s[40:41]
	v_mfma_f32_16x16x32_bf16 v[12:15], v[80:83], v[136:139], v[12:15]
	s_add_u32 m0, s6, 0x800
	v_mfma_f32_16x16x32_bf16 v[56:59], v[84:87], v[120:123], v[56:59]
	global_load_lds_dwordx4 v250, s[40:41]
	v_mfma_f32_16x16x32_bf16 v[40:43], v[84:87], v[124:127], v[40:43]
	s_add_u32 m0, s6, 0xc00
	v_mfma_f32_16x16x32_bf16 v[20:23], v[84:87], v[132:135], v[20:23]
	global_load_lds_dwordx4 v251, s[40:41]
	v_mfma_f32_16x16x32_bf16 v[4:7], v[84:87], v[136:139], v[4:7]
	s_add_u32 m0, s6, 0x8000
	v_mfma_f32_16x16x32_bf16 v[52:55], v[88:91], v[120:123], v[52:55]
	global_load_lds_dwordx4 v248, s[48:49]
	v_mfma_f32_16x16x32_bf16 v[32:35], v[88:91], v[124:127], v[32:35]
	s_add_u32 m0, s6, 0x8400
	v_mfma_f32_16x16x32_bf16 v[16:19], v[88:91], v[132:135], v[16:19]
	global_load_lds_dwordx4 v249, s[48:49]
	v_mfma_f32_16x16x32_bf16 v[0:3], v[88:91], v[136:139], v[0:3]
	s_add_u32 m0, s6, 0x8800
	v_mfma_f32_16x16x32_bf16 v[48:51], v[92:95], v[120:123], v[48:51]
	global_load_lds_dwordx4 v250, s[48:49]
	v_mfma_f32_16x16x32_bf16 v[36:39], v[92:95], v[124:127], v[36:39]
	s_add_u32 m0, s6, 0x8c00
	v_mfma_f32_16x16x32_bf16 v[24:27], v[92:95], v[132:135], v[24:27]
	global_load_lds_dwordx4 v251, s[48:49]
	v_mfma_f32_16x16x32_bf16 v[8:11], v[92:95], v[136:139], v[8:11]
	s_add_u32 s40, s40, 0x80
	s_addc_u32 s41, s41, 0
	s_add_u32 s48, s48, 0x80
	s_addc_u32 s49, s49, 0
	s_waitcnt vmcnt(8)
	s_barrier
	ds_read_b128 v[64:67], v252 offset:16384
	ds_read_b128 v[104:107], v254 offset:49152
	ds_read_b128 v[108:111], v254 offset:51200
	ds_read_b128 v[112:115], v254 offset:53248
	ds_read_b128 v[116:119], v254 offset:55296
	ds_read_b128 v[68:71], v252 offset:18432
	ds_read_b128 v[72:75], v252 offset:20480
	ds_read_b128 v[76:79], v252 offset:22528
	ds_read_b128 v[80:83], v253 offset:16384
	ds_read_b128 v[120:123], v255 offset:49152
	ds_read_b128 v[124:127], v255 offset:51200
	ds_read_b128 v[132:135], v255 offset:53248
	ds_read_b128 v[136:139], v255 offset:55296
	s_waitcnt lgkmcnt(11)
	v_mfma_f32_16x16x32_bf16 v[60:63], v[64:67], v[104:107], v[60:63]
	s_waitcnt lgkmcnt(10)
	v_mfma_f32_16x16x32_bf16 v[44:47], v[64:67], v[108:111], v[44:47]
	s_waitcnt lgkmcnt(9)
	v_mfma_f32_16x16x32_bf16 v[28:31], v[64:67], v[112:115], v[28:31]
	s_waitcnt lgkmcnt(8)
	v_mfma_f32_16x16x32_bf16 v[12:15], v[64:67], v[116:119], v[12:15]
	ds_read_b128 v[84:87], v253 offset:18432
	ds_read_b128 v[88:91], v253 offset:20480
	ds_read_b128 v[92:95], v253 offset:22528
	s_waitcnt lgkmcnt(10)
	v_mfma_f32_16x16x32_bf16 v[56:59], v[68:71], v[104:107], v[56:59]
	v_mfma_f32_16x16x32_bf16 v[40:43], v[68:71], v[108:111], v[40:43]
	v_mfma_f32_16x16x32_bf16 v[20:23], v[68:71], v[112:115], v[20:23]
	v_mfma_f32_16x16x32_bf16 v[4:7], v[68:71], v[116:119], v[4:7]
	s_waitcnt lgkmcnt(9)
	v_mfma_f32_16x16x32_bf16 v[52:55], v[72:75], v[104:107], v[52:55]
	v_mfma_f32_16x16x32_bf16 v[32:35], v[72:75], v[108:111], v[32:35]
	v_mfma_f32_16x16x32_bf16 v[16:19], v[72:75], v[112:115], v[16:19]
	v_mfma_f32_16x16x32_bf16 v[0:3], v[72:75], v[116:119], v[0:3]
	s_waitcnt lgkmcnt(8)
	v_mfma_f32_16x16x32_bf16 v[48:51], v[76:79], v[104:107], v[48:51]
	v_mfma_f32_16x16x32_bf16 v[36:39], v[76:79], v[108:111], v[36:39]
	v_mfma_f32_16x16x32_bf16 v[24:27], v[76:79], v[112:115], v[24:27]
	v_mfma_f32_16x16x32_bf16 v[8:11], v[76:79], v[116:119], v[8:11]
	s_waitcnt lgkmcnt(0)
	s_barrier
	s_add_u32 m0, s6, 0x4000
	v_mfma_f32_16x16x32_bf16 v[60:63], v[80:83], v[120:123], v[60:63]
	global_load_lds_dwordx4 v248, s[40:41]
	v_mfma_f32_16x16x32_bf16 v[44:47], v[80:83], v[124:127], v[44:47]
	s_add_u32 m0, s6, 0x4400
	v_mfma_f32_16x16x32_bf16 v[28:31], v[80:83], v[132:135], v[28:31]
	global_load_lds_dwordx4 v249, s[40:41]
	v_mfma_f32_16x16x32_bf16 v[12:15], v[80:83], v[136:139], v[12:15]
	s_add_u32 m0, s6, 0x4800
	v_mfma_f32_16x16x32_bf16 v[56:59], v[84:87], v[120:123], v[56:59]
	global_load_lds_dwordx4 v250, s[40:41]
	v_mfma_f32_16x16x32_bf16 v[40:43], v[84:87], v[124:127], v[40:43]
	s_add_u32 m0, s6, 0x4c00
	v_mfma_f32_16x16x32_bf16 v[20:23], v[84:87], v[132:135], v[20:23]
	global_load_lds_dwordx4 v251, s[40:41]
	v_mfma_f32_16x16x32_bf16 v[4:7], v[84:87], v[136:139], v[4:7]
	s_add_u32 m0, s6, 0xc000
	v_mfma_f32_16x16x32_bf16 v[52:55], v[88:91], v[120:123], v[52:55]
	global_load_lds_dwordx4 v248, s[48:49]
	v_mfma_f32_16x16x32_bf16 v[32:35], v[88:91], v[124:127], v[32:35]
	s_add_u32 m0, s6, 0xc400
	v_mfma_f32_16x16x32_bf16 v[16:19], v[88:91], v[132:135], v[16:19]
	global_load_lds_dwordx4 v249, s[48:49]
	v_mfma_f32_16x16x32_bf16 v[0:3], v[88:91], v[136:139], v[0:3]
	s_add_u32 m0, s6, 0xc800
	v_mfma_f32_16x16x32_bf16 v[48:51], v[92:95], v[120:123], v[48:51]
	global_load_lds_dwordx4 v250, s[48:49]
	v_mfma_f32_16x16x32_bf16 v[36:39], v[92:95], v[124:127], v[36:39]
	s_add_u32 m0, s6, 0xcc00
	v_mfma_f32_16x16x32_bf16 v[24:27], v[92:95], v[132:135], v[24:27]
	global_load_lds_dwordx4 v251, s[48:49]
	v_mfma_f32_16x16x32_bf16 v[8:11], v[92:95], v[136:139], v[8:11]
	s_add_u32 s40, s40, 0x80
	s_addc_u32 s41, s41, 0
	s_add_u32 s48, s48, 0x80
	s_addc_u32 s49, s49, 0
	s_sub_u32 s32, s32, 1
	s_cmp_lg_u32 s32, 0
	s_cbranch_scc1 .Lg9_loop
	s_waitcnt vmcnt(8)
	s_barrier
	ds_read_b128 v[64:67], v252 offset:0
	ds_read_b128 v[104:107], v254 offset:32768
	ds_read_b128 v[108:111], v254 offset:34816
	ds_read_b128 v[112:115], v254 offset:36864
	ds_read_b128 v[116:119], v254 offset:38912
	ds_read_b128 v[68:71], v252 offset:2048
	ds_read_b128 v[72:75], v252 offset:4096
	ds_read_b128 v[76:79], v252 offset:6144
	ds_read_b128 v[80:83], v253 offset:0
	ds_read_b128 v[120:123], v255 offset:32768
	ds_read_b128 v[124:127], v255 offset:34816
	ds_read_b128 v[132:135], v255 offset:36864
	ds_read_b128 v[136:139], v255 offset:38912
	s_waitcnt lgkmcnt(11)
	v_mfma_f32_16x16x32_bf16 v[60:63], v[64:67], v[104:107], v[60:63]
	s_waitcnt lgkmcnt(10)
	v_mfma_f32_16x16x32_bf16 v[44:47], v[64:67], v[108:111], v[44:47]
	s_waitcnt lgkmcnt(9)
	v_mfma_f32_16x16x32_bf16 v[28:31], v[64:67], v[112:115], v[28:31]
	s_waitcnt lgkmcnt(8)
	v_mfma_f32_16x16x32_bf16 v[12:15], v[64:67], v[116:119], v[12:15]
	ds_read_b128 v[84:87], v253 offset:2048
	ds_read_b128 v[88:91], v253 offset:4096
	ds_read_b128 v[92:95], v253 offset:6144
	s_waitcnt lgkmcnt(10)
	v_mfma_f32_16x16x32_bf16 v[56:59], v[68:71], v[104:107], v[56:59]
	v_mfma_f32_16x16x32_bf16 v[40:43], v[68:71], v[108:111], v[40:43]
	v_mfma_f32_16x16x32_bf16 v[20:23], v[68:71], v[112:115], v[20:23]
	v_mfma_f32_16x16x32_bf16 v[4:7], v[68:71], v[116:119], v[4:7]
	s_waitcnt lgkmcnt(9)
	v_mfma_f32_16x16x32_bf16 v[52:55], v[72:75], v[104:107], v[52:55]
	v_mfma_f32_16x16x32_bf16 v[32:35], v[72:75], v[108:111], v[32:35]
	v_mfma_f32_16x16x32_bf16 v[16:19], v[72:75], v[112:115], v[16:19]
	v_mfma_f32_16x16x32_bf16 v[0:3], v[72:75], v[116:119], v[0:3]
	s_waitcnt lgkmcnt(8)
	v_mfma_f32_16x16x32_bf16 v[48:51], v[76:79], v[104:107], v[48:51]
	v_mfma_f32_16x16x32_bf16 v[36:39], v[76:79], v[108:111], v[36:39]
	v_mfma_f32_16x16x32_bf16 v[24:27], v[76:79], v[112:115], v[24:27]
	v_mfma_f32_16x16x32_bf16 v[8:11], v[76:79], v[116:119], v[8:11]
	s_waitcnt lgkmcnt(0)
	s_barrier
	v_mfma_f32_16x16x32_bf16 v[60:63], v[80:83], v[120:123], v[60:63]
	v_mfma_f32_16x16x32_bf16 v[44:47], v[80:83], v[124:127], v[44:47]
	v_mfma_f32_16x16x32_bf16 v[28:31], v[80:83], v[132:135], v[28:31]
	v_mfma_f32_16x16x32_bf16 v[12:15], v[80:83], v[136:139], v[12:15]
	v_mfma_f32_16x16x32_bf16 v[56:59], v[84:87], v[120:123], v[56:59]
	v_mfma_f32_16x16x32_bf16 v[40:43], v[84:87], v[124:127], v[40:43]
	v_mfma_f32_16x16x32_bf16 v[20:23], v[84:87], v[132:135], v[20:23]
	v_mfma_f32_16x16x32_bf16 v[4:7], v[84:87], v[136:139], v[4:7]
	v_mfma_f32_16x16x32_bf16 v[52:55], v[88:91], v[120:123], v[52:55]
	v_mfma_f32_16x16x32_bf16 v[32:35], v[88:91], v[124:127], v[32:35]
	v_mfma_f32_16x16x32_bf16 v[16:19], v[88:91], v[132:135], v[16:19]
	v_mfma_f32_16x16x32_bf16 v[0:3], v[88:91], v[136:139], v[0:3]
	v_mfma_f32_16x16x32_bf16 v[48:51], v[92:95], v[120:123], v[48:51]
	v_mfma_f32_16x16x32_bf16 v[36:39], v[92:95], v[124:127], v[36:39]
	v_mfma_f32_16x16x32_bf16 v[24:27], v[92:95], v[132:135], v[24:27]
	v_mfma_f32_16x16x32_bf16 v[8:11], v[92:95], v[136:139], v[8:11]
	s_waitcnt vmcnt(0)
	s_barrier
	ds_read_b128 v[64:67], v252 offset:16384
	ds_read_b128 v[104:107], v254 offset:49152
	ds_read_b128 v[108:111], v254 offset:51200
	ds_read_b128 v[112:115], v254 offset:53248
	ds_read_b128 v[116:119], v254 offset:55296
	ds_read_b128 v[68:71], v252 offset:18432
	ds_read_b128 v[72:75], v252 offset:20480
	ds_read_b128 v[76:79], v252 offset:22528
	ds_read_b128 v[80:83], v253 offset:16384
	ds_read_b128 v[120:123], v255 offset:49152
	ds_read_b128 v[124:127], v255 offset:51200
	ds_read_b128 v[132:135], v255 offset:53248
	ds_read_b128 v[136:139], v255 offset:55296
	s_waitcnt lgkmcnt(11)
	v_mfma_f32_16x16x32_bf16 v[60:63], v[64:67], v[104:107], v[60:63]
	s_waitcnt lgkmcnt(10)
	v_mfma_f32_16x16x32_bf16 v[44:47], v[64:67], v[108:111], v[44:47]
	s_waitcnt lgkmcnt(9)
	v_mfma_f32_16x16x32_bf16 v[28:31], v[64:67], v[112:115], v[28:31]
	s_waitcnt lgkmcnt(8)
	v_mfma_f32_16x16x32_bf16 v[12:15], v[64:67], v[116:119], v[12:15]
	ds_read_b128 v[84:87], v253 offset:18432
	ds_read_b128 v[88:91], v253 offset:20480
	ds_read_b128 v[92:95], v253 offset:22528
	s_waitcnt lgkmcnt(10)
	v_mfma_f32_16x16x32_bf16 v[56:59], v[68:71], v[104:107], v[56:59]
	v_mfma_f32_16x16x32_bf16 v[40:43], v[68:71], v[108:111], v[40:43]
	v_mfma_f32_16x16x32_bf16 v[20:23], v[68:71], v[112:115], v[20:23]
	v_mfma_f32_16x16x32_bf16 v[4:7], v[68:71], v[116:119], v[4:7]
	s_waitcnt lgkmcnt(9)
	v_mfma_f32_16x16x32_bf16 v[52:55], v[72:75], v[104:107], v[52:55]
	v_mfma_f32_16x16x32_bf16 v[32:35], v[72:75], v[108:111], v[32:35]
	v_mfma_f32_16x16x32_bf16 v[16:19], v[72:75], v[112:115], v[16:19]
	v_mfma_f32_16x16x32_bf16 v[0:3], v[72:75], v[116:119], v[0:3]
	s_waitcnt lgkmcnt(8)
	v_mfma_f32_16x16x32_bf16 v[48:51], v[76:79], v[104:107], v[48:51]
	v_mfma_f32_16x16x32_bf16 v[36:39], v[76:79], v[108:111], v[36:39]
	v_mfma_f32_16x16x32_bf16 v[24:27], v[76:79], v[112:115], v[24:27]
	v_mfma_f32_16x16x32_bf16 v[8:11], v[76:79], v[116:119], v[8:11]
	s_waitcnt lgkmcnt(0)
	s_barrier
	v_mfma_f32_16x16x32_bf16 v[60:63], v[80:83], v[120:123], v[60:63]
	v_mfma_f32_16x16x32_bf16 v[44:47], v[80:83], v[124:127], v[44:47]
	v_mfma_f32_16x16x32_bf16 v[28:31], v[80:83], v[132:135], v[28:31]
	v_mfma_f32_16x16x32_bf16 v[12:15], v[80:83], v[136:139], v[12:15]
	v_mfma_f32_16x16x32_bf16 v[56:59], v[84:87], v[120:123], v[56:59]
	v_mfma_f32_16x16x32_bf16 v[40:43], v[84:87], v[124:127], v[40:43]
	v_mfma_f32_16x16x32_bf16 v[20:23], v[84:87], v[132:135], v[20:23]
	v_mfma_f32_16x16x32_bf16 v[4:7], v[84:87], v[136:139], v[4:7]
	v_mfma_f32_16x16x32_bf16 v[52:55], v[88:91], v[120:123], v[52:55]
	v_mfma_f32_16x16x32_bf16 v[32:35], v[88:91], v[124:127], v[32:35]
	v_mfma_f32_16x16x32_bf16 v[16:19], v[88:91], v[132:135], v[16:19]
	v_mfma_f32_16x16x32_bf16 v[0:3], v[88:91], v[136:139], v[0:3]
	v_mfma_f32_16x16x32_bf16 v[48:51], v[92:95], v[120:123], v[48:51]
	v_mfma_f32_16x16x32_bf16 v[36:39], v[92:95], v[124:127], v[36:39]
	v_mfma_f32_16x16x32_bf16 v[24:27], v[92:95], v[132:135], v[24:27]
	v_mfma_f32_16x16x32_bf16 v[8:11], v[92:95], v[136:139], v[8:11]
	s_nop 7
	s_nop 1
	v_sub_co_u32_e32 v64, vcc, s37, v151
	s_nop 0
	v_readfirstlane_b32 s6, v64
	s_lshr_b32 s6, s6, 10
	s_add_i32 s6, s6, 1
	s_and_b64 s[40:41], vcc, exec
	s_cselect_b32 s6, 0, s6
	s_mul_hi_u32 s39, s6, 0x6000
	s_mulk_i32 s6, 0x6000
	v_or_b32_e32 v64, s38, v148
	s_add_u32 s40, s2, s6
	v_ashrrev_i32_e32 v65, 31, v64
	s_addc_u32 s41, s3, s39
	v_add_lshl_u32 v94, v149, s37, 12
	v_lshlrev_b64 v[66:67], 2, v[64:65]
	v_lshl_add_u64 v[102:103], s[40:41], 0, v[66:67]
	v_lshl_add_u64 v[136:137], s[4:5], 0, v[66:67]
	v_mov_b32_e32 v95, v97
	v_or_b32_e32 v66, 0x1000, v94
	v_mov_b32_e32 v67, v97
	v_lshl_add_u64 v[104:105], v[136:137], 0, v[94:95]
	global_load_dword v65, v[102:103], off
	global_load_dword v152, v[104:105], off
	v_lshl_add_u64 v[106:107], v[136:137], 0, v[66:67]
	v_or_b32_e32 v68, 0x2000, v94
	v_mov_b32_e32 v69, v97
	v_or_b32_e32 v70, 0x3000, v94
	v_mov_b32_e32 v71, v97
	v_or_b32_e32 v72, 0x10000, v94
	v_mov_b32_e32 v73, v97
	global_load_dword v153, v[106:107], off
	v_lshl_add_u64 v[108:109], v[136:137], 0, v[68:69]
	v_lshl_add_u64 v[110:111], v[136:137], 0, v[70:71]
	v_lshl_add_u64 v[112:113], v[136:137], 0, v[72:73]
	v_or_b32_e32 v74, 0x11000, v94
	v_mov_b32_e32 v75, v97
	global_load_dword v154, v[108:109], off
	global_load_dword v155, v[110:111], off
	global_load_dword v156, v[112:113], off
	v_lshl_add_u64 v[114:115], v[136:137], 0, v[74:75]
	v_or_b32_e32 v76, 0x12000, v94
	v_mov_b32_e32 v77, v97
	v_or_b32_e32 v78, 0x13000, v94
	v_mov_b32_e32 v79, v97
	v_or_b32_e32 v80, 0x20000, v94
	v_mov_b32_e32 v81, v97
	global_load_dword v157, v[114:115], off
	v_or_b32_e32 v96, 0x30000, v94
	v_lshl_add_u64 v[116:117], v[136:137], 0, v[76:77]
	v_lshl_add_u64 v[118:119], v[136:137], 0, v[78:79]
	v_lshl_add_u64 v[120:121], v[136:137], 0, v[80:81]
	v_or_b32_e32 v82, 0x21000, v94
	v_mov_b32_e32 v83, v97
	global_load_dword v158, v[116:117], off
	global_load_dword v159, v[118:119], off
	global_load_dword v160, v[120:121], off
	v_lshl_add_u64 v[122:123], v[136:137], 0, v[82:83]
	v_or_b32_e32 v84, 0x22000, v94
	v_mov_b32_e32 v85, v97
	v_or_b32_e32 v86, 0x23000, v94
	v_mov_b32_e32 v87, v97
	v_lshl_add_u64 v[130:131], v[136:137], 0, v[96:97]
	v_lshl_add_u64 v[124:125], v[136:137], 0, v[84:85]
	v_lshl_add_u64 v[126:127], v[136:137], 0, v[86:87]
	global_load_dword v161, v[122:123], off
	global_load_dword v170, v[124:125], off
	global_load_dword v171, v[126:127], off
	global_load_dword v172, v[130:131], off
	v_or_b32_e32 v88, 0x31000, v94
	v_mov_b32_e32 v89, v97
	v_lshl_add_u64 v[132:133], v[136:137], 0, v[88:89]
	v_or_b32_e32 v90, 0x32000, v94
	v_mov_b32_e32 v91, v97
	v_or_b32_e32 v92, 0x33000, v94
	v_mov_b32_e32 v93, v97
	v_lshl_add_u64 v[134:135], v[136:137], 0, v[90:91]
	v_lshl_add_u64 v[136:137], v[136:137], 0, v[92:93]
	global_load_dword v173, v[132:133], off
	global_load_dword v174, v[134:135], off
	global_load_dword v175, v[136:137], off
	v_or_b32_e32 v138, 16, v64
	v_ashrrev_i32_e32 v139, 31, v138
	v_lshlrev_b64 v[138:139], 2, v[138:139]
	v_lshl_add_u64 v[94:95], s[4:5], 0, v[94:95]
	global_load_dword v176, v[102:103], off offset:64
	v_lshl_add_u64 v[142:143], s[4:5], 0, v[138:139]
	v_lshl_add_u64 v[138:139], v[94:95], 0, v[138:139]
	v_add_f32_e32 v60, 0, v60
	v_lshl_add_u64 v[140:141], v[142:143], 0, v[66:67]
	global_load_dword v177, v[138:139], off
	global_load_dword v178, v[140:141], off
	global_load_dword v179, v[102:103], off offset:128
	global_load_dword v180, v[102:103], off offset:192
	v_lshl_add_u64 v[102:103], v[142:143], 0, v[68:69]
	global_load_dword v181, v[102:103], off
	v_add_f32_e32 v56, 0, v56
	v_add_f32_e32 v58, 0, v58
	v_add_f32_e32 v52, 0, v52
	v_add_f32_e32 v48, 0, v48
	v_add_f32_e32 v44, 0, v44
	v_add_f32_e32 v50, 0, v50
	v_add_f32_e32 v32, 0, v32
	v_add_f32_e32 v34, 0, v34
	v_add_f32_e32 v40, 0, v40
	v_add_f32_e32 v38, 0, v38
	v_add_f32_e32 v36, 0, v36
	v_add_f32_e32 v28, 0, v28
	v_add_f32_e32 v30, 0, v30
	v_add_f32_e32 v20, 0, v20
	s_waitcnt vmcnt(21)
	v_fmac_f32_e32 v152, v60, v65
	v_add_f32_e32 v60, 0, v61
	global_store_dword v[104:105], v152, off
	v_lshl_add_u64 v[104:105], v[142:143], 0, v[72:73]
	v_add_f32_e32 v16, 0, v16
	v_add_f32_e32 v0, 0, v0
	v_add_f32_e32 v12, 0, v12
	v_add_f32_e32 v4, 0, v4
	s_waitcnt vmcnt(21)
	v_fmac_f32_e32 v153, v60, v65
	v_add_f32_e32 v60, 0, v62
	v_add_f32_e32 v62, 0, v63
	global_store_dword v[106:107], v153, off
	v_lshl_add_u64 v[106:107], v[142:143], 0, v[76:77]
	global_load_dword v153, v[104:105], off
	s_waitcnt vmcnt(22)
	v_fmac_f32_e32 v154, v60, v65
	global_store_dword v[108:109], v154, off
	s_waitcnt vmcnt(21)
	v_fmac_f32_e32 v156, v56, v65
	v_add_f32_e32 v56, 0, v57
	v_lshl_add_u64 v[108:109], v[142:143], 0, v[80:81]
	v_lshl_add_u64 v[60:61], v[142:143], 0, v[70:71]
	global_store_dword v[112:113], v156, off
	v_add_f32_e32 v112, 0, v59
	v_fmac_f32_e32 v155, v62, v65
	global_store_dword v[110:111], v155, off
	s_waitcnt vmcnt(22)
	v_fmac_f32_e32 v157, v56, v65
	global_store_dword v[114:115], v157, off
	global_load_dword v157, v[108:109], off
	v_lshl_add_u64 v[62:63], v[142:143], 0, v[74:75]
	global_load_dword v152, v[60:61], off
	global_load_dword v155, v[106:107], off
	v_lshl_add_u64 v[110:111], v[142:143], 0, v[82:83]
	s_waitcnt vmcnt(25)
	v_fmac_f32_e32 v158, v58, v65
	v_lshl_add_u64 v[58:59], v[142:143], 0, v[84:85]
	s_waitcnt vmcnt(23)
	v_fmac_f32_e32 v160, v52, v65
	v_add_f32_e32 v52, 0, v53
	global_store_dword v[116:117], v158, off
	global_load_dword v158, v[58:59], off
	v_fmac_f32_e32 v159, v112, v65
	v_lshl_add_u64 v[112:113], v[142:143], 0, v[86:87]
	global_load_dword v183, v[112:113], off
	s_waitcnt vmcnt(25)
	v_fmac_f32_e32 v161, v52, v65
	v_add_f32_e32 v52, 0, v54
	s_waitcnt vmcnt(24)
	v_fmac_f32_e32 v170, v52, v65
	s_waitcnt vmcnt(22)
	v_fmac_f32_e32 v172, v48, v65
	v_add_f32_e32 v48, 0, v49
	v_lshl_add_u64 v[52:53], v[142:143], 0, v[90:91]
	v_lshl_add_u64 v[114:115], v[142:143], 0, v[96:97]
	global_store_dword v[120:121], v160, off
	global_load_dword v120, v[52:53], off
	v_lshl_add_u64 v[56:57], v[142:143], 0, v[78:79]
	global_load_dword v182, v[110:111], off
	global_load_dword v156, v[56:57], off
	s_waitcnt vmcnt(25)
	v_fmac_f32_e32 v173, v48, v65
	v_lshl_add_u64 v[48:49], v[142:143], 0, v[92:93]
	global_load_dword v121, v[48:49], off
	s_waitcnt vmcnt(25)
	v_fmac_f32_e32 v174, v50, v65
	global_store_dword v[118:119], v159, off
	global_load_dword v118, v[114:115], off
	v_add_f32_e32 v50, 0, v51
	global_load_dword v154, v[62:63], off
	s_waitcnt vmcnt(25)
	v_fmac_f32_e32 v177, v44, v176
	v_add_f32_e32 v44, 0, v45
	s_waitcnt vmcnt(24)
	v_fmac_f32_e32 v178, v44, v176
	v_add_f32_e32 v44, 0, v46
	v_add_f32_e32 v54, 0, v55
	s_waitcnt vmcnt(21)
	v_fmac_f32_e32 v181, v44, v176
	v_or_b32_e32 v44, 32, v64
	v_ashrrev_i32_e32 v45, 31, v44
	v_lshlrev_b64 v[44:45], 2, v[44:45]
	v_fmac_f32_e32 v175, v50, v65
	v_lshl_add_u64 v[50:51], v[94:95], 0, v[44:45]
	v_lshl_add_u64 v[44:45], s[4:5], 0, v[44:45]
	v_fmac_f32_e32 v171, v54, v65
	v_lshl_add_u64 v[54:55], v[44:45], 0, v[78:79]
	v_add_f32_e32 v46, 0, v47
	v_lshl_add_u64 v[116:117], v[142:143], 0, v[88:89]
	global_load_dword v119, v[116:117], off
	v_or_b32_e32 v64, 48, v64
	global_store_dword v[102:103], v181, off
	v_ashrrev_i32_e32 v65, 31, v64
	v_lshlrev_b64 v[64:65], 2, v[64:65]
	global_store_dword v[122:123], v161, off
	global_store_dword v[124:125], v170, off
	global_store_dword v[126:127], v171, off
	global_store_dword v[130:131], v172, off
	global_store_dword v[132:133], v173, off
	global_store_dword v[134:135], v174, off
	global_store_dword v[136:137], v175, off
	global_store_dword v[138:139], v177, off
	global_store_dword v[140:141], v178, off
	v_lshl_add_u64 v[94:95], v[94:95], 0, v[64:65]
	v_lshl_add_u64 v[64:65], s[4:5], 0, v[64:65]
	v_add_f32_e32 v21, 0, v21
	s_waitcnt vmcnt(29)
	v_fmac_f32_e32 v153, v40, v176
	v_add_f32_e32 v40, 0, v41
	global_store_dword v[104:105], v153, off
	s_add_i32 s36, s36, s30
	s_cmpk_gt_i32 s36, 0x1ff
	s_waitcnt vmcnt(25)
	v_fmac_f32_e32 v157, v32, v176
	global_store_dword v[108:109], v157, off
	global_load_dword v109, v[54:55], off
	s_waitcnt vmcnt(26)
	v_fmac_f32_e32 v152, v46, v176
	v_lshl_add_u64 v[46:47], v[44:45], 0, v[66:67]
	global_load_dword v102, v[50:51], off
	global_load_dword v103, v[46:47], off
	v_add_f32_e32 v32, 0, v33
	global_store_dword v[60:61], v152, off
	v_lshl_add_u64 v[60:61], v[44:45], 0, v[88:89]
	s_waitcnt vmcnt(26)
	v_fmac_f32_e32 v158, v34, v176
	global_store_dword v[58:59], v158, off
	v_add_f32_e32 v34, 0, v35
	v_add_f32_e32 v58, 0, v39
	s_waitcnt vmcnt(26)
	v_fmac_f32_e32 v183, v34, v176
	global_store_dword v[112:113], v183, off
	v_lshl_add_u64 v[34:35], v[44:45], 0, v[72:73]
	v_lshl_add_u64 v[66:67], v[64:65], 0, v[66:67]
	s_waitcnt vmcnt(25)
	v_fmac_f32_e32 v120, v38, v176
	global_store_dword v[52:53], v120, off
	s_waitcnt vmcnt(25)
	v_fmac_f32_e32 v182, v32, v176
	v_lshl_add_u64 v[52:53], v[44:45], 0, v[82:83]
	global_store_dword v[110:111], v182, off
	v_lshl_add_u64 v[32:33], v[44:45], 0, v[70:71]
	s_waitcnt vmcnt(24)
	v_fmac_f32_e32 v121, v58, v176
	v_lshl_add_u64 v[58:59], v[44:45], 0, v[86:87]
	global_load_dword v113, v[58:59], off
	global_load_dword v111, v[52:53], off
	s_waitcnt vmcnt(24)
	v_fmac_f32_e32 v118, v36, v176
	s_waitcnt vmcnt(23)
	v_fmac_f32_e32 v154, v40, v176
	v_add_f32_e32 v40, 0, v42
	v_add_f32_e32 v42, 0, v43
	v_fmac_f32_e32 v156, v42, v176
	global_store_dword v[56:57], v156, off
	v_lshl_add_u64 v[56:57], v[44:45], 0, v[80:81]
	global_store_dword v[114:115], v118, off
	global_load_dword v110, v[56:57], off
	global_load_dword v105, v[32:33], off
	v_add_f32_e32 v36, 0, v37
	global_load_dword v115, v[60:61], off
	v_fmac_f32_e32 v155, v40, v176
	v_lshl_add_u64 v[40:41], v[44:45], 0, v[68:69]
	global_load_dword v104, v[40:41], off
	v_lshl_add_u64 v[42:43], v[44:45], 0, v[76:77]
	global_store_dword v[106:107], v155, off
	global_load_dword v106, v[34:35], off
	s_waitcnt vmcnt(30)
	v_fmac_f32_e32 v119, v36, v176
	global_store_dword v[48:49], v121, off
	v_lshl_add_u64 v[48:49], v[44:45], 0, v[96:97]
	global_store_dword v[62:63], v154, off
	v_lshl_add_u64 v[36:37], v[44:45], 0, v[74:75]
	global_store_dword v[116:117], v119, off
	v_lshl_add_u64 v[38:39], v[44:45], 0, v[84:85]
	global_load_dword v114, v[48:49], off
	v_lshl_add_u64 v[62:63], v[44:45], 0, v[90:91]
	global_load_dword v107, v[36:37], off
	global_load_dword v108, v[42:43], off
	global_load_dword v112, v[38:39], off
	v_lshl_add_u64 v[44:45], v[44:45], 0, v[92:93]
	global_load_dword v116, v[62:63], off
	global_load_dword v117, v[44:45], off
	v_lshl_add_u64 v[68:69], v[64:65], 0, v[68:69]
	global_load_dword v120, v[68:69], off
	global_load_dword v118, v[94:95], off
	global_load_dword v119, v[66:67], off
	s_waitcnt vmcnt(28)
	v_fmac_f32_e32 v102, v28, v179
	global_store_dword v[50:51], v102, off
	v_lshl_add_u64 v[50:51], v[64:65], 0, v[70:71]
	v_add_f32_e32 v70, 0, v29
	v_lshl_add_u64 v[28:29], v[64:65], 0, v[72:73]
	s_waitcnt vmcnt(28)
	v_fmac_f32_e32 v103, v70, v179
	v_lshl_add_u64 v[70:71], v[64:65], 0, v[74:75]
	v_lshl_add_u64 v[72:73], v[64:65], 0, v[78:79]
	v_lshl_add_u64 v[74:75], v[64:65], 0, v[80:81]
	global_load_dword v122, v[70:71], off
	global_load_dword v123, v[72:73], off
	global_load_dword v124, v[74:75], off
	global_load_dword v102, v[50:51], off
	global_load_dword v121, v[28:29], off
	v_lshl_add_u64 v[78:79], v[64:65], 0, v[88:89]
	global_store_dword v[46:47], v103, off
	v_lshl_add_u64 v[46:47], v[64:65], 0, v[76:77]
	global_load_dword v103, v[46:47], off
	v_add_f32_e32 v76, 0, v31
	v_lshl_add_u64 v[80:81], v[64:65], 0, v[90:91]
	s_waitcnt vmcnt(25)
	v_fmac_f32_e32 v110, v16, v179
	s_waitcnt vmcnt(24)
	v_fmac_f32_e32 v105, v76, v179
	v_lshl_add_u64 v[76:77], v[64:65], 0, v[86:87]
	global_store_dword v[32:33], v105, off
	v_lshl_add_u64 v[32:33], v[64:65], 0, v[96:97]
	global_load_dword v86, v[78:79], off
	s_waitcnt vmcnt(24)
	v_fmac_f32_e32 v104, v30, v179
	global_store_dword v[40:41], v104, off
	v_lshl_add_u64 v[40:41], v[64:65], 0, v[82:83]
	global_load_dword v82, v[40:41], off
	v_lshl_add_u64 v[30:31], v[64:65], 0, v[84:85]
	global_load_dword v83, v[30:31], off
	global_load_dword v85, v[32:33], off
	global_load_dword v84, v[76:77], off
	s_waitcnt vmcnt(27)
	v_fmac_f32_e32 v106, v20, v179
	global_load_dword v20, v[80:81], off
	v_add_f32_e32 v16, 0, v17
	global_store_dword v[34:35], v106, off
	v_lshl_add_u64 v[34:35], v[64:65], 0, v[92:93]
	global_load_dword v64, v[34:35], off
	v_fmac_f32_e32 v111, v16, v179
	v_add_f32_e32 v16, 0, v18
	s_waitcnt vmcnt(23)
	v_fmac_f32_e32 v112, v16, v179
	v_add_f32_e32 v16, 0, v19
	v_fmac_f32_e32 v113, v16, v179
	v_add_f32_e32 v16, 0, v24
	v_fmac_f32_e32 v114, v16, v179
	v_add_f32_e32 v16, 0, v25
	s_waitcnt vmcnt(19)
	v_fmac_f32_e32 v118, v12, v180
	v_add_f32_e32 v12, 0, v13
	v_fmac_f32_e32 v107, v21, v179
	v_add_f32_e32 v21, 0, v22
	v_fmac_f32_e32 v115, v16, v179
	v_add_f32_e32 v16, 0, v26
	s_waitcnt vmcnt(18)
	v_fmac_f32_e32 v119, v12, v180
	v_add_f32_e32 v12, 0, v14
	v_fmac_f32_e32 v108, v21, v179
	v_add_f32_e32 v21, 0, v23
	v_fmac_f32_e32 v116, v16, v179
	v_add_f32_e32 v16, 0, v27
	v_fmac_f32_e32 v120, v12, v180
	v_add_f32_e32 v12, 0, v15
	v_fmac_f32_e32 v109, v21, v179
	v_fmac_f32_e32 v117, v16, v179
	global_store_dword v[36:37], v107, off
	global_store_dword v[42:43], v108, off
	global_store_dword v[54:55], v109, off
	global_store_dword v[56:57], v110, off
	global_store_dword v[52:53], v111, off
	global_store_dword v[38:39], v112, off
	global_store_dword v[58:59], v113, off
	global_store_dword v[48:49], v114, off
	global_store_dword v[60:61], v115, off
	global_store_dword v[62:63], v116, off
	global_store_dword v[44:45], v117, off
	global_store_dword v[94:95], v118, off
	s_waitcnt vmcnt(26)
	v_fmac_f32_e32 v124, v0, v180
	v_add_f32_e32 v0, 0, v1
	s_waitcnt vmcnt(24)
	v_fmac_f32_e32 v121, v4, v180
	v_add_f32_e32 v4, 0, v5
	v_fmac_f32_e32 v122, v4, v180
	v_add_f32_e32 v4, 0, v6
	s_waitcnt vmcnt(22)
	v_fmac_f32_e32 v103, v4, v180
	v_add_f32_e32 v4, 0, v7
	v_fmac_f32_e32 v102, v12, v180
	v_fmac_f32_e32 v123, v4, v180
	global_store_dword v[66:67], v119, off
	global_store_dword v[68:69], v120, off
	global_store_dword v[50:51], v102, off
	global_store_dword v[28:29], v121, off
	global_store_dword v[70:71], v122, off
	global_store_dword v[46:47], v103, off
	global_store_dword v[72:73], v123, off
	global_store_dword v[74:75], v124, off
	s_waitcnt vmcnt(26)
	v_fmac_f32_e32 v82, v0, v180
	v_add_f32_e32 v0, 0, v2
	s_waitcnt vmcnt(25)
	v_fmac_f32_e32 v83, v0, v180
	v_add_f32_e32 v0, 0, v3
	s_waitcnt vmcnt(23)
	v_fmac_f32_e32 v84, v0, v180
	v_add_f32_e32 v0, 0, v8
	v_fmac_f32_e32 v85, v0, v180
	v_add_f32_e32 v0, 0, v9
	v_fmac_f32_e32 v86, v0, v180
	v_add_f32_e32 v0, 0, v10
	s_waitcnt vmcnt(22)
	v_fmac_f32_e32 v20, v0, v180
	v_add_f32_e32 v0, 0, v11
	s_waitcnt vmcnt(20)
	v_fmac_f32_e32 v64, v0, v180
	global_store_dword v[40:41], v82, off
	global_store_dword v[30:31], v83, off
	global_store_dword v[76:77], v84, off
	global_store_dword v[32:33], v85, off
	global_store_dword v[78:79], v86, off
	global_store_dword v[80:81], v20, off
	global_store_dword v[34:35], v64, off
	s_cbranch_scc0 .LBB0_1018

.Lg13_loop:
	s_waitcnt vmcnt(8)
	s_barrier
	ds_read_b128 v[64:67], v252 offset:0
	ds_read_b128 v[104:107], v254 offset:32768
	ds_read_b128 v[108:111], v254 offset:34816
	ds_read_b128 v[112:115], v254 offset:36864
	ds_read_b128 v[116:119], v254 offset:38912
	ds_read_b128 v[68:71], v252 offset:2048
	ds_read_b128 v[72:75], v252 offset:4096
	ds_read_b128 v[76:79], v252 offset:6144
	ds_read_b128 v[80:83], v253 offset:0
	ds_read_b128 v[120:123], v255 offset:32768
	ds_read_b128 v[124:127], v255 offset:34816
	ds_read_b128 v[132:135], v255 offset:36864
	ds_read_b128 v[136:139], v255 offset:38912
	s_waitcnt lgkmcnt(11)
	v_mfma_f32_16x16x32_bf16 v[60:63], v[64:67], v[104:107], v[60:63]
	s_waitcnt lgkmcnt(10)
	v_mfma_f32_16x16x32_bf16 v[40:43], v[64:67], v[108:111], v[40:43]
	s_waitcnt lgkmcnt(9)
	v_mfma_f32_16x16x32_bf16 v[24:27], v[64:67], v[112:115], v[24:27]
	s_waitcnt lgkmcnt(8)
	v_mfma_f32_16x16x32_bf16 v[8:11], v[64:67], v[116:119], v[8:11]
	ds_read_b128 v[84:87], v253 offset:2048
	ds_read_b128 v[88:91], v253 offset:4096
	ds_read_b128 v[92:95], v253 offset:6144
	s_waitcnt lgkmcnt(10)
	v_mfma_f32_16x16x32_bf16 v[56:59], v[68:71], v[104:107], v[56:59]
	v_mfma_f32_16x16x32_bf16 v[36:39], v[68:71], v[108:111], v[36:39]
	v_mfma_f32_16x16x32_bf16 v[20:23], v[68:71], v[112:115], v[20:23]
	v_mfma_f32_16x16x32_bf16 v[0:3], v[68:71], v[116:119], v[0:3]
	s_waitcnt lgkmcnt(9)
	v_mfma_f32_16x16x32_bf16 v[48:51], v[72:75], v[104:107], v[48:51]
	v_mfma_f32_16x16x32_bf16 v[32:35], v[72:75], v[108:111], v[32:35]
	v_mfma_f32_16x16x32_bf16 v[16:19], v[72:75], v[112:115], v[16:19]
	v_mfma_f32_16x16x32_bf16 v[4:7], v[72:75], v[116:119], v[4:7]
	s_waitcnt lgkmcnt(8)
	v_mfma_f32_16x16x32_bf16 v[52:55], v[76:79], v[104:107], v[52:55]
	v_mfma_f32_16x16x32_bf16 v[44:47], v[76:79], v[108:111], v[44:47]
	v_mfma_f32_16x16x32_bf16 v[28:31], v[76:79], v[112:115], v[28:31]
	v_mfma_f32_16x16x32_bf16 v[12:15], v[76:79], v[116:119], v[12:15]
	s_waitcnt lgkmcnt(0)
	s_barrier
	s_add_u32 m0, s5, 0x0
	v_mfma_f32_16x16x32_bf16 v[60:63], v[80:83], v[120:123], v[60:63]
	global_load_lds_dwordx4 v248, s[44:45]
	v_mfma_f32_16x16x32_bf16 v[40:43], v[80:83], v[124:127], v[40:43]
	s_add_u32 m0, s5, 0x400
	v_mfma_f32_16x16x32_bf16 v[24:27], v[80:83], v[132:135], v[24:27]
	global_load_lds_dwordx4 v249, s[44:45]
	v_mfma_f32_16x16x32_bf16 v[8:11], v[80:83], v[136:139], v[8:11]
	s_add_u32 m0, s5, 0x800
	v_mfma_f32_16x16x32_bf16 v[56:59], v[84:87], v[120:123], v[56:59]
	global_load_lds_dwordx4 v250, s[44:45]
	v_mfma_f32_16x16x32_bf16 v[36:39], v[84:87], v[124:127], v[36:39]
	s_add_u32 m0, s5, 0xc00
	v_mfma_f32_16x16x32_bf16 v[20:23], v[84:87], v[132:135], v[20:23]
	global_load_lds_dwordx4 v251, s[44:45]
	v_mfma_f32_16x16x32_bf16 v[0:3], v[84:87], v[136:139], v[0:3]
	s_add_u32 m0, s5, 0x8000
	v_mfma_f32_16x16x32_bf16 v[48:51], v[88:91], v[120:123], v[48:51]
	global_load_lds_dwordx4 v248, s[48:49]
	v_mfma_f32_16x16x32_bf16 v[32:35], v[88:91], v[124:127], v[32:35]
	s_add_u32 m0, s5, 0x8400
	v_mfma_f32_16x16x32_bf16 v[16:19], v[88:91], v[132:135], v[16:19]
	global_load_lds_dwordx4 v249, s[48:49]
	v_mfma_f32_16x16x32_bf16 v[4:7], v[88:91], v[136:139], v[4:7]
	s_add_u32 m0, s5, 0x8800
	v_mfma_f32_16x16x32_bf16 v[52:55], v[92:95], v[120:123], v[52:55]
	global_load_lds_dwordx4 v250, s[48:49]
	v_mfma_f32_16x16x32_bf16 v[44:47], v[92:95], v[124:127], v[44:47]
	s_add_u32 m0, s5, 0x8c00
	v_mfma_f32_16x16x32_bf16 v[28:31], v[92:95], v[132:135], v[28:31]
	global_load_lds_dwordx4 v251, s[48:49]
	v_mfma_f32_16x16x32_bf16 v[12:15], v[92:95], v[136:139], v[12:15]
	s_add_u32 s44, s44, 0x80
	s_addc_u32 s45, s45, 0
	s_add_u32 s48, s48, 0x80
	s_addc_u32 s49, s49, 0
	s_waitcnt vmcnt(8)
	s_barrier
	ds_read_b128 v[64:67], v252 offset:16384
	ds_read_b128 v[104:107], v254 offset:49152
	ds_read_b128 v[108:111], v254 offset:51200
	ds_read_b128 v[112:115], v254 offset:53248
	ds_read_b128 v[116:119], v254 offset:55296
	ds_read_b128 v[68:71], v252 offset:18432
	ds_read_b128 v[72:75], v252 offset:20480
	ds_read_b128 v[76:79], v252 offset:22528
	ds_read_b128 v[80:83], v253 offset:16384
	ds_read_b128 v[120:123], v255 offset:49152
	ds_read_b128 v[124:127], v255 offset:51200
	ds_read_b128 v[132:135], v255 offset:53248
	ds_read_b128 v[136:139], v255 offset:55296
	s_waitcnt lgkmcnt(11)
	v_mfma_f32_16x16x32_bf16 v[60:63], v[64:67], v[104:107], v[60:63]
	s_waitcnt lgkmcnt(10)
	v_mfma_f32_16x16x32_bf16 v[40:43], v[64:67], v[108:111], v[40:43]
	s_waitcnt lgkmcnt(9)
	v_mfma_f32_16x16x32_bf16 v[24:27], v[64:67], v[112:115], v[24:27]
	s_waitcnt lgkmcnt(8)
	v_mfma_f32_16x16x32_bf16 v[8:11], v[64:67], v[116:119], v[8:11]
	ds_read_b128 v[84:87], v253 offset:18432
	ds_read_b128 v[88:91], v253 offset:20480
	ds_read_b128 v[92:95], v253 offset:22528
	s_waitcnt lgkmcnt(10)
	v_mfma_f32_16x16x32_bf16 v[56:59], v[68:71], v[104:107], v[56:59]
	v_mfma_f32_16x16x32_bf16 v[36:39], v[68:71], v[108:111], v[36:39]
	v_mfma_f32_16x16x32_bf16 v[20:23], v[68:71], v[112:115], v[20:23]
	v_mfma_f32_16x16x32_bf16 v[0:3], v[68:71], v[116:119], v[0:3]
	s_waitcnt lgkmcnt(9)
	v_mfma_f32_16x16x32_bf16 v[48:51], v[72:75], v[104:107], v[48:51]
	v_mfma_f32_16x16x32_bf16 v[32:35], v[72:75], v[108:111], v[32:35]
	v_mfma_f32_16x16x32_bf16 v[16:19], v[72:75], v[112:115], v[16:19]
	v_mfma_f32_16x16x32_bf16 v[4:7], v[72:75], v[116:119], v[4:7]
	s_waitcnt lgkmcnt(8)
	v_mfma_f32_16x16x32_bf16 v[52:55], v[76:79], v[104:107], v[52:55]
	v_mfma_f32_16x16x32_bf16 v[44:47], v[76:79], v[108:111], v[44:47]
	v_mfma_f32_16x16x32_bf16 v[28:31], v[76:79], v[112:115], v[28:31]
	v_mfma_f32_16x16x32_bf16 v[12:15], v[76:79], v[116:119], v[12:15]
	s_waitcnt lgkmcnt(0)
	s_barrier
	s_add_u32 m0, s5, 0x4000
	v_mfma_f32_16x16x32_bf16 v[60:63], v[80:83], v[120:123], v[60:63]
	global_load_lds_dwordx4 v248, s[44:45]
	v_mfma_f32_16x16x32_bf16 v[40:43], v[80:83], v[124:127], v[40:43]
	s_add_u32 m0, s5, 0x4400
	v_mfma_f32_16x16x32_bf16 v[24:27], v[80:83], v[132:135], v[24:27]
	global_load_lds_dwordx4 v249, s[44:45]
	v_mfma_f32_16x16x32_bf16 v[8:11], v[80:83], v[136:139], v[8:11]
	s_add_u32 m0, s5, 0x4800
	v_mfma_f32_16x16x32_bf16 v[56:59], v[84:87], v[120:123], v[56:59]
	global_load_lds_dwordx4 v250, s[44:45]
	v_mfma_f32_16x16x32_bf16 v[36:39], v[84:87], v[124:127], v[36:39]
	s_add_u32 m0, s5, 0x4c00
	v_mfma_f32_16x16x32_bf16 v[20:23], v[84:87], v[132:135], v[20:23]
	global_load_lds_dwordx4 v251, s[44:45]
	v_mfma_f32_16x16x32_bf16 v[0:3], v[84:87], v[136:139], v[0:3]
	s_add_u32 m0, s5, 0xc000
	v_mfma_f32_16x16x32_bf16 v[48:51], v[88:91], v[120:123], v[48:51]
	global_load_lds_dwordx4 v248, s[48:49]
	v_mfma_f32_16x16x32_bf16 v[32:35], v[88:91], v[124:127], v[32:35]
	s_add_u32 m0, s5, 0xc400
	v_mfma_f32_16x16x32_bf16 v[16:19], v[88:91], v[132:135], v[16:19]
	global_load_lds_dwordx4 v249, s[48:49]
	v_mfma_f32_16x16x32_bf16 v[4:7], v[88:91], v[136:139], v[4:7]
	s_add_u32 m0, s5, 0xc800
	v_mfma_f32_16x16x32_bf16 v[52:55], v[92:95], v[120:123], v[52:55]
	global_load_lds_dwordx4 v250, s[48:49]
	v_mfma_f32_16x16x32_bf16 v[44:47], v[92:95], v[124:127], v[44:47]
	s_add_u32 m0, s5, 0xcc00
	v_mfma_f32_16x16x32_bf16 v[28:31], v[92:95], v[132:135], v[28:31]
	global_load_lds_dwordx4 v251, s[48:49]
	v_mfma_f32_16x16x32_bf16 v[12:15], v[92:95], v[136:139], v[12:15]
	s_add_u32 s44, s44, 0x80
	s_addc_u32 s45, s45, 0
	s_add_u32 s48, s48, 0x80
	s_addc_u32 s49, s49, 0
	s_sub_u32 s12, s12, 1
	s_cmp_lg_u32 s12, 0
	s_cbranch_scc1 .Lg13_loop
	s_waitcnt vmcnt(8)
	s_barrier
	ds_read_b128 v[64:67], v252 offset:0
	ds_read_b128 v[104:107], v254 offset:32768
	ds_read_b128 v[108:111], v254 offset:34816
	ds_read_b128 v[112:115], v254 offset:36864
	ds_read_b128 v[116:119], v254 offset:38912
	ds_read_b128 v[68:71], v252 offset:2048
	ds_read_b128 v[72:75], v252 offset:4096
	ds_read_b128 v[76:79], v252 offset:6144
	ds_read_b128 v[80:83], v253 offset:0
	ds_read_b128 v[120:123], v255 offset:32768
	ds_read_b128 v[124:127], v255 offset:34816
	ds_read_b128 v[132:135], v255 offset:36864
	ds_read_b128 v[136:139], v255 offset:38912
	s_waitcnt lgkmcnt(11)
	v_mfma_f32_16x16x32_bf16 v[60:63], v[64:67], v[104:107], v[60:63]
	s_waitcnt lgkmcnt(10)
	v_mfma_f32_16x16x32_bf16 v[40:43], v[64:67], v[108:111], v[40:43]
	s_waitcnt lgkmcnt(9)
	v_mfma_f32_16x16x32_bf16 v[24:27], v[64:67], v[112:115], v[24:27]
	s_waitcnt lgkmcnt(8)
	v_mfma_f32_16x16x32_bf16 v[8:11], v[64:67], v[116:119], v[8:11]
	ds_read_b128 v[84:87], v253 offset:2048
	ds_read_b128 v[88:91], v253 offset:4096
	ds_read_b128 v[92:95], v253 offset:6144
	s_waitcnt lgkmcnt(10)
	v_mfma_f32_16x16x32_bf16 v[56:59], v[68:71], v[104:107], v[56:59]
	v_mfma_f32_16x16x32_bf16 v[36:39], v[68:71], v[108:111], v[36:39]
	v_mfma_f32_16x16x32_bf16 v[20:23], v[68:71], v[112:115], v[20:23]
	v_mfma_f32_16x16x32_bf16 v[0:3], v[68:71], v[116:119], v[0:3]
	s_waitcnt lgkmcnt(9)
	v_mfma_f32_16x16x32_bf16 v[48:51], v[72:75], v[104:107], v[48:51]
	v_mfma_f32_16x16x32_bf16 v[32:35], v[72:75], v[108:111], v[32:35]
	v_mfma_f32_16x16x32_bf16 v[16:19], v[72:75], v[112:115], v[16:19]
	v_mfma_f32_16x16x32_bf16 v[4:7], v[72:75], v[116:119], v[4:7]
	s_waitcnt lgkmcnt(8)
	v_mfma_f32_16x16x32_bf16 v[52:55], v[76:79], v[104:107], v[52:55]
	v_mfma_f32_16x16x32_bf16 v[44:47], v[76:79], v[108:111], v[44:47]
	v_mfma_f32_16x16x32_bf16 v[28:31], v[76:79], v[112:115], v[28:31]
	v_mfma_f32_16x16x32_bf16 v[12:15], v[76:79], v[116:119], v[12:15]
	s_waitcnt lgkmcnt(0)
	s_barrier
	v_mfma_f32_16x16x32_bf16 v[60:63], v[80:83], v[120:123], v[60:63]
	v_mfma_f32_16x16x32_bf16 v[40:43], v[80:83], v[124:127], v[40:43]
	v_mfma_f32_16x16x32_bf16 v[24:27], v[80:83], v[132:135], v[24:27]
	v_mfma_f32_16x16x32_bf16 v[8:11], v[80:83], v[136:139], v[8:11]
	v_mfma_f32_16x16x32_bf16 v[56:59], v[84:87], v[120:123], v[56:59]
	v_mfma_f32_16x16x32_bf16 v[36:39], v[84:87], v[124:127], v[36:39]
	v_mfma_f32_16x16x32_bf16 v[20:23], v[84:87], v[132:135], v[20:23]
	v_mfma_f32_16x16x32_bf16 v[0:3], v[84:87], v[136:139], v[0:3]
	v_mfma_f32_16x16x32_bf16 v[48:51], v[88:91], v[120:123], v[48:51]
	v_mfma_f32_16x16x32_bf16 v[32:35], v[88:91], v[124:127], v[32:35]
	v_mfma_f32_16x16x32_bf16 v[16:19], v[88:91], v[132:135], v[16:19]
	v_mfma_f32_16x16x32_bf16 v[4:7], v[88:91], v[136:139], v[4:7]
	v_mfma_f32_16x16x32_bf16 v[52:55], v[92:95], v[120:123], v[52:55]
	v_mfma_f32_16x16x32_bf16 v[44:47], v[92:95], v[124:127], v[44:47]
	v_mfma_f32_16x16x32_bf16 v[28:31], v[92:95], v[132:135], v[28:31]
	v_mfma_f32_16x16x32_bf16 v[12:15], v[92:95], v[136:139], v[12:15]
	s_waitcnt vmcnt(0)
	s_barrier
	ds_read_b128 v[64:67], v252 offset:16384
	ds_read_b128 v[104:107], v254 offset:49152
	ds_read_b128 v[108:111], v254 offset:51200
	ds_read_b128 v[112:115], v254 offset:53248
	ds_read_b128 v[116:119], v254 offset:55296
	ds_read_b128 v[68:71], v252 offset:18432
	ds_read_b128 v[72:75], v252 offset:20480
	ds_read_b128 v[76:79], v252 offset:22528
	ds_read_b128 v[80:83], v253 offset:16384
	ds_read_b128 v[120:123], v255 offset:49152
	ds_read_b128 v[124:127], v255 offset:51200
	ds_read_b128 v[132:135], v255 offset:53248
	ds_read_b128 v[136:139], v255 offset:55296
	s_waitcnt lgkmcnt(11)
	v_mfma_f32_16x16x32_bf16 v[60:63], v[64:67], v[104:107], v[60:63]
	s_waitcnt lgkmcnt(10)
	v_mfma_f32_16x16x32_bf16 v[40:43], v[64:67], v[108:111], v[40:43]
	s_waitcnt lgkmcnt(9)
	v_mfma_f32_16x16x32_bf16 v[24:27], v[64:67], v[112:115], v[24:27]
	s_waitcnt lgkmcnt(8)
	v_mfma_f32_16x16x32_bf16 v[8:11], v[64:67], v[116:119], v[8:11]
	ds_read_b128 v[84:87], v253 offset:18432
	ds_read_b128 v[88:91], v253 offset:20480
	ds_read_b128 v[92:95], v253 offset:22528
	s_waitcnt lgkmcnt(10)
	v_mfma_f32_16x16x32_bf16 v[56:59], v[68:71], v[104:107], v[56:59]
	v_mfma_f32_16x16x32_bf16 v[36:39], v[68:71], v[108:111], v[36:39]
	v_mfma_f32_16x16x32_bf16 v[20:23], v[68:71], v[112:115], v[20:23]
	v_mfma_f32_16x16x32_bf16 v[0:3], v[68:71], v[116:119], v[0:3]
	s_waitcnt lgkmcnt(9)
	v_mfma_f32_16x16x32_bf16 v[48:51], v[72:75], v[104:107], v[48:51]
	v_mfma_f32_16x16x32_bf16 v[32:35], v[72:75], v[108:111], v[32:35]
	v_mfma_f32_16x16x32_bf16 v[16:19], v[72:75], v[112:115], v[16:19]
	v_mfma_f32_16x16x32_bf16 v[4:7], v[72:75], v[116:119], v[4:7]
	s_waitcnt lgkmcnt(8)
	v_mfma_f32_16x16x32_bf16 v[52:55], v[76:79], v[104:107], v[52:55]
	v_mfma_f32_16x16x32_bf16 v[44:47], v[76:79], v[108:111], v[44:47]
	v_mfma_f32_16x16x32_bf16 v[28:31], v[76:79], v[112:115], v[28:31]
	v_mfma_f32_16x16x32_bf16 v[12:15], v[76:79], v[116:119], v[12:15]
	s_waitcnt lgkmcnt(0)
	s_barrier
	v_mfma_f32_16x16x32_bf16 v[60:63], v[80:83], v[120:123], v[60:63]
	v_mfma_f32_16x16x32_bf16 v[40:43], v[80:83], v[124:127], v[40:43]
	v_mfma_f32_16x16x32_bf16 v[24:27], v[80:83], v[132:135], v[24:27]
	v_mfma_f32_16x16x32_bf16 v[8:11], v[80:83], v[136:139], v[8:11]
	v_mfma_f32_16x16x32_bf16 v[56:59], v[84:87], v[120:123], v[56:59]
	v_mfma_f32_16x16x32_bf16 v[36:39], v[84:87], v[124:127], v[36:39]
	v_mfma_f32_16x16x32_bf16 v[20:23], v[84:87], v[132:135], v[20:23]
	v_mfma_f32_16x16x32_bf16 v[0:3], v[84:87], v[136:139], v[0:3]
	v_mfma_f32_16x16x32_bf16 v[48:51], v[88:91], v[120:123], v[48:51]
	v_mfma_f32_16x16x32_bf16 v[32:35], v[88:91], v[124:127], v[32:35]
	v_mfma_f32_16x16x32_bf16 v[16:19], v[88:91], v[132:135], v[16:19]
	v_mfma_f32_16x16x32_bf16 v[4:7], v[88:91], v[136:139], v[4:7]
	v_mfma_f32_16x16x32_bf16 v[52:55], v[92:95], v[120:123], v[52:55]
	v_mfma_f32_16x16x32_bf16 v[44:47], v[92:95], v[124:127], v[44:47]
	v_mfma_f32_16x16x32_bf16 v[28:31], v[92:95], v[132:135], v[28:31]
	v_mfma_f32_16x16x32_bf16 v[12:15], v[92:95], v[136:139], v[12:15]
	s_nop 7
	s_nop 1
	v_sub_co_u32_e32 v64, vcc, s43, v142
	s_nop 0
	v_readfirstlane_b32 s5, v64
	s_lshr_b32 s5, s5, 10
	s_add_i32 s5, s5, 1
	s_and_b64 s[44:45], vcc, exec
	s_cselect_b32 s5, 0, s5
	s_mul_hi_u32 s12, s5, 0x6000
	s_mulk_i32 s5, 0x6000
	s_add_u32 s44, s2, s5
	v_or_b32_e32 v64, s4, v140
	s_addc_u32 s45, s3, s12
	v_ashrrev_i32_e32 v65, 31, v64
	v_lshl_add_u64 v[66:67], v[64:65], 2, s[44:45]
	global_load_dword v107, v[66:67], off
	s_waitcnt vmcnt(7)
	v_cndmask_b32_e64 v68, 0, 1, s[10:11]
	v_mov_b32_e32 v106, 0
	v_cmp_ne_u32_e64 s[4:5], 1, v68
	s_andn2_b64 vcc, exec, s[10:11]
	v_lshl_add_u64 v[68:69], v[64:65], 2, s[6:7]
	v_mov_b32_e32 v108, 0
	s_cbranch_vccnz .LBB0_1268
	global_load_dword v108, v[68:69], off

.LBB0_1581:
	s_and_b32 s8, s68, 0xffffff80
	s_ashr_i32 s9, s8, 31
	s_lshl_b32 s7, s70, 11
	s_lshl_b64 s[8:9], s[8:9], 11
	s_and_b32 s22, s7, 0xfc0000
	s_add_i32 s2, s2, s3
	s_cmpk_gt_i32 s2, 0xc3f
	s_cselect_b64 s[62:63], -1, 0
	s_lshl_b32 s7, s2, 18
	s_and_b32 s7, s7, 0xfc0000
	s_add_u32 s7, s18, s7
	v_lshl_add_u64 v[126:127], v[114:115], 0, s[8:9]
	s_addc_u32 s10, s19, 0
	s_ashr_i32 s8, s2, 6
	s_ashr_i32 s9, s8, 31
	s_lshl_b64 s[8:9], s[8:9], 18
	v_lshl_add_u64 v[130:131], v[116:117], 0, s[22:23]
	s_add_u32 s22, s20, s8
	s_addc_u32 s11, s21, s9
	s_cmpk_lt_i32 s2, 0xc40
	s_cselect_b64 vcc, -1, 0
	s_and_b64 s[8:9], vcc, exec
	s_cselect_b32 s9, s10, 0
	s_cselect_b32 s8, s7, 0
	v_lshl_add_u64 v[2:3], s[8:9], 0, v[118:119]
	v_lshl_add_u64 v[0:1], v[122:123], 0, s[46:47]
	s_cselect_b32 s11, s11, 0
	s_cselect_b32 s10, s22, 0
	v_lshl_add_u64 v[2:3], v[2:3], 0, v[120:121]
	v_cndmask_b32_e32 v97, v1, v3, vcc
	v_cndmask_b32_e32 v98, v0, v2, vcc
	v_lshl_add_u64 v[0:1], s[10:11], 0, v[118:119]
	v_lshl_add_u64 v[0:1], v[0:1], 0, v[120:121]
	v_lshl_add_u64 v[2:3], v[124:125], 0, s[46:47]
	v_cndmask_b32_e32 v144, v2, v0, vcc
	v_mov_b32_e32 v0, 0
	v_lshl_add_u64 v[146:147], v[122:123], 0, s[30:31]
	v_lshl_add_u64 v[132:133], v[122:123], 0, s[34:35]
	v_lshl_add_u64 v[150:151], v[122:123], 0, s[36:37]
	v_lshl_add_u64 v[134:135], v[122:123], 0, s[38:39]
	v_lshl_add_u64 v[152:153], v[122:123], 0, s[40:41]
	v_lshl_add_u64 v[136:137], v[122:123], 0, s[42:43]
	v_lshl_add_u64 v[154:155], v[122:123], 0, s[44:45]
	v_lshl_add_u64 v[148:149], v[124:125], 0, s[30:31]
	v_lshl_add_u64 v[138:139], v[124:125], 0, s[34:35]
	v_lshl_add_u64 v[156:157], v[124:125], 0, s[36:37]
	v_lshl_add_u64 v[140:141], v[124:125], 0, s[38:39]
	v_lshl_add_u64 v[158:159], v[124:125], 0, s[40:41]
	v_lshl_add_u64 v[142:143], v[124:125], 0, s[42:43]
	v_lshl_add_u64 v[160:161], v[124:125], 0, s[44:45]
	v_cndmask_b32_e32 v129, v3, v1, vcc
	s_mov_b32 s7, -2
	v_mov_b32_e32 v1, v0
	v_mov_b32_e32 v2, v0
	v_mov_b32_e32 v3, v0
	v_mov_b32_e32 v20, v0
	v_mov_b32_e32 v21, v0
	v_mov_b32_e32 v22, v0
	v_mov_b32_e32 v23, v0
	v_mov_b32_e32 v24, v0
	v_mov_b32_e32 v25, v0
	v_mov_b32_e32 v26, v0
	v_mov_b32_e32 v27, v0
	v_mov_b32_e32 v32, v0
	v_mov_b32_e32 v33, v0
	v_mov_b32_e32 v34, v0
	v_mov_b32_e32 v35, v0
	v_mov_b32_e32 v8, v0
	v_mov_b32_e32 v9, v0
	v_mov_b32_e32 v10, v0
	v_mov_b32_e32 v11, v0
	v_mov_b32_e32 v4, v0
	v_mov_b32_e32 v5, v0
	v_mov_b32_e32 v6, v0
	v_mov_b32_e32 v7, v0
	v_mov_b32_e32 v12, v0
	v_mov_b32_e32 v13, v0
	v_mov_b32_e32 v14, v0
	v_mov_b32_e32 v15, v0
	v_mov_b32_e32 v16, v0
	v_mov_b32_e32 v17, v0
	v_mov_b32_e32 v18, v0
	v_mov_b32_e32 v19, v0
	v_mov_b32_e32 v28, v0
	v_mov_b32_e32 v29, v0
	v_mov_b32_e32 v30, v0
	v_mov_b32_e32 v31, v0
	v_mov_b32_e32 v36, v0
	v_mov_b32_e32 v37, v0
	v_mov_b32_e32 v38, v0
	v_mov_b32_e32 v39, v0
	v_mov_b32_e32 v40, v0
	v_mov_b32_e32 v41, v0
	v_mov_b32_e32 v42, v0
	v_mov_b32_e32 v43, v0
	v_mov_b32_e32 v44, v0
	v_mov_b32_e32 v45, v0
	v_mov_b32_e32 v46, v0
	v_mov_b32_e32 v47, v0
	v_mov_b32_e32 v48, v0
	v_mov_b32_e32 v49, v0
	v_mov_b32_e32 v50, v0
	v_mov_b32_e32 v51, v0
	v_mov_b32_e32 v52, v0
	v_mov_b32_e32 v53, v0
	v_mov_b32_e32 v54, v0
	v_mov_b32_e32 v55, v0
	v_mov_b32_e32 v56, v0
	v_mov_b32_e32 v57, v0
	v_mov_b32_e32 v58, v0
	v_mov_b32_e32 v59, v0
	v_mov_b32_e32 v60, v0
	v_mov_b32_e32 v61, v0
	v_mov_b32_e32 v62, v0
	v_mov_b32_e32 v63, v0
	v_readfirstlane_b32 s8, v122
	v_readfirstlane_b32 s9, v123
	v_readfirstlane_b32 s64, v124
	v_readfirstlane_b32 s65, v125
	v_readfirstlane_b32 s7, v247
	s_nop 3
	s_mul_i32 s66, s7, 0x4000
	s_sub_u32 s8, s8, s66
	s_subb_u32 s9, s9, 0
	s_sub_u32 s64, s64, s66
	s_subb_u32 s65, s65, 0
	s_lshl_b32 s7, s7, 12
	s_sub_u32 s66, s2, s3
	s_cmp_eq_u32 s66, s58
	s_cbranch_scc1 .Lg18_first
	v_mov_b32_e32 v60, 0
	v_mov_b32_e32 v61, 0
	v_mov_b32_e32 v62, 0
	v_mov_b32_e32 v63, 0
	v_mov_b32_e32 v56, 0
	v_mov_b32_e32 v57, 0
	v_mov_b32_e32 v58, 0
	v_mov_b32_e32 v59, 0
	v_mov_b32_e32 v52, 0
	v_mov_b32_e32 v53, 0
	v_mov_b32_e32 v54, 0
	v_mov_b32_e32 v55, 0
	v_mov_b32_e32 v48, 0
	v_mov_b32_e32 v49, 0
	v_mov_b32_e32 v50, 0
	v_mov_b32_e32 v51, 0
	v_mov_b32_e32 v44, 0
	v_mov_b32_e32 v45, 0
	v_mov_b32_e32 v46, 0
	v_mov_b32_e32 v47, 0
	v_mov_b32_e32 v40, 0
	v_mov_b32_e32 v41, 0
	v_mov_b32_e32 v42, 0
	v_mov_b32_e32 v43, 0
	v_mov_b32_e32 v36, 0
	v_mov_b32_e32 v37, 0
	v_mov_b32_e32 v38, 0
	v_mov_b32_e32 v39, 0
	v_mov_b32_e32 v28, 0
	v_mov_b32_e32 v29, 0
	v_mov_b32_e32 v30, 0
	v_mov_b32_e32 v31, 0
	v_mov_b32_e32 v16, 0
	v_mov_b32_e32 v17, 0
	v_mov_b32_e32 v18, 0
	v_mov_b32_e32 v19, 0
	v_mov_b32_e32 v12, 0
	v_mov_b32_e32 v13, 0
	v_mov_b32_e32 v14, 0
	v_mov_b32_e32 v15, 0
	v_mov_b32_e32 v4, 0
	v_mov_b32_e32 v5, 0
	v_mov_b32_e32 v6, 0
	v_mov_b32_e32 v7, 0
	v_mov_b32_e32 v8, 0
	v_mov_b32_e32 v9, 0
	v_mov_b32_e32 v10, 0
	v_mov_b32_e32 v11, 0
	v_mov_b32_e32 v32, 0
	v_mov_b32_e32 v33, 0
	v_mov_b32_e32 v34, 0
	v_mov_b32_e32 v35, 0
	v_mov_b32_e32 v24, 0
	v_mov_b32_e32 v25, 0
	v_mov_b32_e32 v26, 0
	v_mov_b32_e32 v27, 0
	v_mov_b32_e32 v20, 0
	v_mov_b32_e32 v21, 0
	v_mov_b32_e32 v22, 0
	v_mov_b32_e32 v23, 0
	v_mov_b32_e32 v0, 0
	v_mov_b32_e32 v1, 0
	v_mov_b32_e32 v2, 0
	v_mov_b32_e32 v3, 0
	s_add_u32 s8, s8, 0x100
	s_addc_u32 s9, s9, 0
	s_add_u32 s64, s64, 0x100
	s_addc_u32 s65, s65, 0
	s_waitcnt vmcnt(8)
	s_barrier
	ds_read_b128 v[80:83], v252 offset:0
	ds_read_b128 v[144:147], v254 offset:32768
	ds_read_b128 v[148:151], v254 offset:34816
	ds_read_b128 v[152:155], v254 offset:36864
	ds_read_b128 v[156:159], v254 offset:38912
	ds_read_b128 v[84:87], v252 offset:2048
	ds_read_b128 v[88:91], v252 offset:4096
	ds_read_b128 v[92:95], v252 offset:6144
	ds_read_b128 v[124:127], v253 offset:0
	ds_read_b128 v[180:183], v255 offset:32768
	ds_read_b128 v[184:187], v255 offset:34816
	ds_read_b128 v[188:191], v255 offset:36864
	ds_read_b128 v[192:195], v255 offset:38912
	s_waitcnt lgkmcnt(11)
	v_mfma_f32_16x16x32_bf16 v[60:63], v[80:83], v[144:147], v[60:63]
	s_waitcnt lgkmcnt(10)
	v_mfma_f32_16x16x32_bf16 v[56:59], v[80:83], v[148:151], v[56:59]
	s_waitcnt lgkmcnt(9)
	v_mfma_f32_16x16x32_bf16 v[52:55], v[80:83], v[152:155], v[52:55]
	s_waitcnt lgkmcnt(8)
	v_mfma_f32_16x16x32_bf16 v[48:51], v[80:83], v[156:159], v[48:51]
	ds_read_b128 v[132:135], v253 offset:2048
	ds_read_b128 v[136:139], v253 offset:4096
	ds_read_b128 v[140:143], v253 offset:6144
	s_waitcnt lgkmcnt(10)
	v_mfma_f32_16x16x32_bf16 v[44:47], v[84:87], v[144:147], v[44:47]
	v_mfma_f32_16x16x32_bf16 v[40:43], v[84:87], v[148:151], v[40:43]
	v_mfma_f32_16x16x32_bf16 v[36:39], v[84:87], v[152:155], v[36:39]
	v_mfma_f32_16x16x32_bf16 v[28:31], v[84:87], v[156:159], v[28:31]
	s_waitcnt lgkmcnt(9)
	v_mfma_f32_16x16x32_bf16 v[16:19], v[88:91], v[144:147], v[16:19]
	v_mfma_f32_16x16x32_bf16 v[12:15], v[88:91], v[148:151], v[12:15]
	v_mfma_f32_16x16x32_bf16 v[4:7], v[88:91], v[152:155], v[4:7]
	v_mfma_f32_16x16x32_bf16 v[8:11], v[88:91], v[156:159], v[8:11]
	s_waitcnt lgkmcnt(8)
	v_mfma_f32_16x16x32_bf16 v[32:35], v[92:95], v[144:147], v[32:35]
	v_mfma_f32_16x16x32_bf16 v[24:27], v[92:95], v[148:151], v[24:27]
	v_mfma_f32_16x16x32_bf16 v[20:23], v[92:95], v[152:155], v[20:23]
	v_mfma_f32_16x16x32_bf16 v[0:3], v[92:95], v[156:159], v[0:3]
	s_waitcnt lgkmcnt(0)
	s_barrier
	s_add_u32 m0, s7, 0x0
	v_mfma_f32_16x16x32_bf16 v[60:63], v[124:127], v[180:183], v[60:63]
	global_load_lds_dwordx4 v248, s[8:9]
	v_mfma_f32_16x16x32_bf16 v[56:59], v[124:127], v[184:187], v[56:59]
	s_add_u32 m0, s7, 0x400
	v_mfma_f32_16x16x32_bf16 v[52:55], v[124:127], v[188:191], v[52:55]
	global_load_lds_dwordx4 v249, s[8:9]
	v_mfma_f32_16x16x32_bf16 v[48:51], v[124:127], v[192:195], v[48:51]
	s_add_u32 m0, s7, 0x800
	v_mfma_f32_16x16x32_bf16 v[44:47], v[132:135], v[180:183], v[44:47]
	global_load_lds_dwordx4 v250, s[8:9]
	v_mfma_f32_16x16x32_bf16 v[40:43], v[132:135], v[184:187], v[40:43]
	s_add_u32 m0, s7, 0xc00
	v_mfma_f32_16x16x32_bf16 v[36:39], v[132:135], v[188:191], v[36:39]
	global_load_lds_dwordx4 v251, s[8:9]
	v_mfma_f32_16x16x32_bf16 v[28:31], v[132:135], v[192:195], v[28:31]
	s_add_u32 m0, s7, 0x8000
	v_mfma_f32_16x16x32_bf16 v[16:19], v[136:139], v[180:183], v[16:19]
	global_load_lds_dwordx4 v248, s[64:65]
	v_mfma_f32_16x16x32_bf16 v[12:15], v[136:139], v[184:187], v[12:15]
	s_add_u32 m0, s7, 0x8400
	v_mfma_f32_16x16x32_bf16 v[4:7], v[136:139], v[188:191], v[4:7]
	global_load_lds_dwordx4 v249, s[64:65]
	v_mfma_f32_16x16x32_bf16 v[8:11], v[136:139], v[192:195], v[8:11]
	s_add_u32 m0, s7, 0x8800
	v_mfma_f32_16x16x32_bf16 v[32:35], v[140:143], v[180:183], v[32:35]
	global_load_lds_dwordx4 v250, s[64:65]
	v_mfma_f32_16x16x32_bf16 v[24:27], v[140:143], v[184:187], v[24:27]
	s_add_u32 m0, s7, 0x8c00
	v_mfma_f32_16x16x32_bf16 v[20:23], v[140:143], v[188:191], v[20:23]
	global_load_lds_dwordx4 v251, s[64:65]
	v_mfma_f32_16x16x32_bf16 v[0:3], v[140:143], v[192:195], v[0:3]
	s_add_u32 s8, s8, 0x80
	s_addc_u32 s9, s9, 0
	s_add_u32 s64, s64, 0x80
	s_addc_u32 s65, s65, 0
	s_waitcnt vmcnt(8)
	s_barrier
	ds_read_b128 v[80:83], v252 offset:16384
	ds_read_b128 v[144:147], v254 offset:49152
	ds_read_b128 v[148:151], v254 offset:51200
	ds_read_b128 v[152:155], v254 offset:53248
	ds_read_b128 v[156:159], v254 offset:55296
	ds_read_b128 v[84:87], v252 offset:18432
	ds_read_b128 v[88:91], v252 offset:20480
	ds_read_b128 v[92:95], v252 offset:22528
	ds_read_b128 v[124:127], v253 offset:16384
	ds_read_b128 v[180:183], v255 offset:49152
	ds_read_b128 v[184:187], v255 offset:51200
	ds_read_b128 v[188:191], v255 offset:53248
	ds_read_b128 v[192:195], v255 offset:55296
	s_waitcnt lgkmcnt(11)
	v_mfma_f32_16x16x32_bf16 v[60:63], v[80:83], v[144:147], v[60:63]
	s_waitcnt lgkmcnt(10)
	v_mfma_f32_16x16x32_bf16 v[56:59], v[80:83], v[148:151], v[56:59]
	s_waitcnt lgkmcnt(9)
	v_mfma_f32_16x16x32_bf16 v[52:55], v[80:83], v[152:155], v[52:55]
	s_waitcnt lgkmcnt(8)
	v_mfma_f32_16x16x32_bf16 v[48:51], v[80:83], v[156:159], v[48:51]
	ds_read_b128 v[132:135], v253 offset:18432
	ds_read_b128 v[136:139], v253 offset:20480
	ds_read_b128 v[140:143], v253 offset:22528
	s_waitcnt lgkmcnt(10)
	v_mfma_f32_16x16x32_bf16 v[44:47], v[84:87], v[144:147], v[44:47]
	v_mfma_f32_16x16x32_bf16 v[40:43], v[84:87], v[148:151], v[40:43]
	v_mfma_f32_16x16x32_bf16 v[36:39], v[84:87], v[152:155], v[36:39]
	v_mfma_f32_16x16x32_bf16 v[28:31], v[84:87], v[156:159], v[28:31]
	s_waitcnt lgkmcnt(9)
	v_mfma_f32_16x16x32_bf16 v[16:19], v[88:91], v[144:147], v[16:19]
	v_mfma_f32_16x16x32_bf16 v[12:15], v[88:91], v[148:151], v[12:15]
	v_mfma_f32_16x16x32_bf16 v[4:7], v[88:91], v[152:155], v[4:7]
	v_mfma_f32_16x16x32_bf16 v[8:11], v[88:91], v[156:159], v[8:11]
	s_waitcnt lgkmcnt(8)
	v_mfma_f32_16x16x32_bf16 v[32:35], v[92:95], v[144:147], v[32:35]
	v_mfma_f32_16x16x32_bf16 v[24:27], v[92:95], v[148:151], v[24:27]
	v_mfma_f32_16x16x32_bf16 v[20:23], v[92:95], v[152:155], v[20:23]
	v_mfma_f32_16x16x32_bf16 v[0:3], v[92:95], v[156:159], v[0:3]
	s_waitcnt lgkmcnt(0)
	s_barrier
	s_add_u32 m0, s7, 0x4000
	v_mfma_f32_16x16x32_bf16 v[60:63], v[124:127], v[180:183], v[60:63]
	global_load_lds_dwordx4 v248, s[8:9]
	v_mfma_f32_16x16x32_bf16 v[56:59], v[124:127], v[184:187], v[56:59]
	s_add_u32 m0, s7, 0x4400
	v_mfma_f32_16x16x32_bf16 v[52:55], v[124:127], v[188:191], v[52:55]
	global_load_lds_dwordx4 v249, s[8:9]
	v_mfma_f32_16x16x32_bf16 v[48:51], v[124:127], v[192:195], v[48:51]
	s_add_u32 m0, s7, 0x4800
	v_mfma_f32_16x16x32_bf16 v[44:47], v[132:135], v[180:183], v[44:47]
	global_load_lds_dwordx4 v250, s[8:9]
	v_mfma_f32_16x16x32_bf16 v[40:43], v[132:135], v[184:187], v[40:43]
	s_add_u32 m0, s7, 0x4c00
	v_mfma_f32_16x16x32_bf16 v[36:39], v[132:135], v[188:191], v[36:39]
	global_load_lds_dwordx4 v251, s[8:9]
	v_mfma_f32_16x16x32_bf16 v[28:31], v[132:135], v[192:195], v[28:31]
	s_add_u32 m0, s7, 0xc000
	v_mfma_f32_16x16x32_bf16 v[16:19], v[136:139], v[180:183], v[16:19]
	global_load_lds_dwordx4 v248, s[64:65]
	v_mfma_f32_16x16x32_bf16 v[12:15], v[136:139], v[184:187], v[12:15]
	s_add_u32 m0, s7, 0xc400
	v_mfma_f32_16x16x32_bf16 v[4:7], v[136:139], v[188:191], v[4:7]
	global_load_lds_dwordx4 v249, s[64:65]
	v_mfma_f32_16x16x32_bf16 v[8:11], v[136:139], v[192:195], v[8:11]
	s_add_u32 m0, s7, 0xc800
	v_mfma_f32_16x16x32_bf16 v[32:35], v[140:143], v[180:183], v[32:35]
	global_load_lds_dwordx4 v250, s[64:65]
	v_mfma_f32_16x16x32_bf16 v[24:27], v[140:143], v[184:187], v[24:27]
	s_add_u32 m0, s7, 0xcc00
	v_mfma_f32_16x16x32_bf16 v[20:23], v[140:143], v[188:191], v[20:23]
	global_load_lds_dwordx4 v251, s[64:65]
	v_mfma_f32_16x16x32_bf16 v[0:3], v[140:143], v[192:195], v[0:3]
	s_add_u32 s8, s8, 0x80
	s_addc_u32 s9, s9, 0
	s_add_u32 s64, s64, 0x80
	s_addc_u32 s65, s65, 0
	s_branch .Lg18_main
.Lg18_first:
	s_add_u32 m0, s7, 0x0
	v_mov_b32_e32 v60, 0
	global_load_lds_dwordx4 v248, s[8:9]
	v_mov_b32_e32 v61, 0
	s_add_u32 m0, s7, 0x400
	v_mov_b32_e32 v62, 0
	global_load_lds_dwordx4 v249, s[8:9]
	v_mov_b32_e32 v63, 0
	s_add_u32 m0, s7, 0x800
	v_mov_b32_e32 v56, 0
	global_load_lds_dwordx4 v250, s[8:9]
	v_mov_b32_e32 v57, 0
	s_add_u32 m0, s7, 0xc00
	v_mov_b32_e32 v58, 0
	global_load_lds_dwordx4 v251, s[8:9]
	v_mov_b32_e32 v59, 0
	s_add_u32 m0, s7, 0x8000
	v_mov_b32_e32 v52, 0
	global_load_lds_dwordx4 v248, s[64:65]
	v_mov_b32_e32 v53, 0
	s_add_u32 m0, s7, 0x8400
	v_mov_b32_e32 v54, 0
	global_load_lds_dwordx4 v249, s[64:65]
	v_mov_b32_e32 v55, 0
	s_add_u32 m0, s7, 0x8800
	v_mov_b32_e32 v48, 0
	global_load_lds_dwordx4 v250, s[64:65]
	v_mov_b32_e32 v49, 0
	s_add_u32 m0, s7, 0x8c00
	v_mov_b32_e32 v50, 0
	global_load_lds_dwordx4 v251, s[64:65]
	v_mov_b32_e32 v51, 0
	s_add_u32 s8, s8, 0x80
	s_addc_u32 s9, s9, 0
	s_add_u32 s64, s64, 0x80
	s_addc_u32 s65, s65, 0
	s_add_u32 m0, s7, 0x4000
	v_mov_b32_e32 v44, 0
	global_load_lds_dwordx4 v248, s[8:9]
	v_mov_b32_e32 v45, 0
	s_add_u32 m0, s7, 0x4400
	v_mov_b32_e32 v46, 0
	global_load_lds_dwordx4 v249, s[8:9]
	v_mov_b32_e32 v47, 0
	s_add_u32 m0, s7, 0x4800
	v_mov_b32_e32 v40, 0
	global_load_lds_dwordx4 v250, s[8:9]
	v_mov_b32_e32 v41, 0
	s_add_u32 m0, s7, 0x4c00
	v_mov_b32_e32 v42, 0
	global_load_lds_dwordx4 v251, s[8:9]
	v_mov_b32_e32 v43, 0
	s_add_u32 m0, s7, 0xc000
	v_mov_b32_e32 v36, 0
	global_load_lds_dwordx4 v248, s[64:65]
	v_mov_b32_e32 v37, 0
	s_add_u32 m0, s7, 0xc400
	v_mov_b32_e32 v38, 0
	global_load_lds_dwordx4 v249, s[64:65]
	v_mov_b32_e32 v39, 0
	s_add_u32 m0, s7, 0xc800
	v_mov_b32_e32 v28, 0
	global_load_lds_dwordx4 v250, s[64:65]
	v_mov_b32_e32 v29, 0
	s_add_u32 m0, s7, 0xcc00
	v_mov_b32_e32 v30, 0
	global_load_lds_dwordx4 v251, s[64:65]
	v_mov_b32_e32 v31, 0
	s_add_u32 s8, s8, 0x80
	s_addc_u32 s9, s9, 0
	s_add_u32 s64, s64, 0x80
	s_addc_u32 s65, s65, 0
	v_mov_b32_e32 v16, 0
	v_mov_b32_e32 v17, 0
	v_mov_b32_e32 v18, 0
	v_mov_b32_e32 v19, 0
	v_mov_b32_e32 v12, 0
	v_mov_b32_e32 v13, 0
	v_mov_b32_e32 v14, 0
	v_mov_b32_e32 v15, 0
	v_mov_b32_e32 v4, 0
	v_mov_b32_e32 v5, 0
	v_mov_b32_e32 v6, 0
	v_mov_b32_e32 v7, 0
	v_mov_b32_e32 v8, 0
	v_mov_b32_e32 v9, 0
	v_mov_b32_e32 v10, 0
	v_mov_b32_e32 v11, 0
	v_mov_b32_e32 v32, 0
	v_mov_b32_e32 v33, 0
	v_mov_b32_e32 v34, 0
	v_mov_b32_e32 v35, 0
	v_mov_b32_e32 v24, 0
	v_mov_b32_e32 v25, 0
	v_mov_b32_e32 v26, 0
	v_mov_b32_e32 v27, 0
	v_mov_b32_e32 v20, 0
	v_mov_b32_e32 v21, 0
	v_mov_b32_e32 v22, 0
	v_mov_b32_e32 v23, 0
	v_mov_b32_e32 v0, 0
	v_mov_b32_e32 v1, 0
	v_mov_b32_e32 v2, 0
	v_mov_b32_e32 v3, 0
	s_waitcnt vmcnt(8)
	s_barrier
	ds_read_b128 v[80:83], v252 offset:0
	ds_read_b128 v[144:147], v254 offset:32768
	ds_read_b128 v[148:151], v254 offset:34816
	ds_read_b128 v[152:155], v254 offset:36864
	ds_read_b128 v[156:159], v254 offset:38912
	ds_read_b128 v[84:87], v252 offset:2048
	ds_read_b128 v[88:91], v252 offset:4096
	ds_read_b128 v[92:95], v252 offset:6144
	ds_read_b128 v[124:127], v253 offset:0
	ds_read_b128 v[180:183], v255 offset:32768
	ds_read_b128 v[184:187], v255 offset:34816
	ds_read_b128 v[188:191], v255 offset:36864
	ds_read_b128 v[192:195], v255 offset:38912
	s_waitcnt lgkmcnt(11)
	v_mfma_f32_16x16x32_bf16 v[60:63], v[80:83], v[144:147], v[60:63]
	s_waitcnt lgkmcnt(10)
	v_mfma_f32_16x16x32_bf16 v[56:59], v[80:83], v[148:151], v[56:59]
	s_waitcnt lgkmcnt(9)
	v_mfma_f32_16x16x32_bf16 v[52:55], v[80:83], v[152:155], v[52:55]
	s_waitcnt lgkmcnt(8)
	v_mfma_f32_16x16x32_bf16 v[48:51], v[80:83], v[156:159], v[48:51]
	ds_read_b128 v[132:135], v253 offset:2048
	ds_read_b128 v[136:139], v253 offset:4096
	ds_read_b128 v[140:143], v253 offset:6144
	s_waitcnt lgkmcnt(10)
	v_mfma_f32_16x16x32_bf16 v[44:47], v[84:87], v[144:147], v[44:47]
	v_mfma_f32_16x16x32_bf16 v[40:43], v[84:87], v[148:151], v[40:43]
	v_mfma_f32_16x16x32_bf16 v[36:39], v[84:87], v[152:155], v[36:39]
	v_mfma_f32_16x16x32_bf16 v[28:31], v[84:87], v[156:159], v[28:31]
	s_waitcnt lgkmcnt(9)
	v_mfma_f32_16x16x32_bf16 v[16:19], v[88:91], v[144:147], v[16:19]
	v_mfma_f32_16x16x32_bf16 v[12:15], v[88:91], v[148:151], v[12:15]
	v_mfma_f32_16x16x32_bf16 v[4:7], v[88:91], v[152:155], v[4:7]
	v_mfma_f32_16x16x32_bf16 v[8:11], v[88:91], v[156:159], v[8:11]
	s_waitcnt lgkmcnt(8)
	v_mfma_f32_16x16x32_bf16 v[32:35], v[92:95], v[144:147], v[32:35]
	v_mfma_f32_16x16x32_bf16 v[24:27], v[92:95], v[148:151], v[24:27]
	v_mfma_f32_16x16x32_bf16 v[20:23], v[92:95], v[152:155], v[20:23]
	v_mfma_f32_16x16x32_bf16 v[0:3], v[92:95], v[156:159], v[0:3]
	s_waitcnt lgkmcnt(0)
	s_barrier
	s_add_u32 m0, s7, 0x0
	v_mfma_f32_16x16x32_bf16 v[60:63], v[124:127], v[180:183], v[60:63]
	global_load_lds_dwordx4 v248, s[8:9]
	v_mfma_f32_16x16x32_bf16 v[56:59], v[124:127], v[184:187], v[56:59]
	s_add_u32 m0, s7, 0x400
	v_mfma_f32_16x16x32_bf16 v[52:55], v[124:127], v[188:191], v[52:55]
	global_load_lds_dwordx4 v249, s[8:9]
	v_mfma_f32_16x16x32_bf16 v[48:51], v[124:127], v[192:195], v[48:51]
	s_add_u32 m0, s7, 0x800
	v_mfma_f32_16x16x32_bf16 v[44:47], v[132:135], v[180:183], v[44:47]
	global_load_lds_dwordx4 v250, s[8:9]
	v_mfma_f32_16x16x32_bf16 v[40:43], v[132:135], v[184:187], v[40:43]
	s_add_u32 m0, s7, 0xc00
	v_mfma_f32_16x16x32_bf16 v[36:39], v[132:135], v[188:191], v[36:39]
	global_load_lds_dwordx4 v251, s[8:9]
	v_mfma_f32_16x16x32_bf16 v[28:31], v[132:135], v[192:195], v[28:31]
	s_add_u32 m0, s7, 0x8000
	v_mfma_f32_16x16x32_bf16 v[16:19], v[136:139], v[180:183], v[16:19]
	global_load_lds_dwordx4 v248, s[64:65]
	v_mfma_f32_16x16x32_bf16 v[12:15], v[136:139], v[184:187], v[12:15]
	s_add_u32 m0, s7, 0x8400
	v_mfma_f32_16x16x32_bf16 v[4:7], v[136:139], v[188:191], v[4:7]
	global_load_lds_dwordx4 v249, s[64:65]
	v_mfma_f32_16x16x32_bf16 v[8:11], v[136:139], v[192:195], v[8:11]
	s_add_u32 m0, s7, 0x8800
	v_mfma_f32_16x16x32_bf16 v[32:35], v[140:143], v[180:183], v[32:35]
	global_load_lds_dwordx4 v250, s[64:65]
	v_mfma_f32_16x16x32_bf16 v[24:27], v[140:143], v[184:187], v[24:27]
	s_add_u32 m0, s7, 0x8c00
	v_mfma_f32_16x16x32_bf16 v[20:23], v[140:143], v[188:191], v[20:23]
	global_load_lds_dwordx4 v251, s[64:65]
	v_mfma_f32_16x16x32_bf16 v[0:3], v[140:143], v[192:195], v[0:3]
	s_add_u32 s8, s8, 0x80
	s_addc_u32 s9, s9, 0
	s_add_u32 s64, s64, 0x80
	s_addc_u32 s65, s65, 0
	s_waitcnt vmcnt(8)
	s_barrier
	ds_read_b128 v[80:83], v252 offset:16384
	ds_read_b128 v[144:147], v254 offset:49152
	ds_read_b128 v[148:151], v254 offset:51200
	ds_read_b128 v[152:155], v254 offset:53248
	ds_read_b128 v[156:159], v254 offset:55296
	ds_read_b128 v[84:87], v252 offset:18432
	ds_read_b128 v[88:91], v252 offset:20480
	ds_read_b128 v[92:95], v252 offset:22528
	ds_read_b128 v[124:127], v253 offset:16384
	ds_read_b128 v[180:183], v255 offset:49152
	ds_read_b128 v[184:187], v255 offset:51200
	ds_read_b128 v[188:191], v255 offset:53248
	ds_read_b128 v[192:195], v255 offset:55296
	s_waitcnt lgkmcnt(11)
	v_mfma_f32_16x16x32_bf16 v[60:63], v[80:83], v[144:147], v[60:63]
	s_waitcnt lgkmcnt(10)
	v_mfma_f32_16x16x32_bf16 v[56:59], v[80:83], v[148:151], v[56:59]
	s_waitcnt lgkmcnt(9)
	v_mfma_f32_16x16x32_bf16 v[52:55], v[80:83], v[152:155], v[52:55]
	s_waitcnt lgkmcnt(8)
	v_mfma_f32_16x16x32_bf16 v[48:51], v[80:83], v[156:159], v[48:51]
	ds_read_b128 v[132:135], v253 offset:18432
	ds_read_b128 v[136:139], v253 offset:20480
	ds_read_b128 v[140:143], v253 offset:22528
	s_waitcnt lgkmcnt(10)
	v_mfma_f32_16x16x32_bf16 v[44:47], v[84:87], v[144:147], v[44:47]
	v_mfma_f32_16x16x32_bf16 v[40:43], v[84:87], v[148:151], v[40:43]
	v_mfma_f32_16x16x32_bf16 v[36:39], v[84:87], v[152:155], v[36:39]
	v_mfma_f32_16x16x32_bf16 v[28:31], v[84:87], v[156:159], v[28:31]
	s_waitcnt lgkmcnt(9)
	v_mfma_f32_16x16x32_bf16 v[16:19], v[88:91], v[144:147], v[16:19]
	v_mfma_f32_16x16x32_bf16 v[12:15], v[88:91], v[148:151], v[12:15]
	v_mfma_f32_16x16x32_bf16 v[4:7], v[88:91], v[152:155], v[4:7]
	v_mfma_f32_16x16x32_bf16 v[8:11], v[88:91], v[156:159], v[8:11]
	s_waitcnt lgkmcnt(8)
	v_mfma_f32_16x16x32_bf16 v[32:35], v[92:95], v[144:147], v[32:35]
	v_mfma_f32_16x16x32_bf16 v[24:27], v[92:95], v[148:151], v[24:27]
	v_mfma_f32_16x16x32_bf16 v[20:23], v[92:95], v[152:155], v[20:23]
	v_mfma_f32_16x16x32_bf16 v[0:3], v[92:95], v[156:159], v[0:3]
	s_waitcnt lgkmcnt(0)
	s_barrier
	s_add_u32 m0, s7, 0x4000
	v_mfma_f32_16x16x32_bf16 v[60:63], v[124:127], v[180:183], v[60:63]
	global_load_lds_dwordx4 v248, s[8:9]
	v_mfma_f32_16x16x32_bf16 v[56:59], v[124:127], v[184:187], v[56:59]
	s_add_u32 m0, s7, 0x4400
	v_mfma_f32_16x16x32_bf16 v[52:55], v[124:127], v[188:191], v[52:55]
	global_load_lds_dwordx4 v249, s[8:9]
	v_mfma_f32_16x16x32_bf16 v[48:51], v[124:127], v[192:195], v[48:51]
	s_add_u32 m0, s7, 0x4800
	v_mfma_f32_16x16x32_bf16 v[44:47], v[132:135], v[180:183], v[44:47]
	global_load_lds_dwordx4 v250, s[8:9]
	v_mfma_f32_16x16x32_bf16 v[40:43], v[132:135], v[184:187], v[40:43]
	s_add_u32 m0, s7, 0x4c00
	v_mfma_f32_16x16x32_bf16 v[36:39], v[132:135], v[188:191], v[36:39]
	global_load_lds_dwordx4 v251, s[8:9]
	v_mfma_f32_16x16x32_bf16 v[28:31], v[132:135], v[192:195], v[28:31]
	s_add_u32 m0, s7, 0xc000
	v_mfma_f32_16x16x32_bf16 v[16:19], v[136:139], v[180:183], v[16:19]
	global_load_lds_dwordx4 v248, s[64:65]
	v_mfma_f32_16x16x32_bf16 v[12:15], v[136:139], v[184:187], v[12:15]
	s_add_u32 m0, s7, 0xc400
	v_mfma_f32_16x16x32_bf16 v[4:7], v[136:139], v[188:191], v[4:7]
	global_load_lds_dwordx4 v249, s[64:65]
	v_mfma_f32_16x16x32_bf16 v[8:11], v[136:139], v[192:195], v[8:11]
	s_add_u32 m0, s7, 0xc800
	v_mfma_f32_16x16x32_bf16 v[32:35], v[140:143], v[180:183], v[32:35]
	global_load_lds_dwordx4 v250, s[64:65]
	v_mfma_f32_16x16x32_bf16 v[24:27], v[140:143], v[184:187], v[24:27]
	s_add_u32 m0, s7, 0xcc00
	v_mfma_f32_16x16x32_bf16 v[20:23], v[140:143], v[188:191], v[20:23]
	global_load_lds_dwordx4 v251, s[64:65]
	v_mfma_f32_16x16x32_bf16 v[0:3], v[140:143], v[192:195], v[0:3]
	s_add_u32 s8, s8, 0x80
	s_addc_u32 s9, s9, 0
	s_add_u32 s64, s64, 0x80
	s_addc_u32 s65, s65, 0

.Lg18_loop:
	s_waitcnt vmcnt(8)
	s_barrier
	ds_read_b128 v[80:83], v252 offset:0
	ds_read_b128 v[144:147], v254 offset:32768
	ds_read_b128 v[148:151], v254 offset:34816
	ds_read_b128 v[152:155], v254 offset:36864
	ds_read_b128 v[156:159], v254 offset:38912
	ds_read_b128 v[84:87], v252 offset:2048
	ds_read_b128 v[88:91], v252 offset:4096
	ds_read_b128 v[92:95], v252 offset:6144
	ds_read_b128 v[124:127], v253 offset:0
	ds_read_b128 v[180:183], v255 offset:32768
	ds_read_b128 v[184:187], v255 offset:34816
	ds_read_b128 v[188:191], v255 offset:36864
	ds_read_b128 v[192:195], v255 offset:38912
	s_waitcnt lgkmcnt(11)
	v_mfma_f32_16x16x32_bf16 v[60:63], v[80:83], v[144:147], v[60:63]
	s_waitcnt lgkmcnt(10)
	v_mfma_f32_16x16x32_bf16 v[56:59], v[80:83], v[148:151], v[56:59]
	s_waitcnt lgkmcnt(9)
	v_mfma_f32_16x16x32_bf16 v[52:55], v[80:83], v[152:155], v[52:55]
	s_waitcnt lgkmcnt(8)
	v_mfma_f32_16x16x32_bf16 v[48:51], v[80:83], v[156:159], v[48:51]
	ds_read_b128 v[132:135], v253 offset:2048
	ds_read_b128 v[136:139], v253 offset:4096
	ds_read_b128 v[140:143], v253 offset:6144
	s_waitcnt lgkmcnt(10)
	v_mfma_f32_16x16x32_bf16 v[44:47], v[84:87], v[144:147], v[44:47]
	v_mfma_f32_16x16x32_bf16 v[40:43], v[84:87], v[148:151], v[40:43]
	v_mfma_f32_16x16x32_bf16 v[36:39], v[84:87], v[152:155], v[36:39]
	v_mfma_f32_16x16x32_bf16 v[28:31], v[84:87], v[156:159], v[28:31]
	s_waitcnt lgkmcnt(9)
	v_mfma_f32_16x16x32_bf16 v[16:19], v[88:91], v[144:147], v[16:19]
	v_mfma_f32_16x16x32_bf16 v[12:15], v[88:91], v[148:151], v[12:15]
	v_mfma_f32_16x16x32_bf16 v[4:7], v[88:91], v[152:155], v[4:7]
	v_mfma_f32_16x16x32_bf16 v[8:11], v[88:91], v[156:159], v[8:11]
	s_waitcnt lgkmcnt(8)
	v_mfma_f32_16x16x32_bf16 v[32:35], v[92:95], v[144:147], v[32:35]
	v_mfma_f32_16x16x32_bf16 v[24:27], v[92:95], v[148:151], v[24:27]
	v_mfma_f32_16x16x32_bf16 v[20:23], v[92:95], v[152:155], v[20:23]
	v_mfma_f32_16x16x32_bf16 v[0:3], v[92:95], v[156:159], v[0:3]
	s_waitcnt lgkmcnt(0)
	s_barrier
	s_add_u32 m0, s7, 0x0
	v_mfma_f32_16x16x32_bf16 v[60:63], v[124:127], v[180:183], v[60:63]
	global_load_lds_dwordx4 v248, s[8:9]
	v_mfma_f32_16x16x32_bf16 v[56:59], v[124:127], v[184:187], v[56:59]
	s_add_u32 m0, s7, 0x400
	v_mfma_f32_16x16x32_bf16 v[52:55], v[124:127], v[188:191], v[52:55]
	global_load_lds_dwordx4 v249, s[8:9]
	v_mfma_f32_16x16x32_bf16 v[48:51], v[124:127], v[192:195], v[48:51]
	s_add_u32 m0, s7, 0x800
	v_mfma_f32_16x16x32_bf16 v[44:47], v[132:135], v[180:183], v[44:47]
	global_load_lds_dwordx4 v250, s[8:9]
	v_mfma_f32_16x16x32_bf16 v[40:43], v[132:135], v[184:187], v[40:43]
	s_add_u32 m0, s7, 0xc00
	v_mfma_f32_16x16x32_bf16 v[36:39], v[132:135], v[188:191], v[36:39]
	global_load_lds_dwordx4 v251, s[8:9]
	v_mfma_f32_16x16x32_bf16 v[28:31], v[132:135], v[192:195], v[28:31]
	s_add_u32 m0, s7, 0x8000
	v_mfma_f32_16x16x32_bf16 v[16:19], v[136:139], v[180:183], v[16:19]
	global_load_lds_dwordx4 v248, s[64:65]
	v_mfma_f32_16x16x32_bf16 v[12:15], v[136:139], v[184:187], v[12:15]
	s_add_u32 m0, s7, 0x8400
	v_mfma_f32_16x16x32_bf16 v[4:7], v[136:139], v[188:191], v[4:7]
	global_load_lds_dwordx4 v249, s[64:65]
	v_mfma_f32_16x16x32_bf16 v[8:11], v[136:139], v[192:195], v[8:11]
	s_add_u32 m0, s7, 0x8800
	v_mfma_f32_16x16x32_bf16 v[32:35], v[140:143], v[180:183], v[32:35]
	global_load_lds_dwordx4 v250, s[64:65]
	v_mfma_f32_16x16x32_bf16 v[24:27], v[140:143], v[184:187], v[24:27]
	s_add_u32 m0, s7, 0x8c00
	v_mfma_f32_16x16x32_bf16 v[20:23], v[140:143], v[188:191], v[20:23]
	global_load_lds_dwordx4 v251, s[64:65]
	v_mfma_f32_16x16x32_bf16 v[0:3], v[140:143], v[192:195], v[0:3]
	s_add_u32 s8, s8, 0x80
	s_addc_u32 s9, s9, 0
	s_add_u32 s64, s64, 0x80
	s_addc_u32 s65, s65, 0
	s_waitcnt vmcnt(8)
	s_barrier
	ds_read_b128 v[80:83], v252 offset:16384
	ds_read_b128 v[144:147], v254 offset:49152
	ds_read_b128 v[148:151], v254 offset:51200
	ds_read_b128 v[152:155], v254 offset:53248
	ds_read_b128 v[156:159], v254 offset:55296
	ds_read_b128 v[84:87], v252 offset:18432
	ds_read_b128 v[88:91], v252 offset:20480
	ds_read_b128 v[92:95], v252 offset:22528
	ds_read_b128 v[124:127], v253 offset:16384
	ds_read_b128 v[180:183], v255 offset:49152
	ds_read_b128 v[184:187], v255 offset:51200
	ds_read_b128 v[188:191], v255 offset:53248
	ds_read_b128 v[192:195], v255 offset:55296
	s_waitcnt lgkmcnt(11)
	v_mfma_f32_16x16x32_bf16 v[60:63], v[80:83], v[144:147], v[60:63]
	s_waitcnt lgkmcnt(10)
	v_mfma_f32_16x16x32_bf16 v[56:59], v[80:83], v[148:151], v[56:59]
	s_waitcnt lgkmcnt(9)
	v_mfma_f32_16x16x32_bf16 v[52:55], v[80:83], v[152:155], v[52:55]
	s_waitcnt lgkmcnt(8)
	v_mfma_f32_16x16x32_bf16 v[48:51], v[80:83], v[156:159], v[48:51]
	ds_read_b128 v[132:135], v253 offset:18432
	ds_read_b128 v[136:139], v253 offset:20480
	ds_read_b128 v[140:143], v253 offset:22528
	s_waitcnt lgkmcnt(10)
	v_mfma_f32_16x16x32_bf16 v[44:47], v[84:87], v[144:147], v[44:47]
	v_mfma_f32_16x16x32_bf16 v[40:43], v[84:87], v[148:151], v[40:43]
	v_mfma_f32_16x16x32_bf16 v[36:39], v[84:87], v[152:155], v[36:39]
	v_mfma_f32_16x16x32_bf16 v[28:31], v[84:87], v[156:159], v[28:31]
	s_waitcnt lgkmcnt(9)
	v_mfma_f32_16x16x32_bf16 v[16:19], v[88:91], v[144:147], v[16:19]
	v_mfma_f32_16x16x32_bf16 v[12:15], v[88:91], v[148:151], v[12:15]
	v_mfma_f32_16x16x32_bf16 v[4:7], v[88:91], v[152:155], v[4:7]
	v_mfma_f32_16x16x32_bf16 v[8:11], v[88:91], v[156:159], v[8:11]
	s_waitcnt lgkmcnt(8)
	v_mfma_f32_16x16x32_bf16 v[32:35], v[92:95], v[144:147], v[32:35]
	v_mfma_f32_16x16x32_bf16 v[24:27], v[92:95], v[148:151], v[24:27]
	v_mfma_f32_16x16x32_bf16 v[20:23], v[92:95], v[152:155], v[20:23]
	v_mfma_f32_16x16x32_bf16 v[0:3], v[92:95], v[156:159], v[0:3]
	s_waitcnt lgkmcnt(0)
	s_barrier
	s_add_u32 m0, s7, 0x4000
	v_mfma_f32_16x16x32_bf16 v[60:63], v[124:127], v[180:183], v[60:63]
	global_load_lds_dwordx4 v248, s[8:9]
	v_mfma_f32_16x16x32_bf16 v[56:59], v[124:127], v[184:187], v[56:59]
	s_add_u32 m0, s7, 0x4400
	v_mfma_f32_16x16x32_bf16 v[52:55], v[124:127], v[188:191], v[52:55]
	global_load_lds_dwordx4 v249, s[8:9]
	v_mfma_f32_16x16x32_bf16 v[48:51], v[124:127], v[192:195], v[48:51]
	s_add_u32 m0, s7, 0x4800
	v_mfma_f32_16x16x32_bf16 v[44:47], v[132:135], v[180:183], v[44:47]
	global_load_lds_dwordx4 v250, s[8:9]
	v_mfma_f32_16x16x32_bf16 v[40:43], v[132:135], v[184:187], v[40:43]
	s_add_u32 m0, s7, 0x4c00
	v_mfma_f32_16x16x32_bf16 v[36:39], v[132:135], v[188:191], v[36:39]
	global_load_lds_dwordx4 v251, s[8:9]
	v_mfma_f32_16x16x32_bf16 v[28:31], v[132:135], v[192:195], v[28:31]
	s_add_u32 m0, s7, 0xc000
	v_mfma_f32_16x16x32_bf16 v[16:19], v[136:139], v[180:183], v[16:19]
	global_load_lds_dwordx4 v248, s[64:65]
	v_mfma_f32_16x16x32_bf16 v[12:15], v[136:139], v[184:187], v[12:15]
	s_add_u32 m0, s7, 0xc400
	v_mfma_f32_16x16x32_bf16 v[4:7], v[136:139], v[188:191], v[4:7]
	global_load_lds_dwordx4 v249, s[64:65]
	v_mfma_f32_16x16x32_bf16 v[8:11], v[136:139], v[192:195], v[8:11]
	s_add_u32 m0, s7, 0xc800
	v_mfma_f32_16x16x32_bf16 v[32:35], v[140:143], v[180:183], v[32:35]
	global_load_lds_dwordx4 v250, s[64:65]
	v_mfma_f32_16x16x32_bf16 v[24:27], v[140:143], v[184:187], v[24:27]
	s_add_u32 m0, s7, 0xcc00
	v_mfma_f32_16x16x32_bf16 v[20:23], v[140:143], v[188:191], v[20:23]
	global_load_lds_dwordx4 v251, s[64:65]
	v_mfma_f32_16x16x32_bf16 v[0:3], v[140:143], v[192:195], v[0:3]
	s_add_u32 s8, s8, 0x80
	s_addc_u32 s9, s9, 0
	s_add_u32 s64, s64, 0x80
	s_addc_u32 s65, s65, 0
	s_sub_u32 s32, s32, 1
	s_cmp_lg_u32 s32, 0
	s_cbranch_scc1 .Lg18_loop
	s_cmp_lt_u32 s2, 0xc40
	s_cbranch_scc0 .Lg18_tailplain
	s_sub_u32 s32, s2, s3
	s_and_b32 s32, s32, 63
	s_and_b32 s66, s2, 63
	s_sub_i32 s66, s66, s32
	s_mul_i32 s66, s66, 0x40000
	s_sub_i32 s66, s66, 0x800
	s_ashr_i32 s32, s66, 31
	s_add_u32 s8, s8, s66
	s_addc_u32 s9, s9, s32
	s_sub_u32 s32, s2, s3
	s_lshr_b32 s32, s32, 6
	s_lshr_b32 s66, s2, 6
	s_sub_i32 s66, s66, s32
	s_mul_i32 s66, s66, 0x40000
	s_sub_i32 s66, s66, 0x800
	s_ashr_i32 s32, s66, 31
	s_add_u32 s64, s64, s66
	s_addc_u32 s65, s65, s32
	s_waitcnt vmcnt(8)
	s_barrier
	ds_read_b128 v[80:83], v252 offset:0
	ds_read_b128 v[144:147], v254 offset:32768
	ds_read_b128 v[148:151], v254 offset:34816
	ds_read_b128 v[152:155], v254 offset:36864
	ds_read_b128 v[156:159], v254 offset:38912
	ds_read_b128 v[84:87], v252 offset:2048
	ds_read_b128 v[88:91], v252 offset:4096
	ds_read_b128 v[92:95], v252 offset:6144
	ds_read_b128 v[124:127], v253 offset:0
	ds_read_b128 v[180:183], v255 offset:32768
	ds_read_b128 v[184:187], v255 offset:34816
	ds_read_b128 v[188:191], v255 offset:36864
	ds_read_b128 v[192:195], v255 offset:38912
	s_waitcnt lgkmcnt(11)
	v_mfma_f32_16x16x32_bf16 v[60:63], v[80:83], v[144:147], v[60:63]
	s_waitcnt lgkmcnt(10)
	v_mfma_f32_16x16x32_bf16 v[56:59], v[80:83], v[148:151], v[56:59]
	s_waitcnt lgkmcnt(9)
	v_mfma_f32_16x16x32_bf16 v[52:55], v[80:83], v[152:155], v[52:55]
	s_waitcnt lgkmcnt(8)
	v_mfma_f32_16x16x32_bf16 v[48:51], v[80:83], v[156:159], v[48:51]
	ds_read_b128 v[132:135], v253 offset:2048
	ds_read_b128 v[136:139], v253 offset:4096
	ds_read_b128 v[140:143], v253 offset:6144
	s_waitcnt lgkmcnt(10)
	v_mfma_f32_16x16x32_bf16 v[44:47], v[84:87], v[144:147], v[44:47]
	v_mfma_f32_16x16x32_bf16 v[40:43], v[84:87], v[148:151], v[40:43]
	v_mfma_f32_16x16x32_bf16 v[36:39], v[84:87], v[152:155], v[36:39]
	v_mfma_f32_16x16x32_bf16 v[28:31], v[84:87], v[156:159], v[28:31]
	s_waitcnt lgkmcnt(9)
	v_mfma_f32_16x16x32_bf16 v[16:19], v[88:91], v[144:147], v[16:19]
	v_mfma_f32_16x16x32_bf16 v[12:15], v[88:91], v[148:151], v[12:15]
	v_mfma_f32_16x16x32_bf16 v[4:7], v[88:91], v[152:155], v[4:7]
	v_mfma_f32_16x16x32_bf16 v[8:11], v[88:91], v[156:159], v[8:11]
	s_waitcnt lgkmcnt(8)
	v_mfma_f32_16x16x32_bf16 v[32:35], v[92:95], v[144:147], v[32:35]
	v_mfma_f32_16x16x32_bf16 v[24:27], v[92:95], v[148:151], v[24:27]
	v_mfma_f32_16x16x32_bf16 v[20:23], v[92:95], v[152:155], v[20:23]
	v_mfma_f32_16x16x32_bf16 v[0:3], v[92:95], v[156:159], v[0:3]
	s_waitcnt lgkmcnt(0)
	s_barrier
	s_add_u32 m0, s7, 0x0
	v_mfma_f32_16x16x32_bf16 v[60:63], v[124:127], v[180:183], v[60:63]
	global_load_lds_dwordx4 v248, s[8:9]
	v_mfma_f32_16x16x32_bf16 v[56:59], v[124:127], v[184:187], v[56:59]
	s_add_u32 m0, s7, 0x400
	v_mfma_f32_16x16x32_bf16 v[52:55], v[124:127], v[188:191], v[52:55]
	global_load_lds_dwordx4 v249, s[8:9]
	v_mfma_f32_16x16x32_bf16 v[48:51], v[124:127], v[192:195], v[48:51]
	s_add_u32 m0, s7, 0x800
	v_mfma_f32_16x16x32_bf16 v[44:47], v[132:135], v[180:183], v[44:47]
	global_load_lds_dwordx4 v250, s[8:9]
	v_mfma_f32_16x16x32_bf16 v[40:43], v[132:135], v[184:187], v[40:43]
	s_add_u32 m0, s7, 0xc00
	v_mfma_f32_16x16x32_bf16 v[36:39], v[132:135], v[188:191], v[36:39]
	global_load_lds_dwordx4 v251, s[8:9]
	v_mfma_f32_16x16x32_bf16 v[28:31], v[132:135], v[192:195], v[28:31]
	s_add_u32 m0, s7, 0x8000
	v_mfma_f32_16x16x32_bf16 v[16:19], v[136:139], v[180:183], v[16:19]
	global_load_lds_dwordx4 v248, s[64:65]
	v_mfma_f32_16x16x32_bf16 v[12:15], v[136:139], v[184:187], v[12:15]
	s_add_u32 m0, s7, 0x8400
	v_mfma_f32_16x16x32_bf16 v[4:7], v[136:139], v[188:191], v[4:7]
	global_load_lds_dwordx4 v249, s[64:65]
	v_mfma_f32_16x16x32_bf16 v[8:11], v[136:139], v[192:195], v[8:11]
	s_add_u32 m0, s7, 0x8800
	v_mfma_f32_16x16x32_bf16 v[32:35], v[140:143], v[180:183], v[32:35]
	global_load_lds_dwordx4 v250, s[64:65]
	v_mfma_f32_16x16x32_bf16 v[24:27], v[140:143], v[184:187], v[24:27]
	s_add_u32 m0, s7, 0x8c00
	v_mfma_f32_16x16x32_bf16 v[20:23], v[140:143], v[188:191], v[20:23]
	global_load_lds_dwordx4 v251, s[64:65]
	v_mfma_f32_16x16x32_bf16 v[0:3], v[140:143], v[192:195], v[0:3]
	s_add_u32 s8, s8, 0x80
	s_addc_u32 s9, s9, 0
	s_add_u32 s64, s64, 0x80
	s_addc_u32 s65, s65, 0
	s_waitcnt vmcnt(8)
	s_barrier
	ds_read_b128 v[80:83], v252 offset:16384
	ds_read_b128 v[144:147], v254 offset:49152
	ds_read_b128 v[148:151], v254 offset:51200
	ds_read_b128 v[152:155], v254 offset:53248
	ds_read_b128 v[156:159], v254 offset:55296
	ds_read_b128 v[84:87], v252 offset:18432
	ds_read_b128 v[88:91], v252 offset:20480
	ds_read_b128 v[92:95], v252 offset:22528
	ds_read_b128 v[124:127], v253 offset:16384
	ds_read_b128 v[180:183], v255 offset:49152
	ds_read_b128 v[184:187], v255 offset:51200
	ds_read_b128 v[188:191], v255 offset:53248
	ds_read_b128 v[192:195], v255 offset:55296
	s_waitcnt lgkmcnt(11)
	v_mfma_f32_16x16x32_bf16 v[60:63], v[80:83], v[144:147], v[60:63]
	s_waitcnt lgkmcnt(10)
	v_mfma_f32_16x16x32_bf16 v[56:59], v[80:83], v[148:151], v[56:59]
	s_waitcnt lgkmcnt(9)
	v_mfma_f32_16x16x32_bf16 v[52:55], v[80:83], v[152:155], v[52:55]
	s_waitcnt lgkmcnt(8)
	v_mfma_f32_16x16x32_bf16 v[48:51], v[80:83], v[156:159], v[48:51]
	ds_read_b128 v[132:135], v253 offset:18432
	ds_read_b128 v[136:139], v253 offset:20480
	ds_read_b128 v[140:143], v253 offset:22528
	s_waitcnt lgkmcnt(10)
	v_mfma_f32_16x16x32_bf16 v[44:47], v[84:87], v[144:147], v[44:47]
	v_mfma_f32_16x16x32_bf16 v[40:43], v[84:87], v[148:151], v[40:43]
	v_mfma_f32_16x16x32_bf16 v[36:39], v[84:87], v[152:155], v[36:39]
	v_mfma_f32_16x16x32_bf16 v[28:31], v[84:87], v[156:159], v[28:31]
	s_waitcnt lgkmcnt(9)
	v_mfma_f32_16x16x32_bf16 v[16:19], v[88:91], v[144:147], v[16:19]
	v_mfma_f32_16x16x32_bf16 v[12:15], v[88:91], v[148:151], v[12:15]
	v_mfma_f32_16x16x32_bf16 v[4:7], v[88:91], v[152:155], v[4:7]
	v_mfma_f32_16x16x32_bf16 v[8:11], v[88:91], v[156:159], v[8:11]
	s_waitcnt lgkmcnt(8)
	v_mfma_f32_16x16x32_bf16 v[32:35], v[92:95], v[144:147], v[32:35]
	v_mfma_f32_16x16x32_bf16 v[24:27], v[92:95], v[148:151], v[24:27]
	v_mfma_f32_16x16x32_bf16 v[20:23], v[92:95], v[152:155], v[20:23]
	v_mfma_f32_16x16x32_bf16 v[0:3], v[92:95], v[156:159], v[0:3]
	s_waitcnt lgkmcnt(0)
	s_barrier
	s_add_u32 m0, s7, 0x4000
	v_mfma_f32_16x16x32_bf16 v[60:63], v[124:127], v[180:183], v[60:63]
	global_load_lds_dwordx4 v248, s[8:9]
	v_mfma_f32_16x16x32_bf16 v[56:59], v[124:127], v[184:187], v[56:59]
	s_add_u32 m0, s7, 0x4400
	v_mfma_f32_16x16x32_bf16 v[52:55], v[124:127], v[188:191], v[52:55]
	global_load_lds_dwordx4 v249, s[8:9]
	v_mfma_f32_16x16x32_bf16 v[48:51], v[124:127], v[192:195], v[48:51]
	s_add_u32 m0, s7, 0x4800
	v_mfma_f32_16x16x32_bf16 v[44:47], v[132:135], v[180:183], v[44:47]
	global_load_lds_dwordx4 v250, s[8:9]
	v_mfma_f32_16x16x32_bf16 v[40:43], v[132:135], v[184:187], v[40:43]
	s_add_u32 m0, s7, 0x4c00
	v_mfma_f32_16x16x32_bf16 v[36:39], v[132:135], v[188:191], v[36:39]
	global_load_lds_dwordx4 v251, s[8:9]
	v_mfma_f32_16x16x32_bf16 v[28:31], v[132:135], v[192:195], v[28:31]
	s_add_u32 m0, s7, 0xc000
	v_mfma_f32_16x16x32_bf16 v[16:19], v[136:139], v[180:183], v[16:19]
	global_load_lds_dwordx4 v248, s[64:65]
	v_mfma_f32_16x16x32_bf16 v[12:15], v[136:139], v[184:187], v[12:15]
	s_add_u32 m0, s7, 0xc400
	v_mfma_f32_16x16x32_bf16 v[4:7], v[136:139], v[188:191], v[4:7]
	global_load_lds_dwordx4 v249, s[64:65]
	v_mfma_f32_16x16x32_bf16 v[8:11], v[136:139], v[192:195], v[8:11]
	s_add_u32 m0, s7, 0xc800
	v_mfma_f32_16x16x32_bf16 v[32:35], v[140:143], v[180:183], v[32:35]
	global_load_lds_dwordx4 v250, s[64:65]
	v_mfma_f32_16x16x32_bf16 v[24:27], v[140:143], v[184:187], v[24:27]
	s_add_u32 m0, s7, 0xcc00
	v_mfma_f32_16x16x32_bf16 v[20:23], v[140:143], v[188:191], v[20:23]
	global_load_lds_dwordx4 v251, s[64:65]
	v_mfma_f32_16x16x32_bf16 v[0:3], v[140:143], v[192:195], v[0:3]
	s_add_u32 s8, s8, 0x80
	s_addc_u32 s9, s9, 0
	s_add_u32 s64, s64, 0x80
	s_addc_u32 s65, s65, 0
	s_branch .Lg18_done
.Lg18_tailplain:
	s_waitcnt vmcnt(8)
	s_barrier
	ds_read_b128 v[80:83], v252 offset:0
	ds_read_b128 v[144:147], v254 offset:32768
	ds_read_b128 v[148:151], v254 offset:34816
	ds_read_b128 v[152:155], v254 offset:36864
	ds_read_b128 v[156:159], v254 offset:38912
	ds_read_b128 v[84:87], v252 offset:2048
	ds_read_b128 v[88:91], v252 offset:4096
	ds_read_b128 v[92:95], v252 offset:6144
	ds_read_b128 v[124:127], v253 offset:0
	ds_read_b128 v[180:183], v255 offset:32768
	ds_read_b128 v[184:187], v255 offset:34816
	ds_read_b128 v[188:191], v255 offset:36864
	ds_read_b128 v[192:195], v255 offset:38912
	s_waitcnt lgkmcnt(11)
	v_mfma_f32_16x16x32_bf16 v[60:63], v[80:83], v[144:147], v[60:63]
	s_waitcnt lgkmcnt(10)
	v_mfma_f32_16x16x32_bf16 v[56:59], v[80:83], v[148:151], v[56:59]
	s_waitcnt lgkmcnt(9)
	v_mfma_f32_16x16x32_bf16 v[52:55], v[80:83], v[152:155], v[52:55]
	s_waitcnt lgkmcnt(8)
	v_mfma_f32_16x16x32_bf16 v[48:51], v[80:83], v[156:159], v[48:51]
	ds_read_b128 v[132:135], v253 offset:2048
	ds_read_b128 v[136:139], v253 offset:4096
	ds_read_b128 v[140:143], v253 offset:6144
	s_waitcnt lgkmcnt(10)
	v_mfma_f32_16x16x32_bf16 v[44:47], v[84:87], v[144:147], v[44:47]
	v_mfma_f32_16x16x32_bf16 v[40:43], v[84:87], v[148:151], v[40:43]
	v_mfma_f32_16x16x32_bf16 v[36:39], v[84:87], v[152:155], v[36:39]
	v_mfma_f32_16x16x32_bf16 v[28:31], v[84:87], v[156:159], v[28:31]
	s_waitcnt lgkmcnt(9)
	v_mfma_f32_16x16x32_bf16 v[16:19], v[88:91], v[144:147], v[16:19]
	v_mfma_f32_16x16x32_bf16 v[12:15], v[88:91], v[148:151], v[12:15]
	v_mfma_f32_16x16x32_bf16 v[4:7], v[88:91], v[152:155], v[4:7]
	v_mfma_f32_16x16x32_bf16 v[8:11], v[88:91], v[156:159], v[8:11]
	s_waitcnt lgkmcnt(8)
	v_mfma_f32_16x16x32_bf16 v[32:35], v[92:95], v[144:147], v[32:35]
	v_mfma_f32_16x16x32_bf16 v[24:27], v[92:95], v[148:151], v[24:27]
	v_mfma_f32_16x16x32_bf16 v[20:23], v[92:95], v[152:155], v[20:23]
	v_mfma_f32_16x16x32_bf16 v[0:3], v[92:95], v[156:159], v[0:3]
	s_waitcnt lgkmcnt(0)
	s_barrier
	v_mfma_f32_16x16x32_bf16 v[60:63], v[124:127], v[180:183], v[60:63]
	v_mfma_f32_16x16x32_bf16 v[56:59], v[124:127], v[184:187], v[56:59]
	v_mfma_f32_16x16x32_bf16 v[52:55], v[124:127], v[188:191], v[52:55]
	v_mfma_f32_16x16x32_bf16 v[48:51], v[124:127], v[192:195], v[48:51]
	v_mfma_f32_16x16x32_bf16 v[44:47], v[132:135], v[180:183], v[44:47]
	v_mfma_f32_16x16x32_bf16 v[40:43], v[132:135], v[184:187], v[40:43]
	v_mfma_f32_16x16x32_bf16 v[36:39], v[132:135], v[188:191], v[36:39]
	v_mfma_f32_16x16x32_bf16 v[28:31], v[132:135], v[192:195], v[28:31]
	v_mfma_f32_16x16x32_bf16 v[16:19], v[136:139], v[180:183], v[16:19]
	v_mfma_f32_16x16x32_bf16 v[12:15], v[136:139], v[184:187], v[12:15]
	v_mfma_f32_16x16x32_bf16 v[4:7], v[136:139], v[188:191], v[4:7]
	v_mfma_f32_16x16x32_bf16 v[8:11], v[136:139], v[192:195], v[8:11]
	v_mfma_f32_16x16x32_bf16 v[32:35], v[140:143], v[180:183], v[32:35]
	v_mfma_f32_16x16x32_bf16 v[24:27], v[140:143], v[184:187], v[24:27]
	v_mfma_f32_16x16x32_bf16 v[20:23], v[140:143], v[188:191], v[20:23]
	v_mfma_f32_16x16x32_bf16 v[0:3], v[140:143], v[192:195], v[0:3]
	s_waitcnt vmcnt(0)
	s_barrier
	ds_read_b128 v[80:83], v252 offset:16384
	ds_read_b128 v[144:147], v254 offset:49152
	ds_read_b128 v[148:151], v254 offset:51200
	ds_read_b128 v[152:155], v254 offset:53248
	ds_read_b128 v[156:159], v254 offset:55296
	ds_read_b128 v[84:87], v252 offset:18432
	ds_read_b128 v[88:91], v252 offset:20480
	ds_read_b128 v[92:95], v252 offset:22528
	ds_read_b128 v[124:127], v253 offset:16384
	ds_read_b128 v[180:183], v255 offset:49152
	ds_read_b128 v[184:187], v255 offset:51200
	ds_read_b128 v[188:191], v255 offset:53248
	ds_read_b128 v[192:195], v255 offset:55296
	s_waitcnt lgkmcnt(11)
	v_mfma_f32_16x16x32_bf16 v[60:63], v[80:83], v[144:147], v[60:63]
	s_waitcnt lgkmcnt(10)
	v_mfma_f32_16x16x32_bf16 v[56:59], v[80:83], v[148:151], v[56:59]
	s_waitcnt lgkmcnt(9)
	v_mfma_f32_16x16x32_bf16 v[52:55], v[80:83], v[152:155], v[52:55]
	s_waitcnt lgkmcnt(8)
	v_mfma_f32_16x16x32_bf16 v[48:51], v[80:83], v[156:159], v[48:51]
	ds_read_b128 v[132:135], v253 offset:18432
	ds_read_b128 v[136:139], v253 offset:20480
	ds_read_b128 v[140:143], v253 offset:22528
	s_waitcnt lgkmcnt(10)
	v_mfma_f32_16x16x32_bf16 v[44:47], v[84:87], v[144:147], v[44:47]
	v_mfma_f32_16x16x32_bf16 v[40:43], v[84:87], v[148:151], v[40:43]
	v_mfma_f32_16x16x32_bf16 v[36:39], v[84:87], v[152:155], v[36:39]
	v_mfma_f32_16x16x32_bf16 v[28:31], v[84:87], v[156:159], v[28:31]
	s_waitcnt lgkmcnt(9)
	v_mfma_f32_16x16x32_bf16 v[16:19], v[88:91], v[144:147], v[16:19]
	v_mfma_f32_16x16x32_bf16 v[12:15], v[88:91], v[148:151], v[12:15]
	v_mfma_f32_16x16x32_bf16 v[4:7], v[88:91], v[152:155], v[4:7]
	v_mfma_f32_16x16x32_bf16 v[8:11], v[88:91], v[156:159], v[8:11]
	s_waitcnt lgkmcnt(8)
	v_mfma_f32_16x16x32_bf16 v[32:35], v[92:95], v[144:147], v[32:35]
	v_mfma_f32_16x16x32_bf16 v[24:27], v[92:95], v[148:151], v[24:27]
	v_mfma_f32_16x16x32_bf16 v[20:23], v[92:95], v[152:155], v[20:23]
	v_mfma_f32_16x16x32_bf16 v[0:3], v[92:95], v[156:159], v[0:3]
	s_waitcnt lgkmcnt(0)
	s_barrier
	v_mfma_f32_16x16x32_bf16 v[60:63], v[124:127], v[180:183], v[60:63]
	v_mfma_f32_16x16x32_bf16 v[56:59], v[124:127], v[184:187], v[56:59]
	v_mfma_f32_16x16x32_bf16 v[52:55], v[124:127], v[188:191], v[52:55]
	v_mfma_f32_16x16x32_bf16 v[48:51], v[124:127], v[192:195], v[48:51]
	v_mfma_f32_16x16x32_bf16 v[44:47], v[132:135], v[180:183], v[44:47]
	v_mfma_f32_16x16x32_bf16 v[40:43], v[132:135], v[184:187], v[40:43]
	v_mfma_f32_16x16x32_bf16 v[36:39], v[132:135], v[188:191], v[36:39]
	v_mfma_f32_16x16x32_bf16 v[28:31], v[132:135], v[192:195], v[28:31]
	v_mfma_f32_16x16x32_bf16 v[16:19], v[136:139], v[180:183], v[16:19]
	v_mfma_f32_16x16x32_bf16 v[12:15], v[136:139], v[184:187], v[12:15]
	v_mfma_f32_16x16x32_bf16 v[4:7], v[136:139], v[188:191], v[4:7]
	v_mfma_f32_16x16x32_bf16 v[8:11], v[136:139], v[192:195], v[8:11]
	v_mfma_f32_16x16x32_bf16 v[32:35], v[140:143], v[180:183], v[32:35]
	v_mfma_f32_16x16x32_bf16 v[24:27], v[140:143], v[184:187], v[24:27]
	v_mfma_f32_16x16x32_bf16 v[20:23], v[140:143], v[188:191], v[20:23]
	v_mfma_f32_16x16x32_bf16 v[0:3], v[140:143], v[192:195], v[0:3]
.Lg18_done:
	s_nop 7
	s_nop 1
	v_add_u32_e32 v80, s12, v174
	v_or_b32_e32 v64, s6, v175
	s_cmpk_gt_i32 s6, 0x3ff
	s_mov_b64 s[6:7], -1
	s_cbranch_scc0 .LBB0_1789
	s_cmpk_gt_u32 s13, 0xbff
	s_cbranch_scc0 .LBB0_1786
	s_cmpk_gt_u32 s13, 0x13ff
	s_cbranch_scc0 .LBB0_1609
	s_cmpk_gt_u32 s13, 0x17ff
	s_cbranch_scc0 .LBB0_1590
	s_and_saveexec_b64 s[6:7], s[4:5]
	s_cbranch_execz .LBB0_1589
	v_lshlrev_b32_e32 v98, 7, v80
	v_lshl_add_u64 v[66:67], v[104:105], 0, v[98:99]
	global_store_dword v[66:67], v60, off
	global_store_dword v[66:67], v61, off offset:128
	global_store_dword v[66:67], v62, off offset:256
	global_store_dword v[66:67], v63, off offset:384
	global_store_dword v[66:67], v56, off offset:64
	global_store_dword v[66:67], v57, off offset:192
	global_store_dword v[66:67], v58, off offset:320
	global_store_dword v[66:67], v59, off offset:448
	global_store_dword v[66:67], v44, off offset:2048
	global_store_dword v[66:67], v45, off offset:2176
	global_store_dword v[66:67], v46, off offset:2304
	global_store_dword v[66:67], v47, off offset:2432
	global_store_dword v[66:67], v40, off offset:2112
	global_store_dword v[66:67], v41, off offset:2240
	global_store_dword v[66:67], v42, off offset:2368
	global_store_dword v[66:67], v43, off offset:2496
	v_or_b32_e32 v66, 0x1000, v98
	v_mov_b32_e32 v67, v99
	v_lshl_add_u64 v[68:69], v[104:105], 0, v[66:67]
	global_store_dword v[68:69], v16, off
	v_or_b32_e32 v68, 0x1080, v98
	v_mov_b32_e32 v69, v99
	v_lshl_add_u64 v[70:71], v[104:105], 0, v[68:69]
	global_store_dword v[70:71], v17, off
	v_or_b32_e32 v70, 0x1100, v98
	v_mov_b32_e32 v71, v99
	v_lshl_add_u64 v[66:67], v[106:107], 0, v[66:67]
	v_lshl_add_u64 v[72:73], v[104:105], 0, v[70:71]
	global_store_dword v[66:67], v12, off
	v_lshl_add_u64 v[66:67], v[106:107], 0, v[68:69]
	global_store_dword v[72:73], v18, off
	v_or_b32_e32 v72, 0x1180, v98
	v_mov_b32_e32 v73, v99
	global_store_dword v[66:67], v13, off
	v_lshl_add_u64 v[66:67], v[106:107], 0, v[70:71]
	global_store_dword v[66:67], v14, off
	v_lshl_add_u64 v[66:67], v[106:107], 0, v[72:73]
	global_store_dword v[66:67], v15, off
	v_or_b32_e32 v66, 0x1800, v98
	v_mov_b32_e32 v67, v99
	v_lshl_add_u64 v[68:69], v[104:105], 0, v[66:67]
	global_store_dword v[68:69], v32, off
	v_or_b32_e32 v68, 0x1880, v98
	v_mov_b32_e32 v69, v99
	v_lshl_add_u64 v[70:71], v[104:105], 0, v[68:69]
	v_lshl_add_u64 v[66:67], v[106:107], 0, v[66:67]
	global_store_dword v[70:71], v33, off
	v_or_b32_e32 v70, 0x1900, v98
	v_mov_b32_e32 v71, v99
	global_store_dword v[66:67], v24, off
	v_lshl_add_u64 v[66:67], v[106:107], 0, v[68:69]
	v_lshl_add_u64 v[74:75], v[104:105], 0, v[72:73]
	v_lshl_add_u64 v[72:73], v[104:105], 0, v[70:71]
	v_or_b32_e32 v98, 0x1980, v98
	global_store_dword v[66:67], v25, off
	v_lshl_add_u64 v[66:67], v[106:107], 0, v[70:71]
	global_store_dword v[72:73], v34, off
	v_lshl_add_u64 v[72:73], v[104:105], 0, v[98:99]
	global_store_dword v[66:67], v26, off
	v_lshl_add_u64 v[66:67], v[106:107], 0, v[98:99]
	global_store_dword v[74:75], v19, off
	global_store_dword v[72:73], v35, off
	global_store_dword v[66:67], v27, off

.Lg22_loop:
	s_waitcnt vmcnt(8)
	s_barrier
	ds_read_b128 v[64:67], v252 offset:0
	ds_read_b128 v[104:107], v254 offset:32768
	ds_read_b128 v[108:111], v254 offset:34816
	ds_read_b128 v[112:115], v254 offset:36864
	ds_read_b128 v[116:119], v254 offset:38912
	ds_read_b128 v[68:71], v252 offset:2048
	ds_read_b128 v[72:75], v252 offset:4096
	ds_read_b128 v[76:79], v252 offset:6144
	ds_read_b128 v[80:83], v253 offset:0
	ds_read_b128 v[120:123], v255 offset:32768
	ds_read_b128 v[124:127], v255 offset:34816
	ds_read_b128 v[132:135], v255 offset:36864
	ds_read_b128 v[136:139], v255 offset:38912
	s_waitcnt lgkmcnt(11)
	v_mfma_f32_16x16x32_bf16 v[60:63], v[64:67], v[104:107], v[60:63]
	s_waitcnt lgkmcnt(10)
	v_mfma_f32_16x16x32_bf16 v[44:47], v[64:67], v[108:111], v[44:47]
	s_waitcnt lgkmcnt(9)
	v_mfma_f32_16x16x32_bf16 v[28:31], v[64:67], v[112:115], v[28:31]
	s_waitcnt lgkmcnt(8)
	v_mfma_f32_16x16x32_bf16 v[12:15], v[64:67], v[116:119], v[12:15]
	ds_read_b128 v[84:87], v253 offset:2048
	ds_read_b128 v[88:91], v253 offset:4096
	ds_read_b128 v[92:95], v253 offset:6144
	s_waitcnt lgkmcnt(10)
	v_mfma_f32_16x16x32_bf16 v[56:59], v[68:71], v[104:107], v[56:59]
	v_mfma_f32_16x16x32_bf16 v[40:43], v[68:71], v[108:111], v[40:43]
	v_mfma_f32_16x16x32_bf16 v[20:23], v[68:71], v[112:115], v[20:23]
	v_mfma_f32_16x16x32_bf16 v[4:7], v[68:71], v[116:119], v[4:7]
	s_waitcnt lgkmcnt(9)
	v_mfma_f32_16x16x32_bf16 v[52:55], v[72:75], v[104:107], v[52:55]
	v_mfma_f32_16x16x32_bf16 v[32:35], v[72:75], v[108:111], v[32:35]
	v_mfma_f32_16x16x32_bf16 v[16:19], v[72:75], v[112:115], v[16:19]
	v_mfma_f32_16x16x32_bf16 v[0:3], v[72:75], v[116:119], v[0:3]
	s_waitcnt lgkmcnt(8)
	v_mfma_f32_16x16x32_bf16 v[48:51], v[76:79], v[104:107], v[48:51]
	v_mfma_f32_16x16x32_bf16 v[36:39], v[76:79], v[108:111], v[36:39]
	v_mfma_f32_16x16x32_bf16 v[24:27], v[76:79], v[112:115], v[24:27]
	v_mfma_f32_16x16x32_bf16 v[8:11], v[76:79], v[116:119], v[8:11]
	s_waitcnt lgkmcnt(0)
	s_barrier
	s_add_u32 m0, s6, 0x0
	v_mfma_f32_16x16x32_bf16 v[60:63], v[80:83], v[120:123], v[60:63]
	global_load_lds_dwordx4 v248, s[40:41]
	v_mfma_f32_16x16x32_bf16 v[44:47], v[80:83], v[124:127], v[44:47]
	s_add_u32 m0, s6, 0x400
	v_mfma_f32_16x16x32_bf16 v[28:31], v[80:83], v[132:135], v[28:31]
	global_load_lds_dwordx4 v249, s[40:41]
	v_mfma_f32_16x16x32_bf16 v[12:15], v[80:83], v[136:139], v[12:15]
	s_add_u32 m0, s6, 0x800
	v_mfma_f32_16x16x32_bf16 v[56:59], v[84:87], v[120:123], v[56:59]
	global_load_lds_dwordx4 v250, s[40:41]
	v_mfma_f32_16x16x32_bf16 v[40:43], v[84:87], v[124:127], v[40:43]
	s_add_u32 m0, s6, 0xc00
	v_mfma_f32_16x16x32_bf16 v[20:23], v[84:87], v[132:135], v[20:23]
	global_load_lds_dwordx4 v251, s[40:41]
	v_mfma_f32_16x16x32_bf16 v[4:7], v[84:87], v[136:139], v[4:7]
	s_add_u32 m0, s6, 0x8000
	v_mfma_f32_16x16x32_bf16 v[52:55], v[88:91], v[120:123], v[52:55]
	global_load_lds_dwordx4 v248, s[48:49]
	v_mfma_f32_16x16x32_bf16 v[32:35], v[88:91], v[124:127], v[32:35]
	s_add_u32 m0, s6, 0x8400
	v_mfma_f32_16x16x32_bf16 v[16:19], v[88:91], v[132:135], v[16:19]
	global_load_lds_dwordx4 v249, s[48:49]
	v_mfma_f32_16x16x32_bf16 v[0:3], v[88:91], v[136:139], v[0:3]
	s_add_u32 m0, s6, 0x8800
	v_mfma_f32_16x16x32_bf16 v[48:51], v[92:95], v[120:123], v[48:51]
	global_load_lds_dwordx4 v250, s[48:49]
	v_mfma_f32_16x16x32_bf16 v[36:39], v[92:95], v[124:127], v[36:39]
	s_add_u32 m0, s6, 0x8c00
	v_mfma_f32_16x16x32_bf16 v[24:27], v[92:95], v[132:135], v[24:27]
	global_load_lds_dwordx4 v251, s[48:49]
	v_mfma_f32_16x16x32_bf16 v[8:11], v[92:95], v[136:139], v[8:11]
	s_add_u32 s40, s40, 0x80
	s_addc_u32 s41, s41, 0
	s_add_u32 s48, s48, 0x80
	s_addc_u32 s49, s49, 0
	s_waitcnt vmcnt(8)
	s_barrier
	ds_read_b128 v[64:67], v252 offset:16384
	ds_read_b128 v[104:107], v254 offset:49152
	ds_read_b128 v[108:111], v254 offset:51200
	ds_read_b128 v[112:115], v254 offset:53248
	ds_read_b128 v[116:119], v254 offset:55296
	ds_read_b128 v[68:71], v252 offset:18432
	ds_read_b128 v[72:75], v252 offset:20480
	ds_read_b128 v[76:79], v252 offset:22528
	ds_read_b128 v[80:83], v253 offset:16384
	ds_read_b128 v[120:123], v255 offset:49152
	ds_read_b128 v[124:127], v255 offset:51200
	ds_read_b128 v[132:135], v255 offset:53248
	ds_read_b128 v[136:139], v255 offset:55296
	s_waitcnt lgkmcnt(11)
	v_mfma_f32_16x16x32_bf16 v[60:63], v[64:67], v[104:107], v[60:63]
	s_waitcnt lgkmcnt(10)
	v_mfma_f32_16x16x32_bf16 v[44:47], v[64:67], v[108:111], v[44:47]
	s_waitcnt lgkmcnt(9)
	v_mfma_f32_16x16x32_bf16 v[28:31], v[64:67], v[112:115], v[28:31]
	s_waitcnt lgkmcnt(8)
	v_mfma_f32_16x16x32_bf16 v[12:15], v[64:67], v[116:119], v[12:15]
	ds_read_b128 v[84:87], v253 offset:18432
	ds_read_b128 v[88:91], v253 offset:20480
	ds_read_b128 v[92:95], v253 offset:22528
	s_waitcnt lgkmcnt(10)
	v_mfma_f32_16x16x32_bf16 v[56:59], v[68:71], v[104:107], v[56:59]
	v_mfma_f32_16x16x32_bf16 v[40:43], v[68:71], v[108:111], v[40:43]
	v_mfma_f32_16x16x32_bf16 v[20:23], v[68:71], v[112:115], v[20:23]
	v_mfma_f32_16x16x32_bf16 v[4:7], v[68:71], v[116:119], v[4:7]
	s_waitcnt lgkmcnt(9)
	v_mfma_f32_16x16x32_bf16 v[52:55], v[72:75], v[104:107], v[52:55]
	v_mfma_f32_16x16x32_bf16 v[32:35], v[72:75], v[108:111], v[32:35]
	v_mfma_f32_16x16x32_bf16 v[16:19], v[72:75], v[112:115], v[16:19]
	v_mfma_f32_16x16x32_bf16 v[0:3], v[72:75], v[116:119], v[0:3]
	s_waitcnt lgkmcnt(8)
	v_mfma_f32_16x16x32_bf16 v[48:51], v[76:79], v[104:107], v[48:51]
	v_mfma_f32_16x16x32_bf16 v[36:39], v[76:79], v[108:111], v[36:39]
	v_mfma_f32_16x16x32_bf16 v[24:27], v[76:79], v[112:115], v[24:27]
	v_mfma_f32_16x16x32_bf16 v[8:11], v[76:79], v[116:119], v[8:11]
	s_waitcnt lgkmcnt(0)
	s_barrier
	s_add_u32 m0, s6, 0x4000
	v_mfma_f32_16x16x32_bf16 v[60:63], v[80:83], v[120:123], v[60:63]
	global_load_lds_dwordx4 v248, s[40:41]
	v_mfma_f32_16x16x32_bf16 v[44:47], v[80:83], v[124:127], v[44:47]
	s_add_u32 m0, s6, 0x4400
	v_mfma_f32_16x16x32_bf16 v[28:31], v[80:83], v[132:135], v[28:31]
	global_load_lds_dwordx4 v249, s[40:41]
	v_mfma_f32_16x16x32_bf16 v[12:15], v[80:83], v[136:139], v[12:15]
	s_add_u32 m0, s6, 0x4800
	v_mfma_f32_16x16x32_bf16 v[56:59], v[84:87], v[120:123], v[56:59]
	global_load_lds_dwordx4 v250, s[40:41]
	v_mfma_f32_16x16x32_bf16 v[40:43], v[84:87], v[124:127], v[40:43]
	s_add_u32 m0, s6, 0x4c00
	v_mfma_f32_16x16x32_bf16 v[20:23], v[84:87], v[132:135], v[20:23]
	global_load_lds_dwordx4 v251, s[40:41]
	v_mfma_f32_16x16x32_bf16 v[4:7], v[84:87], v[136:139], v[4:7]
	s_add_u32 m0, s6, 0xc000
	v_mfma_f32_16x16x32_bf16 v[52:55], v[88:91], v[120:123], v[52:55]
	global_load_lds_dwordx4 v248, s[48:49]
	v_mfma_f32_16x16x32_bf16 v[32:35], v[88:91], v[124:127], v[32:35]
	s_add_u32 m0, s6, 0xc400
	v_mfma_f32_16x16x32_bf16 v[16:19], v[88:91], v[132:135], v[16:19]
	global_load_lds_dwordx4 v249, s[48:49]
	v_mfma_f32_16x16x32_bf16 v[0:3], v[88:91], v[136:139], v[0:3]
	s_add_u32 m0, s6, 0xc800
	v_mfma_f32_16x16x32_bf16 v[48:51], v[92:95], v[120:123], v[48:51]
	global_load_lds_dwordx4 v250, s[48:49]
	v_mfma_f32_16x16x32_bf16 v[36:39], v[92:95], v[124:127], v[36:39]
	s_add_u32 m0, s6, 0xcc00
	v_mfma_f32_16x16x32_bf16 v[24:27], v[92:95], v[132:135], v[24:27]
	global_load_lds_dwordx4 v251, s[48:49]
	v_mfma_f32_16x16x32_bf16 v[8:11], v[92:95], v[136:139], v[8:11]
	s_add_u32 s40, s40, 0x80
	s_addc_u32 s41, s41, 0
	s_add_u32 s48, s48, 0x80
	s_addc_u32 s49, s49, 0
	s_sub_u32 s31, s31, 1
	s_cmp_lg_u32 s31, 0
	s_cbranch_scc1 .Lg22_loop
	s_waitcnt vmcnt(8)
	s_barrier
	ds_read_b128 v[64:67], v252 offset:0
	ds_read_b128 v[104:107], v254 offset:32768
	ds_read_b128 v[108:111], v254 offset:34816
	ds_read_b128 v[112:115], v254 offset:36864
	ds_read_b128 v[116:119], v254 offset:38912
	ds_read_b128 v[68:71], v252 offset:2048
	ds_read_b128 v[72:75], v252 offset:4096
	ds_read_b128 v[76:79], v252 offset:6144
	ds_read_b128 v[80:83], v253 offset:0
	ds_read_b128 v[120:123], v255 offset:32768
	ds_read_b128 v[124:127], v255 offset:34816
	ds_read_b128 v[132:135], v255 offset:36864
	ds_read_b128 v[136:139], v255 offset:38912
	s_waitcnt lgkmcnt(11)
	v_mfma_f32_16x16x32_bf16 v[60:63], v[64:67], v[104:107], v[60:63]
	s_waitcnt lgkmcnt(10)
	v_mfma_f32_16x16x32_bf16 v[44:47], v[64:67], v[108:111], v[44:47]
	s_waitcnt lgkmcnt(9)
	v_mfma_f32_16x16x32_bf16 v[28:31], v[64:67], v[112:115], v[28:31]
	s_waitcnt lgkmcnt(8)
	v_mfma_f32_16x16x32_bf16 v[12:15], v[64:67], v[116:119], v[12:15]
	ds_read_b128 v[84:87], v253 offset:2048
	ds_read_b128 v[88:91], v253 offset:4096
	ds_read_b128 v[92:95], v253 offset:6144
	s_waitcnt lgkmcnt(10)
	v_mfma_f32_16x16x32_bf16 v[56:59], v[68:71], v[104:107], v[56:59]
	v_mfma_f32_16x16x32_bf16 v[40:43], v[68:71], v[108:111], v[40:43]
	v_mfma_f32_16x16x32_bf16 v[20:23], v[68:71], v[112:115], v[20:23]
	v_mfma_f32_16x16x32_bf16 v[4:7], v[68:71], v[116:119], v[4:7]
	s_waitcnt lgkmcnt(9)
	v_mfma_f32_16x16x32_bf16 v[52:55], v[72:75], v[104:107], v[52:55]
	v_mfma_f32_16x16x32_bf16 v[32:35], v[72:75], v[108:111], v[32:35]
	v_mfma_f32_16x16x32_bf16 v[16:19], v[72:75], v[112:115], v[16:19]
	v_mfma_f32_16x16x32_bf16 v[0:3], v[72:75], v[116:119], v[0:3]
	s_waitcnt lgkmcnt(8)
	v_mfma_f32_16x16x32_bf16 v[48:51], v[76:79], v[104:107], v[48:51]
	v_mfma_f32_16x16x32_bf16 v[36:39], v[76:79], v[108:111], v[36:39]
	v_mfma_f32_16x16x32_bf16 v[24:27], v[76:79], v[112:115], v[24:27]
	v_mfma_f32_16x16x32_bf16 v[8:11], v[76:79], v[116:119], v[8:11]
	s_waitcnt lgkmcnt(0)
	s_barrier
	v_mfma_f32_16x16x32_bf16 v[60:63], v[80:83], v[120:123], v[60:63]
	v_mfma_f32_16x16x32_bf16 v[44:47], v[80:83], v[124:127], v[44:47]
	v_mfma_f32_16x16x32_bf16 v[28:31], v[80:83], v[132:135], v[28:31]
	v_mfma_f32_16x16x32_bf16 v[12:15], v[80:83], v[136:139], v[12:15]
	v_mfma_f32_16x16x32_bf16 v[56:59], v[84:87], v[120:123], v[56:59]
	v_mfma_f32_16x16x32_bf16 v[40:43], v[84:87], v[124:127], v[40:43]
	v_mfma_f32_16x16x32_bf16 v[20:23], v[84:87], v[132:135], v[20:23]
	v_mfma_f32_16x16x32_bf16 v[4:7], v[84:87], v[136:139], v[4:7]
	v_mfma_f32_16x16x32_bf16 v[52:55], v[88:91], v[120:123], v[52:55]
	v_mfma_f32_16x16x32_bf16 v[32:35], v[88:91], v[124:127], v[32:35]
	v_mfma_f32_16x16x32_bf16 v[16:19], v[88:91], v[132:135], v[16:19]
	v_mfma_f32_16x16x32_bf16 v[0:3], v[88:91], v[136:139], v[0:3]
	v_mfma_f32_16x16x32_bf16 v[48:51], v[92:95], v[120:123], v[48:51]
	v_mfma_f32_16x16x32_bf16 v[36:39], v[92:95], v[124:127], v[36:39]
	v_mfma_f32_16x16x32_bf16 v[24:27], v[92:95], v[132:135], v[24:27]
	v_mfma_f32_16x16x32_bf16 v[8:11], v[92:95], v[136:139], v[8:11]
	s_waitcnt vmcnt(0)
	s_barrier
	ds_read_b128 v[64:67], v252 offset:16384
	ds_read_b128 v[104:107], v254 offset:49152
	ds_read_b128 v[108:111], v254 offset:51200
	ds_read_b128 v[112:115], v254 offset:53248
	ds_read_b128 v[116:119], v254 offset:55296
	ds_read_b128 v[68:71], v252 offset:18432
	ds_read_b128 v[72:75], v252 offset:20480
	ds_read_b128 v[76:79], v252 offset:22528
	ds_read_b128 v[80:83], v253 offset:16384
	ds_read_b128 v[120:123], v255 offset:49152
	ds_read_b128 v[124:127], v255 offset:51200
	ds_read_b128 v[132:135], v255 offset:53248
	ds_read_b128 v[136:139], v255 offset:55296
	s_waitcnt lgkmcnt(11)
	v_mfma_f32_16x16x32_bf16 v[60:63], v[64:67], v[104:107], v[60:63]
	s_waitcnt lgkmcnt(10)
	v_mfma_f32_16x16x32_bf16 v[44:47], v[64:67], v[108:111], v[44:47]
	s_waitcnt lgkmcnt(9)
	v_mfma_f32_16x16x32_bf16 v[28:31], v[64:67], v[112:115], v[28:31]
	s_waitcnt lgkmcnt(8)
	v_mfma_f32_16x16x32_bf16 v[12:15], v[64:67], v[116:119], v[12:15]
	ds_read_b128 v[84:87], v253 offset:18432
	ds_read_b128 v[88:91], v253 offset:20480
	ds_read_b128 v[92:95], v253 offset:22528
	s_waitcnt lgkmcnt(10)
	v_mfma_f32_16x16x32_bf16 v[56:59], v[68:71], v[104:107], v[56:59]
	v_mfma_f32_16x16x32_bf16 v[40:43], v[68:71], v[108:111], v[40:43]
	v_mfma_f32_16x16x32_bf16 v[20:23], v[68:71], v[112:115], v[20:23]
	v_mfma_f32_16x16x32_bf16 v[4:7], v[68:71], v[116:119], v[4:7]
	s_waitcnt lgkmcnt(9)
	v_mfma_f32_16x16x32_bf16 v[52:55], v[72:75], v[104:107], v[52:55]
	v_mfma_f32_16x16x32_bf16 v[32:35], v[72:75], v[108:111], v[32:35]
	v_mfma_f32_16x16x32_bf16 v[16:19], v[72:75], v[112:115], v[16:19]
	v_mfma_f32_16x16x32_bf16 v[0:3], v[72:75], v[116:119], v[0:3]
	s_waitcnt lgkmcnt(8)
	v_mfma_f32_16x16x32_bf16 v[48:51], v[76:79], v[104:107], v[48:51]
	v_mfma_f32_16x16x32_bf16 v[36:39], v[76:79], v[108:111], v[36:39]
	v_mfma_f32_16x16x32_bf16 v[24:27], v[76:79], v[112:115], v[24:27]
	v_mfma_f32_16x16x32_bf16 v[8:11], v[76:79], v[116:119], v[8:11]
	s_waitcnt lgkmcnt(0)
	s_barrier
	v_mfma_f32_16x16x32_bf16 v[60:63], v[80:83], v[120:123], v[60:63]
	v_mfma_f32_16x16x32_bf16 v[44:47], v[80:83], v[124:127], v[44:47]
	v_mfma_f32_16x16x32_bf16 v[28:31], v[80:83], v[132:135], v[28:31]
	v_mfma_f32_16x16x32_bf16 v[12:15], v[80:83], v[136:139], v[12:15]
	v_mfma_f32_16x16x32_bf16 v[56:59], v[84:87], v[120:123], v[56:59]
	v_mfma_f32_16x16x32_bf16 v[40:43], v[84:87], v[124:127], v[40:43]
	v_mfma_f32_16x16x32_bf16 v[20:23], v[84:87], v[132:135], v[20:23]
	v_mfma_f32_16x16x32_bf16 v[4:7], v[84:87], v[136:139], v[4:7]
	v_mfma_f32_16x16x32_bf16 v[52:55], v[88:91], v[120:123], v[52:55]
	v_mfma_f32_16x16x32_bf16 v[32:35], v[88:91], v[124:127], v[32:35]
	v_mfma_f32_16x16x32_bf16 v[16:19], v[88:91], v[132:135], v[16:19]
	v_mfma_f32_16x16x32_bf16 v[0:3], v[88:91], v[136:139], v[0:3]
	v_mfma_f32_16x16x32_bf16 v[48:51], v[92:95], v[120:123], v[48:51]
	v_mfma_f32_16x16x32_bf16 v[36:39], v[92:95], v[124:127], v[36:39]
	v_mfma_f32_16x16x32_bf16 v[24:27], v[92:95], v[132:135], v[24:27]
	v_mfma_f32_16x16x32_bf16 v[8:11], v[92:95], v[136:139], v[8:11]
	s_nop 7
	s_nop 1
	v_sub_co_u32_e32 v64, vcc, s39, v149
	s_nop 0
	v_readfirstlane_b32 s6, v64
	s_lshr_b32 s6, s6, 10
	s_add_i32 s6, s6, 1
	s_and_b64 s[40:41], vcc, exec
	s_cselect_b32 s6, 0, s6
	s_mul_hi_u32 s31, s6, 0x6000
	s_mulk_i32 s6, 0x6000
	v_or_b32_e32 v64, s30, v147
	s_add_u32 s40, s2, s6
	v_ashrrev_i32_e32 v65, 31, v64
	s_addc_u32 s41, s3, s31
	v_add_lshl_u32 v94, v148, s39, 12
	v_lshlrev_b64 v[66:67], 2, v[64:65]
	v_lshl_add_u64 v[102:103], s[40:41], 0, v[66:67]
	v_lshl_add_u64 v[134:135], s[4:5], 0, v[66:67]
	v_mov_b32_e32 v95, v97
	v_or_b32_e32 v66, 0x1000, v94
	v_mov_b32_e32 v67, v97
	v_lshl_add_u64 v[104:105], v[134:135], 0, v[94:95]
	global_load_dword v65, v[102:103], off
	global_load_dword v150, v[104:105], off
	v_lshl_add_u64 v[106:107], v[134:135], 0, v[66:67]
	v_or_b32_e32 v68, 0x2000, v94
	v_mov_b32_e32 v69, v97
	v_or_b32_e32 v70, 0x3000, v94
	v_mov_b32_e32 v71, v97
	v_or_b32_e32 v72, 0x10000, v94
	v_mov_b32_e32 v73, v97
	global_load_dword v151, v[106:107], off
	v_lshl_add_u64 v[108:109], v[134:135], 0, v[68:69]
	v_lshl_add_u64 v[110:111], v[134:135], 0, v[70:71]
	v_lshl_add_u64 v[112:113], v[134:135], 0, v[72:73]
	v_or_b32_e32 v74, 0x11000, v94
	v_mov_b32_e32 v75, v97
	global_load_dword v152, v[108:109], off
	global_load_dword v153, v[110:111], off
	global_load_dword v154, v[112:113], off
	v_lshl_add_u64 v[114:115], v[134:135], 0, v[74:75]
	v_or_b32_e32 v76, 0x12000, v94
	v_mov_b32_e32 v77, v97
	v_or_b32_e32 v78, 0x13000, v94
	v_mov_b32_e32 v79, v97
	v_or_b32_e32 v80, 0x20000, v94
	v_mov_b32_e32 v81, v97
	global_load_dword v155, v[114:115], off
	v_or_b32_e32 v96, 0x30000, v94
	v_lshl_add_u64 v[116:117], v[134:135], 0, v[76:77]
	v_lshl_add_u64 v[118:119], v[134:135], 0, v[78:79]
	v_lshl_add_u64 v[120:121], v[134:135], 0, v[80:81]
	v_or_b32_e32 v82, 0x21000, v94
	v_mov_b32_e32 v83, v97
	global_load_dword v156, v[116:117], off
	global_load_dword v157, v[118:119], off
	global_load_dword v158, v[120:121], off
	v_lshl_add_u64 v[122:123], v[134:135], 0, v[82:83]
	v_or_b32_e32 v84, 0x22000, v94
	v_mov_b32_e32 v85, v97
	v_or_b32_e32 v86, 0x23000, v94
	v_mov_b32_e32 v87, v97
	v_lshl_add_u64 v[128:129], v[134:135], 0, v[96:97]
	v_lshl_add_u64 v[124:125], v[134:135], 0, v[84:85]
	v_lshl_add_u64 v[126:127], v[134:135], 0, v[86:87]
	global_load_dword v159, v[122:123], off
	global_load_dword v160, v[124:125], off
	global_load_dword v161, v[126:127], off
	global_load_dword v164, v[128:129], off
	v_or_b32_e32 v88, 0x31000, v94
	v_mov_b32_e32 v89, v97
	v_lshl_add_u64 v[130:131], v[134:135], 0, v[88:89]
	v_or_b32_e32 v90, 0x32000, v94
	v_mov_b32_e32 v91, v97
	v_or_b32_e32 v92, 0x33000, v94
	v_mov_b32_e32 v93, v97
	v_lshl_add_u64 v[132:133], v[134:135], 0, v[90:91]
	v_lshl_add_u64 v[134:135], v[134:135], 0, v[92:93]
	global_load_dword v165, v[130:131], off
	global_load_dword v166, v[132:133], off
	global_load_dword v167, v[134:135], off
	v_or_b32_e32 v136, 16, v64
	v_ashrrev_i32_e32 v137, 31, v136
	v_lshlrev_b64 v[136:137], 2, v[136:137]
	v_lshl_add_u64 v[94:95], s[4:5], 0, v[94:95]
	global_load_dword v168, v[102:103], off offset:64
	v_lshl_add_u64 v[140:141], s[4:5], 0, v[136:137]
	v_lshl_add_u64 v[136:137], v[94:95], 0, v[136:137]
	v_add_f32_e32 v60, 0, v60
	v_lshl_add_u64 v[138:139], v[140:141], 0, v[66:67]
	global_load_dword v169, v[136:137], off
	global_load_dword v170, v[138:139], off
	global_load_dword v171, v[102:103], off offset:128
	global_load_dword v172, v[102:103], off offset:192
	v_lshl_add_u64 v[102:103], v[140:141], 0, v[68:69]
	global_load_dword v173, v[102:103], off
	v_add_f32_e32 v56, 0, v56
	v_add_f32_e32 v58, 0, v58
	v_add_f32_e32 v52, 0, v52
	v_add_f32_e32 v48, 0, v48
	v_add_f32_e32 v44, 0, v44
	v_add_f32_e32 v50, 0, v50
	v_add_f32_e32 v32, 0, v32
	v_add_f32_e32 v34, 0, v34
	v_add_f32_e32 v40, 0, v40
	v_add_f32_e32 v38, 0, v38
	v_add_f32_e32 v36, 0, v36
	v_add_f32_e32 v28, 0, v28
	v_add_f32_e32 v30, 0, v30
	v_add_f32_e32 v20, 0, v20
	s_waitcnt vmcnt(21)
	v_fmac_f32_e32 v150, v60, v65
	v_add_f32_e32 v60, 0, v61
	global_store_dword v[104:105], v150, off
	v_lshl_add_u64 v[104:105], v[140:141], 0, v[72:73]
	v_add_f32_e32 v16, 0, v16
	v_add_f32_e32 v0, 0, v0
	v_add_f32_e32 v12, 0, v12
	v_add_f32_e32 v4, 0, v4
	s_waitcnt vmcnt(21)
	v_fmac_f32_e32 v151, v60, v65
	v_add_f32_e32 v60, 0, v62
	v_add_f32_e32 v62, 0, v63
	global_store_dword v[106:107], v151, off
	v_lshl_add_u64 v[106:107], v[140:141], 0, v[76:77]
	global_load_dword v151, v[104:105], off
	s_waitcnt vmcnt(22)
	v_fmac_f32_e32 v152, v60, v65
	global_store_dword v[108:109], v152, off
	s_waitcnt vmcnt(21)
	v_fmac_f32_e32 v154, v56, v65
	v_add_f32_e32 v56, 0, v57
	v_lshl_add_u64 v[108:109], v[140:141], 0, v[80:81]
	v_lshl_add_u64 v[60:61], v[140:141], 0, v[70:71]
	global_store_dword v[112:113], v154, off
	v_add_f32_e32 v112, 0, v59
	v_fmac_f32_e32 v153, v62, v65
	global_store_dword v[110:111], v153, off
	s_waitcnt vmcnt(22)
	v_fmac_f32_e32 v155, v56, v65
	global_store_dword v[114:115], v155, off
	global_load_dword v155, v[108:109], off
	v_lshl_add_u64 v[62:63], v[140:141], 0, v[74:75]
	global_load_dword v150, v[60:61], off
	global_load_dword v153, v[106:107], off
	v_lshl_add_u64 v[110:111], v[140:141], 0, v[82:83]
	s_waitcnt vmcnt(25)
	v_fmac_f32_e32 v156, v58, v65
	v_lshl_add_u64 v[58:59], v[140:141], 0, v[84:85]
	s_waitcnt vmcnt(23)
	v_fmac_f32_e32 v158, v52, v65
	v_add_f32_e32 v52, 0, v53
	global_store_dword v[116:117], v156, off
	global_load_dword v156, v[58:59], off
	v_fmac_f32_e32 v157, v112, v65
	v_lshl_add_u64 v[112:113], v[140:141], 0, v[86:87]
	global_load_dword v175, v[112:113], off
	s_waitcnt vmcnt(25)
	v_fmac_f32_e32 v159, v52, v65
	v_add_f32_e32 v52, 0, v54
	s_waitcnt vmcnt(24)
	v_fmac_f32_e32 v160, v52, v65
	s_waitcnt vmcnt(22)
	v_fmac_f32_e32 v164, v48, v65
	v_add_f32_e32 v48, 0, v49
	v_lshl_add_u64 v[52:53], v[140:141], 0, v[90:91]
	v_lshl_add_u64 v[114:115], v[140:141], 0, v[96:97]
	global_store_dword v[120:121], v158, off
	global_load_dword v120, v[52:53], off
	v_lshl_add_u64 v[56:57], v[140:141], 0, v[78:79]
	global_load_dword v174, v[110:111], off
	global_load_dword v154, v[56:57], off
	s_waitcnt vmcnt(25)
	v_fmac_f32_e32 v165, v48, v65
	v_lshl_add_u64 v[48:49], v[140:141], 0, v[92:93]
	global_load_dword v121, v[48:49], off
	s_waitcnt vmcnt(25)
	v_fmac_f32_e32 v166, v50, v65
	global_store_dword v[118:119], v157, off
	global_load_dword v118, v[114:115], off
	v_add_f32_e32 v50, 0, v51
	global_load_dword v152, v[62:63], off
	s_waitcnt vmcnt(25)
	v_fmac_f32_e32 v169, v44, v168
	v_add_f32_e32 v44, 0, v45
	s_waitcnt vmcnt(24)
	v_fmac_f32_e32 v170, v44, v168
	v_add_f32_e32 v44, 0, v46
	v_add_f32_e32 v54, 0, v55
	s_waitcnt vmcnt(21)
	v_fmac_f32_e32 v173, v44, v168
	v_or_b32_e32 v44, 32, v64
	v_ashrrev_i32_e32 v45, 31, v44
	v_lshlrev_b64 v[44:45], 2, v[44:45]
	v_fmac_f32_e32 v167, v50, v65
	v_lshl_add_u64 v[50:51], v[94:95], 0, v[44:45]
	v_lshl_add_u64 v[44:45], s[4:5], 0, v[44:45]
	v_fmac_f32_e32 v161, v54, v65
	v_lshl_add_u64 v[54:55], v[44:45], 0, v[78:79]
	v_add_f32_e32 v46, 0, v47
	v_lshl_add_u64 v[116:117], v[140:141], 0, v[88:89]
	global_load_dword v119, v[116:117], off
	v_or_b32_e32 v64, 48, v64
	global_store_dword v[102:103], v173, off
	v_ashrrev_i32_e32 v65, 31, v64
	v_lshlrev_b64 v[64:65], 2, v[64:65]
	global_store_dword v[122:123], v159, off
	global_store_dword v[124:125], v160, off
	global_store_dword v[126:127], v161, off
	global_store_dword v[128:129], v164, off
	global_store_dword v[130:131], v165, off
	global_store_dword v[132:133], v166, off
	global_store_dword v[134:135], v167, off
	global_store_dword v[136:137], v169, off
	global_store_dword v[138:139], v170, off
	v_lshl_add_u64 v[94:95], v[94:95], 0, v[64:65]
	v_lshl_add_u64 v[64:65], s[4:5], 0, v[64:65]
	v_add_f32_e32 v21, 0, v21
	s_waitcnt vmcnt(29)
	v_fmac_f32_e32 v151, v40, v168
	v_add_f32_e32 v40, 0, v41
	global_store_dword v[104:105], v151, off
	s_add_i32 s38, s38, s34
	s_cmpk_gt_i32 s38, 0x1ff
	s_waitcnt vmcnt(25)
	v_fmac_f32_e32 v155, v32, v168
	global_store_dword v[108:109], v155, off
	global_load_dword v109, v[54:55], off
	s_waitcnt vmcnt(26)
	v_fmac_f32_e32 v150, v46, v168
	v_lshl_add_u64 v[46:47], v[44:45], 0, v[66:67]
	global_load_dword v102, v[50:51], off
	global_load_dword v103, v[46:47], off
	v_add_f32_e32 v32, 0, v33
	global_store_dword v[60:61], v150, off
	v_lshl_add_u64 v[60:61], v[44:45], 0, v[88:89]
	s_waitcnt vmcnt(26)
	v_fmac_f32_e32 v156, v34, v168
	global_store_dword v[58:59], v156, off
	v_add_f32_e32 v34, 0, v35
	v_add_f32_e32 v58, 0, v39
	s_waitcnt vmcnt(26)
	v_fmac_f32_e32 v175, v34, v168
	global_store_dword v[112:113], v175, off
	v_lshl_add_u64 v[34:35], v[44:45], 0, v[72:73]
	v_lshl_add_u64 v[66:67], v[64:65], 0, v[66:67]
	s_waitcnt vmcnt(25)
	v_fmac_f32_e32 v120, v38, v168
	global_store_dword v[52:53], v120, off
	s_waitcnt vmcnt(25)
	v_fmac_f32_e32 v174, v32, v168
	v_lshl_add_u64 v[52:53], v[44:45], 0, v[82:83]
	global_store_dword v[110:111], v174, off
	v_lshl_add_u64 v[32:33], v[44:45], 0, v[70:71]
	s_waitcnt vmcnt(24)
	v_fmac_f32_e32 v121, v58, v168
	v_lshl_add_u64 v[58:59], v[44:45], 0, v[86:87]
	global_load_dword v113, v[58:59], off
	global_load_dword v111, v[52:53], off
	s_waitcnt vmcnt(24)
	v_fmac_f32_e32 v118, v36, v168
	s_waitcnt vmcnt(23)
	v_fmac_f32_e32 v152, v40, v168
	v_add_f32_e32 v40, 0, v42
	v_add_f32_e32 v42, 0, v43
	v_fmac_f32_e32 v154, v42, v168
	global_store_dword v[56:57], v154, off
	v_lshl_add_u64 v[56:57], v[44:45], 0, v[80:81]
	global_store_dword v[114:115], v118, off
	global_load_dword v110, v[56:57], off
	global_load_dword v105, v[32:33], off
	v_add_f32_e32 v36, 0, v37
	global_load_dword v115, v[60:61], off
	v_fmac_f32_e32 v153, v40, v168
	v_lshl_add_u64 v[40:41], v[44:45], 0, v[68:69]
	global_load_dword v104, v[40:41], off
	v_lshl_add_u64 v[42:43], v[44:45], 0, v[76:77]
	global_store_dword v[106:107], v153, off
	global_load_dword v106, v[34:35], off
	s_waitcnt vmcnt(30)
	v_fmac_f32_e32 v119, v36, v168
	global_store_dword v[48:49], v121, off
	v_lshl_add_u64 v[48:49], v[44:45], 0, v[96:97]
	global_store_dword v[62:63], v152, off
	v_lshl_add_u64 v[36:37], v[44:45], 0, v[74:75]
	global_store_dword v[116:117], v119, off
	v_lshl_add_u64 v[38:39], v[44:45], 0, v[84:85]
	global_load_dword v114, v[48:49], off
	v_lshl_add_u64 v[62:63], v[44:45], 0, v[90:91]
	global_load_dword v107, v[36:37], off
	global_load_dword v108, v[42:43], off
	global_load_dword v112, v[38:39], off
	v_lshl_add_u64 v[44:45], v[44:45], 0, v[92:93]
	global_load_dword v116, v[62:63], off
	global_load_dword v117, v[44:45], off
	v_lshl_add_u64 v[68:69], v[64:65], 0, v[68:69]
	global_load_dword v120, v[68:69], off
	global_load_dword v118, v[94:95], off
	global_load_dword v119, v[66:67], off
	s_waitcnt vmcnt(28)
	v_fmac_f32_e32 v102, v28, v171
	global_store_dword v[50:51], v102, off
	v_lshl_add_u64 v[50:51], v[64:65], 0, v[70:71]
	v_add_f32_e32 v70, 0, v29
	v_lshl_add_u64 v[28:29], v[64:65], 0, v[72:73]
	s_waitcnt vmcnt(28)
	v_fmac_f32_e32 v103, v70, v171
	v_lshl_add_u64 v[70:71], v[64:65], 0, v[74:75]
	v_lshl_add_u64 v[72:73], v[64:65], 0, v[78:79]
	v_lshl_add_u64 v[74:75], v[64:65], 0, v[80:81]
	global_load_dword v122, v[70:71], off
	global_load_dword v123, v[72:73], off
	global_load_dword v124, v[74:75], off
	global_load_dword v102, v[50:51], off
	global_load_dword v121, v[28:29], off
	v_lshl_add_u64 v[78:79], v[64:65], 0, v[88:89]
	global_store_dword v[46:47], v103, off
	v_lshl_add_u64 v[46:47], v[64:65], 0, v[76:77]
	global_load_dword v103, v[46:47], off
	v_add_f32_e32 v76, 0, v31
	v_lshl_add_u64 v[80:81], v[64:65], 0, v[90:91]
	s_waitcnt vmcnt(25)
	v_fmac_f32_e32 v110, v16, v171
	s_waitcnt vmcnt(24)
	v_fmac_f32_e32 v105, v76, v171
	v_lshl_add_u64 v[76:77], v[64:65], 0, v[86:87]
	global_store_dword v[32:33], v105, off
	v_lshl_add_u64 v[32:33], v[64:65], 0, v[96:97]
	global_load_dword v86, v[78:79], off
	s_waitcnt vmcnt(24)
	v_fmac_f32_e32 v104, v30, v171
	global_store_dword v[40:41], v104, off
	v_lshl_add_u64 v[40:41], v[64:65], 0, v[82:83]
	global_load_dword v82, v[40:41], off
	v_lshl_add_u64 v[30:31], v[64:65], 0, v[84:85]
	global_load_dword v83, v[30:31], off
	global_load_dword v85, v[32:33], off
	global_load_dword v84, v[76:77], off
	s_waitcnt vmcnt(27)
	v_fmac_f32_e32 v106, v20, v171
	global_load_dword v20, v[80:81], off
	v_add_f32_e32 v16, 0, v17
	global_store_dword v[34:35], v106, off
	v_lshl_add_u64 v[34:35], v[64:65], 0, v[92:93]
	global_load_dword v64, v[34:35], off
	v_fmac_f32_e32 v111, v16, v171
	v_add_f32_e32 v16, 0, v18
	s_waitcnt vmcnt(23)
	v_fmac_f32_e32 v112, v16, v171
	v_add_f32_e32 v16, 0, v19
	v_fmac_f32_e32 v113, v16, v171
	v_add_f32_e32 v16, 0, v24
	v_fmac_f32_e32 v114, v16, v171
	v_add_f32_e32 v16, 0, v25
	s_waitcnt vmcnt(19)
	v_fmac_f32_e32 v118, v12, v172
	v_add_f32_e32 v12, 0, v13
	v_fmac_f32_e32 v107, v21, v171
	v_add_f32_e32 v21, 0, v22
	v_fmac_f32_e32 v115, v16, v171
	v_add_f32_e32 v16, 0, v26
	s_waitcnt vmcnt(18)
	v_fmac_f32_e32 v119, v12, v172
	v_add_f32_e32 v12, 0, v14
	v_fmac_f32_e32 v108, v21, v171
	v_add_f32_e32 v21, 0, v23
	v_fmac_f32_e32 v116, v16, v171
	v_add_f32_e32 v16, 0, v27
	v_fmac_f32_e32 v120, v12, v172
	v_add_f32_e32 v12, 0, v15
	v_fmac_f32_e32 v109, v21, v171
	v_fmac_f32_e32 v117, v16, v171
	global_store_dword v[36:37], v107, off
	global_store_dword v[42:43], v108, off
	global_store_dword v[54:55], v109, off
	global_store_dword v[56:57], v110, off
	global_store_dword v[52:53], v111, off
	global_store_dword v[38:39], v112, off
	global_store_dword v[58:59], v113, off
	global_store_dword v[48:49], v114, off
	global_store_dword v[60:61], v115, off
	global_store_dword v[62:63], v116, off
	global_store_dword v[44:45], v117, off
	global_store_dword v[94:95], v118, off
	s_waitcnt vmcnt(26)
	v_fmac_f32_e32 v124, v0, v172
	v_add_f32_e32 v0, 0, v1
	s_waitcnt vmcnt(24)
	v_fmac_f32_e32 v121, v4, v172
	v_add_f32_e32 v4, 0, v5
	v_fmac_f32_e32 v122, v4, v172
	v_add_f32_e32 v4, 0, v6
	s_waitcnt vmcnt(22)
	v_fmac_f32_e32 v103, v4, v172
	v_add_f32_e32 v4, 0, v7
	v_fmac_f32_e32 v102, v12, v172
	v_fmac_f32_e32 v123, v4, v172
	global_store_dword v[66:67], v119, off
	global_store_dword v[68:69], v120, off
	global_store_dword v[50:51], v102, off
	global_store_dword v[28:29], v121, off
	global_store_dword v[70:71], v122, off
	global_store_dword v[46:47], v103, off
	global_store_dword v[72:73], v123, off
	global_store_dword v[74:75], v124, off
	s_waitcnt vmcnt(26)
	v_fmac_f32_e32 v82, v0, v172
	v_add_f32_e32 v0, 0, v2
	s_waitcnt vmcnt(25)
	v_fmac_f32_e32 v83, v0, v172
	v_add_f32_e32 v0, 0, v3
	s_waitcnt vmcnt(23)
	v_fmac_f32_e32 v84, v0, v172
	v_add_f32_e32 v0, 0, v8
	v_fmac_f32_e32 v85, v0, v172
	v_add_f32_e32 v0, 0, v9
	v_fmac_f32_e32 v86, v0, v172
	v_add_f32_e32 v0, 0, v10
	s_waitcnt vmcnt(22)
	v_fmac_f32_e32 v20, v0, v172
	v_add_f32_e32 v0, 0, v11
	s_waitcnt vmcnt(20)
	v_fmac_f32_e32 v64, v0, v172
	global_store_dword v[40:41], v82, off
	global_store_dword v[30:31], v83, off
	global_store_dword v[76:77], v84, off
	global_store_dword v[32:33], v85, off
	global_store_dword v[78:79], v86, off
	global_store_dword v[80:81], v20, off
	global_store_dword v[34:35], v64, off
	s_cbranch_scc0 .LBB0_2295

.LBB0_2417:
	s_lshl_b32 s8, s3, 11
	s_and_b32 s8, s8, 0xfc0000
	s_add_i32 s51, s55, s2
	s_cmpk_gt_i32 s51, 0xaff
	v_lshl_add_u64 v[116:117], v[106:107], 0, s[8:9]
	s_cselect_b64 s[26:27], -1, 0
	s_lshl_b32 s8, s51, 18
	s_and_b32 s8, s8, 0xfc0000
	s_add_u32 s8, s4, s8
	s_addc_u32 s59, s5, 0
	s_ashr_i32 s30, s51, 6
	s_ashr_i32 s31, s30, 31
	s_lshl_b64 s[30:31], s[30:31], 18
	s_add_u32 s62, s6, s30
	s_addc_u32 s63, s7, s31
	s_cmpk_lt_i32 s51, 0xb00
	s_cselect_b64 vcc, -1, 0
	s_and_b64 s[30:31], vcc, exec
	s_cselect_b32 s31, s59, 0
	s_cselect_b32 s30, s8, 0
	v_lshl_add_u64 v[2:3], s[30:31], 0, v[108:109]
	v_lshl_add_u64 v[0:1], v[112:113], 0, s[24:25]
	s_cselect_b32 s63, s63, 0
	s_cselect_b32 s62, s62, 0
	v_lshl_add_u64 v[2:3], v[2:3], 0, v[110:111]
	v_cndmask_b32_e32 v131, v1, v3, vcc
	v_cndmask_b32_e32 v96, v0, v2, vcc
	v_lshl_add_u64 v[0:1], s[62:63], 0, v[108:109]
	v_lshl_add_u64 v[0:1], v[0:1], 0, v[110:111]
	v_lshl_add_u64 v[2:3], v[114:115], 0, s[24:25]
	v_cndmask_b32_e32 v130, v2, v0, vcc
	v_mov_b32_e32 v0, 0
	v_lshl_add_u64 v[136:137], v[112:113], 0, s[10:11]
	v_lshl_add_u64 v[118:119], v[112:113], 0, s[12:13]
	v_lshl_add_u64 v[140:141], v[112:113], 0, s[14:15]
	v_lshl_add_u64 v[120:121], v[112:113], 0, s[16:17]
	v_lshl_add_u64 v[142:143], v[112:113], 0, s[18:19]
	v_lshl_add_u64 v[122:123], v[112:113], 0, s[20:21]
	v_lshl_add_u64 v[144:145], v[112:113], 0, s[22:23]
	v_lshl_add_u64 v[138:139], v[114:115], 0, s[10:11]
	v_lshl_add_u64 v[124:125], v[114:115], 0, s[12:13]
	v_lshl_add_u64 v[146:147], v[114:115], 0, s[14:15]
	v_lshl_add_u64 v[126:127], v[114:115], 0, s[16:17]
	v_lshl_add_u64 v[148:149], v[114:115], 0, s[18:19]
	v_lshl_add_u64 v[128:129], v[114:115], 0, s[20:21]
	v_lshl_add_u64 v[150:151], v[114:115], 0, s[22:23]
	v_cndmask_b32_e32 v133, v3, v1, vcc
	v_lshl_add_u64 v[134:135], v[104:105], 0, s[28:29]
	s_mov_b32 s28, -2
	v_mov_b32_e32 v1, v0
	v_mov_b32_e32 v2, v0
	v_mov_b32_e32 v3, v0
	v_mov_b32_e32 v16, v0
	v_mov_b32_e32 v17, v0
	v_mov_b32_e32 v18, v0
	v_mov_b32_e32 v19, v0
	v_mov_b32_e32 v4, v0
	v_mov_b32_e32 v5, v0
	v_mov_b32_e32 v6, v0
	v_mov_b32_e32 v7, v0
	v_mov_b32_e32 v20, v0
	v_mov_b32_e32 v21, v0
	v_mov_b32_e32 v22, v0
	v_mov_b32_e32 v23, v0
	v_mov_b32_e32 v12, v0
	v_mov_b32_e32 v13, v0
	v_mov_b32_e32 v14, v0
	v_mov_b32_e32 v15, v0
	v_mov_b32_e32 v24, v0
	v_mov_b32_e32 v25, v0
	v_mov_b32_e32 v26, v0
	v_mov_b32_e32 v27, v0
	v_mov_b32_e32 v8, v0
	v_mov_b32_e32 v9, v0
	v_mov_b32_e32 v10, v0
	v_mov_b32_e32 v11, v0
	v_mov_b32_e32 v32, v0
	v_mov_b32_e32 v33, v0
	v_mov_b32_e32 v34, v0
	v_mov_b32_e32 v35, v0
	v_mov_b32_e32 v64, v0
	v_mov_b32_e32 v65, v0
	v_mov_b32_e32 v66, v0
	v_mov_b32_e32 v67, v0
	v_mov_b32_e32 v72, v0
	v_mov_b32_e32 v73, v0
	v_mov_b32_e32 v74, v0
	v_mov_b32_e32 v75, v0
	v_mov_b32_e32 v68, v0
	v_mov_b32_e32 v69, v0
	v_mov_b32_e32 v70, v0
	v_mov_b32_e32 v71, v0
	v_mov_b32_e32 v76, v0
	v_mov_b32_e32 v77, v0
	v_mov_b32_e32 v78, v0
	v_mov_b32_e32 v79, v0
	v_mov_b32_e32 v80, v0
	v_mov_b32_e32 v81, v0
	v_mov_b32_e32 v82, v0
	v_mov_b32_e32 v83, v0
	v_mov_b32_e32 v88, v0
	v_mov_b32_e32 v89, v0
	v_mov_b32_e32 v90, v0
	v_mov_b32_e32 v91, v0
	v_mov_b32_e32 v84, v0
	v_mov_b32_e32 v85, v0
	v_mov_b32_e32 v86, v0
	v_mov_b32_e32 v87, v0
	v_mov_b32_e32 v92, v0
	v_mov_b32_e32 v93, v0
	v_mov_b32_e32 v94, v0
	v_mov_b32_e32 v95, v0
	v_readfirstlane_b32 s30, v112
	v_readfirstlane_b32 s31, v113
	v_readfirstlane_b32 s62, v114
	v_readfirstlane_b32 s63, v115
	v_readfirstlane_b32 s8, v247
	s_nop 3
	s_mul_i32 s59, s8, 0x4000
	s_sub_u32 s30, s30, s59
	s_subb_u32 s31, s31, 0
	s_sub_u32 s62, s62, s59
	s_subb_u32 s63, s63, 0
	s_lshl_b32 s8, s8, 12
	s_cmp_eq_u32 s55, s58
	s_cbranch_scc1 .Lg24_first
	v_mov_b32_e32 v92, 0
	v_mov_b32_e32 v93, 0
	v_mov_b32_e32 v94, 0
	v_mov_b32_e32 v95, 0
	v_mov_b32_e32 v84, 0
	v_mov_b32_e32 v85, 0
	v_mov_b32_e32 v86, 0
	v_mov_b32_e32 v87, 0
	v_mov_b32_e32 v88, 0
	v_mov_b32_e32 v89, 0
	v_mov_b32_e32 v90, 0
	v_mov_b32_e32 v91, 0
	v_mov_b32_e32 v80, 0
	v_mov_b32_e32 v81, 0
	v_mov_b32_e32 v82, 0
	v_mov_b32_e32 v83, 0
	v_mov_b32_e32 v76, 0
	v_mov_b32_e32 v77, 0
	v_mov_b32_e32 v78, 0
	v_mov_b32_e32 v79, 0
	v_mov_b32_e32 v68, 0
	v_mov_b32_e32 v69, 0
	v_mov_b32_e32 v70, 0
	v_mov_b32_e32 v71, 0
	v_mov_b32_e32 v72, 0
	v_mov_b32_e32 v73, 0
	v_mov_b32_e32 v74, 0
	v_mov_b32_e32 v75, 0
	v_mov_b32_e32 v64, 0
	v_mov_b32_e32 v65, 0
	v_mov_b32_e32 v66, 0
	v_mov_b32_e32 v67, 0
	v_mov_b32_e32 v32, 0
	v_mov_b32_e32 v33, 0
	v_mov_b32_e32 v34, 0
	v_mov_b32_e32 v35, 0
	v_mov_b32_e32 v8, 0
	v_mov_b32_e32 v9, 0
	v_mov_b32_e32 v10, 0
	v_mov_b32_e32 v11, 0
	v_mov_b32_e32 v24, 0
	v_mov_b32_e32 v25, 0
	v_mov_b32_e32 v26, 0
	v_mov_b32_e32 v27, 0
	v_mov_b32_e32 v12, 0
	v_mov_b32_e32 v13, 0
	v_mov_b32_e32 v14, 0
	v_mov_b32_e32 v15, 0
	v_mov_b32_e32 v20, 0
	v_mov_b32_e32 v21, 0
	v_mov_b32_e32 v22, 0
	v_mov_b32_e32 v23, 0
	v_mov_b32_e32 v4, 0
	v_mov_b32_e32 v5, 0
	v_mov_b32_e32 v6, 0
	v_mov_b32_e32 v7, 0
	v_mov_b32_e32 v16, 0
	v_mov_b32_e32 v17, 0
	v_mov_b32_e32 v18, 0
	v_mov_b32_e32 v19, 0
	v_mov_b32_e32 v0, 0
	v_mov_b32_e32 v1, 0
	v_mov_b32_e32 v2, 0
	v_mov_b32_e32 v3, 0
	s_add_u32 s30, s30, 0x100
	s_addc_u32 s31, s31, 0
	s_add_u32 s62, s62, 0x100
	s_addc_u32 s63, s63, 0
	s_waitcnt vmcnt(40)
	s_barrier
	ds_read_b128 v[28:31], v252 offset:0
	ds_read_b128 v[112:115], v254 offset:32768
	ds_read_b128 v[116:119], v254 offset:34816
	ds_read_b128 v[120:123], v254 offset:36864
	ds_read_b128 v[124:127], v254 offset:38912
	ds_read_b128 v[36:39], v252 offset:2048
	ds_read_b128 v[40:43], v252 offset:4096
	ds_read_b128 v[44:47], v252 offset:6144
	ds_read_b128 v[48:51], v253 offset:0
	ds_read_b128 v[132:135], v255 offset:32768
	ds_read_b128 v[136:139], v255 offset:34816
	ds_read_b128 v[140:143], v255 offset:36864
	ds_read_b128 v[144:147], v255 offset:38912
	s_waitcnt lgkmcnt(11)
	v_mfma_f32_16x16x32_bf16 v[92:95], v[28:31], v[112:115], v[92:95]
	s_waitcnt lgkmcnt(10)
	v_mfma_f32_16x16x32_bf16 v[84:87], v[28:31], v[116:119], v[84:87]
	s_waitcnt lgkmcnt(9)
	v_mfma_f32_16x16x32_bf16 v[88:91], v[28:31], v[120:123], v[88:91]
	s_waitcnt lgkmcnt(8)
	v_mfma_f32_16x16x32_bf16 v[80:83], v[28:31], v[124:127], v[80:83]
	ds_read_b128 v[52:55], v253 offset:2048
	ds_read_b128 v[56:59], v253 offset:4096
	ds_read_b128 v[60:63], v253 offset:6144
	s_waitcnt lgkmcnt(10)
	v_mfma_f32_16x16x32_bf16 v[76:79], v[36:39], v[112:115], v[76:79]
	v_mfma_f32_16x16x32_bf16 v[68:71], v[36:39], v[116:119], v[68:71]
	v_mfma_f32_16x16x32_bf16 v[72:75], v[36:39], v[120:123], v[72:75]
	v_mfma_f32_16x16x32_bf16 v[64:67], v[36:39], v[124:127], v[64:67]
	s_waitcnt lgkmcnt(9)
	v_mfma_f32_16x16x32_bf16 v[32:35], v[40:43], v[112:115], v[32:35]
	v_mfma_f32_16x16x32_bf16 v[8:11], v[40:43], v[116:119], v[8:11]
	v_mfma_f32_16x16x32_bf16 v[24:27], v[40:43], v[120:123], v[24:27]
	v_mfma_f32_16x16x32_bf16 v[12:15], v[40:43], v[124:127], v[12:15]
	s_waitcnt lgkmcnt(8)
	v_mfma_f32_16x16x32_bf16 v[20:23], v[44:47], v[112:115], v[20:23]
	v_mfma_f32_16x16x32_bf16 v[4:7], v[44:47], v[116:119], v[4:7]
	v_mfma_f32_16x16x32_bf16 v[16:19], v[44:47], v[120:123], v[16:19]
	v_mfma_f32_16x16x32_bf16 v[0:3], v[44:47], v[124:127], v[0:3]
	s_waitcnt lgkmcnt(0)
	s_barrier
	s_add_u32 m0, s8, 0x0
	v_mfma_f32_16x16x32_bf16 v[92:95], v[48:51], v[132:135], v[92:95]
	global_load_lds_dwordx4 v248, s[30:31]
	v_mfma_f32_16x16x32_bf16 v[84:87], v[48:51], v[136:139], v[84:87]
	s_add_u32 m0, s8, 0x400
	v_mfma_f32_16x16x32_bf16 v[88:91], v[48:51], v[140:143], v[88:91]
	global_load_lds_dwordx4 v249, s[30:31]
	v_mfma_f32_16x16x32_bf16 v[80:83], v[48:51], v[144:147], v[80:83]
	s_add_u32 m0, s8, 0x800
	v_mfma_f32_16x16x32_bf16 v[76:79], v[52:55], v[132:135], v[76:79]
	global_load_lds_dwordx4 v250, s[30:31]
	v_mfma_f32_16x16x32_bf16 v[68:71], v[52:55], v[136:139], v[68:71]
	s_add_u32 m0, s8, 0xc00
	v_mfma_f32_16x16x32_bf16 v[72:75], v[52:55], v[140:143], v[72:75]
	global_load_lds_dwordx4 v251, s[30:31]
	v_mfma_f32_16x16x32_bf16 v[64:67], v[52:55], v[144:147], v[64:67]
	s_add_u32 m0, s8, 0x8000
	v_mfma_f32_16x16x32_bf16 v[32:35], v[56:59], v[132:135], v[32:35]
	global_load_lds_dwordx4 v248, s[62:63]
	v_mfma_f32_16x16x32_bf16 v[8:11], v[56:59], v[136:139], v[8:11]
	s_add_u32 m0, s8, 0x8400
	v_mfma_f32_16x16x32_bf16 v[24:27], v[56:59], v[140:143], v[24:27]
	global_load_lds_dwordx4 v249, s[62:63]
	v_mfma_f32_16x16x32_bf16 v[12:15], v[56:59], v[144:147], v[12:15]
	s_add_u32 m0, s8, 0x8800
	v_mfma_f32_16x16x32_bf16 v[20:23], v[60:63], v[132:135], v[20:23]
	global_load_lds_dwordx4 v250, s[62:63]
	v_mfma_f32_16x16x32_bf16 v[4:7], v[60:63], v[136:139], v[4:7]
	s_add_u32 m0, s8, 0x8c00
	v_mfma_f32_16x16x32_bf16 v[16:19], v[60:63], v[140:143], v[16:19]
	global_load_lds_dwordx4 v251, s[62:63]
	v_mfma_f32_16x16x32_bf16 v[0:3], v[60:63], v[144:147], v[0:3]
	s_add_u32 s30, s30, 0x80
	s_addc_u32 s31, s31, 0
	s_add_u32 s62, s62, 0x80
	s_addc_u32 s63, s63, 0
	s_waitcnt vmcnt(40)
	s_barrier
	ds_read_b128 v[28:31], v252 offset:16384
	ds_read_b128 v[112:115], v254 offset:49152
	ds_read_b128 v[116:119], v254 offset:51200
	ds_read_b128 v[120:123], v254 offset:53248
	ds_read_b128 v[124:127], v254 offset:55296
	ds_read_b128 v[36:39], v252 offset:18432
	ds_read_b128 v[40:43], v252 offset:20480
	ds_read_b128 v[44:47], v252 offset:22528
	ds_read_b128 v[48:51], v253 offset:16384
	ds_read_b128 v[132:135], v255 offset:49152
	ds_read_b128 v[136:139], v255 offset:51200
	ds_read_b128 v[140:143], v255 offset:53248
	ds_read_b128 v[144:147], v255 offset:55296
	s_waitcnt lgkmcnt(11)
	v_mfma_f32_16x16x32_bf16 v[92:95], v[28:31], v[112:115], v[92:95]
	s_waitcnt lgkmcnt(10)
	v_mfma_f32_16x16x32_bf16 v[84:87], v[28:31], v[116:119], v[84:87]
	s_waitcnt lgkmcnt(9)
	v_mfma_f32_16x16x32_bf16 v[88:91], v[28:31], v[120:123], v[88:91]
	s_waitcnt lgkmcnt(8)
	v_mfma_f32_16x16x32_bf16 v[80:83], v[28:31], v[124:127], v[80:83]
	ds_read_b128 v[52:55], v253 offset:18432
	ds_read_b128 v[56:59], v253 offset:20480
	ds_read_b128 v[60:63], v253 offset:22528
	s_waitcnt lgkmcnt(10)
	v_mfma_f32_16x16x32_bf16 v[76:79], v[36:39], v[112:115], v[76:79]
	v_mfma_f32_16x16x32_bf16 v[68:71], v[36:39], v[116:119], v[68:71]
	v_mfma_f32_16x16x32_bf16 v[72:75], v[36:39], v[120:123], v[72:75]
	v_mfma_f32_16x16x32_bf16 v[64:67], v[36:39], v[124:127], v[64:67]
	s_waitcnt lgkmcnt(9)
	v_mfma_f32_16x16x32_bf16 v[32:35], v[40:43], v[112:115], v[32:35]
	v_mfma_f32_16x16x32_bf16 v[8:11], v[40:43], v[116:119], v[8:11]
	v_mfma_f32_16x16x32_bf16 v[24:27], v[40:43], v[120:123], v[24:27]
	v_mfma_f32_16x16x32_bf16 v[12:15], v[40:43], v[124:127], v[12:15]
	s_waitcnt lgkmcnt(8)
	v_mfma_f32_16x16x32_bf16 v[20:23], v[44:47], v[112:115], v[20:23]
	v_mfma_f32_16x16x32_bf16 v[4:7], v[44:47], v[116:119], v[4:7]
	v_mfma_f32_16x16x32_bf16 v[16:19], v[44:47], v[120:123], v[16:19]
	v_mfma_f32_16x16x32_bf16 v[0:3], v[44:47], v[124:127], v[0:3]
	s_waitcnt lgkmcnt(0)
	s_barrier
	s_add_u32 m0, s8, 0x4000
	v_mfma_f32_16x16x32_bf16 v[92:95], v[48:51], v[132:135], v[92:95]
	global_load_lds_dwordx4 v248, s[30:31]
	v_mfma_f32_16x16x32_bf16 v[84:87], v[48:51], v[136:139], v[84:87]
	s_add_u32 m0, s8, 0x4400
	v_mfma_f32_16x16x32_bf16 v[88:91], v[48:51], v[140:143], v[88:91]
	global_load_lds_dwordx4 v249, s[30:31]
	v_mfma_f32_16x16x32_bf16 v[80:83], v[48:51], v[144:147], v[80:83]
	s_add_u32 m0, s8, 0x4800
	v_mfma_f32_16x16x32_bf16 v[76:79], v[52:55], v[132:135], v[76:79]
	global_load_lds_dwordx4 v250, s[30:31]
	v_mfma_f32_16x16x32_bf16 v[68:71], v[52:55], v[136:139], v[68:71]
	s_add_u32 m0, s8, 0x4c00
	v_mfma_f32_16x16x32_bf16 v[72:75], v[52:55], v[140:143], v[72:75]
	global_load_lds_dwordx4 v251, s[30:31]
	v_mfma_f32_16x16x32_bf16 v[64:67], v[52:55], v[144:147], v[64:67]
	s_add_u32 m0, s8, 0xc000
	v_mfma_f32_16x16x32_bf16 v[32:35], v[56:59], v[132:135], v[32:35]
	global_load_lds_dwordx4 v248, s[62:63]
	v_mfma_f32_16x16x32_bf16 v[8:11], v[56:59], v[136:139], v[8:11]
	s_add_u32 m0, s8, 0xc400
	v_mfma_f32_16x16x32_bf16 v[24:27], v[56:59], v[140:143], v[24:27]
	global_load_lds_dwordx4 v249, s[62:63]
	v_mfma_f32_16x16x32_bf16 v[12:15], v[56:59], v[144:147], v[12:15]
	s_add_u32 m0, s8, 0xc800
	v_mfma_f32_16x16x32_bf16 v[20:23], v[60:63], v[132:135], v[20:23]
	global_load_lds_dwordx4 v250, s[62:63]
	v_mfma_f32_16x16x32_bf16 v[4:7], v[60:63], v[136:139], v[4:7]
	s_add_u32 m0, s8, 0xcc00
	v_mfma_f32_16x16x32_bf16 v[16:19], v[60:63], v[140:143], v[16:19]
	global_load_lds_dwordx4 v251, s[62:63]
	v_mfma_f32_16x16x32_bf16 v[0:3], v[60:63], v[144:147], v[0:3]
	s_add_u32 s30, s30, 0x80
	s_addc_u32 s31, s31, 0
	s_add_u32 s62, s62, 0x80
	s_addc_u32 s63, s63, 0
	s_branch .Lg24_main

.Lg24_done:
	s_nop 7
	s_nop 1
	v_mul_f32_e32 v28, 0xbfb8aa3b, v92
	v_exp_f32_e32 v30, v28
	v_mul_f32_e32 v36, 0xbfb8aa3b, v93
	v_exp_f32_e32 v36, v36
	s_and_b32 s8, s55, 0xffffffc0
	v_add_f32_e32 v30, 1.0, v30
	v_rcp_f32_e32 v30, v30
	v_add_f32_e32 v36, 1.0, v36
	v_or_b32_e32 v28, s8, v156
	v_rcp_f32_e32 v36, v36
	v_add_u32_e32 v31, s54, v157
	v_ashrrev_i32_e32 v29, 31, v28
	v_mul_f32_e32 v30, v92, v30
	v_lshl_add_u64 v[28:29], v[28:29], 1, v[102:103]
	v_mul_f32_e32 v30, v88, v30
	v_mul_u32_u24_e32 v96, 0x1600, v31
	v_cvt_pk_bf16_f32 v30, v30, s0
	v_lshl_add_u64 v[28:29], v[28:29], 0, v[96:97]
	global_store_short v[28:29], v30, off
	v_mul_f32_e32 v30, v93, v36
	v_mul_f32_e32 v30, v89, v30
	v_cvt_pk_bf16_f32 v36, v30, s0
	v_mul_f32_e32 v30, 0xbfb8aa3b, v94
	v_exp_f32_e32 v37, v30
	v_add_co_u32_e32 v30, vcc, s37, v28
	s_add_i32 s3, s3, s34
	s_nop 0
	v_addc_co_u32_e32 v31, vcc, 0, v29, vcc
	global_store_short v[30:31], v36, off offset:1536
	v_mul_f32_e32 v36, 0xbfb8aa3b, v95
	v_exp_f32_e32 v36, v36
	v_add_f32_e32 v37, 1.0, v37
	v_rcp_f32_e32 v37, v37
	s_mov_b64 s[30:31], -1
	v_add_f32_e32 v36, 1.0, v36
	v_rcp_f32_e32 v39, v36
	v_mul_f32_e32 v37, v94, v37
	v_mul_f32_e32 v37, v90, v37
	v_add_co_u32_e32 v36, vcc, s38, v28
	v_cvt_pk_bf16_f32 v38, v37, s0
	s_nop 0
	v_addc_co_u32_e32 v37, vcc, 0, v29, vcc
	global_store_short v[36:37], v38, off offset:3072
	v_mul_f32_e32 v38, v95, v39
	v_mul_f32_e32 v38, v91, v38
	v_cvt_pk_bf16_f32 v40, v38, s0
	v_mul_f32_e32 v38, 0xbfb8aa3b, v84
	v_exp_f32_e32 v41, v38
	v_add_co_u32_e32 v38, vcc, s39, v28
	s_mov_b32 s55, s51
	s_nop 0
	v_addc_co_u32_e32 v39, vcc, 0, v29, vcc
	global_store_short v[38:39], v40, off offset:512
	v_mul_f32_e32 v40, 0xbfb8aa3b, v85
	v_exp_f32_e32 v40, v40
	v_add_f32_e32 v41, 1.0, v41
	v_rcp_f32_e32 v41, v41
	v_add_f32_e32 v40, 1.0, v40
	v_rcp_f32_e32 v40, v40
	v_mul_f32_e32 v41, v84, v41
	v_mul_f32_e32 v41, v80, v41
	v_cvt_pk_bf16_f32 v41, v41, s0
	global_store_short v[28:29], v41, off offset:32
	v_mul_f32_e32 v41, 0xbfb8aa3b, v86
	v_mul_f32_e32 v40, v85, v40
	v_exp_f32_e32 v41, v41
	v_mul_f32_e32 v40, v81, v40
	v_cvt_pk_bf16_f32 v40, v40, s0
	global_store_short v[30:31], v40, off offset:1568
	v_mul_f32_e32 v30, 0xbfb8aa3b, v87
	v_exp_f32_e32 v30, v30
	v_add_f32_e32 v41, 1.0, v41
	v_rcp_f32_e32 v41, v41
	v_add_f32_e32 v30, 1.0, v30
	v_rcp_f32_e32 v30, v30
	v_mul_f32_e32 v31, v86, v41
	v_mul_f32_e32 v31, v82, v31
	v_cvt_pk_bf16_f32 v31, v31, s0
	global_store_short v[36:37], v31, off offset:3104
	v_mul_f32_e32 v31, 0xbfb8aa3b, v76
	v_mul_f32_e32 v30, v87, v30
	v_exp_f32_e32 v31, v31
	v_mul_f32_e32 v30, v83, v30
	v_cvt_pk_bf16_f32 v30, v30, s0
	global_store_short v[38:39], v30, off offset:544
	v_mul_f32_e32 v30, 0xbfb8aa3b, v77
	v_exp_f32_e32 v30, v30
	v_add_f32_e32 v31, 1.0, v31
	v_rcp_f32_e32 v31, v31
	v_add_f32_e32 v30, 1.0, v30
	v_rcp_f32_e32 v37, v30
	v_mul_f32_e32 v31, v76, v31
	v_mul_f32_e32 v31, v72, v31
	v_add_co_u32_e32 v30, vcc, s40, v28
	v_cvt_pk_bf16_f32 v36, v31, s0
	s_nop 0
	v_addc_co_u32_e32 v31, vcc, 0, v29, vcc
	global_store_short v[30:31], v36, off
	v_mul_f32_e32 v36, v77, v37
	v_mul_f32_e32 v36, v73, v36
	v_cvt_pk_bf16_f32 v38, v36, s0
	v_mul_f32_e32 v36, 0xbfb8aa3b, v78
	v_exp_f32_e32 v39, v36
	v_add_co_u32_e32 v36, vcc, s41, v28
	v_add_f32_e32 v39, 1.0, v39
	s_nop 0
	v_addc_co_u32_e32 v37, vcc, 0, v29, vcc
	global_store_short v[36:37], v38, off offset:1536
	v_mul_f32_e32 v38, 0xbfb8aa3b, v79
	v_exp_f32_e32 v38, v38
	v_rcp_f32_e32 v39, v39
	v_add_f32_e32 v38, 1.0, v38
	v_rcp_f32_e32 v41, v38
	v_mul_f32_e32 v39, v78, v39
	v_mul_f32_e32 v39, v74, v39
	v_add_co_u32_e32 v38, vcc, s42, v28
	v_cvt_pk_bf16_f32 v40, v39, s0
	s_nop 0
	v_addc_co_u32_e32 v39, vcc, 0, v29, vcc
	global_store_short v[38:39], v40, off offset:3072
	v_mul_f32_e32 v40, v79, v41
	v_mul_f32_e32 v40, v75, v40
	v_cvt_pk_bf16_f32 v42, v40, s0
	v_mul_f32_e32 v40, 0xbfb8aa3b, v68
	v_exp_f32_e32 v43, v40
	v_add_co_u32_e32 v40, vcc, s43, v28
	v_add_f32_e32 v43, 1.0, v43
	s_nop 0
	v_addc_co_u32_e32 v41, vcc, 0, v29, vcc
	v_rcp_f32_e32 v43, v43
	global_store_short v[40:41], v42, off offset:512
	v_mul_f32_e32 v42, 0xbfb8aa3b, v69
	v_exp_f32_e32 v42, v42
	v_mul_f32_e32 v43, v68, v43
	v_mul_f32_e32 v43, v64, v43
	v_cvt_pk_bf16_f32 v43, v43, s0
	v_add_f32_e32 v42, 1.0, v42
	v_rcp_f32_e32 v42, v42
	global_store_short v[30:31], v43, off offset:32
	v_mul_f32_e32 v30, 0xbfb8aa3b, v70
	v_exp_f32_e32 v30, v30
	v_mul_f32_e32 v31, v69, v42
	v_mul_f32_e32 v31, v65, v31
	v_cvt_pk_bf16_f32 v31, v31, s0
	v_add_f32_e32 v30, 1.0, v30
	v_rcp_f32_e32 v30, v30
	global_store_short v[36:37], v31, off offset:1568
	v_mul_f32_e32 v31, 0xbfb8aa3b, v71
	v_exp_f32_e32 v31, v31
	v_mul_f32_e32 v30, v70, v30
	v_mul_f32_e32 v30, v66, v30
	v_cvt_pk_bf16_f32 v30, v30, s0
	v_add_f32_e32 v31, 1.0, v31
	v_rcp_f32_e32 v31, v31
	global_store_short v[38:39], v30, off offset:3104
	v_mul_f32_e32 v30, 0xbfb8aa3b, v32
	v_exp_f32_e32 v30, v30
	v_mul_f32_e32 v31, v71, v31
	v_mul_f32_e32 v31, v67, v31
	v_cvt_pk_bf16_f32 v31, v31, s0
	v_add_f32_e32 v30, 1.0, v30
	v_rcp_f32_e32 v30, v30
	global_store_short v[40:41], v31, off offset:544
	v_mul_f32_e32 v31, 0xbfb8aa3b, v33
	v_exp_f32_e32 v31, v31
	v_mul_f32_e32 v30, v32, v30
	v_mul_f32_e32 v24, v24, v30
	v_cvt_pk_bf16_f32 v24, v24, s0
	v_add_f32_e32 v30, 1.0, v31
	v_rcp_f32_e32 v32, v30
	v_add_co_u32_e32 v30, vcc, s44, v28
	s_nop 1
	v_addc_co_u32_e32 v31, vcc, 0, v29, vcc
	global_store_short v[30:31], v24, off
	v_mul_f32_e32 v24, v33, v32
	v_mul_f32_e32 v24, v25, v24
	v_cvt_pk_bf16_f32 v32, v24, s0
	v_mul_f32_e32 v24, 0xbfb8aa3b, v34
	v_exp_f32_e32 v33, v24
	v_add_co_u32_e32 v24, vcc, s45, v28
	v_add_f32_e32 v33, 1.0, v33
	s_nop 0
	v_addc_co_u32_e32 v25, vcc, 0, v29, vcc
	global_store_short v[24:25], v32, off offset:1536
	v_mul_f32_e32 v32, 0xbfb8aa3b, v35
	v_exp_f32_e32 v32, v32
	v_rcp_f32_e32 v33, v33
	v_add_f32_e32 v32, 1.0, v32
	v_mul_f32_e32 v33, v34, v33
	v_rcp_f32_e32 v34, v32
	v_mul_f32_e32 v26, v26, v33
	v_add_co_u32_e32 v32, vcc, s46, v28
	v_cvt_pk_bf16_f32 v26, v26, s0
	s_nop 0
	v_addc_co_u32_e32 v33, vcc, 0, v29, vcc
	global_store_short v[32:33], v26, off offset:3072
	v_mul_f32_e32 v26, v35, v34
	v_mul_f32_e32 v26, v27, v26
	v_cvt_pk_bf16_f32 v34, v26, s0
	v_mul_f32_e32 v26, 0xbfb8aa3b, v8
	v_exp_f32_e32 v35, v26
	v_add_co_u32_e32 v26, vcc, s36, v28
	v_add_f32_e32 v35, 1.0, v35
	s_nop 0
	v_addc_co_u32_e32 v27, vcc, 0, v29, vcc
	v_rcp_f32_e32 v35, v35
	global_store_short v[26:27], v34, off offset:512
	v_mul_f32_e32 v34, 0xbfb8aa3b, v9
	v_exp_f32_e32 v34, v34
	v_mul_f32_e32 v8, v8, v35
	v_mul_f32_e32 v8, v12, v8
	v_cvt_pk_bf16_f32 v8, v8, s0
	v_add_f32_e32 v12, 1.0, v34
	v_rcp_f32_e32 v12, v12
	global_store_short v[30:31], v8, off offset:32
	v_mul_f32_e32 v8, 0xbfb8aa3b, v10
	v_exp_f32_e32 v8, v8
	v_mul_f32_e32 v9, v9, v12
	v_mul_f32_e32 v9, v13, v9
	v_cvt_pk_bf16_f32 v9, v9, s0
	v_add_f32_e32 v8, 1.0, v8
	v_rcp_f32_e32 v8, v8
	global_store_short v[24:25], v9, off offset:1568
	v_mul_f32_e32 v9, 0xbfb8aa3b, v11
	v_exp_f32_e32 v9, v9
	v_mul_f32_e32 v8, v10, v8
	v_mul_f32_e32 v8, v14, v8
	v_cvt_pk_bf16_f32 v8, v8, s0
	v_add_f32_e32 v9, 1.0, v9
	v_rcp_f32_e32 v9, v9
	global_store_short v[32:33], v8, off offset:3104
	v_mul_f32_e32 v8, 0xbfb8aa3b, v20
	v_exp_f32_e32 v8, v8
	v_mul_f32_e32 v9, v11, v9
	v_mul_f32_e32 v9, v15, v9
	v_cvt_pk_bf16_f32 v9, v9, s0
	v_add_f32_e32 v8, 1.0, v8
	v_rcp_f32_e32 v8, v8
	global_store_short v[26:27], v9, off offset:544
	v_mul_f32_e32 v9, 0xbfb8aa3b, v21
	v_exp_f32_e32 v9, v9
	v_mul_f32_e32 v8, v20, v8
	v_mul_f32_e32 v8, v16, v8
	v_cvt_pk_bf16_f32 v10, v8, s0
	v_add_f32_e32 v8, 1.0, v9
	v_rcp_f32_e32 v11, v8
	v_add_co_u32_e32 v8, vcc, s47, v28
	s_nop 1
	v_addc_co_u32_e32 v9, vcc, 0, v29, vcc
	global_store_short v[8:9], v10, off
	v_mul_f32_e32 v10, v21, v11
	v_mul_f32_e32 v10, v17, v10
	v_cvt_pk_bf16_f32 v12, v10, s0
	v_mul_f32_e32 v10, 0xbfb8aa3b, v22
	v_exp_f32_e32 v13, v10
	v_add_co_u32_e32 v10, vcc, s48, v28
	v_add_f32_e32 v13, 1.0, v13
	s_nop 0
	v_addc_co_u32_e32 v11, vcc, 0, v29, vcc
	global_store_short v[10:11], v12, off offset:1536
	v_mul_f32_e32 v12, 0xbfb8aa3b, v23
	v_exp_f32_e32 v12, v12
	v_rcp_f32_e32 v13, v13
	v_add_f32_e32 v12, 1.0, v12
	v_rcp_f32_e32 v15, v12
	v_mul_f32_e32 v13, v22, v13
	v_mul_f32_e32 v13, v18, v13
	v_add_co_u32_e32 v12, vcc, s49, v28
	v_cvt_pk_bf16_f32 v14, v13, s0
	s_nop 0
	v_addc_co_u32_e32 v13, vcc, 0, v29, vcc
	global_store_short v[12:13], v14, off offset:3072
	v_mul_f32_e32 v14, v23, v15
	v_mul_f32_e32 v14, v19, v14
	v_cvt_pk_bf16_f32 v16, v14, s0
	v_mul_f32_e32 v14, 0xbfb8aa3b, v4
	v_exp_f32_e32 v17, v14
	v_add_co_u32_e32 v14, vcc, s50, v28
	v_add_f32_e32 v17, 1.0, v17
	s_nop 0
	v_addc_co_u32_e32 v15, vcc, 0, v29, vcc
	v_rcp_f32_e32 v17, v17
	global_store_short v[14:15], v16, off offset:512
	v_mul_f32_e32 v16, 0xbfb8aa3b, v5
	v_exp_f32_e32 v16, v16
	v_mul_f32_e32 v4, v4, v17
	v_mul_f32_e32 v0, v0, v4
	v_cvt_pk_bf16_f32 v0, v0, s0
	v_add_f32_e32 v4, 1.0, v16
	v_rcp_f32_e32 v4, v4
	v_mul_f32_e32 v16, 0xbfb8aa3b, v6
	v_exp_f32_e32 v16, v16
	global_store_short v[8:9], v0, off offset:32
	v_mul_f32_e32 v0, v5, v4
	v_mul_f32_e32 v0, v1, v0
	v_add_f32_e32 v1, 1.0, v16
	v_mul_f32_e32 v4, 0xbfb8aa3b, v7
	v_rcp_f32_e32 v1, v1
	v_exp_f32_e32 v4, v4
	v_cvt_pk_bf16_f32 v0, v0, s0
	global_store_short v[10:11], v0, off offset:1568
	v_mul_f32_e32 v0, v6, v1
	v_add_f32_e32 v1, 1.0, v4
	v_rcp_f32_e32 v1, v1
	v_mul_f32_e32 v0, v2, v0
	v_cvt_pk_bf16_f32 v0, v0, s0
	global_store_short v[12:13], v0, off offset:3104
	v_mul_f32_e32 v0, v7, v1
	v_mul_f32_e32 v0, v3, v0
	v_cvt_pk_bf16_f32 v0, v0, s0
	s_andn2_b64 vcc, exec, s[26:27]
	global_store_short v[14:15], v0, off offset:544
	s_cbranch_vccnz .LBB0_2413

.Lg25_loop:
	s_waitcnt vmcnt(8)
	s_barrier
	ds_read_b128 v[64:67], v252 offset:0
	ds_read_b128 v[104:107], v254 offset:32768
	ds_read_b128 v[108:111], v254 offset:34816
	ds_read_b128 v[112:115], v254 offset:36864
	ds_read_b128 v[116:119], v254 offset:38912
	ds_read_b128 v[68:71], v252 offset:2048
	ds_read_b128 v[72:75], v252 offset:4096
	ds_read_b128 v[76:79], v252 offset:6144
	ds_read_b128 v[80:83], v253 offset:0
	ds_read_b128 v[120:123], v255 offset:32768
	ds_read_b128 v[124:127], v255 offset:34816
	ds_read_b128 v[132:135], v255 offset:36864
	ds_read_b128 v[136:139], v255 offset:38912
	s_waitcnt lgkmcnt(11)
	v_mfma_f32_16x16x32_bf16 v[60:63], v[64:67], v[104:107], v[60:63]
	s_waitcnt lgkmcnt(10)
	v_mfma_f32_16x16x32_bf16 v[44:47], v[64:67], v[108:111], v[44:47]
	s_waitcnt lgkmcnt(9)
	v_mfma_f32_16x16x32_bf16 v[28:31], v[64:67], v[112:115], v[28:31]
	s_waitcnt lgkmcnt(8)
	v_mfma_f32_16x16x32_bf16 v[12:15], v[64:67], v[116:119], v[12:15]
	ds_read_b128 v[84:87], v253 offset:2048
	ds_read_b128 v[88:91], v253 offset:4096
	ds_read_b128 v[92:95], v253 offset:6144
	s_waitcnt lgkmcnt(10)
	v_mfma_f32_16x16x32_bf16 v[56:59], v[68:71], v[104:107], v[56:59]
	v_mfma_f32_16x16x32_bf16 v[40:43], v[68:71], v[108:111], v[40:43]
	v_mfma_f32_16x16x32_bf16 v[20:23], v[68:71], v[112:115], v[20:23]
	v_mfma_f32_16x16x32_bf16 v[4:7], v[68:71], v[116:119], v[4:7]
	s_waitcnt lgkmcnt(9)
	v_mfma_f32_16x16x32_bf16 v[52:55], v[72:75], v[104:107], v[52:55]
	v_mfma_f32_16x16x32_bf16 v[32:35], v[72:75], v[108:111], v[32:35]
	v_mfma_f32_16x16x32_bf16 v[16:19], v[72:75], v[112:115], v[16:19]
	v_mfma_f32_16x16x32_bf16 v[0:3], v[72:75], v[116:119], v[0:3]
	s_waitcnt lgkmcnt(8)
	v_mfma_f32_16x16x32_bf16 v[48:51], v[76:79], v[104:107], v[48:51]
	v_mfma_f32_16x16x32_bf16 v[36:39], v[76:79], v[108:111], v[36:39]
	v_mfma_f32_16x16x32_bf16 v[24:27], v[76:79], v[112:115], v[24:27]
	v_mfma_f32_16x16x32_bf16 v[8:11], v[76:79], v[116:119], v[8:11]
	s_waitcnt lgkmcnt(0)
	s_barrier
	s_add_u32 m0, s6, 0x0
	v_mfma_f32_16x16x32_bf16 v[60:63], v[80:83], v[120:123], v[60:63]
	global_load_lds_dwordx4 v248, s[40:41]
	v_mfma_f32_16x16x32_bf16 v[44:47], v[80:83], v[124:127], v[44:47]
	s_add_u32 m0, s6, 0x400
	v_mfma_f32_16x16x32_bf16 v[28:31], v[80:83], v[132:135], v[28:31]
	global_load_lds_dwordx4 v249, s[40:41]
	v_mfma_f32_16x16x32_bf16 v[12:15], v[80:83], v[136:139], v[12:15]
	s_add_u32 m0, s6, 0x800
	v_mfma_f32_16x16x32_bf16 v[56:59], v[84:87], v[120:123], v[56:59]
	global_load_lds_dwordx4 v250, s[40:41]
	v_mfma_f32_16x16x32_bf16 v[40:43], v[84:87], v[124:127], v[40:43]
	s_add_u32 m0, s6, 0xc00
	v_mfma_f32_16x16x32_bf16 v[20:23], v[84:87], v[132:135], v[20:23]
	global_load_lds_dwordx4 v251, s[40:41]
	v_mfma_f32_16x16x32_bf16 v[4:7], v[84:87], v[136:139], v[4:7]
	s_add_u32 m0, s6, 0x8000
	v_mfma_f32_16x16x32_bf16 v[52:55], v[88:91], v[120:123], v[52:55]
	global_load_lds_dwordx4 v248, s[48:49]
	v_mfma_f32_16x16x32_bf16 v[32:35], v[88:91], v[124:127], v[32:35]
	s_add_u32 m0, s6, 0x8400
	v_mfma_f32_16x16x32_bf16 v[16:19], v[88:91], v[132:135], v[16:19]
	global_load_lds_dwordx4 v249, s[48:49]
	v_mfma_f32_16x16x32_bf16 v[0:3], v[88:91], v[136:139], v[0:3]
	s_add_u32 m0, s6, 0x8800
	v_mfma_f32_16x16x32_bf16 v[48:51], v[92:95], v[120:123], v[48:51]
	global_load_lds_dwordx4 v250, s[48:49]
	v_mfma_f32_16x16x32_bf16 v[36:39], v[92:95], v[124:127], v[36:39]
	s_add_u32 m0, s6, 0x8c00
	v_mfma_f32_16x16x32_bf16 v[24:27], v[92:95], v[132:135], v[24:27]
	global_load_lds_dwordx4 v251, s[48:49]
	v_mfma_f32_16x16x32_bf16 v[8:11], v[92:95], v[136:139], v[8:11]
	s_add_u32 s40, s40, 0x80
	s_addc_u32 s41, s41, 0
	s_add_u32 s48, s48, 0x80
	s_addc_u32 s49, s49, 0
	s_waitcnt vmcnt(8)
	s_barrier
	ds_read_b128 v[64:67], v252 offset:16384
	ds_read_b128 v[104:107], v254 offset:49152
	ds_read_b128 v[108:111], v254 offset:51200
	ds_read_b128 v[112:115], v254 offset:53248
	ds_read_b128 v[116:119], v254 offset:55296
	ds_read_b128 v[68:71], v252 offset:18432
	ds_read_b128 v[72:75], v252 offset:20480
	ds_read_b128 v[76:79], v252 offset:22528
	ds_read_b128 v[80:83], v253 offset:16384
	ds_read_b128 v[120:123], v255 offset:49152
	ds_read_b128 v[124:127], v255 offset:51200
	ds_read_b128 v[132:135], v255 offset:53248
	ds_read_b128 v[136:139], v255 offset:55296
	s_waitcnt lgkmcnt(11)
	v_mfma_f32_16x16x32_bf16 v[60:63], v[64:67], v[104:107], v[60:63]
	s_waitcnt lgkmcnt(10)
	v_mfma_f32_16x16x32_bf16 v[44:47], v[64:67], v[108:111], v[44:47]
	s_waitcnt lgkmcnt(9)
	v_mfma_f32_16x16x32_bf16 v[28:31], v[64:67], v[112:115], v[28:31]
	s_waitcnt lgkmcnt(8)
	v_mfma_f32_16x16x32_bf16 v[12:15], v[64:67], v[116:119], v[12:15]
	ds_read_b128 v[84:87], v253 offset:18432
	ds_read_b128 v[88:91], v253 offset:20480
	ds_read_b128 v[92:95], v253 offset:22528
	s_waitcnt lgkmcnt(10)
	v_mfma_f32_16x16x32_bf16 v[56:59], v[68:71], v[104:107], v[56:59]
	v_mfma_f32_16x16x32_bf16 v[40:43], v[68:71], v[108:111], v[40:43]
	v_mfma_f32_16x16x32_bf16 v[20:23], v[68:71], v[112:115], v[20:23]
	v_mfma_f32_16x16x32_bf16 v[4:7], v[68:71], v[116:119], v[4:7]
	s_waitcnt lgkmcnt(9)
	v_mfma_f32_16x16x32_bf16 v[52:55], v[72:75], v[104:107], v[52:55]
	v_mfma_f32_16x16x32_bf16 v[32:35], v[72:75], v[108:111], v[32:35]
	v_mfma_f32_16x16x32_bf16 v[16:19], v[72:75], v[112:115], v[16:19]
	v_mfma_f32_16x16x32_bf16 v[0:3], v[72:75], v[116:119], v[0:3]
	s_waitcnt lgkmcnt(8)
	v_mfma_f32_16x16x32_bf16 v[48:51], v[76:79], v[104:107], v[48:51]
	v_mfma_f32_16x16x32_bf16 v[36:39], v[76:79], v[108:111], v[36:39]
	v_mfma_f32_16x16x32_bf16 v[24:27], v[76:79], v[112:115], v[24:27]
	v_mfma_f32_16x16x32_bf16 v[8:11], v[76:79], v[116:119], v[8:11]
	s_waitcnt lgkmcnt(0)
	s_barrier
	s_add_u32 m0, s6, 0x4000
	v_mfma_f32_16x16x32_bf16 v[60:63], v[80:83], v[120:123], v[60:63]
	global_load_lds_dwordx4 v248, s[40:41]
	v_mfma_f32_16x16x32_bf16 v[44:47], v[80:83], v[124:127], v[44:47]
	s_add_u32 m0, s6, 0x4400
	v_mfma_f32_16x16x32_bf16 v[28:31], v[80:83], v[132:135], v[28:31]
	global_load_lds_dwordx4 v249, s[40:41]
	v_mfma_f32_16x16x32_bf16 v[12:15], v[80:83], v[136:139], v[12:15]
	s_add_u32 m0, s6, 0x4800
	v_mfma_f32_16x16x32_bf16 v[56:59], v[84:87], v[120:123], v[56:59]
	global_load_lds_dwordx4 v250, s[40:41]
	v_mfma_f32_16x16x32_bf16 v[40:43], v[84:87], v[124:127], v[40:43]
	s_add_u32 m0, s6, 0x4c00
	v_mfma_f32_16x16x32_bf16 v[20:23], v[84:87], v[132:135], v[20:23]
	global_load_lds_dwordx4 v251, s[40:41]
	v_mfma_f32_16x16x32_bf16 v[4:7], v[84:87], v[136:139], v[4:7]
	s_add_u32 m0, s6, 0xc000
	v_mfma_f32_16x16x32_bf16 v[52:55], v[88:91], v[120:123], v[52:55]
	global_load_lds_dwordx4 v248, s[48:49]
	v_mfma_f32_16x16x32_bf16 v[32:35], v[88:91], v[124:127], v[32:35]
	s_add_u32 m0, s6, 0xc400
	v_mfma_f32_16x16x32_bf16 v[16:19], v[88:91], v[132:135], v[16:19]
	global_load_lds_dwordx4 v249, s[48:49]
	v_mfma_f32_16x16x32_bf16 v[0:3], v[88:91], v[136:139], v[0:3]
	s_add_u32 m0, s6, 0xc800
	v_mfma_f32_16x16x32_bf16 v[48:51], v[92:95], v[120:123], v[48:51]
	global_load_lds_dwordx4 v250, s[48:49]
	v_mfma_f32_16x16x32_bf16 v[36:39], v[92:95], v[124:127], v[36:39]
	s_add_u32 m0, s6, 0xcc00
	v_mfma_f32_16x16x32_bf16 v[24:27], v[92:95], v[132:135], v[24:27]
	global_load_lds_dwordx4 v251, s[48:49]
	v_mfma_f32_16x16x32_bf16 v[8:11], v[92:95], v[136:139], v[8:11]
	s_add_u32 s40, s40, 0x80
	s_addc_u32 s41, s41, 0
	s_add_u32 s48, s48, 0x80
	s_addc_u32 s49, s49, 0
	s_sub_u32 s32, s32, 1
	s_cmp_lg_u32 s32, 0
	s_cbranch_scc1 .Lg25_loop
	s_waitcnt vmcnt(8)
	s_barrier
	ds_read_b128 v[64:67], v252 offset:0
	ds_read_b128 v[104:107], v254 offset:32768
	ds_read_b128 v[108:111], v254 offset:34816
	ds_read_b128 v[112:115], v254 offset:36864
	ds_read_b128 v[116:119], v254 offset:38912
	ds_read_b128 v[68:71], v252 offset:2048
	ds_read_b128 v[72:75], v252 offset:4096
	ds_read_b128 v[76:79], v252 offset:6144
	ds_read_b128 v[80:83], v253 offset:0
	ds_read_b128 v[120:123], v255 offset:32768
	ds_read_b128 v[124:127], v255 offset:34816
	ds_read_b128 v[132:135], v255 offset:36864
	ds_read_b128 v[136:139], v255 offset:38912
	s_waitcnt lgkmcnt(11)
	v_mfma_f32_16x16x32_bf16 v[60:63], v[64:67], v[104:107], v[60:63]
	s_waitcnt lgkmcnt(10)
	v_mfma_f32_16x16x32_bf16 v[44:47], v[64:67], v[108:111], v[44:47]
	s_waitcnt lgkmcnt(9)
	v_mfma_f32_16x16x32_bf16 v[28:31], v[64:67], v[112:115], v[28:31]
	s_waitcnt lgkmcnt(8)
	v_mfma_f32_16x16x32_bf16 v[12:15], v[64:67], v[116:119], v[12:15]
	ds_read_b128 v[84:87], v253 offset:2048
	ds_read_b128 v[88:91], v253 offset:4096
	ds_read_b128 v[92:95], v253 offset:6144
	s_waitcnt lgkmcnt(10)
	v_mfma_f32_16x16x32_bf16 v[56:59], v[68:71], v[104:107], v[56:59]
	v_mfma_f32_16x16x32_bf16 v[40:43], v[68:71], v[108:111], v[40:43]
	v_mfma_f32_16x16x32_bf16 v[20:23], v[68:71], v[112:115], v[20:23]
	v_mfma_f32_16x16x32_bf16 v[4:7], v[68:71], v[116:119], v[4:7]
	s_waitcnt lgkmcnt(9)
	v_mfma_f32_16x16x32_bf16 v[52:55], v[72:75], v[104:107], v[52:55]
	v_mfma_f32_16x16x32_bf16 v[32:35], v[72:75], v[108:111], v[32:35]
	v_mfma_f32_16x16x32_bf16 v[16:19], v[72:75], v[112:115], v[16:19]
	v_mfma_f32_16x16x32_bf16 v[0:3], v[72:75], v[116:119], v[0:3]
	s_waitcnt lgkmcnt(8)
	v_mfma_f32_16x16x32_bf16 v[48:51], v[76:79], v[104:107], v[48:51]
	v_mfma_f32_16x16x32_bf16 v[36:39], v[76:79], v[108:111], v[36:39]
	v_mfma_f32_16x16x32_bf16 v[24:27], v[76:79], v[112:115], v[24:27]
	v_mfma_f32_16x16x32_bf16 v[8:11], v[76:79], v[116:119], v[8:11]
	s_waitcnt lgkmcnt(0)
	s_barrier
	v_mfma_f32_16x16x32_bf16 v[60:63], v[80:83], v[120:123], v[60:63]
	v_mfma_f32_16x16x32_bf16 v[44:47], v[80:83], v[124:127], v[44:47]
	v_mfma_f32_16x16x32_bf16 v[28:31], v[80:83], v[132:135], v[28:31]
	v_mfma_f32_16x16x32_bf16 v[12:15], v[80:83], v[136:139], v[12:15]
	v_mfma_f32_16x16x32_bf16 v[56:59], v[84:87], v[120:123], v[56:59]
	v_mfma_f32_16x16x32_bf16 v[40:43], v[84:87], v[124:127], v[40:43]
	v_mfma_f32_16x16x32_bf16 v[20:23], v[84:87], v[132:135], v[20:23]
	v_mfma_f32_16x16x32_bf16 v[4:7], v[84:87], v[136:139], v[4:7]
	v_mfma_f32_16x16x32_bf16 v[52:55], v[88:91], v[120:123], v[52:55]
	v_mfma_f32_16x16x32_bf16 v[32:35], v[88:91], v[124:127], v[32:35]
	v_mfma_f32_16x16x32_bf16 v[16:19], v[88:91], v[132:135], v[16:19]
	v_mfma_f32_16x16x32_bf16 v[0:3], v[88:91], v[136:139], v[0:3]
	v_mfma_f32_16x16x32_bf16 v[48:51], v[92:95], v[120:123], v[48:51]
	v_mfma_f32_16x16x32_bf16 v[36:39], v[92:95], v[124:127], v[36:39]
	v_mfma_f32_16x16x32_bf16 v[24:27], v[92:95], v[132:135], v[24:27]
	v_mfma_f32_16x16x32_bf16 v[8:11], v[92:95], v[136:139], v[8:11]
	s_waitcnt vmcnt(0)
	s_barrier
	ds_read_b128 v[64:67], v252 offset:16384
	ds_read_b128 v[104:107], v254 offset:49152
	ds_read_b128 v[108:111], v254 offset:51200
	ds_read_b128 v[112:115], v254 offset:53248
	ds_read_b128 v[116:119], v254 offset:55296
	ds_read_b128 v[68:71], v252 offset:18432
	ds_read_b128 v[72:75], v252 offset:20480
	ds_read_b128 v[76:79], v252 offset:22528
	ds_read_b128 v[80:83], v253 offset:16384
	ds_read_b128 v[120:123], v255 offset:49152
	ds_read_b128 v[124:127], v255 offset:51200
	ds_read_b128 v[132:135], v255 offset:53248
	ds_read_b128 v[136:139], v255 offset:55296
	s_waitcnt lgkmcnt(11)
	v_mfma_f32_16x16x32_bf16 v[60:63], v[64:67], v[104:107], v[60:63]
	s_waitcnt lgkmcnt(10)
	v_mfma_f32_16x16x32_bf16 v[44:47], v[64:67], v[108:111], v[44:47]
	s_waitcnt lgkmcnt(9)
	v_mfma_f32_16x16x32_bf16 v[28:31], v[64:67], v[112:115], v[28:31]
	s_waitcnt lgkmcnt(8)
	v_mfma_f32_16x16x32_bf16 v[12:15], v[64:67], v[116:119], v[12:15]
	ds_read_b128 v[84:87], v253 offset:18432
	ds_read_b128 v[88:91], v253 offset:20480
	ds_read_b128 v[92:95], v253 offset:22528
	s_waitcnt lgkmcnt(10)
	v_mfma_f32_16x16x32_bf16 v[56:59], v[68:71], v[104:107], v[56:59]
	v_mfma_f32_16x16x32_bf16 v[40:43], v[68:71], v[108:111], v[40:43]
	v_mfma_f32_16x16x32_bf16 v[20:23], v[68:71], v[112:115], v[20:23]
	v_mfma_f32_16x16x32_bf16 v[4:7], v[68:71], v[116:119], v[4:7]
	s_waitcnt lgkmcnt(9)
	v_mfma_f32_16x16x32_bf16 v[52:55], v[72:75], v[104:107], v[52:55]
	v_mfma_f32_16x16x32_bf16 v[32:35], v[72:75], v[108:111], v[32:35]
	v_mfma_f32_16x16x32_bf16 v[16:19], v[72:75], v[112:115], v[16:19]
	v_mfma_f32_16x16x32_bf16 v[0:3], v[72:75], v[116:119], v[0:3]
	s_waitcnt lgkmcnt(8)
	v_mfma_f32_16x16x32_bf16 v[48:51], v[76:79], v[104:107], v[48:51]
	v_mfma_f32_16x16x32_bf16 v[36:39], v[76:79], v[108:111], v[36:39]
	v_mfma_f32_16x16x32_bf16 v[24:27], v[76:79], v[112:115], v[24:27]
	v_mfma_f32_16x16x32_bf16 v[8:11], v[76:79], v[116:119], v[8:11]
	s_waitcnt lgkmcnt(0)
	s_barrier
	v_mfma_f32_16x16x32_bf16 v[60:63], v[80:83], v[120:123], v[60:63]
	v_mfma_f32_16x16x32_bf16 v[44:47], v[80:83], v[124:127], v[44:47]
	v_mfma_f32_16x16x32_bf16 v[28:31], v[80:83], v[132:135], v[28:31]
	v_mfma_f32_16x16x32_bf16 v[12:15], v[80:83], v[136:139], v[12:15]
	v_mfma_f32_16x16x32_bf16 v[56:59], v[84:87], v[120:123], v[56:59]
	v_mfma_f32_16x16x32_bf16 v[40:43], v[84:87], v[124:127], v[40:43]
	v_mfma_f32_16x16x32_bf16 v[20:23], v[84:87], v[132:135], v[20:23]
	v_mfma_f32_16x16x32_bf16 v[4:7], v[84:87], v[136:139], v[4:7]
	v_mfma_f32_16x16x32_bf16 v[52:55], v[88:91], v[120:123], v[52:55]
	v_mfma_f32_16x16x32_bf16 v[32:35], v[88:91], v[124:127], v[32:35]
	v_mfma_f32_16x16x32_bf16 v[16:19], v[88:91], v[132:135], v[16:19]
	v_mfma_f32_16x16x32_bf16 v[0:3], v[88:91], v[136:139], v[0:3]
	v_mfma_f32_16x16x32_bf16 v[48:51], v[92:95], v[120:123], v[48:51]
	v_mfma_f32_16x16x32_bf16 v[36:39], v[92:95], v[124:127], v[36:39]
	v_mfma_f32_16x16x32_bf16 v[24:27], v[92:95], v[132:135], v[24:27]
	v_mfma_f32_16x16x32_bf16 v[8:11], v[92:95], v[136:139], v[8:11]
	s_nop 7
	s_nop 1
	v_sub_co_u32_e32 v64, vcc, s37, v150
	s_nop 0
	v_readfirstlane_b32 s6, v64
	s_lshr_b32 s6, s6, 10
	s_add_i32 s6, s6, 1
	s_and_b64 s[40:41], vcc, exec
	s_cselect_b32 s6, 0, s6
	s_mul_hi_u32 s39, s6, 0x6000
	s_mulk_i32 s6, 0x6000
	v_or_b32_e32 v64, s38, v147
	s_add_u32 s40, s2, s6
	v_ashrrev_i32_e32 v65, 31, v64
	s_addc_u32 s41, s3, s39
	v_add_lshl_u32 v94, v148, s37, 12
	v_lshlrev_b64 v[66:67], 2, v[64:65]
	v_lshl_add_u64 v[102:103], s[40:41], 0, v[66:67]
	v_lshl_add_u64 v[134:135], s[4:5], 0, v[66:67]
	v_mov_b32_e32 v95, v97
	v_or_b32_e32 v66, 0x1000, v94
	v_mov_b32_e32 v67, v97
	v_lshl_add_u64 v[104:105], v[134:135], 0, v[94:95]
	global_load_dword v65, v[102:103], off
	global_load_dword v151, v[104:105], off
	v_lshl_add_u64 v[106:107], v[134:135], 0, v[66:67]
	v_or_b32_e32 v68, 0x2000, v94
	v_mov_b32_e32 v69, v97
	v_or_b32_e32 v70, 0x3000, v94
	v_mov_b32_e32 v71, v97
	v_or_b32_e32 v72, 0x10000, v94
	v_mov_b32_e32 v73, v97
	global_load_dword v152, v[106:107], off
	v_lshl_add_u64 v[108:109], v[134:135], 0, v[68:69]
	v_lshl_add_u64 v[110:111], v[134:135], 0, v[70:71]
	v_lshl_add_u64 v[112:113], v[134:135], 0, v[72:73]
	v_or_b32_e32 v74, 0x11000, v94
	v_mov_b32_e32 v75, v97
	global_load_dword v153, v[108:109], off
	global_load_dword v154, v[110:111], off
	global_load_dword v155, v[112:113], off
	v_lshl_add_u64 v[114:115], v[134:135], 0, v[74:75]
	v_or_b32_e32 v76, 0x12000, v94
	v_mov_b32_e32 v77, v97
	v_or_b32_e32 v78, 0x13000, v94
	v_mov_b32_e32 v79, v97
	v_or_b32_e32 v80, 0x20000, v94
	v_mov_b32_e32 v81, v97
	global_load_dword v156, v[114:115], off
	v_or_b32_e32 v96, 0x30000, v94
	v_lshl_add_u64 v[116:117], v[134:135], 0, v[76:77]
	v_lshl_add_u64 v[118:119], v[134:135], 0, v[78:79]
	v_lshl_add_u64 v[120:121], v[134:135], 0, v[80:81]
	v_or_b32_e32 v82, 0x21000, v94
	v_mov_b32_e32 v83, v97
	global_load_dword v157, v[116:117], off
	global_load_dword v158, v[118:119], off
	global_load_dword v159, v[120:121], off
	v_lshl_add_u64 v[122:123], v[134:135], 0, v[82:83]
	v_or_b32_e32 v84, 0x22000, v94
	v_mov_b32_e32 v85, v97
	v_or_b32_e32 v86, 0x23000, v94
	v_mov_b32_e32 v87, v97
	v_lshl_add_u64 v[128:129], v[134:135], 0, v[96:97]
	v_lshl_add_u64 v[124:125], v[134:135], 0, v[84:85]
	v_lshl_add_u64 v[126:127], v[134:135], 0, v[86:87]
	global_load_dword v160, v[122:123], off
	global_load_dword v161, v[124:125], off
	global_load_dword v164, v[126:127], off
	global_load_dword v165, v[128:129], off
	v_or_b32_e32 v88, 0x31000, v94
	v_mov_b32_e32 v89, v97
	v_lshl_add_u64 v[130:131], v[134:135], 0, v[88:89]
	v_or_b32_e32 v90, 0x32000, v94
	v_mov_b32_e32 v91, v97
	v_or_b32_e32 v92, 0x33000, v94
	v_mov_b32_e32 v93, v97
	v_lshl_add_u64 v[132:133], v[134:135], 0, v[90:91]
	v_lshl_add_u64 v[134:135], v[134:135], 0, v[92:93]
	global_load_dword v166, v[130:131], off
	global_load_dword v167, v[132:133], off
	global_load_dword v168, v[134:135], off
	v_or_b32_e32 v136, 16, v64
	v_ashrrev_i32_e32 v137, 31, v136
	v_lshlrev_b64 v[136:137], 2, v[136:137]
	v_lshl_add_u64 v[94:95], s[4:5], 0, v[94:95]
	global_load_dword v169, v[102:103], off offset:64
	v_lshl_add_u64 v[140:141], s[4:5], 0, v[136:137]
	v_lshl_add_u64 v[136:137], v[94:95], 0, v[136:137]
	v_add_f32_e32 v60, 0, v60
	v_lshl_add_u64 v[138:139], v[140:141], 0, v[66:67]
	global_load_dword v170, v[136:137], off
	global_load_dword v171, v[138:139], off
	global_load_dword v172, v[102:103], off offset:128
	global_load_dword v173, v[102:103], off offset:192
	v_lshl_add_u64 v[102:103], v[140:141], 0, v[68:69]
	global_load_dword v174, v[102:103], off
	v_add_f32_e32 v56, 0, v56
	v_add_f32_e32 v58, 0, v58
	v_add_f32_e32 v52, 0, v52
	v_add_f32_e32 v48, 0, v48
	v_add_f32_e32 v44, 0, v44
	v_add_f32_e32 v50, 0, v50
	v_add_f32_e32 v32, 0, v32
	v_add_f32_e32 v34, 0, v34
	v_add_f32_e32 v40, 0, v40
	v_add_f32_e32 v38, 0, v38
	v_add_f32_e32 v36, 0, v36
	v_add_f32_e32 v28, 0, v28
	v_add_f32_e32 v30, 0, v30
	v_add_f32_e32 v20, 0, v20
	s_waitcnt vmcnt(21)
	v_fmac_f32_e32 v151, v60, v65
	v_add_f32_e32 v60, 0, v61
	global_store_dword v[104:105], v151, off
	v_lshl_add_u64 v[104:105], v[140:141], 0, v[72:73]
	v_add_f32_e32 v16, 0, v16
	v_add_f32_e32 v0, 0, v0
	v_add_f32_e32 v12, 0, v12
	v_add_f32_e32 v4, 0, v4
	s_waitcnt vmcnt(21)
	v_fmac_f32_e32 v152, v60, v65
	v_add_f32_e32 v60, 0, v62
	v_add_f32_e32 v62, 0, v63
	global_store_dword v[106:107], v152, off
	v_lshl_add_u64 v[106:107], v[140:141], 0, v[76:77]
	global_load_dword v152, v[104:105], off
	s_waitcnt vmcnt(22)
	v_fmac_f32_e32 v153, v60, v65
	global_store_dword v[108:109], v153, off
	s_waitcnt vmcnt(21)
	v_fmac_f32_e32 v155, v56, v65
	v_add_f32_e32 v56, 0, v57
	v_lshl_add_u64 v[108:109], v[140:141], 0, v[80:81]
	v_lshl_add_u64 v[60:61], v[140:141], 0, v[70:71]
	global_store_dword v[112:113], v155, off
	v_add_f32_e32 v112, 0, v59
	v_fmac_f32_e32 v154, v62, v65
	global_store_dword v[110:111], v154, off
	s_waitcnt vmcnt(22)
	v_fmac_f32_e32 v156, v56, v65
	global_store_dword v[114:115], v156, off
	global_load_dword v156, v[108:109], off
	v_lshl_add_u64 v[62:63], v[140:141], 0, v[74:75]
	global_load_dword v151, v[60:61], off
	global_load_dword v154, v[106:107], off
	v_lshl_add_u64 v[110:111], v[140:141], 0, v[82:83]
	s_waitcnt vmcnt(25)
	v_fmac_f32_e32 v157, v58, v65
	v_lshl_add_u64 v[58:59], v[140:141], 0, v[84:85]
	s_waitcnt vmcnt(23)
	v_fmac_f32_e32 v159, v52, v65
	v_add_f32_e32 v52, 0, v53
	global_store_dword v[116:117], v157, off
	global_load_dword v157, v[58:59], off
	v_fmac_f32_e32 v158, v112, v65
	v_lshl_add_u64 v[112:113], v[140:141], 0, v[86:87]
	global_load_dword v176, v[112:113], off
	s_waitcnt vmcnt(25)
	v_fmac_f32_e32 v160, v52, v65
	v_add_f32_e32 v52, 0, v54
	s_waitcnt vmcnt(24)
	v_fmac_f32_e32 v161, v52, v65
	s_waitcnt vmcnt(22)
	v_fmac_f32_e32 v165, v48, v65
	v_add_f32_e32 v48, 0, v49
	v_lshl_add_u64 v[52:53], v[140:141], 0, v[90:91]
	v_lshl_add_u64 v[114:115], v[140:141], 0, v[96:97]
	global_store_dword v[120:121], v159, off
	global_load_dword v120, v[52:53], off
	v_lshl_add_u64 v[56:57], v[140:141], 0, v[78:79]
	global_load_dword v175, v[110:111], off
	global_load_dword v155, v[56:57], off
	s_waitcnt vmcnt(25)
	v_fmac_f32_e32 v166, v48, v65
	v_lshl_add_u64 v[48:49], v[140:141], 0, v[92:93]
	global_load_dword v121, v[48:49], off
	s_waitcnt vmcnt(25)
	v_fmac_f32_e32 v167, v50, v65
	global_store_dword v[118:119], v158, off
	global_load_dword v118, v[114:115], off
	v_add_f32_e32 v50, 0, v51
	global_load_dword v153, v[62:63], off
	s_waitcnt vmcnt(25)
	v_fmac_f32_e32 v170, v44, v169
	v_add_f32_e32 v44, 0, v45
	s_waitcnt vmcnt(24)
	v_fmac_f32_e32 v171, v44, v169
	v_add_f32_e32 v44, 0, v46
	v_add_f32_e32 v54, 0, v55
	s_waitcnt vmcnt(21)
	v_fmac_f32_e32 v174, v44, v169
	v_or_b32_e32 v44, 32, v64
	v_ashrrev_i32_e32 v45, 31, v44
	v_lshlrev_b64 v[44:45], 2, v[44:45]
	v_fmac_f32_e32 v168, v50, v65
	v_lshl_add_u64 v[50:51], v[94:95], 0, v[44:45]
	v_lshl_add_u64 v[44:45], s[4:5], 0, v[44:45]
	v_fmac_f32_e32 v164, v54, v65
	v_lshl_add_u64 v[54:55], v[44:45], 0, v[78:79]
	v_add_f32_e32 v46, 0, v47
	v_lshl_add_u64 v[116:117], v[140:141], 0, v[88:89]
	global_load_dword v119, v[116:117], off
	v_or_b32_e32 v64, 48, v64
	global_store_dword v[102:103], v174, off
	v_ashrrev_i32_e32 v65, 31, v64
	v_lshlrev_b64 v[64:65], 2, v[64:65]
	global_store_dword v[122:123], v160, off
	global_store_dword v[124:125], v161, off
	global_store_dword v[126:127], v164, off
	global_store_dword v[128:129], v165, off
	global_store_dword v[130:131], v166, off
	global_store_dword v[132:133], v167, off
	global_store_dword v[134:135], v168, off
	global_store_dword v[136:137], v170, off
	global_store_dword v[138:139], v171, off
	v_lshl_add_u64 v[94:95], v[94:95], 0, v[64:65]
	v_lshl_add_u64 v[64:65], s[4:5], 0, v[64:65]
	v_add_f32_e32 v21, 0, v21
	s_waitcnt vmcnt(29)
	v_fmac_f32_e32 v152, v40, v169
	v_add_f32_e32 v40, 0, v41
	global_store_dword v[104:105], v152, off
	s_add_i32 s36, s36, s30
	s_cmpk_gt_i32 s36, 0x1ff
	s_waitcnt vmcnt(25)
	v_fmac_f32_e32 v156, v32, v169
	global_store_dword v[108:109], v156, off
	global_load_dword v109, v[54:55], off
	s_waitcnt vmcnt(26)
	v_fmac_f32_e32 v151, v46, v169
	v_lshl_add_u64 v[46:47], v[44:45], 0, v[66:67]
	global_load_dword v102, v[50:51], off
	global_load_dword v103, v[46:47], off
	v_add_f32_e32 v32, 0, v33
	global_store_dword v[60:61], v151, off
	v_lshl_add_u64 v[60:61], v[44:45], 0, v[88:89]
	s_waitcnt vmcnt(26)
	v_fmac_f32_e32 v157, v34, v169
	global_store_dword v[58:59], v157, off
	v_add_f32_e32 v34, 0, v35
	v_add_f32_e32 v58, 0, v39
	s_waitcnt vmcnt(26)
	v_fmac_f32_e32 v176, v34, v169
	global_store_dword v[112:113], v176, off
	v_lshl_add_u64 v[34:35], v[44:45], 0, v[72:73]
	v_lshl_add_u64 v[66:67], v[64:65], 0, v[66:67]
	s_waitcnt vmcnt(25)
	v_fmac_f32_e32 v120, v38, v169
	global_store_dword v[52:53], v120, off
	s_waitcnt vmcnt(25)
	v_fmac_f32_e32 v175, v32, v169
	v_lshl_add_u64 v[52:53], v[44:45], 0, v[82:83]
	global_store_dword v[110:111], v175, off
	v_lshl_add_u64 v[32:33], v[44:45], 0, v[70:71]
	s_waitcnt vmcnt(24)
	v_fmac_f32_e32 v121, v58, v169
	v_lshl_add_u64 v[58:59], v[44:45], 0, v[86:87]
	global_load_dword v113, v[58:59], off
	global_load_dword v111, v[52:53], off
	s_waitcnt vmcnt(24)
	v_fmac_f32_e32 v118, v36, v169
	s_waitcnt vmcnt(23)
	v_fmac_f32_e32 v153, v40, v169
	v_add_f32_e32 v40, 0, v42
	v_add_f32_e32 v42, 0, v43
	v_fmac_f32_e32 v155, v42, v169
	global_store_dword v[56:57], v155, off
	v_lshl_add_u64 v[56:57], v[44:45], 0, v[80:81]
	global_store_dword v[114:115], v118, off
	global_load_dword v110, v[56:57], off
	global_load_dword v105, v[32:33], off
	v_add_f32_e32 v36, 0, v37
	global_load_dword v115, v[60:61], off
	v_fmac_f32_e32 v154, v40, v169
	v_lshl_add_u64 v[40:41], v[44:45], 0, v[68:69]
	global_load_dword v104, v[40:41], off
	v_lshl_add_u64 v[42:43], v[44:45], 0, v[76:77]
	global_store_dword v[106:107], v154, off
	global_load_dword v106, v[34:35], off
	s_waitcnt vmcnt(30)
	v_fmac_f32_e32 v119, v36, v169
	global_store_dword v[48:49], v121, off
	v_lshl_add_u64 v[48:49], v[44:45], 0, v[96:97]
	global_store_dword v[62:63], v153, off
	v_lshl_add_u64 v[36:37], v[44:45], 0, v[74:75]
	global_store_dword v[116:117], v119, off
	v_lshl_add_u64 v[38:39], v[44:45], 0, v[84:85]
	global_load_dword v114, v[48:49], off
	v_lshl_add_u64 v[62:63], v[44:45], 0, v[90:91]
	global_load_dword v107, v[36:37], off
	global_load_dword v108, v[42:43], off
	global_load_dword v112, v[38:39], off
	v_lshl_add_u64 v[44:45], v[44:45], 0, v[92:93]
	global_load_dword v116, v[62:63], off
	global_load_dword v117, v[44:45], off
	v_lshl_add_u64 v[68:69], v[64:65], 0, v[68:69]
	global_load_dword v120, v[68:69], off
	global_load_dword v118, v[94:95], off
	global_load_dword v119, v[66:67], off
	s_waitcnt vmcnt(28)
	v_fmac_f32_e32 v102, v28, v172
	global_store_dword v[50:51], v102, off
	v_lshl_add_u64 v[50:51], v[64:65], 0, v[70:71]
	v_add_f32_e32 v70, 0, v29
	v_lshl_add_u64 v[28:29], v[64:65], 0, v[72:73]
	s_waitcnt vmcnt(28)
	v_fmac_f32_e32 v103, v70, v172
	v_lshl_add_u64 v[70:71], v[64:65], 0, v[74:75]
	v_lshl_add_u64 v[72:73], v[64:65], 0, v[78:79]
	v_lshl_add_u64 v[74:75], v[64:65], 0, v[80:81]
	global_load_dword v122, v[70:71], off
	global_load_dword v123, v[72:73], off
	global_load_dword v124, v[74:75], off
	global_load_dword v102, v[50:51], off
	global_load_dword v121, v[28:29], off
	v_lshl_add_u64 v[78:79], v[64:65], 0, v[88:89]
	global_store_dword v[46:47], v103, off
	v_lshl_add_u64 v[46:47], v[64:65], 0, v[76:77]
	global_load_dword v103, v[46:47], off
	v_add_f32_e32 v76, 0, v31
	v_lshl_add_u64 v[80:81], v[64:65], 0, v[90:91]
	s_waitcnt vmcnt(25)
	v_fmac_f32_e32 v110, v16, v172
	s_waitcnt vmcnt(24)
	v_fmac_f32_e32 v105, v76, v172
	v_lshl_add_u64 v[76:77], v[64:65], 0, v[86:87]
	global_store_dword v[32:33], v105, off
	v_lshl_add_u64 v[32:33], v[64:65], 0, v[96:97]
	global_load_dword v86, v[78:79], off
	s_waitcnt vmcnt(24)
	v_fmac_f32_e32 v104, v30, v172
	global_store_dword v[40:41], v104, off
	v_lshl_add_u64 v[40:41], v[64:65], 0, v[82:83]
	global_load_dword v82, v[40:41], off
	v_lshl_add_u64 v[30:31], v[64:65], 0, v[84:85]
	global_load_dword v83, v[30:31], off
	global_load_dword v85, v[32:33], off
	global_load_dword v84, v[76:77], off
	s_waitcnt vmcnt(27)
	v_fmac_f32_e32 v106, v20, v172
	global_load_dword v20, v[80:81], off
	v_add_f32_e32 v16, 0, v17
	global_store_dword v[34:35], v106, off
	v_lshl_add_u64 v[34:35], v[64:65], 0, v[92:93]
	global_load_dword v64, v[34:35], off
	v_fmac_f32_e32 v111, v16, v172
	v_add_f32_e32 v16, 0, v18
	s_waitcnt vmcnt(23)
	v_fmac_f32_e32 v112, v16, v172
	v_add_f32_e32 v16, 0, v19
	v_fmac_f32_e32 v113, v16, v172
	v_add_f32_e32 v16, 0, v24
	v_fmac_f32_e32 v114, v16, v172
	v_add_f32_e32 v16, 0, v25
	s_waitcnt vmcnt(19)
	v_fmac_f32_e32 v118, v12, v173
	v_add_f32_e32 v12, 0, v13
	v_fmac_f32_e32 v107, v21, v172
	v_add_f32_e32 v21, 0, v22
	v_fmac_f32_e32 v115, v16, v172
	v_add_f32_e32 v16, 0, v26
	s_waitcnt vmcnt(18)
	v_fmac_f32_e32 v119, v12, v173
	v_add_f32_e32 v12, 0, v14
	v_fmac_f32_e32 v108, v21, v172
	v_add_f32_e32 v21, 0, v23
	v_fmac_f32_e32 v116, v16, v172
	v_add_f32_e32 v16, 0, v27
	v_fmac_f32_e32 v120, v12, v173
	v_add_f32_e32 v12, 0, v15
	v_fmac_f32_e32 v109, v21, v172
	v_fmac_f32_e32 v117, v16, v172
	global_store_dword v[36:37], v107, off
	global_store_dword v[42:43], v108, off
	global_store_dword v[54:55], v109, off
	global_store_dword v[56:57], v110, off
	global_store_dword v[52:53], v111, off
	global_store_dword v[38:39], v112, off
	global_store_dword v[58:59], v113, off
	global_store_dword v[48:49], v114, off
	global_store_dword v[60:61], v115, off
	global_store_dword v[62:63], v116, off
	global_store_dword v[44:45], v117, off
	global_store_dword v[94:95], v118, off
	s_waitcnt vmcnt(26)
	v_fmac_f32_e32 v124, v0, v173
	v_add_f32_e32 v0, 0, v1
	s_waitcnt vmcnt(24)
	v_fmac_f32_e32 v121, v4, v173
	v_add_f32_e32 v4, 0, v5
	v_fmac_f32_e32 v122, v4, v173
	v_add_f32_e32 v4, 0, v6
	s_waitcnt vmcnt(22)
	v_fmac_f32_e32 v103, v4, v173
	v_add_f32_e32 v4, 0, v7
	v_fmac_f32_e32 v102, v12, v173
	v_fmac_f32_e32 v123, v4, v173
	global_store_dword v[66:67], v119, off
	global_store_dword v[68:69], v120, off
	global_store_dword v[50:51], v102, off
	global_store_dword v[28:29], v121, off
	global_store_dword v[70:71], v122, off
	global_store_dword v[46:47], v103, off
	global_store_dword v[72:73], v123, off
	global_store_dword v[74:75], v124, off
	s_waitcnt vmcnt(26)
	v_fmac_f32_e32 v82, v0, v173
	v_add_f32_e32 v0, 0, v2
	s_waitcnt vmcnt(25)
	v_fmac_f32_e32 v83, v0, v173
	v_add_f32_e32 v0, 0, v3
	s_waitcnt vmcnt(23)
	v_fmac_f32_e32 v84, v0, v173
	v_add_f32_e32 v0, 0, v8
	v_fmac_f32_e32 v85, v0, v173
	v_add_f32_e32 v0, 0, v9
	v_fmac_f32_e32 v86, v0, v173
	v_add_f32_e32 v0, 0, v10
	s_waitcnt vmcnt(22)
	v_fmac_f32_e32 v20, v0, v173
	v_add_f32_e32 v0, 0, v11
	s_waitcnt vmcnt(20)
	v_fmac_f32_e32 v64, v0, v173
	global_store_dword v[40:41], v82, off
	global_store_dword v[30:31], v83, off
	global_store_dword v[76:77], v84, off
	global_store_dword v[32:33], v85, off
	global_store_dword v[78:79], v86, off
	global_store_dword v[80:81], v20, off
	global_store_dword v[34:35], v64, off
	s_cbranch_scc0 .LBB0_2477

.Lg29_loop:
	s_waitcnt vmcnt(8)
	s_barrier
	ds_read_b128 v[64:67], v252 offset:0
	ds_read_b128 v[104:107], v254 offset:32768
	ds_read_b128 v[108:111], v254 offset:34816
	ds_read_b128 v[112:115], v254 offset:36864
	ds_read_b128 v[116:119], v254 offset:38912
	ds_read_b128 v[68:71], v252 offset:2048
	ds_read_b128 v[72:75], v252 offset:4096
	ds_read_b128 v[76:79], v252 offset:6144
	ds_read_b128 v[80:83], v253 offset:0
	ds_read_b128 v[120:123], v255 offset:32768
	ds_read_b128 v[124:127], v255 offset:34816
	ds_read_b128 v[132:135], v255 offset:36864
	ds_read_b128 v[144:147], v255 offset:38912
	s_waitcnt lgkmcnt(11)
	v_mfma_f32_16x16x32_bf16 v[60:63], v[64:67], v[104:107], v[60:63]
	s_waitcnt lgkmcnt(10)
	v_mfma_f32_16x16x32_bf16 v[40:43], v[64:67], v[108:111], v[40:43]
	s_waitcnt lgkmcnt(9)
	v_mfma_f32_16x16x32_bf16 v[24:27], v[64:67], v[112:115], v[24:27]
	s_waitcnt lgkmcnt(8)
	v_mfma_f32_16x16x32_bf16 v[8:11], v[64:67], v[116:119], v[8:11]
	ds_read_b128 v[84:87], v253 offset:2048
	ds_read_b128 v[88:91], v253 offset:4096
	ds_read_b128 v[92:95], v253 offset:6144
	s_waitcnt lgkmcnt(10)
	v_mfma_f32_16x16x32_bf16 v[56:59], v[68:71], v[104:107], v[56:59]
	v_mfma_f32_16x16x32_bf16 v[36:39], v[68:71], v[108:111], v[36:39]
	v_mfma_f32_16x16x32_bf16 v[20:23], v[68:71], v[112:115], v[20:23]
	v_mfma_f32_16x16x32_bf16 v[0:3], v[68:71], v[116:119], v[0:3]
	s_waitcnt lgkmcnt(9)
	v_mfma_f32_16x16x32_bf16 v[48:51], v[72:75], v[104:107], v[48:51]
	v_mfma_f32_16x16x32_bf16 v[32:35], v[72:75], v[108:111], v[32:35]
	v_mfma_f32_16x16x32_bf16 v[16:19], v[72:75], v[112:115], v[16:19]
	v_mfma_f32_16x16x32_bf16 v[4:7], v[72:75], v[116:119], v[4:7]
	s_waitcnt lgkmcnt(8)
	v_mfma_f32_16x16x32_bf16 v[52:55], v[76:79], v[104:107], v[52:55]
	v_mfma_f32_16x16x32_bf16 v[44:47], v[76:79], v[108:111], v[44:47]
	v_mfma_f32_16x16x32_bf16 v[28:31], v[76:79], v[112:115], v[28:31]
	v_mfma_f32_16x16x32_bf16 v[12:15], v[76:79], v[116:119], v[12:15]
	s_waitcnt lgkmcnt(0)
	s_barrier
	s_add_u32 m0, s5, 0x0
	v_mfma_f32_16x16x32_bf16 v[60:63], v[80:83], v[120:123], v[60:63]
	global_load_lds_dwordx4 v248, s[44:45]
	v_mfma_f32_16x16x32_bf16 v[40:43], v[80:83], v[124:127], v[40:43]
	s_add_u32 m0, s5, 0x400
	v_mfma_f32_16x16x32_bf16 v[24:27], v[80:83], v[132:135], v[24:27]
	global_load_lds_dwordx4 v249, s[44:45]
	v_mfma_f32_16x16x32_bf16 v[8:11], v[80:83], v[144:147], v[8:11]
	s_add_u32 m0, s5, 0x800
	v_mfma_f32_16x16x32_bf16 v[56:59], v[84:87], v[120:123], v[56:59]
	global_load_lds_dwordx4 v250, s[44:45]
	v_mfma_f32_16x16x32_bf16 v[36:39], v[84:87], v[124:127], v[36:39]
	s_add_u32 m0, s5, 0xc00
	v_mfma_f32_16x16x32_bf16 v[20:23], v[84:87], v[132:135], v[20:23]
	global_load_lds_dwordx4 v251, s[44:45]
	v_mfma_f32_16x16x32_bf16 v[0:3], v[84:87], v[144:147], v[0:3]
	s_add_u32 m0, s5, 0x8000
	v_mfma_f32_16x16x32_bf16 v[48:51], v[88:91], v[120:123], v[48:51]
	global_load_lds_dwordx4 v248, s[48:49]
	v_mfma_f32_16x16x32_bf16 v[32:35], v[88:91], v[124:127], v[32:35]
	s_add_u32 m0, s5, 0x8400
	v_mfma_f32_16x16x32_bf16 v[16:19], v[88:91], v[132:135], v[16:19]
	global_load_lds_dwordx4 v249, s[48:49]
	v_mfma_f32_16x16x32_bf16 v[4:7], v[88:91], v[144:147], v[4:7]
	s_add_u32 m0, s5, 0x8800
	v_mfma_f32_16x16x32_bf16 v[52:55], v[92:95], v[120:123], v[52:55]
	global_load_lds_dwordx4 v250, s[48:49]
	v_mfma_f32_16x16x32_bf16 v[44:47], v[92:95], v[124:127], v[44:47]
	s_add_u32 m0, s5, 0x8c00
	v_mfma_f32_16x16x32_bf16 v[28:31], v[92:95], v[132:135], v[28:31]
	global_load_lds_dwordx4 v251, s[48:49]
	v_mfma_f32_16x16x32_bf16 v[12:15], v[92:95], v[144:147], v[12:15]
	s_add_u32 s44, s44, 0x80
	s_addc_u32 s45, s45, 0
	s_add_u32 s48, s48, 0x80
	s_addc_u32 s49, s49, 0
	s_waitcnt vmcnt(8)
	s_barrier
	ds_read_b128 v[64:67], v252 offset:16384
	ds_read_b128 v[104:107], v254 offset:49152
	ds_read_b128 v[108:111], v254 offset:51200
	ds_read_b128 v[112:115], v254 offset:53248
	ds_read_b128 v[116:119], v254 offset:55296
	ds_read_b128 v[68:71], v252 offset:18432
	ds_read_b128 v[72:75], v252 offset:20480
	ds_read_b128 v[76:79], v252 offset:22528
	ds_read_b128 v[80:83], v253 offset:16384
	ds_read_b128 v[120:123], v255 offset:49152
	ds_read_b128 v[124:127], v255 offset:51200
	ds_read_b128 v[132:135], v255 offset:53248
	ds_read_b128 v[144:147], v255 offset:55296
	s_waitcnt lgkmcnt(11)
	v_mfma_f32_16x16x32_bf16 v[60:63], v[64:67], v[104:107], v[60:63]
	s_waitcnt lgkmcnt(10)
	v_mfma_f32_16x16x32_bf16 v[40:43], v[64:67], v[108:111], v[40:43]
	s_waitcnt lgkmcnt(9)
	v_mfma_f32_16x16x32_bf16 v[24:27], v[64:67], v[112:115], v[24:27]
	s_waitcnt lgkmcnt(8)
	v_mfma_f32_16x16x32_bf16 v[8:11], v[64:67], v[116:119], v[8:11]
	ds_read_b128 v[84:87], v253 offset:18432
	ds_read_b128 v[88:91], v253 offset:20480
	ds_read_b128 v[92:95], v253 offset:22528
	s_waitcnt lgkmcnt(10)
	v_mfma_f32_16x16x32_bf16 v[56:59], v[68:71], v[104:107], v[56:59]
	v_mfma_f32_16x16x32_bf16 v[36:39], v[68:71], v[108:111], v[36:39]
	v_mfma_f32_16x16x32_bf16 v[20:23], v[68:71], v[112:115], v[20:23]
	v_mfma_f32_16x16x32_bf16 v[0:3], v[68:71], v[116:119], v[0:3]
	s_waitcnt lgkmcnt(9)
	v_mfma_f32_16x16x32_bf16 v[48:51], v[72:75], v[104:107], v[48:51]
	v_mfma_f32_16x16x32_bf16 v[32:35], v[72:75], v[108:111], v[32:35]
	v_mfma_f32_16x16x32_bf16 v[16:19], v[72:75], v[112:115], v[16:19]
	v_mfma_f32_16x16x32_bf16 v[4:7], v[72:75], v[116:119], v[4:7]
	s_waitcnt lgkmcnt(8)
	v_mfma_f32_16x16x32_bf16 v[52:55], v[76:79], v[104:107], v[52:55]
	v_mfma_f32_16x16x32_bf16 v[44:47], v[76:79], v[108:111], v[44:47]
	v_mfma_f32_16x16x32_bf16 v[28:31], v[76:79], v[112:115], v[28:31]
	v_mfma_f32_16x16x32_bf16 v[12:15], v[76:79], v[116:119], v[12:15]
	s_waitcnt lgkmcnt(0)
	s_barrier
	s_add_u32 m0, s5, 0x4000
	v_mfma_f32_16x16x32_bf16 v[60:63], v[80:83], v[120:123], v[60:63]
	global_load_lds_dwordx4 v248, s[44:45]
	v_mfma_f32_16x16x32_bf16 v[40:43], v[80:83], v[124:127], v[40:43]
	s_add_u32 m0, s5, 0x4400
	v_mfma_f32_16x16x32_bf16 v[24:27], v[80:83], v[132:135], v[24:27]
	global_load_lds_dwordx4 v249, s[44:45]
	v_mfma_f32_16x16x32_bf16 v[8:11], v[80:83], v[144:147], v[8:11]
	s_add_u32 m0, s5, 0x4800
	v_mfma_f32_16x16x32_bf16 v[56:59], v[84:87], v[120:123], v[56:59]
	global_load_lds_dwordx4 v250, s[44:45]
	v_mfma_f32_16x16x32_bf16 v[36:39], v[84:87], v[124:127], v[36:39]
	s_add_u32 m0, s5, 0x4c00
	v_mfma_f32_16x16x32_bf16 v[20:23], v[84:87], v[132:135], v[20:23]
	global_load_lds_dwordx4 v251, s[44:45]
	v_mfma_f32_16x16x32_bf16 v[0:3], v[84:87], v[144:147], v[0:3]
	s_add_u32 m0, s5, 0xc000
	v_mfma_f32_16x16x32_bf16 v[48:51], v[88:91], v[120:123], v[48:51]
	global_load_lds_dwordx4 v248, s[48:49]
	v_mfma_f32_16x16x32_bf16 v[32:35], v[88:91], v[124:127], v[32:35]
	s_add_u32 m0, s5, 0xc400
	v_mfma_f32_16x16x32_bf16 v[16:19], v[88:91], v[132:135], v[16:19]
	global_load_lds_dwordx4 v249, s[48:49]
	v_mfma_f32_16x16x32_bf16 v[4:7], v[88:91], v[144:147], v[4:7]
	s_add_u32 m0, s5, 0xc800
	v_mfma_f32_16x16x32_bf16 v[52:55], v[92:95], v[120:123], v[52:55]
	global_load_lds_dwordx4 v250, s[48:49]
	v_mfma_f32_16x16x32_bf16 v[44:47], v[92:95], v[124:127], v[44:47]
	s_add_u32 m0, s5, 0xcc00
	v_mfma_f32_16x16x32_bf16 v[28:31], v[92:95], v[132:135], v[28:31]
	global_load_lds_dwordx4 v251, s[48:49]
	v_mfma_f32_16x16x32_bf16 v[12:15], v[92:95], v[144:147], v[12:15]
	s_add_u32 s44, s44, 0x80
	s_addc_u32 s45, s45, 0
	s_add_u32 s48, s48, 0x80
	s_addc_u32 s49, s49, 0
	s_sub_u32 s12, s12, 1
	s_cmp_lg_u32 s12, 0
	s_cbranch_scc1 .Lg29_loop
	s_waitcnt vmcnt(8)
	s_barrier
	ds_read_b128 v[64:67], v252 offset:0
	ds_read_b128 v[104:107], v254 offset:32768
	ds_read_b128 v[108:111], v254 offset:34816
	ds_read_b128 v[112:115], v254 offset:36864
	ds_read_b128 v[116:119], v254 offset:38912
	ds_read_b128 v[68:71], v252 offset:2048
	ds_read_b128 v[72:75], v252 offset:4096
	ds_read_b128 v[76:79], v252 offset:6144
	ds_read_b128 v[80:83], v253 offset:0
	ds_read_b128 v[120:123], v255 offset:32768
	ds_read_b128 v[124:127], v255 offset:34816
	ds_read_b128 v[132:135], v255 offset:36864
	ds_read_b128 v[144:147], v255 offset:38912
	s_waitcnt lgkmcnt(11)
	v_mfma_f32_16x16x32_bf16 v[60:63], v[64:67], v[104:107], v[60:63]
	s_waitcnt lgkmcnt(10)
	v_mfma_f32_16x16x32_bf16 v[40:43], v[64:67], v[108:111], v[40:43]
	s_waitcnt lgkmcnt(9)
	v_mfma_f32_16x16x32_bf16 v[24:27], v[64:67], v[112:115], v[24:27]
	s_waitcnt lgkmcnt(8)
	v_mfma_f32_16x16x32_bf16 v[8:11], v[64:67], v[116:119], v[8:11]
	ds_read_b128 v[84:87], v253 offset:2048
	ds_read_b128 v[88:91], v253 offset:4096
	ds_read_b128 v[92:95], v253 offset:6144
	s_waitcnt lgkmcnt(10)
	v_mfma_f32_16x16x32_bf16 v[56:59], v[68:71], v[104:107], v[56:59]
	v_mfma_f32_16x16x32_bf16 v[36:39], v[68:71], v[108:111], v[36:39]
	v_mfma_f32_16x16x32_bf16 v[20:23], v[68:71], v[112:115], v[20:23]
	v_mfma_f32_16x16x32_bf16 v[0:3], v[68:71], v[116:119], v[0:3]
	s_waitcnt lgkmcnt(9)
	v_mfma_f32_16x16x32_bf16 v[48:51], v[72:75], v[104:107], v[48:51]
	v_mfma_f32_16x16x32_bf16 v[32:35], v[72:75], v[108:111], v[32:35]
	v_mfma_f32_16x16x32_bf16 v[16:19], v[72:75], v[112:115], v[16:19]
	v_mfma_f32_16x16x32_bf16 v[4:7], v[72:75], v[116:119], v[4:7]
	s_waitcnt lgkmcnt(8)
	v_mfma_f32_16x16x32_bf16 v[52:55], v[76:79], v[104:107], v[52:55]
	v_mfma_f32_16x16x32_bf16 v[44:47], v[76:79], v[108:111], v[44:47]
	v_mfma_f32_16x16x32_bf16 v[28:31], v[76:79], v[112:115], v[28:31]
	v_mfma_f32_16x16x32_bf16 v[12:15], v[76:79], v[116:119], v[12:15]
	s_waitcnt lgkmcnt(0)
	s_barrier
	v_mfma_f32_16x16x32_bf16 v[60:63], v[80:83], v[120:123], v[60:63]
	v_mfma_f32_16x16x32_bf16 v[40:43], v[80:83], v[124:127], v[40:43]
	v_mfma_f32_16x16x32_bf16 v[24:27], v[80:83], v[132:135], v[24:27]
	v_mfma_f32_16x16x32_bf16 v[8:11], v[80:83], v[144:147], v[8:11]
	v_mfma_f32_16x16x32_bf16 v[56:59], v[84:87], v[120:123], v[56:59]
	v_mfma_f32_16x16x32_bf16 v[36:39], v[84:87], v[124:127], v[36:39]
	v_mfma_f32_16x16x32_bf16 v[20:23], v[84:87], v[132:135], v[20:23]
	v_mfma_f32_16x16x32_bf16 v[0:3], v[84:87], v[144:147], v[0:3]
	v_mfma_f32_16x16x32_bf16 v[48:51], v[88:91], v[120:123], v[48:51]
	v_mfma_f32_16x16x32_bf16 v[32:35], v[88:91], v[124:127], v[32:35]
	v_mfma_f32_16x16x32_bf16 v[16:19], v[88:91], v[132:135], v[16:19]
	v_mfma_f32_16x16x32_bf16 v[4:7], v[88:91], v[144:147], v[4:7]
	v_mfma_f32_16x16x32_bf16 v[52:55], v[92:95], v[120:123], v[52:55]
	v_mfma_f32_16x16x32_bf16 v[44:47], v[92:95], v[124:127], v[44:47]
	v_mfma_f32_16x16x32_bf16 v[28:31], v[92:95], v[132:135], v[28:31]
	v_mfma_f32_16x16x32_bf16 v[12:15], v[92:95], v[144:147], v[12:15]
	s_waitcnt vmcnt(0)
	s_barrier
	ds_read_b128 v[64:67], v252 offset:16384
	ds_read_b128 v[104:107], v254 offset:49152
	ds_read_b128 v[108:111], v254 offset:51200
	ds_read_b128 v[112:115], v254 offset:53248
	ds_read_b128 v[116:119], v254 offset:55296
	ds_read_b128 v[68:71], v252 offset:18432
	ds_read_b128 v[72:75], v252 offset:20480
	ds_read_b128 v[76:79], v252 offset:22528
	ds_read_b128 v[80:83], v253 offset:16384
	ds_read_b128 v[120:123], v255 offset:49152
	ds_read_b128 v[124:127], v255 offset:51200
	ds_read_b128 v[132:135], v255 offset:53248
	ds_read_b128 v[144:147], v255 offset:55296
	s_waitcnt lgkmcnt(11)
	v_mfma_f32_16x16x32_bf16 v[60:63], v[64:67], v[104:107], v[60:63]
	s_waitcnt lgkmcnt(10)
	v_mfma_f32_16x16x32_bf16 v[40:43], v[64:67], v[108:111], v[40:43]
	s_waitcnt lgkmcnt(9)
	v_mfma_f32_16x16x32_bf16 v[24:27], v[64:67], v[112:115], v[24:27]
	s_waitcnt lgkmcnt(8)
	v_mfma_f32_16x16x32_bf16 v[8:11], v[64:67], v[116:119], v[8:11]
	ds_read_b128 v[84:87], v253 offset:18432
	ds_read_b128 v[88:91], v253 offset:20480
	ds_read_b128 v[92:95], v253 offset:22528
	s_waitcnt lgkmcnt(10)
	v_mfma_f32_16x16x32_bf16 v[56:59], v[68:71], v[104:107], v[56:59]
	v_mfma_f32_16x16x32_bf16 v[36:39], v[68:71], v[108:111], v[36:39]
	v_mfma_f32_16x16x32_bf16 v[20:23], v[68:71], v[112:115], v[20:23]
	v_mfma_f32_16x16x32_bf16 v[0:3], v[68:71], v[116:119], v[0:3]
	s_waitcnt lgkmcnt(9)
	v_mfma_f32_16x16x32_bf16 v[48:51], v[72:75], v[104:107], v[48:51]
	v_mfma_f32_16x16x32_bf16 v[32:35], v[72:75], v[108:111], v[32:35]
	v_mfma_f32_16x16x32_bf16 v[16:19], v[72:75], v[112:115], v[16:19]
	v_mfma_f32_16x16x32_bf16 v[4:7], v[72:75], v[116:119], v[4:7]
	s_waitcnt lgkmcnt(8)
	v_mfma_f32_16x16x32_bf16 v[52:55], v[76:79], v[104:107], v[52:55]
	v_mfma_f32_16x16x32_bf16 v[44:47], v[76:79], v[108:111], v[44:47]
	v_mfma_f32_16x16x32_bf16 v[28:31], v[76:79], v[112:115], v[28:31]
	v_mfma_f32_16x16x32_bf16 v[12:15], v[76:79], v[116:119], v[12:15]
	s_waitcnt lgkmcnt(0)
	s_barrier
	v_mfma_f32_16x16x32_bf16 v[60:63], v[80:83], v[120:123], v[60:63]
	v_mfma_f32_16x16x32_bf16 v[40:43], v[80:83], v[124:127], v[40:43]
	v_mfma_f32_16x16x32_bf16 v[24:27], v[80:83], v[132:135], v[24:27]
	v_mfma_f32_16x16x32_bf16 v[8:11], v[80:83], v[144:147], v[8:11]
	v_mfma_f32_16x16x32_bf16 v[56:59], v[84:87], v[120:123], v[56:59]
	v_mfma_f32_16x16x32_bf16 v[36:39], v[84:87], v[124:127], v[36:39]
	v_mfma_f32_16x16x32_bf16 v[20:23], v[84:87], v[132:135], v[20:23]
	v_mfma_f32_16x16x32_bf16 v[0:3], v[84:87], v[144:147], v[0:3]
	v_mfma_f32_16x16x32_bf16 v[48:51], v[88:91], v[120:123], v[48:51]
	v_mfma_f32_16x16x32_bf16 v[32:35], v[88:91], v[124:127], v[32:35]
	v_mfma_f32_16x16x32_bf16 v[16:19], v[88:91], v[132:135], v[16:19]
	v_mfma_f32_16x16x32_bf16 v[4:7], v[88:91], v[144:147], v[4:7]
	v_mfma_f32_16x16x32_bf16 v[52:55], v[92:95], v[120:123], v[52:55]
	v_mfma_f32_16x16x32_bf16 v[44:47], v[92:95], v[124:127], v[44:47]
	v_mfma_f32_16x16x32_bf16 v[28:31], v[92:95], v[132:135], v[28:31]
	v_mfma_f32_16x16x32_bf16 v[12:15], v[92:95], v[144:147], v[12:15]
	s_nop 7
	s_nop 1
	v_sub_co_u32_e32 v64, vcc, s43, v141
	s_nop 0
	v_readfirstlane_b32 s5, v64
	s_lshr_b32 s5, s5, 10
	s_add_i32 s5, s5, 1
	s_and_b64 s[44:45], vcc, exec
	s_cselect_b32 s5, 0, s5
	s_mul_hi_u32 s12, s5, 0x6000
	s_mulk_i32 s5, 0x6000
	s_add_u32 s44, s2, s5
	v_or_b32_e32 v64, s4, v139
	s_addc_u32 s45, s3, s12
	v_ashrrev_i32_e32 v65, 31, v64
	v_lshl_add_u64 v[66:67], v[64:65], 2, s[44:45]
	global_load_dword v105, v[66:67], off
	s_waitcnt vmcnt(7)
	v_cndmask_b32_e64 v68, 0, 1, s[10:11]
	v_mov_b32_e32 v104, 0
	v_cmp_ne_u32_e64 s[4:5], 1, v68
	s_andn2_b64 vcc, exec, s[10:11]
	v_mov_b32_e32 v106, 0
	s_cbranch_vccnz .LBB0_2727
	v_lshl_add_u64 v[68:69], v[64:65], 2, s[6:7]
	global_load_dword v106, v[68:69], off
